# row phases: each wave takes 8 consecutive rows (one modulation vector pair per wave instead of one per row)
# baseline (speedup 1.0000x reference)
; DI const float* modp(const Frame& F, int l, int mr, int which) { return (const float*)(F.ws + WS_MOD) + ((size_t)(l * 9 + mr) * 6 + which) * 1024; }
; DI void ln_row_v(const Frame& F, f32x4 (&v)[4], float* xout, const float* g, const float* b, const float* sh, const float* sc, bf16_t* hout, const float* slab, const float* gres, float* stat = nullptr) {
;     ...
;     if (g) {
;         float s = 0.f, s2 = 0.f;
; #pragma unroll
;         for (int j = 0; j < 4; ++j) { s += (v[j][0] + v[j][1]) + (v[j][2] + v[j][3]); s2 += (v[j][0] * v[j][0] + v[j][1] * v[j][1]) + (v[j][2] * v[j][2] + v[j][3] * v[j][3]); }
;         wave_sum2(s, s2, F.lane);
;         const float mean = s * (1.f / D); const float rstd = 1.f / sqrtf(fmaxf(s2 * (1.f / D) - mean * mean, 0.f) + EPS);
; DI void ln_phase(const Frame& F, int which) {
;     const int gw = F.vcu * 8 + F.wave, NGW = F.G * 8; const int l = F.l;
;     const int nrows = (l == NL - 1) ? ML : MT;
;     bf16_t* H = (bf16_t*)(F.ws + WS_HB);
;     const float* g = pin(F, which == 0 ? I_LN1G : I_LN2G) + l * 1024; const float* b = pin(F, which == 0 ? I_LN1B : I_LN2B) + l * 1024;
;     const bool wh = !(which == 1 && l == NL - 1);
;     f32x4 vc[4], vn[4];
;     if (gw < nrows) ln_load(F, xrow_ptr(F, gw), vc);
;     for (int row = gw; row < nrows; row += NGW) {
;         if (row + NGW < nrows) ln_load(F, xrow_ptr(F, row + NGW), vn);
;         const int mr = row < ML ? (row >> 11) : 8;
;         const float* sh = which == 0 ? modp(F, l, mr, 3) : modp(F, l + 1 < NL ? l + 1 : l, mr, 0);
;         const float* sc = which == 0 ? modp(F, l, mr, 4) : modp(F, l + 1 < NL ? l + 1 : l, mr, 1);
;         const bool sl = (which == 1 && row >= ML);
;         const bool st_only = row < ML && !(which == 1 && l == NL - 1);
;         float* stp = st_only ? (float*)(F.ws + (which == 0 ? WS_ST1 : WS_ST2)) + 2 * (size_t)row : nullptr;
;         ln_row_v(F, vc, st_only ? nullptr : xrow_ptr(F, row), g, b, sh, sc, wh ? H + (size_t)row * D : nullptr, sl ? (const float*)(F.ws + WS_KN) + (size_t)(row - ML) * 1024 : nullptr, modp(F, l, mr, 5), stp);
.LBB0_107:
	s_cmp_gt_i32 s28, 4
	s_mov_b64 s[2:3], -1
	s_cbranch_scc0 .LBB0_125
	v_readlane_b32 s2, v255, 29
	s_lshl_b32 s2, s2, 3
	v_readlane_b32 s3, v255, 31
	s_add_i32 s16, s3, s2
	v_lshlrev_b32_e32 v0, 4, v186
	v_lshlrev_b32_e32 v1, 3, v186
	v_lshlrev_b32_e32 v96, 2, v186
	v_xor_b32_e32 v3, 4, v96
	v_xor_b32_e32 v4, 8, v96
	v_xor_b32_e32 v5, 16, v96
	v_xor_b32_e32 v6, 32, v96
	v_xor_b32_e32 v7, 64, v96
	v_xor_b32_e32 v8, 128, v96
	s_load_dwordx4 s[4:7], s[62:63], 0x98
	v_readlane_b32 s22, v255, 35
	v_readlane_b32 s8, v255, 17
	v_readlane_b32 s9, v255, 18
	s_add_u32 s20, s94, 0x3600000
	s_addc_u32 s21, s95, 0
	s_lshl_b32 s2, s16, 12
	s_lshl_b32 s3, s16, 15
	s_add_u32 s8, s8, s3
	s_addc_u32 s9, s9, 0
	s_add_u32 s20, s20, s2
	s_addc_u32 s21, s21, 0
	s_lshl_b32 s2, s16, 14
	s_add_u32 s10, s94, s2
	s_addc_u32 s11, s95, 0
	s_add_u32 s10, s10, 0x3e00000
	s_addc_u32 s11, s11, 0
	s_lshl_b32 s2, s16, 6
	s_add_u32 s12, s94, s2
	s_addc_u32 s13, s95, 0
	s_add_u32 s12, s12, 0x480000
	s_addc_u32 s13, s13, 0
	s_mov_b32 s3, s22
	s_mul_i32 s3, s3, 0x36000
	s_add_u32 s14, s94, s3
	s_addc_u32 s15, s95, 0
	s_add_u32 s14, s14, 0x103000
	s_addc_u32 s15, s15, 0
	s_add_u32 s18, s14, 0x1000
	s_addc_u32 s19, s15, 0
	s_lshl_b32 s2, s22, 12
	s_waitcnt lgkmcnt(0)
	s_add_u32 s4, s4, s2
	s_addc_u32 s5, s5, 0
	s_add_u32 s6, s6, s2
	s_addc_u32 s7, s7, 0
	global_load_dwordx4 v[10:13], v0, s[4:5]
	global_load_dwordx4 v[14:17], v0, s[4:5] offset:1024
	global_load_dwordx4 v[18:21], v0, s[4:5] offset:2048
	global_load_dwordx4 v[22:25], v0, s[4:5] offset:3072
	global_load_dwordx4 v[26:29], v0, s[6:7]
	global_load_dwordx4 v[30:33], v0, s[6:7] offset:1024
	global_load_dwordx4 v[34:37], v0, s[6:7] offset:2048
	global_load_dwordx4 v[38:41], v0, s[6:7] offset:3072
	s_add_u32 s2, s8, 0x0
	s_addc_u32 s3, s9, 0
	global_load_dwordx4 v[42:45], v0, s[2:3]
	global_load_dwordx4 v[46:49], v0, s[2:3] offset:1024
	global_load_dwordx4 v[50:53], v0, s[2:3] offset:2048
	global_load_dwordx4 v[54:57], v0, s[2:3] offset:3072
	s_lshr_b32 s23, s16, 8
	s_mul_i32 s23, s23, 0x6000
	s_add_u32 s2, s14, s23
	s_addc_u32 s3, s15, 0
	global_load_dwordx4 v[114:117], v0, s[2:3]
	global_load_dwordx4 v[118:121], v0, s[2:3] offset:1024
	global_load_dwordx4 v[122:125], v0, s[2:3] offset:2048
	global_load_dwordx4 v[126:129], v0, s[2:3] offset:3072
	s_add_u32 s2, s18, s23
	s_addc_u32 s3, s19, 0
	global_load_dwordx4 v[130:133], v0, s[2:3]
	global_load_dwordx4 v[134:137], v0, s[2:3] offset:1024
	global_load_dwordx4 v[138:141], v0, s[2:3] offset:2048
	global_load_dwordx4 v[142:145], v0, s[2:3] offset:3072
	s_add_u32 s2, s8, 0x1000
	s_addc_u32 s3, s9, 0
	global_load_dwordx4 v[58:61], v0, s[2:3]
	global_load_dwordx4 v[62:65], v0, s[2:3] offset:1024
	global_load_dwordx4 v[66:69], v0, s[2:3] offset:2048
	global_load_dwordx4 v[70:73], v0, s[2:3] offset:3072
	s_mov_b32 s23, 0x30000
	s_add_u32 s2, s14, s23
	s_addc_u32 s3, s15, 0
	global_load_dwordx4 v[146:149], v0, s[2:3]
	global_load_dwordx4 v[150:153], v0, s[2:3] offset:1024
	global_load_dwordx4 v[154:157], v0, s[2:3] offset:2048
	global_load_dwordx4 v[158:161], v0, s[2:3] offset:3072
	s_add_u32 s2, s18, s23
	s_addc_u32 s3, s19, 0
	global_load_dwordx4 v[162:165], v0, s[2:3]
	global_load_dwordx4 v[166:169], v0, s[2:3] offset:1024
	global_load_dwordx4 v[170:173], v0, s[2:3] offset:2048
	global_load_dwordx4 v[174:177], v0, s[2:3] offset:3072
	s_add_u32 s2, s8, 0x2000
	s_addc_u32 s3, s9, 0
	global_load_dwordx4 v[74:77], v0, s[2:3]
	global_load_dwordx4 v[78:81], v0, s[2:3] offset:1024
	global_load_dwordx4 v[82:85], v0, s[2:3] offset:2048
	global_load_dwordx4 v[86:89], v0, s[2:3] offset:3072
	s_add_u32 s2, s8, 0x3000
	s_addc_u32 s3, s9, 0
	global_load_dwordx4 v[98:101], v0, s[2:3]
	global_load_dwordx4 v[102:105], v0, s[2:3] offset:1024
	global_load_dwordx4 v[106:109], v0, s[2:3] offset:2048
	global_load_dwordx4 v[110:113], v0, s[2:3] offset:3072
	s_waitcnt vmcnt(28)
	v_add_f32_e32 v9, v42, v43
	v_add_f32_e32 v91, v44, v45
	v_mul_f32_e32 v90, v42, v42
	v_mul_f32_e32 v92, v43, v43
	v_add_f32_e32 v9, v9, v46
	v_add_f32_e32 v91, v91, v47
	v_add_f32_e32 v9, v9, v48
	v_add_f32_e32 v91, v91, v49
	v_add_f32_e32 v9, v9, v50
	v_add_f32_e32 v91, v91, v51
	v_add_f32_e32 v9, v9, v52
	v_add_f32_e32 v91, v91, v53
	v_add_f32_e32 v9, v9, v54
	v_add_f32_e32 v91, v91, v55
	v_add_f32_e32 v9, v9, v56
	v_add_f32_e32 v91, v91, v57
	v_fmac_f32_e32 v90, v44, v44
	v_fmac_f32_e32 v92, v45, v45
	v_fmac_f32_e32 v90, v46, v46
	v_fmac_f32_e32 v92, v47, v47
	v_fmac_f32_e32 v90, v48, v48
	v_fmac_f32_e32 v92, v49, v49
	v_fmac_f32_e32 v90, v50, v50
	v_fmac_f32_e32 v92, v51, v51
	v_fmac_f32_e32 v90, v52, v52
	v_fmac_f32_e32 v92, v53, v53
	v_fmac_f32_e32 v90, v54, v54
	v_fmac_f32_e32 v92, v55, v55
	v_fmac_f32_e32 v90, v56, v56
	v_fmac_f32_e32 v92, v57, v57
	v_add_f32_e32 v9, v9, v91
	v_add_f32_e32 v90, v90, v92
	ds_bpermute_b32 v91, v3, v9
	ds_bpermute_b32 v92, v3, v90
	s_waitcnt lgkmcnt(0)
	v_add_f32_e32 v9, v9, v91
	v_add_f32_e32 v90, v90, v92
	ds_bpermute_b32 v91, v4, v9
	ds_bpermute_b32 v92, v4, v90
	s_waitcnt lgkmcnt(0)
	v_add_f32_e32 v9, v9, v91
	v_add_f32_e32 v90, v90, v92
	ds_bpermute_b32 v91, v5, v9
	ds_bpermute_b32 v92, v5, v90
	s_waitcnt lgkmcnt(0)
	v_add_f32_e32 v9, v9, v91
	v_add_f32_e32 v90, v90, v92
	ds_bpermute_b32 v91, v6, v9
	ds_bpermute_b32 v92, v6, v90
	s_waitcnt lgkmcnt(0)
	v_add_f32_e32 v9, v9, v91
	v_add_f32_e32 v90, v90, v92
	ds_bpermute_b32 v91, v7, v9
	ds_bpermute_b32 v92, v7, v90
	s_waitcnt lgkmcnt(0)
	v_add_f32_e32 v9, v9, v91
	v_add_f32_e32 v90, v90, v92
	ds_bpermute_b32 v91, v8, v9
	ds_bpermute_b32 v92, v8, v90
	s_waitcnt lgkmcnt(0)
; DI unsigned pk2(float lo, float hi) { f32x2 v = {lo, hi}; bf16x2_t b = __builtin_convertvector(v, bf16x2_t); return __builtin_bit_cast(unsigned, b); }
; DI void ln_row_v(const Frame& F, f32x4 (&v)[4], float* xout, const float* g, const float* b, const float* sh, const float* sc, bf16_t* hout, const float* slab, const float* gres, float* stat = nullptr) {
;     ...
;     if (g) {
;         float s = 0.f, s2 = 0.f;
; #pragma unroll
;         for (int j = 0; j < 4; ++j) { s += (v[j][0] + v[j][1]) + (v[j][2] + v[j][3]); s2 += (v[j][0] * v[j][0] + v[j][1] * v[j][1]) + (v[j][2] * v[j][2] + v[j][3] * v[j][3]); }
;         wave_sum2(s, s2, F.lane);
;         const float mean = s * (1.f / D); const float rstd = 1.f / sqrtf(fmaxf(s2 * (1.f / D) - mean * mean, 0.f) + EPS);
;         if (stat && F.lane == 0) { f32x2 sv = {mean, rstd}; *(f32x2*)stat = sv; }
; #pragma unroll
;         for (int j = 0; j < 4; ++j) { const f32x4 gg = ((const f32x4*)g)[F.lane + 64 * j], bb = ((const f32x4*)b)[F.lane + 64 * j];
;             v[j] = (v[j] - mean) * rstd * gg + bb; if (xout) ((f32x4*)xout)[F.lane + 64 * j] = v[j]; }
;     }
;     if (hout) {
;         float s = 0.f, s2 = 0.f;
; #pragma unroll
;         for (int j = 0; j < 4; ++j) { s += (v[j][0] + v[j][1]) + (v[j][2] + v[j][3]); s2 += (v[j][0] * v[j][0] + v[j][1] * v[j][1]) + (v[j][2] * v[j][2] + v[j][3] * v[j][3]); }
;         wave_sum2(s, s2, F.lane);
;         const float mean = s * (1.f / D); const float rstd = 1.f / sqrtf(fmaxf(s2 * (1.f / D) - mean * mean, 0.f) + EPS);
; #pragma unroll
;         for (int j = 0; j < 4; ++j) { const f32x4 hh = ((const f32x4*)sh)[F.lane + 64 * j], cc = ((const f32x4*)sc)[F.lane + 64 * j];
;             const f32x4 o = (v[j] - mean) * rstd * (cc + 1.f) + hh; u32x2 wv; wv.x = pk2(o[0], o[1]); wv.y = pk2(o[2], o[3]);
;             ((u32x2*)hout)[F.lane + 64 * j] = wv; }
;     }
	v_add_f32_e32 v9, v9, v91
	v_add_f32_e32 v90, v90, v92
	v_mul_f32_e32 v93, 0x3a800000, v9
	v_mul_f32_e32 v91, 0x3a800000, v90
	v_fma_f32 v91, -v93, v93, v91
	v_max_f32_e32 v91, 0, v91
	v_add_f32_e32 v91, 0x358637bd, v91
	v_rsq_f32_e32 v94, v91
	v_mul_f32_e32 v91, 0.5, v91
	v_mul_f32_e32 v92, v94, v94
	v_fma_f32 v92, -v91, v92, 0.5
	v_fma_f32 v94, v94, v92, v94
	s_add_u32 s2, s12, 0x0
	s_addc_u32 s3, s13, 0
	v_mov_b32_e32 v188, v93
	v_mov_b32_e32 v189, v94
	s_mov_b64 exec, 1
	global_store_dwordx2 v97, v[188:189], s[2:3]
	s_mov_b64 exec, -1
	v_sub_f32_e32 v42, v42, v93
	v_sub_f32_e32 v43, v43, v93
	v_sub_f32_e32 v44, v44, v93
	v_sub_f32_e32 v45, v45, v93
	v_sub_f32_e32 v46, v46, v93
	v_sub_f32_e32 v47, v47, v93
	v_sub_f32_e32 v48, v48, v93
	v_sub_f32_e32 v49, v49, v93
	v_sub_f32_e32 v50, v50, v93
	v_sub_f32_e32 v51, v51, v93
	v_sub_f32_e32 v52, v52, v93
	v_sub_f32_e32 v53, v53, v93
	v_sub_f32_e32 v54, v54, v93
	v_sub_f32_e32 v55, v55, v93
	v_sub_f32_e32 v56, v56, v93
	v_sub_f32_e32 v57, v57, v93
	v_mul_f32_e32 v42, v94, v42
	v_mul_f32_e32 v43, v94, v43
	v_mul_f32_e32 v44, v94, v44
	v_mul_f32_e32 v45, v94, v45
	v_mul_f32_e32 v46, v94, v46
	v_mul_f32_e32 v47, v94, v47
	v_mul_f32_e32 v48, v94, v48
	v_mul_f32_e32 v49, v94, v49
	v_mul_f32_e32 v50, v94, v50
	v_mul_f32_e32 v51, v94, v51
	v_mul_f32_e32 v52, v94, v52
	v_mul_f32_e32 v53, v94, v53
	v_mul_f32_e32 v54, v94, v54
	v_mul_f32_e32 v55, v94, v55
	v_mul_f32_e32 v56, v94, v56
	v_mul_f32_e32 v57, v94, v57
	v_fma_f32 v42, v42, v10, v26
	v_fma_f32 v43, v43, v11, v27
	v_fma_f32 v44, v44, v12, v28
	v_fma_f32 v45, v45, v13, v29
	v_fma_f32 v46, v46, v14, v30
	v_fma_f32 v47, v47, v15, v31
	v_fma_f32 v48, v48, v16, v32
	v_fma_f32 v49, v49, v17, v33
	v_fma_f32 v50, v50, v18, v34
	v_fma_f32 v51, v51, v19, v35
	v_fma_f32 v52, v52, v20, v36
	v_fma_f32 v53, v53, v21, v37
	v_fma_f32 v54, v54, v22, v38
	v_fma_f32 v55, v55, v23, v39
	v_fma_f32 v56, v56, v24, v40
	v_fma_f32 v57, v57, v25, v41
	v_add_f32_e32 v9, v42, v43
	v_add_f32_e32 v91, v44, v45
	v_mul_f32_e32 v90, v42, v42
	v_mul_f32_e32 v92, v43, v43
	v_add_f32_e32 v9, v9, v46
	v_add_f32_e32 v91, v91, v47
	v_add_f32_e32 v9, v9, v48
	v_add_f32_e32 v91, v91, v49
	v_add_f32_e32 v9, v9, v50
	v_add_f32_e32 v91, v91, v51
	v_add_f32_e32 v9, v9, v52
	v_add_f32_e32 v91, v91, v53
	v_add_f32_e32 v9, v9, v54
	v_add_f32_e32 v91, v91, v55
	v_add_f32_e32 v9, v9, v56
	v_add_f32_e32 v91, v91, v57
	v_fmac_f32_e32 v90, v44, v44
	v_fmac_f32_e32 v92, v45, v45
	v_fmac_f32_e32 v90, v46, v46
	v_fmac_f32_e32 v92, v47, v47
	v_fmac_f32_e32 v90, v48, v48
	v_fmac_f32_e32 v92, v49, v49
	v_fmac_f32_e32 v90, v50, v50
	v_fmac_f32_e32 v92, v51, v51
	v_fmac_f32_e32 v90, v52, v52
	v_fmac_f32_e32 v92, v53, v53
	v_fmac_f32_e32 v90, v54, v54
	v_fmac_f32_e32 v92, v55, v55
	v_fmac_f32_e32 v90, v56, v56
	v_fmac_f32_e32 v92, v57, v57
	v_add_f32_e32 v9, v9, v91
	v_add_f32_e32 v90, v90, v92
	ds_bpermute_b32 v91, v3, v9
	ds_bpermute_b32 v92, v3, v90
	s_waitcnt lgkmcnt(0)
	v_add_f32_e32 v9, v9, v91
	v_add_f32_e32 v90, v90, v92
	ds_bpermute_b32 v91, v4, v9
	ds_bpermute_b32 v92, v4, v90
	s_waitcnt lgkmcnt(0)
	v_add_f32_e32 v9, v9, v91
	v_add_f32_e32 v90, v90, v92
	ds_bpermute_b32 v91, v5, v9
	ds_bpermute_b32 v92, v5, v90
	s_waitcnt lgkmcnt(0)
	v_add_f32_e32 v9, v9, v91
	v_add_f32_e32 v90, v90, v92
	ds_bpermute_b32 v91, v6, v9
	ds_bpermute_b32 v92, v6, v90
	s_waitcnt lgkmcnt(0)
	v_add_f32_e32 v9, v9, v91
	v_add_f32_e32 v90, v90, v92
	ds_bpermute_b32 v91, v7, v9
	ds_bpermute_b32 v92, v7, v90
	s_waitcnt lgkmcnt(0)
	v_add_f32_e32 v9, v9, v91
	v_add_f32_e32 v90, v90, v92
	ds_bpermute_b32 v91, v8, v9
	ds_bpermute_b32 v92, v8, v90
	s_waitcnt lgkmcnt(0)
	v_add_f32_e32 v9, v9, v91
	v_add_f32_e32 v90, v90, v92
	v_mul_f32_e32 v93, 0x3a800000, v9
	v_mul_f32_e32 v91, 0x3a800000, v90
	v_fma_f32 v91, -v93, v93, v91
	v_max_f32_e32 v91, 0, v91
	v_add_f32_e32 v91, 0x358637bd, v91
	v_rsq_f32_e32 v94, v91
	v_mul_f32_e32 v91, 0.5, v91
	v_mul_f32_e32 v92, v94, v94
	v_fma_f32 v92, -v91, v92, 0.5
	v_fma_f32 v94, v94, v92, v94
	s_waitcnt vmcnt(21)
	v_sub_f32_e32 v42, v42, v93
	v_sub_f32_e32 v43, v43, v93
	v_sub_f32_e32 v44, v44, v93
	v_sub_f32_e32 v45, v45, v93
	v_sub_f32_e32 v46, v46, v93
	v_sub_f32_e32 v47, v47, v93
	v_sub_f32_e32 v48, v48, v93
	v_sub_f32_e32 v49, v49, v93
	v_sub_f32_e32 v50, v50, v93
	v_sub_f32_e32 v51, v51, v93
	v_sub_f32_e32 v52, v52, v93
	v_sub_f32_e32 v53, v53, v93
	v_sub_f32_e32 v54, v54, v93
	v_sub_f32_e32 v55, v55, v93
	v_sub_f32_e32 v56, v56, v93
	v_sub_f32_e32 v57, v57, v93
	v_add_f32_e32 v130, 1.0, v130
	v_add_f32_e32 v131, 1.0, v131
	v_add_f32_e32 v132, 1.0, v132
	v_add_f32_e32 v133, 1.0, v133
	v_add_f32_e32 v134, 1.0, v134
	v_add_f32_e32 v135, 1.0, v135
	v_add_f32_e32 v136, 1.0, v136
	v_add_f32_e32 v137, 1.0, v137
	v_add_f32_e32 v138, 1.0, v138
	v_add_f32_e32 v139, 1.0, v139
	v_add_f32_e32 v140, 1.0, v140
	v_add_f32_e32 v141, 1.0, v141
	v_add_f32_e32 v142, 1.0, v142
	v_add_f32_e32 v143, 1.0, v143
	v_add_f32_e32 v144, 1.0, v144
	v_add_f32_e32 v145, 1.0, v145
	v_mul_f32_e32 v42, v94, v42
	v_mul_f32_e32 v43, v94, v43
	v_mul_f32_e32 v44, v94, v44
	v_mul_f32_e32 v45, v94, v45
	v_mul_f32_e32 v46, v94, v46
	v_mul_f32_e32 v47, v94, v47
	v_mul_f32_e32 v48, v94, v48
	v_mul_f32_e32 v49, v94, v49
	v_mul_f32_e32 v50, v94, v50
	v_mul_f32_e32 v51, v94, v51
	v_mul_f32_e32 v52, v94, v52
	v_mul_f32_e32 v53, v94, v53
	v_mul_f32_e32 v54, v94, v54
	v_mul_f32_e32 v55, v94, v55
	v_mul_f32_e32 v56, v94, v56
	v_mul_f32_e32 v57, v94, v57
	v_fma_f32 v42, v42, v130, v114
	v_fma_f32 v43, v43, v131, v115
	v_fma_f32 v44, v44, v132, v116
	v_fma_f32 v45, v45, v133, v117
	v_fma_f32 v46, v46, v134, v118
	v_fma_f32 v47, v47, v135, v119
	v_fma_f32 v48, v48, v136, v120
	v_fma_f32 v49, v49, v137, v121
	v_fma_f32 v50, v50, v138, v122
	v_fma_f32 v51, v51, v139, v123
	v_fma_f32 v52, v52, v140, v124
	v_fma_f32 v53, v53, v141, v125
	v_fma_f32 v54, v54, v142, v126
	v_fma_f32 v55, v55, v143, v127
	v_fma_f32 v56, v56, v144, v128
	v_fma_f32 v57, v57, v145, v129
	v_cvt_pk_bf16_f32 v190, v42, v43
	v_cvt_pk_bf16_f32 v191, v44, v45
	v_cvt_pk_bf16_f32 v192, v46, v47
	v_cvt_pk_bf16_f32 v193, v48, v49
	v_cvt_pk_bf16_f32 v194, v50, v51
	v_cvt_pk_bf16_f32 v195, v52, v53
	v_cvt_pk_bf16_f32 v196, v54, v55
	v_cvt_pk_bf16_f32 v197, v56, v57
	s_add_u32 s2, s10, 0x0
	s_addc_u32 s3, s11, 0
	global_store_dwordx2 v1, v[190:191], s[2:3]
	global_store_dwordx2 v1, v[192:193], s[2:3] offset:512
	global_store_dwordx2 v1, v[194:195], s[2:3] offset:1024
	global_store_dwordx2 v1, v[196:197], s[2:3] offset:1536
	s_add_u32 s2, s8, 0x4000
	s_addc_u32 s3, s9, 0
	global_load_dwordx4 v[42:45], v0, s[2:3]
	global_load_dwordx4 v[46:49], v0, s[2:3] offset:1024
	global_load_dwordx4 v[50:53], v0, s[2:3] offset:2048
	global_load_dwordx4 v[54:57], v0, s[2:3] offset:3072
	s_waitcnt vmcnt(25)
; DI void ln_row_v(const Frame& F, f32x4 (&v)[4], float* xout, const float* g, const float* b, const float* sh, const float* sc, bf16_t* hout, const float* slab, const float* gres, float* stat = nullptr) {
;     ...
;     if (g) {
;         float s = 0.f, s2 = 0.f;
; #pragma unroll
;         for (int j = 0; j < 4; ++j) { s += (v[j][0] + v[j][1]) + (v[j][2] + v[j][3]); s2 += (v[j][0] * v[j][0] + v[j][1] * v[j][1]) + (v[j][2] * v[j][2] + v[j][3] * v[j][3]); }
;         wave_sum2(s, s2, F.lane);
;         const float mean = s * (1.f / D); const float rstd = 1.f / sqrtf(fmaxf(s2 * (1.f / D) - mean * mean, 0.f) + EPS);
;         if (stat && F.lane == 0) { f32x2 sv = {mean, rstd}; *(f32x2*)stat = sv; }
; #pragma unroll
;         for (int j = 0; j < 4; ++j) { const f32x4 gg = ((const f32x4*)g)[F.lane + 64 * j], bb = ((const f32x4*)b)[F.lane + 64 * j];
;             v[j] = (v[j] - mean) * rstd * gg + bb; if (xout) ((f32x4*)xout)[F.lane + 64 * j] = v[j]; }
;     }
;     if (hout) {
;         float s = 0.f, s2 = 0.f;
; #pragma unroll
;         for (int j = 0; j < 4; ++j) { s += (v[j][0] + v[j][1]) + (v[j][2] + v[j][3]); s2 += (v[j][0] * v[j][0] + v[j][1] * v[j][1]) + (v[j][2] * v[j][2] + v[j][3] * v[j][3]); }
;         wave_sum2(s, s2, F.lane);
;         const float mean = s * (1.f / D); const float rstd = 1.f / sqrtf(fmaxf(s2 * (1.f / D) - mean * mean, 0.f) + EPS);
	v_add_f32_e32 v9, v58, v59
	v_add_f32_e32 v91, v60, v61
	v_mul_f32_e32 v90, v58, v58
	v_mul_f32_e32 v92, v59, v59
	v_add_f32_e32 v9, v9, v62
	v_add_f32_e32 v91, v91, v63
	v_add_f32_e32 v9, v9, v64
	v_add_f32_e32 v91, v91, v65
	v_add_f32_e32 v9, v9, v66
	v_add_f32_e32 v91, v91, v67
	v_add_f32_e32 v9, v9, v68
	v_add_f32_e32 v91, v91, v69
	v_add_f32_e32 v9, v9, v70
	v_add_f32_e32 v91, v91, v71
	v_add_f32_e32 v9, v9, v72
	v_add_f32_e32 v91, v91, v73
	v_fmac_f32_e32 v90, v60, v60
	v_fmac_f32_e32 v92, v61, v61
	v_fmac_f32_e32 v90, v62, v62
	v_fmac_f32_e32 v92, v63, v63
	v_fmac_f32_e32 v90, v64, v64
	v_fmac_f32_e32 v92, v65, v65
	v_fmac_f32_e32 v90, v66, v66
	v_fmac_f32_e32 v92, v67, v67
	v_fmac_f32_e32 v90, v68, v68
	v_fmac_f32_e32 v92, v69, v69
	v_fmac_f32_e32 v90, v70, v70
	v_fmac_f32_e32 v92, v71, v71
	v_fmac_f32_e32 v90, v72, v72
	v_fmac_f32_e32 v92, v73, v73
	v_add_f32_e32 v9, v9, v91
	v_add_f32_e32 v90, v90, v92
	ds_bpermute_b32 v91, v3, v9
	ds_bpermute_b32 v92, v3, v90
	s_waitcnt lgkmcnt(0)
	v_add_f32_e32 v9, v9, v91
	v_add_f32_e32 v90, v90, v92
	ds_bpermute_b32 v91, v4, v9
	ds_bpermute_b32 v92, v4, v90
	s_waitcnt lgkmcnt(0)
	v_add_f32_e32 v9, v9, v91
	v_add_f32_e32 v90, v90, v92
	ds_bpermute_b32 v91, v5, v9
	ds_bpermute_b32 v92, v5, v90
	s_waitcnt lgkmcnt(0)
	v_add_f32_e32 v9, v9, v91
	v_add_f32_e32 v90, v90, v92
	ds_bpermute_b32 v91, v6, v9
	ds_bpermute_b32 v92, v6, v90
	s_waitcnt lgkmcnt(0)
	v_add_f32_e32 v9, v9, v91
	v_add_f32_e32 v90, v90, v92
	ds_bpermute_b32 v91, v7, v9
	ds_bpermute_b32 v92, v7, v90
	s_waitcnt lgkmcnt(0)
	v_add_f32_e32 v9, v9, v91
	v_add_f32_e32 v90, v90, v92
	ds_bpermute_b32 v91, v8, v9
	ds_bpermute_b32 v92, v8, v90
	s_waitcnt lgkmcnt(0)
	v_add_f32_e32 v9, v9, v91
	v_add_f32_e32 v90, v90, v92
	v_mul_f32_e32 v93, 0x3a800000, v9
	v_mul_f32_e32 v91, 0x3a800000, v90
	v_fma_f32 v91, -v93, v93, v91
	v_max_f32_e32 v91, 0, v91
	v_add_f32_e32 v91, 0x358637bd, v91
	v_rsq_f32_e32 v94, v91
	v_mul_f32_e32 v91, 0.5, v91
	v_mul_f32_e32 v92, v94, v94
	v_fma_f32 v92, -v91, v92, 0.5
	v_fma_f32 v94, v94, v92, v94
	s_add_u32 s2, s12, 0x8
	s_addc_u32 s3, s13, 0
	v_mov_b32_e32 v188, v93
	v_mov_b32_e32 v189, v94
	s_mov_b64 exec, 1
	global_store_dwordx2 v97, v[188:189], s[2:3]
	s_mov_b64 exec, -1
	v_sub_f32_e32 v58, v58, v93
	v_sub_f32_e32 v59, v59, v93
	v_sub_f32_e32 v60, v60, v93
	v_sub_f32_e32 v61, v61, v93
	v_sub_f32_e32 v62, v62, v93
	v_sub_f32_e32 v63, v63, v93
	v_sub_f32_e32 v64, v64, v93
	v_sub_f32_e32 v65, v65, v93
	v_sub_f32_e32 v66, v66, v93
	v_sub_f32_e32 v67, v67, v93
	v_sub_f32_e32 v68, v68, v93
	v_sub_f32_e32 v69, v69, v93
	v_sub_f32_e32 v70, v70, v93
	v_sub_f32_e32 v71, v71, v93
	v_sub_f32_e32 v72, v72, v93
	v_sub_f32_e32 v73, v73, v93
	v_mul_f32_e32 v58, v94, v58
	v_mul_f32_e32 v59, v94, v59
	v_mul_f32_e32 v60, v94, v60
	v_mul_f32_e32 v61, v94, v61
	v_mul_f32_e32 v62, v94, v62
	v_mul_f32_e32 v63, v94, v63
	v_mul_f32_e32 v64, v94, v64
	v_mul_f32_e32 v65, v94, v65
	v_mul_f32_e32 v66, v94, v66
	v_mul_f32_e32 v67, v94, v67
	v_mul_f32_e32 v68, v94, v68
	v_mul_f32_e32 v69, v94, v69
	v_mul_f32_e32 v70, v94, v70
	v_mul_f32_e32 v71, v94, v71
	v_mul_f32_e32 v72, v94, v72
	v_mul_f32_e32 v73, v94, v73
	v_fma_f32 v58, v58, v10, v26
	v_fma_f32 v59, v59, v11, v27
	v_fma_f32 v60, v60, v12, v28
	v_fma_f32 v61, v61, v13, v29
	v_fma_f32 v62, v62, v14, v30
	v_fma_f32 v63, v63, v15, v31
	v_fma_f32 v64, v64, v16, v32
	v_fma_f32 v65, v65, v17, v33
	v_fma_f32 v66, v66, v18, v34
	v_fma_f32 v67, v67, v19, v35
	v_fma_f32 v68, v68, v20, v36
	v_fma_f32 v69, v69, v21, v37
	v_fma_f32 v70, v70, v22, v38
	v_fma_f32 v71, v71, v23, v39
	v_fma_f32 v72, v72, v24, v40
	v_fma_f32 v73, v73, v25, v41
	v_add_f32_e32 v9, v58, v59
	v_add_f32_e32 v91, v60, v61
	v_mul_f32_e32 v90, v58, v58
	v_mul_f32_e32 v92, v59, v59
	v_add_f32_e32 v9, v9, v62
	v_add_f32_e32 v91, v91, v63
	v_add_f32_e32 v9, v9, v64
	v_add_f32_e32 v91, v91, v65
	v_add_f32_e32 v9, v9, v66
	v_add_f32_e32 v91, v91, v67
	v_add_f32_e32 v9, v9, v68
	v_add_f32_e32 v91, v91, v69
	v_add_f32_e32 v9, v9, v70
	v_add_f32_e32 v91, v91, v71
	v_add_f32_e32 v9, v9, v72
	v_add_f32_e32 v91, v91, v73
	v_fmac_f32_e32 v90, v60, v60
	v_fmac_f32_e32 v92, v61, v61
	v_fmac_f32_e32 v90, v62, v62
	v_fmac_f32_e32 v92, v63, v63
	v_fmac_f32_e32 v90, v64, v64
	v_fmac_f32_e32 v92, v65, v65
	v_fmac_f32_e32 v90, v66, v66
	v_fmac_f32_e32 v92, v67, v67
	v_fmac_f32_e32 v90, v68, v68
	v_fmac_f32_e32 v92, v69, v69
	v_fmac_f32_e32 v90, v70, v70
	v_fmac_f32_e32 v92, v71, v71
	v_fmac_f32_e32 v90, v72, v72
	v_fmac_f32_e32 v92, v73, v73
	v_add_f32_e32 v9, v9, v91
	v_add_f32_e32 v90, v90, v92
	ds_bpermute_b32 v91, v3, v9
	ds_bpermute_b32 v92, v3, v90
	s_waitcnt lgkmcnt(0)
	v_add_f32_e32 v9, v9, v91
	v_add_f32_e32 v90, v90, v92
	ds_bpermute_b32 v91, v4, v9
	ds_bpermute_b32 v92, v4, v90
	s_waitcnt lgkmcnt(0)
	v_add_f32_e32 v9, v9, v91
	v_add_f32_e32 v90, v90, v92
	ds_bpermute_b32 v91, v5, v9
	ds_bpermute_b32 v92, v5, v90
	s_waitcnt lgkmcnt(0)
	v_add_f32_e32 v9, v9, v91
	v_add_f32_e32 v90, v90, v92
	ds_bpermute_b32 v91, v6, v9
	ds_bpermute_b32 v92, v6, v90
	s_waitcnt lgkmcnt(0)
	v_add_f32_e32 v9, v9, v91
	v_add_f32_e32 v90, v90, v92
	ds_bpermute_b32 v91, v7, v9
	ds_bpermute_b32 v92, v7, v90
	s_waitcnt lgkmcnt(0)
	v_add_f32_e32 v9, v9, v91
	v_add_f32_e32 v90, v90, v92
	ds_bpermute_b32 v91, v8, v9
	ds_bpermute_b32 v92, v8, v90
	s_waitcnt lgkmcnt(0)
; DI unsigned pk2(float lo, float hi) { f32x2 v = {lo, hi}; bf16x2_t b = __builtin_convertvector(v, bf16x2_t); return __builtin_bit_cast(unsigned, b); }
; DI void ln_row_v(const Frame& F, f32x4 (&v)[4], float* xout, const float* g, const float* b, const float* sh, const float* sc, bf16_t* hout, const float* slab, const float* gres, float* stat = nullptr) {
;     ...
;         const float mean = s * (1.f / D); const float rstd = 1.f / sqrtf(fmaxf(s2 * (1.f / D) - mean * mean, 0.f) + EPS);
; #pragma unroll
;         for (int j = 0; j < 4; ++j) { const f32x4 hh = ((const f32x4*)sh)[F.lane + 64 * j], cc = ((const f32x4*)sc)[F.lane + 64 * j];
;             const f32x4 o = (v[j] - mean) * rstd * (cc + 1.f) + hh; u32x2 wv; wv.x = pk2(o[0], o[1]); wv.y = pk2(o[2], o[3]);
;             ((u32x2*)hout)[F.lane + 64 * j] = wv; }
;     }
	v_add_f32_e32 v9, v9, v91
	v_add_f32_e32 v90, v90, v92
	v_mul_f32_e32 v93, 0x3a800000, v9
	v_mul_f32_e32 v91, 0x3a800000, v90
	v_fma_f32 v91, -v93, v93, v91
	v_max_f32_e32 v91, 0, v91
	v_add_f32_e32 v91, 0x358637bd, v91
	v_rsq_f32_e32 v94, v91
	v_mul_f32_e32 v91, 0.5, v91
	v_mul_f32_e32 v92, v94, v94
	v_fma_f32 v92, -v91, v92, 0.5
	v_fma_f32 v94, v94, v92, v94
	v_sub_f32_e32 v58, v58, v93
	v_sub_f32_e32 v59, v59, v93
	v_sub_f32_e32 v60, v60, v93
	v_sub_f32_e32 v61, v61, v93
	v_sub_f32_e32 v62, v62, v93
	v_sub_f32_e32 v63, v63, v93
	v_sub_f32_e32 v64, v64, v93
	v_sub_f32_e32 v65, v65, v93
	v_sub_f32_e32 v66, v66, v93
	v_sub_f32_e32 v67, v67, v93
	v_sub_f32_e32 v68, v68, v93
	v_sub_f32_e32 v69, v69, v93
	v_sub_f32_e32 v70, v70, v93
	v_sub_f32_e32 v71, v71, v93
	v_sub_f32_e32 v72, v72, v93
	v_sub_f32_e32 v73, v73, v93
	v_mul_f32_e32 v58, v94, v58
	v_mul_f32_e32 v59, v94, v59
	v_mul_f32_e32 v60, v94, v60
	v_mul_f32_e32 v61, v94, v61
	v_mul_f32_e32 v62, v94, v62
	v_mul_f32_e32 v63, v94, v63
	v_mul_f32_e32 v64, v94, v64
	v_mul_f32_e32 v65, v94, v65
	v_mul_f32_e32 v66, v94, v66
	v_mul_f32_e32 v67, v94, v67
	v_mul_f32_e32 v68, v94, v68
	v_mul_f32_e32 v69, v94, v69
	v_mul_f32_e32 v70, v94, v70
	v_mul_f32_e32 v71, v94, v71
	v_mul_f32_e32 v72, v94, v72
	v_mul_f32_e32 v73, v94, v73
	v_fma_f32 v58, v58, v130, v114
	v_fma_f32 v59, v59, v131, v115
	v_fma_f32 v60, v60, v132, v116
	v_fma_f32 v61, v61, v133, v117
	v_fma_f32 v62, v62, v134, v118
	v_fma_f32 v63, v63, v135, v119
	v_fma_f32 v64, v64, v136, v120
	v_fma_f32 v65, v65, v137, v121
	v_fma_f32 v66, v66, v138, v122
	v_fma_f32 v67, v67, v139, v123
	v_fma_f32 v68, v68, v140, v124
	v_fma_f32 v69, v69, v141, v125
	v_fma_f32 v70, v70, v142, v126
	v_fma_f32 v71, v71, v143, v127
	v_fma_f32 v72, v72, v144, v128
	v_fma_f32 v73, v73, v145, v129
	v_cvt_pk_bf16_f32 v190, v58, v59
	v_cvt_pk_bf16_f32 v191, v60, v61
	v_cvt_pk_bf16_f32 v192, v62, v63
	v_cvt_pk_bf16_f32 v193, v64, v65
	v_cvt_pk_bf16_f32 v194, v66, v67
	v_cvt_pk_bf16_f32 v195, v68, v69
	v_cvt_pk_bf16_f32 v196, v70, v71
	v_cvt_pk_bf16_f32 v197, v72, v73
	s_add_u32 s2, s10, 0x800
	s_addc_u32 s3, s11, 0
	global_store_dwordx2 v1, v[190:191], s[2:3]
	global_store_dwordx2 v1, v[192:193], s[2:3] offset:512
	global_store_dwordx2 v1, v[194:195], s[2:3] offset:1024
	global_store_dwordx2 v1, v[196:197], s[2:3] offset:1536
	s_add_u32 s2, s8, 0x5000
	s_addc_u32 s3, s9, 0
	global_load_dwordx4 v[58:61], v0, s[2:3]
	global_load_dwordx4 v[62:65], v0, s[2:3] offset:1024
	global_load_dwordx4 v[66:69], v0, s[2:3] offset:2048
	global_load_dwordx4 v[70:73], v0, s[2:3] offset:3072
	s_waitcnt vmcnt(22)
	v_add_f32_e32 v9, v74, v75
	v_add_f32_e32 v91, v76, v77
	v_mul_f32_e32 v90, v74, v74
	v_mul_f32_e32 v92, v75, v75
	v_add_f32_e32 v9, v9, v78
	v_add_f32_e32 v91, v91, v79
	v_add_f32_e32 v9, v9, v80
	v_add_f32_e32 v91, v91, v81
	v_add_f32_e32 v9, v9, v82
	v_add_f32_e32 v91, v91, v83
	v_add_f32_e32 v9, v9, v84
	v_add_f32_e32 v91, v91, v85
	v_add_f32_e32 v9, v9, v86
	v_add_f32_e32 v91, v91, v87
	v_add_f32_e32 v9, v9, v88
	v_add_f32_e32 v91, v91, v89
	v_fmac_f32_e32 v90, v76, v76
	v_fmac_f32_e32 v92, v77, v77
	v_fmac_f32_e32 v90, v78, v78
	v_fmac_f32_e32 v92, v79, v79
	v_fmac_f32_e32 v90, v80, v80
	v_fmac_f32_e32 v92, v81, v81
	v_fmac_f32_e32 v90, v82, v82
	v_fmac_f32_e32 v92, v83, v83
	v_fmac_f32_e32 v90, v84, v84
	v_fmac_f32_e32 v92, v85, v85
	v_fmac_f32_e32 v90, v86, v86
	v_fmac_f32_e32 v92, v87, v87
	v_fmac_f32_e32 v90, v88, v88
	v_fmac_f32_e32 v92, v89, v89
	v_add_f32_e32 v9, v9, v91
	v_add_f32_e32 v90, v90, v92
	ds_bpermute_b32 v91, v3, v9
	ds_bpermute_b32 v92, v3, v90
	s_waitcnt lgkmcnt(0)
	v_add_f32_e32 v9, v9, v91
	v_add_f32_e32 v90, v90, v92
	ds_bpermute_b32 v91, v4, v9
	ds_bpermute_b32 v92, v4, v90
	s_waitcnt lgkmcnt(0)
	v_add_f32_e32 v9, v9, v91
	v_add_f32_e32 v90, v90, v92
	ds_bpermute_b32 v91, v5, v9
	ds_bpermute_b32 v92, v5, v90
	s_waitcnt lgkmcnt(0)
	v_add_f32_e32 v9, v9, v91
	v_add_f32_e32 v90, v90, v92
	ds_bpermute_b32 v91, v6, v9
	ds_bpermute_b32 v92, v6, v90
	s_waitcnt lgkmcnt(0)
	v_add_f32_e32 v9, v9, v91
	v_add_f32_e32 v90, v90, v92
	ds_bpermute_b32 v91, v7, v9
	ds_bpermute_b32 v92, v7, v90
	s_waitcnt lgkmcnt(0)
	v_add_f32_e32 v9, v9, v91
	v_add_f32_e32 v90, v90, v92
	ds_bpermute_b32 v91, v8, v9
	ds_bpermute_b32 v92, v8, v90
	s_waitcnt lgkmcnt(0)
; DI unsigned pk2(float lo, float hi) { f32x2 v = {lo, hi}; bf16x2_t b = __builtin_convertvector(v, bf16x2_t); return __builtin_bit_cast(unsigned, b); }
; DI void ln_row_v(const Frame& F, f32x4 (&v)[4], float* xout, const float* g, const float* b, const float* sh, const float* sc, bf16_t* hout, const float* slab, const float* gres, float* stat = nullptr) {
;     ...
;     if (g) {
;         float s = 0.f, s2 = 0.f;
; #pragma unroll
;         for (int j = 0; j < 4; ++j) { s += (v[j][0] + v[j][1]) + (v[j][2] + v[j][3]); s2 += (v[j][0] * v[j][0] + v[j][1] * v[j][1]) + (v[j][2] * v[j][2] + v[j][3] * v[j][3]); }
;         wave_sum2(s, s2, F.lane);
;         const float mean = s * (1.f / D); const float rstd = 1.f / sqrtf(fmaxf(s2 * (1.f / D) - mean * mean, 0.f) + EPS);
;         if (stat && F.lane == 0) { f32x2 sv = {mean, rstd}; *(f32x2*)stat = sv; }
; #pragma unroll
;         for (int j = 0; j < 4; ++j) { const f32x4 gg = ((const f32x4*)g)[F.lane + 64 * j], bb = ((const f32x4*)b)[F.lane + 64 * j];
;             v[j] = (v[j] - mean) * rstd * gg + bb; if (xout) ((f32x4*)xout)[F.lane + 64 * j] = v[j]; }
;     }
;     if (hout) {
;         float s = 0.f, s2 = 0.f;
; #pragma unroll
;         for (int j = 0; j < 4; ++j) { s += (v[j][0] + v[j][1]) + (v[j][2] + v[j][3]); s2 += (v[j][0] * v[j][0] + v[j][1] * v[j][1]) + (v[j][2] * v[j][2] + v[j][3] * v[j][3]); }
;         wave_sum2(s, s2, F.lane);
;         const float mean = s * (1.f / D); const float rstd = 1.f / sqrtf(fmaxf(s2 * (1.f / D) - mean * mean, 0.f) + EPS);
; #pragma unroll
;         for (int j = 0; j < 4; ++j) { const f32x4 hh = ((const f32x4*)sh)[F.lane + 64 * j], cc = ((const f32x4*)sc)[F.lane + 64 * j];
;             const f32x4 o = (v[j] - mean) * rstd * (cc + 1.f) + hh; u32x2 wv; wv.x = pk2(o[0], o[1]); wv.y = pk2(o[2], o[3]);
;             ((u32x2*)hout)[F.lane + 64 * j] = wv; }
;     }
	v_add_f32_e32 v9, v9, v91
	v_add_f32_e32 v90, v90, v92
	v_mul_f32_e32 v93, 0x3a800000, v9
	v_mul_f32_e32 v91, 0x3a800000, v90
	v_fma_f32 v91, -v93, v93, v91
	v_max_f32_e32 v91, 0, v91
	v_add_f32_e32 v91, 0x358637bd, v91
	v_rsq_f32_e32 v94, v91
	v_mul_f32_e32 v91, 0.5, v91
	v_mul_f32_e32 v92, v94, v94
	v_fma_f32 v92, -v91, v92, 0.5
	v_fma_f32 v94, v94, v92, v94
	s_add_u32 s2, s12, 0x10
	s_addc_u32 s3, s13, 0
	v_mov_b32_e32 v188, v93
	v_mov_b32_e32 v189, v94
	s_mov_b64 exec, 1
	global_store_dwordx2 v97, v[188:189], s[2:3]
	s_mov_b64 exec, -1
	v_sub_f32_e32 v74, v74, v93
	v_sub_f32_e32 v75, v75, v93
	v_sub_f32_e32 v76, v76, v93
	v_sub_f32_e32 v77, v77, v93
	v_sub_f32_e32 v78, v78, v93
	v_sub_f32_e32 v79, v79, v93
	v_sub_f32_e32 v80, v80, v93
	v_sub_f32_e32 v81, v81, v93
	v_sub_f32_e32 v82, v82, v93
	v_sub_f32_e32 v83, v83, v93
	v_sub_f32_e32 v84, v84, v93
	v_sub_f32_e32 v85, v85, v93
	v_sub_f32_e32 v86, v86, v93
	v_sub_f32_e32 v87, v87, v93
	v_sub_f32_e32 v88, v88, v93
	v_sub_f32_e32 v89, v89, v93
	v_mul_f32_e32 v74, v94, v74
	v_mul_f32_e32 v75, v94, v75
	v_mul_f32_e32 v76, v94, v76
	v_mul_f32_e32 v77, v94, v77
	v_mul_f32_e32 v78, v94, v78
	v_mul_f32_e32 v79, v94, v79
	v_mul_f32_e32 v80, v94, v80
	v_mul_f32_e32 v81, v94, v81
	v_mul_f32_e32 v82, v94, v82
	v_mul_f32_e32 v83, v94, v83
	v_mul_f32_e32 v84, v94, v84
	v_mul_f32_e32 v85, v94, v85
	v_mul_f32_e32 v86, v94, v86
	v_mul_f32_e32 v87, v94, v87
	v_mul_f32_e32 v88, v94, v88
	v_mul_f32_e32 v89, v94, v89
	v_fma_f32 v74, v74, v10, v26
	v_fma_f32 v75, v75, v11, v27
	v_fma_f32 v76, v76, v12, v28
	v_fma_f32 v77, v77, v13, v29
	v_fma_f32 v78, v78, v14, v30
	v_fma_f32 v79, v79, v15, v31
	v_fma_f32 v80, v80, v16, v32
	v_fma_f32 v81, v81, v17, v33
	v_fma_f32 v82, v82, v18, v34
	v_fma_f32 v83, v83, v19, v35
	v_fma_f32 v84, v84, v20, v36
	v_fma_f32 v85, v85, v21, v37
	v_fma_f32 v86, v86, v22, v38
	v_fma_f32 v87, v87, v23, v39
	v_fma_f32 v88, v88, v24, v40
	v_fma_f32 v89, v89, v25, v41
	v_add_f32_e32 v9, v74, v75
	v_add_f32_e32 v91, v76, v77
	v_mul_f32_e32 v90, v74, v74
	v_mul_f32_e32 v92, v75, v75
	v_add_f32_e32 v9, v9, v78
	v_add_f32_e32 v91, v91, v79
	v_add_f32_e32 v9, v9, v80
	v_add_f32_e32 v91, v91, v81
	v_add_f32_e32 v9, v9, v82
	v_add_f32_e32 v91, v91, v83
	v_add_f32_e32 v9, v9, v84
	v_add_f32_e32 v91, v91, v85
	v_add_f32_e32 v9, v9, v86
	v_add_f32_e32 v91, v91, v87
	v_add_f32_e32 v9, v9, v88
	v_add_f32_e32 v91, v91, v89
	v_fmac_f32_e32 v90, v76, v76
	v_fmac_f32_e32 v92, v77, v77
	v_fmac_f32_e32 v90, v78, v78
	v_fmac_f32_e32 v92, v79, v79
	v_fmac_f32_e32 v90, v80, v80
	v_fmac_f32_e32 v92, v81, v81
	v_fmac_f32_e32 v90, v82, v82
	v_fmac_f32_e32 v92, v83, v83
	v_fmac_f32_e32 v90, v84, v84
	v_fmac_f32_e32 v92, v85, v85
	v_fmac_f32_e32 v90, v86, v86
	v_fmac_f32_e32 v92, v87, v87
	v_fmac_f32_e32 v90, v88, v88
	v_fmac_f32_e32 v92, v89, v89
	v_add_f32_e32 v9, v9, v91
	v_add_f32_e32 v90, v90, v92
	ds_bpermute_b32 v91, v3, v9
	ds_bpermute_b32 v92, v3, v90
	s_waitcnt lgkmcnt(0)
	v_add_f32_e32 v9, v9, v91
	v_add_f32_e32 v90, v90, v92
	ds_bpermute_b32 v91, v4, v9
	ds_bpermute_b32 v92, v4, v90
	s_waitcnt lgkmcnt(0)
	v_add_f32_e32 v9, v9, v91
	v_add_f32_e32 v90, v90, v92
	ds_bpermute_b32 v91, v5, v9
	ds_bpermute_b32 v92, v5, v90
	s_waitcnt lgkmcnt(0)
	v_add_f32_e32 v9, v9, v91
	v_add_f32_e32 v90, v90, v92
	ds_bpermute_b32 v91, v6, v9
	ds_bpermute_b32 v92, v6, v90
	s_waitcnt lgkmcnt(0)
	v_add_f32_e32 v9, v9, v91
	v_add_f32_e32 v90, v90, v92
	ds_bpermute_b32 v91, v7, v9
	ds_bpermute_b32 v92, v7, v90
	s_waitcnt lgkmcnt(0)
	v_add_f32_e32 v9, v9, v91
	v_add_f32_e32 v90, v90, v92
	ds_bpermute_b32 v91, v8, v9
	ds_bpermute_b32 v92, v8, v90
	s_waitcnt lgkmcnt(0)
	v_add_f32_e32 v9, v9, v91
	v_add_f32_e32 v90, v90, v92
	v_mul_f32_e32 v93, 0x3a800000, v9
	v_mul_f32_e32 v91, 0x3a800000, v90
	v_fma_f32 v91, -v93, v93, v91
	v_max_f32_e32 v91, 0, v91
	v_add_f32_e32 v91, 0x358637bd, v91
	v_rsq_f32_e32 v94, v91
	v_mul_f32_e32 v91, 0.5, v91
	v_mul_f32_e32 v92, v94, v94
	v_fma_f32 v92, -v91, v92, 0.5
	v_fma_f32 v94, v94, v92, v94
	v_sub_f32_e32 v74, v74, v93
	v_sub_f32_e32 v75, v75, v93
	v_sub_f32_e32 v76, v76, v93
	v_sub_f32_e32 v77, v77, v93
	v_sub_f32_e32 v78, v78, v93
	v_sub_f32_e32 v79, v79, v93
	v_sub_f32_e32 v80, v80, v93
	v_sub_f32_e32 v81, v81, v93
	v_sub_f32_e32 v82, v82, v93
	v_sub_f32_e32 v83, v83, v93
	v_sub_f32_e32 v84, v84, v93
	v_sub_f32_e32 v85, v85, v93
	v_sub_f32_e32 v86, v86, v93
	v_sub_f32_e32 v87, v87, v93
	v_sub_f32_e32 v88, v88, v93
	v_sub_f32_e32 v89, v89, v93
	v_mul_f32_e32 v74, v94, v74
	v_mul_f32_e32 v75, v94, v75
	v_mul_f32_e32 v76, v94, v76
	v_mul_f32_e32 v77, v94, v77
	v_mul_f32_e32 v78, v94, v78
	v_mul_f32_e32 v79, v94, v79
	v_mul_f32_e32 v80, v94, v80
	v_mul_f32_e32 v81, v94, v81
	v_mul_f32_e32 v82, v94, v82
	v_mul_f32_e32 v83, v94, v83
	v_mul_f32_e32 v84, v94, v84
	v_mul_f32_e32 v85, v94, v85
	v_mul_f32_e32 v86, v94, v86
	v_mul_f32_e32 v87, v94, v87
	v_mul_f32_e32 v88, v94, v88
	v_mul_f32_e32 v89, v94, v89
	v_fma_f32 v74, v74, v130, v114
	v_fma_f32 v75, v75, v131, v115
	v_fma_f32 v76, v76, v132, v116
	v_fma_f32 v77, v77, v133, v117
	v_fma_f32 v78, v78, v134, v118
	v_fma_f32 v79, v79, v135, v119
	v_fma_f32 v80, v80, v136, v120
	v_fma_f32 v81, v81, v137, v121
	v_fma_f32 v82, v82, v138, v122
	v_fma_f32 v83, v83, v139, v123
	v_fma_f32 v84, v84, v140, v124
	v_fma_f32 v85, v85, v141, v125
	v_fma_f32 v86, v86, v142, v126
	v_fma_f32 v87, v87, v143, v127
	v_fma_f32 v88, v88, v144, v128
	v_fma_f32 v89, v89, v145, v129
	v_cvt_pk_bf16_f32 v190, v74, v75
	v_cvt_pk_bf16_f32 v191, v76, v77
	v_cvt_pk_bf16_f32 v192, v78, v79
	v_cvt_pk_bf16_f32 v193, v80, v81
	v_cvt_pk_bf16_f32 v194, v82, v83
	v_cvt_pk_bf16_f32 v195, v84, v85
	v_cvt_pk_bf16_f32 v196, v86, v87
	v_cvt_pk_bf16_f32 v197, v88, v89
	s_add_u32 s2, s10, 0x1000
	s_addc_u32 s3, s11, 0
	global_store_dwordx2 v1, v[190:191], s[2:3]
	global_store_dwordx2 v1, v[192:193], s[2:3] offset:512
	global_store_dwordx2 v1, v[194:195], s[2:3] offset:1024
	global_store_dwordx2 v1, v[196:197], s[2:3] offset:1536
	s_add_u32 s2, s8, 0x6000
	s_addc_u32 s3, s9, 0
	global_load_dwordx4 v[74:77], v0, s[2:3]
	global_load_dwordx4 v[78:81], v0, s[2:3] offset:1024
	global_load_dwordx4 v[82:85], v0, s[2:3] offset:2048
	global_load_dwordx4 v[86:89], v0, s[2:3] offset:3072
	s_waitcnt vmcnt(27)
; DI void ln_row_v(const Frame& F, f32x4 (&v)[4], float* xout, const float* g, const float* b, const float* sh, const float* sc, bf16_t* hout, const float* slab, const float* gres, float* stat = nullptr) {
;     ...
;     if (g) {
;         float s = 0.f, s2 = 0.f;
; #pragma unroll
;         for (int j = 0; j < 4; ++j) { s += (v[j][0] + v[j][1]) + (v[j][2] + v[j][3]); s2 += (v[j][0] * v[j][0] + v[j][1] * v[j][1]) + (v[j][2] * v[j][2] + v[j][3] * v[j][3]); }
;         wave_sum2(s, s2, F.lane);
;         const float mean = s * (1.f / D); const float rstd = 1.f / sqrtf(fmaxf(s2 * (1.f / D) - mean * mean, 0.f) + EPS);
;         if (stat && F.lane == 0) { f32x2 sv = {mean, rstd}; *(f32x2*)stat = sv; }
; #pragma unroll
;         for (int j = 0; j < 4; ++j) { const f32x4 gg = ((const f32x4*)g)[F.lane + 64 * j], bb = ((const f32x4*)b)[F.lane + 64 * j];
;             v[j] = (v[j] - mean) * rstd * gg + bb; if (xout) ((f32x4*)xout)[F.lane + 64 * j] = v[j]; }
;     }
;     if (hout) {
;         float s = 0.f, s2 = 0.f;
; #pragma unroll
;         for (int j = 0; j < 4; ++j) { s += (v[j][0] + v[j][1]) + (v[j][2] + v[j][3]); s2 += (v[j][0] * v[j][0] + v[j][1] * v[j][1]) + (v[j][2] * v[j][2] + v[j][3] * v[j][3]); }
;         wave_sum2(s, s2, F.lane);
;         const float mean = s * (1.f / D); const float rstd = 1.f / sqrtf(fmaxf(s2 * (1.f / D) - mean * mean, 0.f) + EPS);
	v_add_f32_e32 v9, v98, v99
	v_add_f32_e32 v91, v100, v101
	v_mul_f32_e32 v90, v98, v98
	v_mul_f32_e32 v92, v99, v99
	v_add_f32_e32 v9, v9, v102
	v_add_f32_e32 v91, v91, v103
	v_add_f32_e32 v9, v9, v104
	v_add_f32_e32 v91, v91, v105
	v_add_f32_e32 v9, v9, v106
	v_add_f32_e32 v91, v91, v107
	v_add_f32_e32 v9, v9, v108
	v_add_f32_e32 v91, v91, v109
	v_add_f32_e32 v9, v9, v110
	v_add_f32_e32 v91, v91, v111
	v_add_f32_e32 v9, v9, v112
	v_add_f32_e32 v91, v91, v113
	v_fmac_f32_e32 v90, v100, v100
	v_fmac_f32_e32 v92, v101, v101
	v_fmac_f32_e32 v90, v102, v102
	v_fmac_f32_e32 v92, v103, v103
	v_fmac_f32_e32 v90, v104, v104
	v_fmac_f32_e32 v92, v105, v105
	v_fmac_f32_e32 v90, v106, v106
	v_fmac_f32_e32 v92, v107, v107
	v_fmac_f32_e32 v90, v108, v108
	v_fmac_f32_e32 v92, v109, v109
	v_fmac_f32_e32 v90, v110, v110
	v_fmac_f32_e32 v92, v111, v111
	v_fmac_f32_e32 v90, v112, v112
	v_fmac_f32_e32 v92, v113, v113
	v_add_f32_e32 v9, v9, v91
	v_add_f32_e32 v90, v90, v92
	ds_bpermute_b32 v91, v3, v9
	ds_bpermute_b32 v92, v3, v90
	s_waitcnt lgkmcnt(0)
	v_add_f32_e32 v9, v9, v91
	v_add_f32_e32 v90, v90, v92
	ds_bpermute_b32 v91, v4, v9
	ds_bpermute_b32 v92, v4, v90
	s_waitcnt lgkmcnt(0)
	v_add_f32_e32 v9, v9, v91
	v_add_f32_e32 v90, v90, v92
	ds_bpermute_b32 v91, v5, v9
	ds_bpermute_b32 v92, v5, v90
	s_waitcnt lgkmcnt(0)
	v_add_f32_e32 v9, v9, v91
	v_add_f32_e32 v90, v90, v92
	ds_bpermute_b32 v91, v6, v9
	ds_bpermute_b32 v92, v6, v90
	s_waitcnt lgkmcnt(0)
	v_add_f32_e32 v9, v9, v91
	v_add_f32_e32 v90, v90, v92
	ds_bpermute_b32 v91, v7, v9
	ds_bpermute_b32 v92, v7, v90
	s_waitcnt lgkmcnt(0)
	v_add_f32_e32 v9, v9, v91
	v_add_f32_e32 v90, v90, v92
	ds_bpermute_b32 v91, v8, v9
	ds_bpermute_b32 v92, v8, v90
	s_waitcnt lgkmcnt(0)
	v_add_f32_e32 v9, v9, v91
	v_add_f32_e32 v90, v90, v92
	v_mul_f32_e32 v93, 0x3a800000, v9
	v_mul_f32_e32 v91, 0x3a800000, v90
	v_fma_f32 v91, -v93, v93, v91
	v_max_f32_e32 v91, 0, v91
	v_add_f32_e32 v91, 0x358637bd, v91
	v_rsq_f32_e32 v94, v91
	v_mul_f32_e32 v91, 0.5, v91
	v_mul_f32_e32 v92, v94, v94
	v_fma_f32 v92, -v91, v92, 0.5
	v_fma_f32 v94, v94, v92, v94
	s_add_u32 s2, s12, 0x18
	s_addc_u32 s3, s13, 0
	v_mov_b32_e32 v188, v93
	v_mov_b32_e32 v189, v94
	s_mov_b64 exec, 1
	global_store_dwordx2 v97, v[188:189], s[2:3]
	s_mov_b64 exec, -1
	v_sub_f32_e32 v98, v98, v93
	v_sub_f32_e32 v99, v99, v93
	v_sub_f32_e32 v100, v100, v93
	v_sub_f32_e32 v101, v101, v93
	v_sub_f32_e32 v102, v102, v93
	v_sub_f32_e32 v103, v103, v93
	v_sub_f32_e32 v104, v104, v93
	v_sub_f32_e32 v105, v105, v93
	v_sub_f32_e32 v106, v106, v93
	v_sub_f32_e32 v107, v107, v93
	v_sub_f32_e32 v108, v108, v93
	v_sub_f32_e32 v109, v109, v93
	v_sub_f32_e32 v110, v110, v93
	v_sub_f32_e32 v111, v111, v93
	v_sub_f32_e32 v112, v112, v93
	v_sub_f32_e32 v113, v113, v93
	v_mul_f32_e32 v98, v94, v98
	v_mul_f32_e32 v99, v94, v99
	v_mul_f32_e32 v100, v94, v100
	v_mul_f32_e32 v101, v94, v101
	v_mul_f32_e32 v102, v94, v102
	v_mul_f32_e32 v103, v94, v103
	v_mul_f32_e32 v104, v94, v104
	v_mul_f32_e32 v105, v94, v105
	v_mul_f32_e32 v106, v94, v106
	v_mul_f32_e32 v107, v94, v107
	v_mul_f32_e32 v108, v94, v108
	v_mul_f32_e32 v109, v94, v109
	v_mul_f32_e32 v110, v94, v110
	v_mul_f32_e32 v111, v94, v111
	v_mul_f32_e32 v112, v94, v112
	v_mul_f32_e32 v113, v94, v113
	v_fma_f32 v98, v98, v10, v26
	v_fma_f32 v99, v99, v11, v27
	v_fma_f32 v100, v100, v12, v28
	v_fma_f32 v101, v101, v13, v29
	v_fma_f32 v102, v102, v14, v30
	v_fma_f32 v103, v103, v15, v31
	v_fma_f32 v104, v104, v16, v32
	v_fma_f32 v105, v105, v17, v33
	v_fma_f32 v106, v106, v18, v34
	v_fma_f32 v107, v107, v19, v35
	v_fma_f32 v108, v108, v20, v36
	v_fma_f32 v109, v109, v21, v37
	v_fma_f32 v110, v110, v22, v38
	v_fma_f32 v111, v111, v23, v39
	v_fma_f32 v112, v112, v24, v40
	v_fma_f32 v113, v113, v25, v41
	v_add_f32_e32 v9, v98, v99
	v_add_f32_e32 v91, v100, v101
	v_mul_f32_e32 v90, v98, v98
	v_mul_f32_e32 v92, v99, v99
	v_add_f32_e32 v9, v9, v102
	v_add_f32_e32 v91, v91, v103
	v_add_f32_e32 v9, v9, v104
	v_add_f32_e32 v91, v91, v105
	v_add_f32_e32 v9, v9, v106
	v_add_f32_e32 v91, v91, v107
	v_add_f32_e32 v9, v9, v108
	v_add_f32_e32 v91, v91, v109
	v_add_f32_e32 v9, v9, v110
	v_add_f32_e32 v91, v91, v111
	v_add_f32_e32 v9, v9, v112
	v_add_f32_e32 v91, v91, v113
	v_fmac_f32_e32 v90, v100, v100
	v_fmac_f32_e32 v92, v101, v101
	v_fmac_f32_e32 v90, v102, v102
	v_fmac_f32_e32 v92, v103, v103
	v_fmac_f32_e32 v90, v104, v104
	v_fmac_f32_e32 v92, v105, v105
	v_fmac_f32_e32 v90, v106, v106
	v_fmac_f32_e32 v92, v107, v107
	v_fmac_f32_e32 v90, v108, v108
	v_fmac_f32_e32 v92, v109, v109
	v_fmac_f32_e32 v90, v110, v110
	v_fmac_f32_e32 v92, v111, v111
	v_fmac_f32_e32 v90, v112, v112
	v_fmac_f32_e32 v92, v113, v113
	v_add_f32_e32 v9, v9, v91
	v_add_f32_e32 v90, v90, v92
	ds_bpermute_b32 v91, v3, v9
	ds_bpermute_b32 v92, v3, v90
	s_waitcnt lgkmcnt(0)
	v_add_f32_e32 v9, v9, v91
	v_add_f32_e32 v90, v90, v92
	ds_bpermute_b32 v91, v4, v9
	ds_bpermute_b32 v92, v4, v90
	s_waitcnt lgkmcnt(0)
	v_add_f32_e32 v9, v9, v91
	v_add_f32_e32 v90, v90, v92
	ds_bpermute_b32 v91, v5, v9
	ds_bpermute_b32 v92, v5, v90
	s_waitcnt lgkmcnt(0)
	v_add_f32_e32 v9, v9, v91
	v_add_f32_e32 v90, v90, v92
	ds_bpermute_b32 v91, v6, v9
	ds_bpermute_b32 v92, v6, v90
	s_waitcnt lgkmcnt(0)
	v_add_f32_e32 v9, v9, v91
	v_add_f32_e32 v90, v90, v92
	ds_bpermute_b32 v91, v7, v9
	ds_bpermute_b32 v92, v7, v90
	s_waitcnt lgkmcnt(0)
	v_add_f32_e32 v9, v9, v91
	v_add_f32_e32 v90, v90, v92
	ds_bpermute_b32 v91, v8, v9
	ds_bpermute_b32 v92, v8, v90
	s_waitcnt lgkmcnt(0)
; DI unsigned pk2(float lo, float hi) { f32x2 v = {lo, hi}; bf16x2_t b = __builtin_convertvector(v, bf16x2_t); return __builtin_bit_cast(unsigned, b); }
; DI void ln_row_v(const Frame& F, f32x4 (&v)[4], float* xout, const float* g, const float* b, const float* sh, const float* sc, bf16_t* hout, const float* slab, const float* gres, float* stat = nullptr) {
;     ...
;         const float mean = s * (1.f / D); const float rstd = 1.f / sqrtf(fmaxf(s2 * (1.f / D) - mean * mean, 0.f) + EPS);
; #pragma unroll
;         for (int j = 0; j < 4; ++j) { const f32x4 hh = ((const f32x4*)sh)[F.lane + 64 * j], cc = ((const f32x4*)sc)[F.lane + 64 * j];
;             const f32x4 o = (v[j] - mean) * rstd * (cc + 1.f) + hh; u32x2 wv; wv.x = pk2(o[0], o[1]); wv.y = pk2(o[2], o[3]);
;             ((u32x2*)hout)[F.lane + 64 * j] = wv; }
;     }
	v_add_f32_e32 v9, v9, v91
	v_add_f32_e32 v90, v90, v92
	v_mul_f32_e32 v93, 0x3a800000, v9
	v_mul_f32_e32 v91, 0x3a800000, v90
	v_fma_f32 v91, -v93, v93, v91
	v_max_f32_e32 v91, 0, v91
	v_add_f32_e32 v91, 0x358637bd, v91
	v_rsq_f32_e32 v94, v91
	v_mul_f32_e32 v91, 0.5, v91
	v_mul_f32_e32 v92, v94, v94
	v_fma_f32 v92, -v91, v92, 0.5
	v_fma_f32 v94, v94, v92, v94
	v_sub_f32_e32 v98, v98, v93
	v_sub_f32_e32 v99, v99, v93
	v_sub_f32_e32 v100, v100, v93
	v_sub_f32_e32 v101, v101, v93
	v_sub_f32_e32 v102, v102, v93
	v_sub_f32_e32 v103, v103, v93
	v_sub_f32_e32 v104, v104, v93
	v_sub_f32_e32 v105, v105, v93
	v_sub_f32_e32 v106, v106, v93
	v_sub_f32_e32 v107, v107, v93
	v_sub_f32_e32 v108, v108, v93
	v_sub_f32_e32 v109, v109, v93
	v_sub_f32_e32 v110, v110, v93
	v_sub_f32_e32 v111, v111, v93
	v_sub_f32_e32 v112, v112, v93
	v_sub_f32_e32 v113, v113, v93
	v_mul_f32_e32 v98, v94, v98
	v_mul_f32_e32 v99, v94, v99
	v_mul_f32_e32 v100, v94, v100
	v_mul_f32_e32 v101, v94, v101
	v_mul_f32_e32 v102, v94, v102
	v_mul_f32_e32 v103, v94, v103
	v_mul_f32_e32 v104, v94, v104
	v_mul_f32_e32 v105, v94, v105
	v_mul_f32_e32 v106, v94, v106
	v_mul_f32_e32 v107, v94, v107
	v_mul_f32_e32 v108, v94, v108
	v_mul_f32_e32 v109, v94, v109
	v_mul_f32_e32 v110, v94, v110
	v_mul_f32_e32 v111, v94, v111
	v_mul_f32_e32 v112, v94, v112
	v_mul_f32_e32 v113, v94, v113
	v_fma_f32 v98, v98, v130, v114
	v_fma_f32 v99, v99, v131, v115
	v_fma_f32 v100, v100, v132, v116
	v_fma_f32 v101, v101, v133, v117
	v_fma_f32 v102, v102, v134, v118
	v_fma_f32 v103, v103, v135, v119
	v_fma_f32 v104, v104, v136, v120
	v_fma_f32 v105, v105, v137, v121
	v_fma_f32 v106, v106, v138, v122
	v_fma_f32 v107, v107, v139, v123
	v_fma_f32 v108, v108, v140, v124
	v_fma_f32 v109, v109, v141, v125
	v_fma_f32 v110, v110, v142, v126
	v_fma_f32 v111, v111, v143, v127
	v_fma_f32 v112, v112, v144, v128
	v_fma_f32 v113, v113, v145, v129
	v_cvt_pk_bf16_f32 v190, v98, v99
	v_cvt_pk_bf16_f32 v191, v100, v101
	v_cvt_pk_bf16_f32 v192, v102, v103
	v_cvt_pk_bf16_f32 v193, v104, v105
	v_cvt_pk_bf16_f32 v194, v106, v107
	v_cvt_pk_bf16_f32 v195, v108, v109
	v_cvt_pk_bf16_f32 v196, v110, v111
	v_cvt_pk_bf16_f32 v197, v112, v113
	s_add_u32 s2, s10, 0x1800
	s_addc_u32 s3, s11, 0
	global_store_dwordx2 v1, v[190:191], s[2:3]
	global_store_dwordx2 v1, v[192:193], s[2:3] offset:512
	global_store_dwordx2 v1, v[194:195], s[2:3] offset:1024
	global_store_dwordx2 v1, v[196:197], s[2:3] offset:1536
	s_add_u32 s2, s8, 0x7000
	s_addc_u32 s3, s9, 0
	global_load_dwordx4 v[98:101], v0, s[2:3]
	global_load_dwordx4 v[102:105], v0, s[2:3] offset:1024
	global_load_dwordx4 v[106:109], v0, s[2:3] offset:2048
	global_load_dwordx4 v[110:113], v0, s[2:3] offset:3072
	s_waitcnt vmcnt(27)
	v_add_f32_e32 v9, v42, v43
	v_add_f32_e32 v91, v44, v45
	v_mul_f32_e32 v90, v42, v42
	v_mul_f32_e32 v92, v43, v43
	v_add_f32_e32 v9, v9, v46
	v_add_f32_e32 v91, v91, v47
	v_add_f32_e32 v9, v9, v48
	v_add_f32_e32 v91, v91, v49
	v_add_f32_e32 v9, v9, v50
	v_add_f32_e32 v91, v91, v51
	v_add_f32_e32 v9, v9, v52
	v_add_f32_e32 v91, v91, v53
	v_add_f32_e32 v9, v9, v54
	v_add_f32_e32 v91, v91, v55
	v_add_f32_e32 v9, v9, v56
	v_add_f32_e32 v91, v91, v57
	v_fmac_f32_e32 v90, v44, v44
	v_fmac_f32_e32 v92, v45, v45
	v_fmac_f32_e32 v90, v46, v46
	v_fmac_f32_e32 v92, v47, v47
	v_fmac_f32_e32 v90, v48, v48
	v_fmac_f32_e32 v92, v49, v49
	v_fmac_f32_e32 v90, v50, v50
	v_fmac_f32_e32 v92, v51, v51
	v_fmac_f32_e32 v90, v52, v52
	v_fmac_f32_e32 v92, v53, v53
	v_fmac_f32_e32 v90, v54, v54
	v_fmac_f32_e32 v92, v55, v55
	v_fmac_f32_e32 v90, v56, v56
	v_fmac_f32_e32 v92, v57, v57
	v_add_f32_e32 v9, v9, v91
	v_add_f32_e32 v90, v90, v92
	ds_bpermute_b32 v91, v3, v9
	ds_bpermute_b32 v92, v3, v90
	s_waitcnt lgkmcnt(0)
	v_add_f32_e32 v9, v9, v91
	v_add_f32_e32 v90, v90, v92
	ds_bpermute_b32 v91, v4, v9
	ds_bpermute_b32 v92, v4, v90
	s_waitcnt lgkmcnt(0)
	v_add_f32_e32 v9, v9, v91
	v_add_f32_e32 v90, v90, v92
	ds_bpermute_b32 v91, v5, v9
	ds_bpermute_b32 v92, v5, v90
	s_waitcnt lgkmcnt(0)
	v_add_f32_e32 v9, v9, v91
	v_add_f32_e32 v90, v90, v92
	ds_bpermute_b32 v91, v6, v9
	ds_bpermute_b32 v92, v6, v90
	s_waitcnt lgkmcnt(0)
	v_add_f32_e32 v9, v9, v91
	v_add_f32_e32 v90, v90, v92
	ds_bpermute_b32 v91, v7, v9
	ds_bpermute_b32 v92, v7, v90
	s_waitcnt lgkmcnt(0)
	v_add_f32_e32 v9, v9, v91
	v_add_f32_e32 v90, v90, v92
	ds_bpermute_b32 v91, v8, v9
	ds_bpermute_b32 v92, v8, v90
	s_waitcnt lgkmcnt(0)
; DI unsigned pk2(float lo, float hi) { f32x2 v = {lo, hi}; bf16x2_t b = __builtin_convertvector(v, bf16x2_t); return __builtin_bit_cast(unsigned, b); }
; DI void ln_row_v(const Frame& F, f32x4 (&v)[4], float* xout, const float* g, const float* b, const float* sh, const float* sc, bf16_t* hout, const float* slab, const float* gres, float* stat = nullptr) {
;     ...
;     if (g) {
;         float s = 0.f, s2 = 0.f;
; #pragma unroll
;         for (int j = 0; j < 4; ++j) { s += (v[j][0] + v[j][1]) + (v[j][2] + v[j][3]); s2 += (v[j][0] * v[j][0] + v[j][1] * v[j][1]) + (v[j][2] * v[j][2] + v[j][3] * v[j][3]); }
;         wave_sum2(s, s2, F.lane);
;         const float mean = s * (1.f / D); const float rstd = 1.f / sqrtf(fmaxf(s2 * (1.f / D) - mean * mean, 0.f) + EPS);
;         if (stat && F.lane == 0) { f32x2 sv = {mean, rstd}; *(f32x2*)stat = sv; }
; #pragma unroll
;         for (int j = 0; j < 4; ++j) { const f32x4 gg = ((const f32x4*)g)[F.lane + 64 * j], bb = ((const f32x4*)b)[F.lane + 64 * j];
;             v[j] = (v[j] - mean) * rstd * gg + bb; if (xout) ((f32x4*)xout)[F.lane + 64 * j] = v[j]; }
;     }
;     if (hout) {
;         float s = 0.f, s2 = 0.f;
; #pragma unroll
;         for (int j = 0; j < 4; ++j) { s += (v[j][0] + v[j][1]) + (v[j][2] + v[j][3]); s2 += (v[j][0] * v[j][0] + v[j][1] * v[j][1]) + (v[j][2] * v[j][2] + v[j][3] * v[j][3]); }
;         wave_sum2(s, s2, F.lane);
;         const float mean = s * (1.f / D); const float rstd = 1.f / sqrtf(fmaxf(s2 * (1.f / D) - mean * mean, 0.f) + EPS);
; #pragma unroll
;         for (int j = 0; j < 4; ++j) { const f32x4 hh = ((const f32x4*)sh)[F.lane + 64 * j], cc = ((const f32x4*)sc)[F.lane + 64 * j];
;             const f32x4 o = (v[j] - mean) * rstd * (cc + 1.f) + hh; u32x2 wv; wv.x = pk2(o[0], o[1]); wv.y = pk2(o[2], o[3]);
;             ((u32x2*)hout)[F.lane + 64 * j] = wv; }
;     }
	v_add_f32_e32 v9, v9, v91
	v_add_f32_e32 v90, v90, v92
	v_mul_f32_e32 v93, 0x3a800000, v9
	v_mul_f32_e32 v91, 0x3a800000, v90
	v_fma_f32 v91, -v93, v93, v91
	v_max_f32_e32 v91, 0, v91
	v_add_f32_e32 v91, 0x358637bd, v91
	v_rsq_f32_e32 v94, v91
	v_mul_f32_e32 v91, 0.5, v91
	v_mul_f32_e32 v92, v94, v94
	v_fma_f32 v92, -v91, v92, 0.5
	v_fma_f32 v94, v94, v92, v94
	s_add_u32 s2, s12, 0x20
	s_addc_u32 s3, s13, 0
	v_mov_b32_e32 v188, v93
	v_mov_b32_e32 v189, v94
	s_mov_b64 exec, 1
	global_store_dwordx2 v97, v[188:189], s[2:3]
	s_mov_b64 exec, -1
	v_sub_f32_e32 v42, v42, v93
	v_sub_f32_e32 v43, v43, v93
	v_sub_f32_e32 v44, v44, v93
	v_sub_f32_e32 v45, v45, v93
	v_sub_f32_e32 v46, v46, v93
	v_sub_f32_e32 v47, v47, v93
	v_sub_f32_e32 v48, v48, v93
	v_sub_f32_e32 v49, v49, v93
	v_sub_f32_e32 v50, v50, v93
	v_sub_f32_e32 v51, v51, v93
	v_sub_f32_e32 v52, v52, v93
	v_sub_f32_e32 v53, v53, v93
	v_sub_f32_e32 v54, v54, v93
	v_sub_f32_e32 v55, v55, v93
	v_sub_f32_e32 v56, v56, v93
	v_sub_f32_e32 v57, v57, v93
	v_mul_f32_e32 v42, v94, v42
	v_mul_f32_e32 v43, v94, v43
	v_mul_f32_e32 v44, v94, v44
	v_mul_f32_e32 v45, v94, v45
	v_mul_f32_e32 v46, v94, v46
	v_mul_f32_e32 v47, v94, v47
	v_mul_f32_e32 v48, v94, v48
	v_mul_f32_e32 v49, v94, v49
	v_mul_f32_e32 v50, v94, v50
	v_mul_f32_e32 v51, v94, v51
	v_mul_f32_e32 v52, v94, v52
	v_mul_f32_e32 v53, v94, v53
	v_mul_f32_e32 v54, v94, v54
	v_mul_f32_e32 v55, v94, v55
	v_mul_f32_e32 v56, v94, v56
	v_mul_f32_e32 v57, v94, v57
	v_fma_f32 v42, v42, v10, v26
	v_fma_f32 v43, v43, v11, v27
	v_fma_f32 v44, v44, v12, v28
	v_fma_f32 v45, v45, v13, v29
	v_fma_f32 v46, v46, v14, v30
	v_fma_f32 v47, v47, v15, v31
	v_fma_f32 v48, v48, v16, v32
	v_fma_f32 v49, v49, v17, v33
	v_fma_f32 v50, v50, v18, v34
	v_fma_f32 v51, v51, v19, v35
	v_fma_f32 v52, v52, v20, v36
	v_fma_f32 v53, v53, v21, v37
	v_fma_f32 v54, v54, v22, v38
	v_fma_f32 v55, v55, v23, v39
	v_fma_f32 v56, v56, v24, v40
	v_fma_f32 v57, v57, v25, v41
	v_add_f32_e32 v9, v42, v43
	v_add_f32_e32 v91, v44, v45
	v_mul_f32_e32 v90, v42, v42
	v_mul_f32_e32 v92, v43, v43
	v_add_f32_e32 v9, v9, v46
	v_add_f32_e32 v91, v91, v47
	v_add_f32_e32 v9, v9, v48
	v_add_f32_e32 v91, v91, v49
	v_add_f32_e32 v9, v9, v50
	v_add_f32_e32 v91, v91, v51
	v_add_f32_e32 v9, v9, v52
	v_add_f32_e32 v91, v91, v53
	v_add_f32_e32 v9, v9, v54
	v_add_f32_e32 v91, v91, v55
	v_add_f32_e32 v9, v9, v56
	v_add_f32_e32 v91, v91, v57
	v_fmac_f32_e32 v90, v44, v44
	v_fmac_f32_e32 v92, v45, v45
	v_fmac_f32_e32 v90, v46, v46
	v_fmac_f32_e32 v92, v47, v47
	v_fmac_f32_e32 v90, v48, v48
	v_fmac_f32_e32 v92, v49, v49
	v_fmac_f32_e32 v90, v50, v50
	v_fmac_f32_e32 v92, v51, v51
	v_fmac_f32_e32 v90, v52, v52
	v_fmac_f32_e32 v92, v53, v53
	v_fmac_f32_e32 v90, v54, v54
	v_fmac_f32_e32 v92, v55, v55
	v_fmac_f32_e32 v90, v56, v56
	v_fmac_f32_e32 v92, v57, v57
	v_add_f32_e32 v9, v9, v91
	v_add_f32_e32 v90, v90, v92
	ds_bpermute_b32 v91, v3, v9
	ds_bpermute_b32 v92, v3, v90
	s_waitcnt lgkmcnt(0)
	v_add_f32_e32 v9, v9, v91
	v_add_f32_e32 v90, v90, v92
	ds_bpermute_b32 v91, v4, v9
	ds_bpermute_b32 v92, v4, v90
	s_waitcnt lgkmcnt(0)
	v_add_f32_e32 v9, v9, v91
	v_add_f32_e32 v90, v90, v92
	ds_bpermute_b32 v91, v5, v9
	ds_bpermute_b32 v92, v5, v90
	s_waitcnt lgkmcnt(0)
	v_add_f32_e32 v9, v9, v91
	v_add_f32_e32 v90, v90, v92
	ds_bpermute_b32 v91, v6, v9
	ds_bpermute_b32 v92, v6, v90
	s_waitcnt lgkmcnt(0)
	v_add_f32_e32 v9, v9, v91
	v_add_f32_e32 v90, v90, v92
	ds_bpermute_b32 v91, v7, v9
	ds_bpermute_b32 v92, v7, v90
	s_waitcnt lgkmcnt(0)
	v_add_f32_e32 v9, v9, v91
	v_add_f32_e32 v90, v90, v92
	ds_bpermute_b32 v91, v8, v9
	ds_bpermute_b32 v92, v8, v90
	s_waitcnt lgkmcnt(0)
	v_add_f32_e32 v9, v9, v91
	v_add_f32_e32 v90, v90, v92
	v_mul_f32_e32 v93, 0x3a800000, v9
	v_mul_f32_e32 v91, 0x3a800000, v90
	v_fma_f32 v91, -v93, v93, v91
	v_max_f32_e32 v91, 0, v91
	v_add_f32_e32 v91, 0x358637bd, v91
	v_rsq_f32_e32 v94, v91
	v_mul_f32_e32 v91, 0.5, v91
	v_mul_f32_e32 v92, v94, v94
	v_fma_f32 v92, -v91, v92, 0.5
	v_fma_f32 v94, v94, v92, v94
	v_sub_f32_e32 v42, v42, v93
	v_sub_f32_e32 v43, v43, v93
	v_sub_f32_e32 v44, v44, v93
	v_sub_f32_e32 v45, v45, v93
	v_sub_f32_e32 v46, v46, v93
	v_sub_f32_e32 v47, v47, v93
	v_sub_f32_e32 v48, v48, v93
	v_sub_f32_e32 v49, v49, v93
	v_sub_f32_e32 v50, v50, v93
	v_sub_f32_e32 v51, v51, v93
	v_sub_f32_e32 v52, v52, v93
	v_sub_f32_e32 v53, v53, v93
	v_sub_f32_e32 v54, v54, v93
	v_sub_f32_e32 v55, v55, v93
	v_sub_f32_e32 v56, v56, v93
	v_sub_f32_e32 v57, v57, v93
	v_mul_f32_e32 v42, v94, v42
	v_mul_f32_e32 v43, v94, v43
	v_mul_f32_e32 v44, v94, v44
	v_mul_f32_e32 v45, v94, v45
	v_mul_f32_e32 v46, v94, v46
	v_mul_f32_e32 v47, v94, v47
	v_mul_f32_e32 v48, v94, v48
	v_mul_f32_e32 v49, v94, v49
	v_mul_f32_e32 v50, v94, v50
	v_mul_f32_e32 v51, v94, v51
	v_mul_f32_e32 v52, v94, v52
	v_mul_f32_e32 v53, v94, v53
	v_mul_f32_e32 v54, v94, v54
	v_mul_f32_e32 v55, v94, v55
	v_mul_f32_e32 v56, v94, v56
	v_mul_f32_e32 v57, v94, v57
	v_fma_f32 v42, v42, v130, v114
	v_fma_f32 v43, v43, v131, v115
	v_fma_f32 v44, v44, v132, v116
	v_fma_f32 v45, v45, v133, v117
	v_fma_f32 v46, v46, v134, v118
	v_fma_f32 v47, v47, v135, v119
	v_fma_f32 v48, v48, v136, v120
	v_fma_f32 v49, v49, v137, v121
	v_fma_f32 v50, v50, v138, v122
	v_fma_f32 v51, v51, v139, v123
	v_fma_f32 v52, v52, v140, v124
	v_fma_f32 v53, v53, v141, v125
	v_fma_f32 v54, v54, v142, v126
	v_fma_f32 v55, v55, v143, v127
	v_fma_f32 v56, v56, v144, v128
	v_fma_f32 v57, v57, v145, v129
	v_cvt_pk_bf16_f32 v190, v42, v43
	v_cvt_pk_bf16_f32 v191, v44, v45
	v_cvt_pk_bf16_f32 v192, v46, v47
	v_cvt_pk_bf16_f32 v193, v48, v49
	v_cvt_pk_bf16_f32 v194, v50, v51
	v_cvt_pk_bf16_f32 v195, v52, v53
	v_cvt_pk_bf16_f32 v196, v54, v55
	v_cvt_pk_bf16_f32 v197, v56, v57
	s_add_u32 s2, s10, 0x2000
	s_addc_u32 s3, s11, 0
	global_store_dwordx2 v1, v[190:191], s[2:3]
	global_store_dwordx2 v1, v[192:193], s[2:3] offset:512
	global_store_dwordx2 v1, v[194:195], s[2:3] offset:1024
	global_store_dwordx2 v1, v[196:197], s[2:3] offset:1536
	s_mov_b64 s[2:3], s[20:21]
	global_load_dwordx4 v[42:45], v0, s[2:3]
	global_load_dwordx4 v[46:49], v0, s[2:3] offset:1024
	global_load_dwordx4 v[50:53], v0, s[2:3] offset:2048
	global_load_dwordx4 v[54:57], v0, s[2:3] offset:3072
	s_waitcnt vmcnt(27)
; DI void ln_row_v(const Frame& F, f32x4 (&v)[4], float* xout, const float* g, const float* b, const float* sh, const float* sc, bf16_t* hout, const float* slab, const float* gres, float* stat = nullptr) {
;     ...
;     if (g) {
;         float s = 0.f, s2 = 0.f;
; #pragma unroll
;         for (int j = 0; j < 4; ++j) { s += (v[j][0] + v[j][1]) + (v[j][2] + v[j][3]); s2 += (v[j][0] * v[j][0] + v[j][1] * v[j][1]) + (v[j][2] * v[j][2] + v[j][3] * v[j][3]); }
;         wave_sum2(s, s2, F.lane);
;         const float mean = s * (1.f / D); const float rstd = 1.f / sqrtf(fmaxf(s2 * (1.f / D) - mean * mean, 0.f) + EPS);
;         if (stat && F.lane == 0) { f32x2 sv = {mean, rstd}; *(f32x2*)stat = sv; }
; #pragma unroll
;         for (int j = 0; j < 4; ++j) { const f32x4 gg = ((const f32x4*)g)[F.lane + 64 * j], bb = ((const f32x4*)b)[F.lane + 64 * j];
;             v[j] = (v[j] - mean) * rstd * gg + bb; if (xout) ((f32x4*)xout)[F.lane + 64 * j] = v[j]; }
;     }
;     if (hout) {
;         float s = 0.f, s2 = 0.f;
; #pragma unroll
;         for (int j = 0; j < 4; ++j) { s += (v[j][0] + v[j][1]) + (v[j][2] + v[j][3]); s2 += (v[j][0] * v[j][0] + v[j][1] * v[j][1]) + (v[j][2] * v[j][2] + v[j][3] * v[j][3]); }
;         wave_sum2(s, s2, F.lane);
;         const float mean = s * (1.f / D); const float rstd = 1.f / sqrtf(fmaxf(s2 * (1.f / D) - mean * mean, 0.f) + EPS);
	v_add_f32_e32 v9, v58, v59
	v_add_f32_e32 v91, v60, v61
	v_mul_f32_e32 v90, v58, v58
	v_mul_f32_e32 v92, v59, v59
	v_add_f32_e32 v9, v9, v62
	v_add_f32_e32 v91, v91, v63
	v_add_f32_e32 v9, v9, v64
	v_add_f32_e32 v91, v91, v65
	v_add_f32_e32 v9, v9, v66
	v_add_f32_e32 v91, v91, v67
	v_add_f32_e32 v9, v9, v68
	v_add_f32_e32 v91, v91, v69
	v_add_f32_e32 v9, v9, v70
	v_add_f32_e32 v91, v91, v71
	v_add_f32_e32 v9, v9, v72
	v_add_f32_e32 v91, v91, v73
	v_fmac_f32_e32 v90, v60, v60
	v_fmac_f32_e32 v92, v61, v61
	v_fmac_f32_e32 v90, v62, v62
	v_fmac_f32_e32 v92, v63, v63
	v_fmac_f32_e32 v90, v64, v64
	v_fmac_f32_e32 v92, v65, v65
	v_fmac_f32_e32 v90, v66, v66
	v_fmac_f32_e32 v92, v67, v67
	v_fmac_f32_e32 v90, v68, v68
	v_fmac_f32_e32 v92, v69, v69
	v_fmac_f32_e32 v90, v70, v70
	v_fmac_f32_e32 v92, v71, v71
	v_fmac_f32_e32 v90, v72, v72
	v_fmac_f32_e32 v92, v73, v73
	v_add_f32_e32 v9, v9, v91
	v_add_f32_e32 v90, v90, v92
	ds_bpermute_b32 v91, v3, v9
	ds_bpermute_b32 v92, v3, v90
	s_waitcnt lgkmcnt(0)
	v_add_f32_e32 v9, v9, v91
	v_add_f32_e32 v90, v90, v92
	ds_bpermute_b32 v91, v4, v9
	ds_bpermute_b32 v92, v4, v90
	s_waitcnt lgkmcnt(0)
	v_add_f32_e32 v9, v9, v91
	v_add_f32_e32 v90, v90, v92
	ds_bpermute_b32 v91, v5, v9
	ds_bpermute_b32 v92, v5, v90
	s_waitcnt lgkmcnt(0)
	v_add_f32_e32 v9, v9, v91
	v_add_f32_e32 v90, v90, v92
	ds_bpermute_b32 v91, v6, v9
	ds_bpermute_b32 v92, v6, v90
	s_waitcnt lgkmcnt(0)
	v_add_f32_e32 v9, v9, v91
	v_add_f32_e32 v90, v90, v92
	ds_bpermute_b32 v91, v7, v9
	ds_bpermute_b32 v92, v7, v90
	s_waitcnt lgkmcnt(0)
	v_add_f32_e32 v9, v9, v91
	v_add_f32_e32 v90, v90, v92
	ds_bpermute_b32 v91, v8, v9
	ds_bpermute_b32 v92, v8, v90
	s_waitcnt lgkmcnt(0)
	v_add_f32_e32 v9, v9, v91
	v_add_f32_e32 v90, v90, v92
	v_mul_f32_e32 v93, 0x3a800000, v9
	v_mul_f32_e32 v91, 0x3a800000, v90
	v_fma_f32 v91, -v93, v93, v91
	v_max_f32_e32 v91, 0, v91
	v_add_f32_e32 v91, 0x358637bd, v91
	v_rsq_f32_e32 v94, v91
	v_mul_f32_e32 v91, 0.5, v91
	v_mul_f32_e32 v92, v94, v94
	v_fma_f32 v92, -v91, v92, 0.5
	v_fma_f32 v94, v94, v92, v94
	s_add_u32 s2, s12, 0x28
	s_addc_u32 s3, s13, 0
	v_mov_b32_e32 v188, v93
	v_mov_b32_e32 v189, v94
	s_mov_b64 exec, 1
	global_store_dwordx2 v97, v[188:189], s[2:3]
	s_mov_b64 exec, -1
	v_sub_f32_e32 v58, v58, v93
	v_sub_f32_e32 v59, v59, v93
	v_sub_f32_e32 v60, v60, v93
	v_sub_f32_e32 v61, v61, v93
	v_sub_f32_e32 v62, v62, v93
	v_sub_f32_e32 v63, v63, v93
	v_sub_f32_e32 v64, v64, v93
	v_sub_f32_e32 v65, v65, v93
	v_sub_f32_e32 v66, v66, v93
	v_sub_f32_e32 v67, v67, v93
	v_sub_f32_e32 v68, v68, v93
	v_sub_f32_e32 v69, v69, v93
	v_sub_f32_e32 v70, v70, v93
	v_sub_f32_e32 v71, v71, v93
	v_sub_f32_e32 v72, v72, v93
	v_sub_f32_e32 v73, v73, v93
	v_mul_f32_e32 v58, v94, v58
	v_mul_f32_e32 v59, v94, v59
	v_mul_f32_e32 v60, v94, v60
	v_mul_f32_e32 v61, v94, v61
	v_mul_f32_e32 v62, v94, v62
	v_mul_f32_e32 v63, v94, v63
	v_mul_f32_e32 v64, v94, v64
	v_mul_f32_e32 v65, v94, v65
	v_mul_f32_e32 v66, v94, v66
	v_mul_f32_e32 v67, v94, v67
	v_mul_f32_e32 v68, v94, v68
	v_mul_f32_e32 v69, v94, v69
	v_mul_f32_e32 v70, v94, v70
	v_mul_f32_e32 v71, v94, v71
	v_mul_f32_e32 v72, v94, v72
	v_mul_f32_e32 v73, v94, v73
	v_fma_f32 v58, v58, v10, v26
	v_fma_f32 v59, v59, v11, v27
	v_fma_f32 v60, v60, v12, v28
	v_fma_f32 v61, v61, v13, v29
	v_fma_f32 v62, v62, v14, v30
	v_fma_f32 v63, v63, v15, v31
	v_fma_f32 v64, v64, v16, v32
	v_fma_f32 v65, v65, v17, v33
	v_fma_f32 v66, v66, v18, v34
	v_fma_f32 v67, v67, v19, v35
	v_fma_f32 v68, v68, v20, v36
	v_fma_f32 v69, v69, v21, v37
	v_fma_f32 v70, v70, v22, v38
	v_fma_f32 v71, v71, v23, v39
	v_fma_f32 v72, v72, v24, v40
	v_fma_f32 v73, v73, v25, v41
	v_add_f32_e32 v9, v58, v59
	v_add_f32_e32 v91, v60, v61
	v_mul_f32_e32 v90, v58, v58
	v_mul_f32_e32 v92, v59, v59
	v_add_f32_e32 v9, v9, v62
	v_add_f32_e32 v91, v91, v63
	v_add_f32_e32 v9, v9, v64
	v_add_f32_e32 v91, v91, v65
	v_add_f32_e32 v9, v9, v66
	v_add_f32_e32 v91, v91, v67
	v_add_f32_e32 v9, v9, v68
	v_add_f32_e32 v91, v91, v69
	v_add_f32_e32 v9, v9, v70
	v_add_f32_e32 v91, v91, v71
	v_add_f32_e32 v9, v9, v72
	v_add_f32_e32 v91, v91, v73
	v_fmac_f32_e32 v90, v60, v60
	v_fmac_f32_e32 v92, v61, v61
	v_fmac_f32_e32 v90, v62, v62
	v_fmac_f32_e32 v92, v63, v63
	v_fmac_f32_e32 v90, v64, v64
	v_fmac_f32_e32 v92, v65, v65
	v_fmac_f32_e32 v90, v66, v66
	v_fmac_f32_e32 v92, v67, v67
	v_fmac_f32_e32 v90, v68, v68
	v_fmac_f32_e32 v92, v69, v69
	v_fmac_f32_e32 v90, v70, v70
	v_fmac_f32_e32 v92, v71, v71
	v_fmac_f32_e32 v90, v72, v72
	v_fmac_f32_e32 v92, v73, v73
	v_add_f32_e32 v9, v9, v91
	v_add_f32_e32 v90, v90, v92
	ds_bpermute_b32 v91, v3, v9
	ds_bpermute_b32 v92, v3, v90
	s_waitcnt lgkmcnt(0)
	v_add_f32_e32 v9, v9, v91
	v_add_f32_e32 v90, v90, v92
	ds_bpermute_b32 v91, v4, v9
	ds_bpermute_b32 v92, v4, v90
	s_waitcnt lgkmcnt(0)
	v_add_f32_e32 v9, v9, v91
	v_add_f32_e32 v90, v90, v92
	ds_bpermute_b32 v91, v5, v9
	ds_bpermute_b32 v92, v5, v90
	s_waitcnt lgkmcnt(0)
	v_add_f32_e32 v9, v9, v91
	v_add_f32_e32 v90, v90, v92
	ds_bpermute_b32 v91, v6, v9
	ds_bpermute_b32 v92, v6, v90
	s_waitcnt lgkmcnt(0)
	v_add_f32_e32 v9, v9, v91
	v_add_f32_e32 v90, v90, v92
	ds_bpermute_b32 v91, v7, v9
	ds_bpermute_b32 v92, v7, v90
	s_waitcnt lgkmcnt(0)
	v_add_f32_e32 v9, v9, v91
	v_add_f32_e32 v90, v90, v92
	ds_bpermute_b32 v91, v8, v9
	ds_bpermute_b32 v92, v8, v90
	s_waitcnt lgkmcnt(0)
; DI unsigned pk2(float lo, float hi) { f32x2 v = {lo, hi}; bf16x2_t b = __builtin_convertvector(v, bf16x2_t); return __builtin_bit_cast(unsigned, b); }
; DI void ln_row_v(const Frame& F, f32x4 (&v)[4], float* xout, const float* g, const float* b, const float* sh, const float* sc, bf16_t* hout, const float* slab, const float* gres, float* stat = nullptr) {
;     ...
;     if (g) {
;         float s = 0.f, s2 = 0.f;
; #pragma unroll
;         for (int j = 0; j < 4; ++j) { s += (v[j][0] + v[j][1]) + (v[j][2] + v[j][3]); s2 += (v[j][0] * v[j][0] + v[j][1] * v[j][1]) + (v[j][2] * v[j][2] + v[j][3] * v[j][3]); }
;         wave_sum2(s, s2, F.lane);
;         const float mean = s * (1.f / D); const float rstd = 1.f / sqrtf(fmaxf(s2 * (1.f / D) - mean * mean, 0.f) + EPS);
;         if (stat && F.lane == 0) { f32x2 sv = {mean, rstd}; *(f32x2*)stat = sv; }
; #pragma unroll
;         for (int j = 0; j < 4; ++j) { const f32x4 gg = ((const f32x4*)g)[F.lane + 64 * j], bb = ((const f32x4*)b)[F.lane + 64 * j];
;             v[j] = (v[j] - mean) * rstd * gg + bb; if (xout) ((f32x4*)xout)[F.lane + 64 * j] = v[j]; }
;     }
;     if (hout) {
;         float s = 0.f, s2 = 0.f;
; #pragma unroll
;         for (int j = 0; j < 4; ++j) { s += (v[j][0] + v[j][1]) + (v[j][2] + v[j][3]); s2 += (v[j][0] * v[j][0] + v[j][1] * v[j][1]) + (v[j][2] * v[j][2] + v[j][3] * v[j][3]); }
;         wave_sum2(s, s2, F.lane);
;         const float mean = s * (1.f / D); const float rstd = 1.f / sqrtf(fmaxf(s2 * (1.f / D) - mean * mean, 0.f) + EPS);
; #pragma unroll
;         for (int j = 0; j < 4; ++j) { const f32x4 hh = ((const f32x4*)sh)[F.lane + 64 * j], cc = ((const f32x4*)sc)[F.lane + 64 * j];
;             const f32x4 o = (v[j] - mean) * rstd * (cc + 1.f) + hh; u32x2 wv; wv.x = pk2(o[0], o[1]); wv.y = pk2(o[2], o[3]);
;             ((u32x2*)hout)[F.lane + 64 * j] = wv; }
;     }
	v_add_f32_e32 v9, v9, v91
	v_add_f32_e32 v90, v90, v92
	v_mul_f32_e32 v93, 0x3a800000, v9
	v_mul_f32_e32 v91, 0x3a800000, v90
	v_fma_f32 v91, -v93, v93, v91
	v_max_f32_e32 v91, 0, v91
	v_add_f32_e32 v91, 0x358637bd, v91
	v_rsq_f32_e32 v94, v91
	v_mul_f32_e32 v91, 0.5, v91
	v_mul_f32_e32 v92, v94, v94
	v_fma_f32 v92, -v91, v92, 0.5
	v_fma_f32 v94, v94, v92, v94
	v_sub_f32_e32 v58, v58, v93
	v_sub_f32_e32 v59, v59, v93
	v_sub_f32_e32 v60, v60, v93
	v_sub_f32_e32 v61, v61, v93
	v_sub_f32_e32 v62, v62, v93
	v_sub_f32_e32 v63, v63, v93
	v_sub_f32_e32 v64, v64, v93
	v_sub_f32_e32 v65, v65, v93
	v_sub_f32_e32 v66, v66, v93
	v_sub_f32_e32 v67, v67, v93
	v_sub_f32_e32 v68, v68, v93
	v_sub_f32_e32 v69, v69, v93
	v_sub_f32_e32 v70, v70, v93
	v_sub_f32_e32 v71, v71, v93
	v_sub_f32_e32 v72, v72, v93
	v_sub_f32_e32 v73, v73, v93
	v_mul_f32_e32 v58, v94, v58
	v_mul_f32_e32 v59, v94, v59
	v_mul_f32_e32 v60, v94, v60
	v_mul_f32_e32 v61, v94, v61
	v_mul_f32_e32 v62, v94, v62
	v_mul_f32_e32 v63, v94, v63
	v_mul_f32_e32 v64, v94, v64
	v_mul_f32_e32 v65, v94, v65
	v_mul_f32_e32 v66, v94, v66
	v_mul_f32_e32 v67, v94, v67
	v_mul_f32_e32 v68, v94, v68
	v_mul_f32_e32 v69, v94, v69
	v_mul_f32_e32 v70, v94, v70
	v_mul_f32_e32 v71, v94, v71
	v_mul_f32_e32 v72, v94, v72
	v_mul_f32_e32 v73, v94, v73
	v_fma_f32 v58, v58, v130, v114
	v_fma_f32 v59, v59, v131, v115
	v_fma_f32 v60, v60, v132, v116
	v_fma_f32 v61, v61, v133, v117
	v_fma_f32 v62, v62, v134, v118
	v_fma_f32 v63, v63, v135, v119
	v_fma_f32 v64, v64, v136, v120
	v_fma_f32 v65, v65, v137, v121
	v_fma_f32 v66, v66, v138, v122
	v_fma_f32 v67, v67, v139, v123
	v_fma_f32 v68, v68, v140, v124
	v_fma_f32 v69, v69, v141, v125
	v_fma_f32 v70, v70, v142, v126
	v_fma_f32 v71, v71, v143, v127
	v_fma_f32 v72, v72, v144, v128
	v_fma_f32 v73, v73, v145, v129
	v_cvt_pk_bf16_f32 v190, v58, v59
	v_cvt_pk_bf16_f32 v191, v60, v61
	v_cvt_pk_bf16_f32 v192, v62, v63
	v_cvt_pk_bf16_f32 v193, v64, v65
	v_cvt_pk_bf16_f32 v194, v66, v67
	v_cvt_pk_bf16_f32 v195, v68, v69
	v_cvt_pk_bf16_f32 v196, v70, v71
	v_cvt_pk_bf16_f32 v197, v72, v73
	s_add_u32 s2, s10, 0x2800
	s_addc_u32 s3, s11, 0
	global_store_dwordx2 v1, v[190:191], s[2:3]
	global_store_dwordx2 v1, v[192:193], s[2:3] offset:512
	global_store_dwordx2 v1, v[194:195], s[2:3] offset:1024
	global_store_dwordx2 v1, v[196:197], s[2:3] offset:1536
	s_waitcnt vmcnt(23)
	v_add_f32_e32 v9, v74, v75
	v_add_f32_e32 v91, v76, v77
	v_mul_f32_e32 v90, v74, v74
	v_mul_f32_e32 v92, v75, v75
	v_add_f32_e32 v9, v9, v78
	v_add_f32_e32 v91, v91, v79
	v_add_f32_e32 v9, v9, v80
	v_add_f32_e32 v91, v91, v81
	v_add_f32_e32 v9, v9, v82
	v_add_f32_e32 v91, v91, v83
	v_add_f32_e32 v9, v9, v84
	v_add_f32_e32 v91, v91, v85
	v_add_f32_e32 v9, v9, v86
	v_add_f32_e32 v91, v91, v87
	v_add_f32_e32 v9, v9, v88
	v_add_f32_e32 v91, v91, v89
	v_fmac_f32_e32 v90, v76, v76
	v_fmac_f32_e32 v92, v77, v77
	v_fmac_f32_e32 v90, v78, v78
	v_fmac_f32_e32 v92, v79, v79
	v_fmac_f32_e32 v90, v80, v80
	v_fmac_f32_e32 v92, v81, v81
	v_fmac_f32_e32 v90, v82, v82
	v_fmac_f32_e32 v92, v83, v83
	v_fmac_f32_e32 v90, v84, v84
	v_fmac_f32_e32 v92, v85, v85
	v_fmac_f32_e32 v90, v86, v86
	v_fmac_f32_e32 v92, v87, v87
	v_fmac_f32_e32 v90, v88, v88
	v_fmac_f32_e32 v92, v89, v89
	v_add_f32_e32 v9, v9, v91
	v_add_f32_e32 v90, v90, v92
	ds_bpermute_b32 v91, v3, v9
	ds_bpermute_b32 v92, v3, v90
	s_waitcnt lgkmcnt(0)
	v_add_f32_e32 v9, v9, v91
	v_add_f32_e32 v90, v90, v92
	ds_bpermute_b32 v91, v4, v9
	ds_bpermute_b32 v92, v4, v90
	s_waitcnt lgkmcnt(0)
	v_add_f32_e32 v9, v9, v91
	v_add_f32_e32 v90, v90, v92
	ds_bpermute_b32 v91, v5, v9
	ds_bpermute_b32 v92, v5, v90
	s_waitcnt lgkmcnt(0)
	v_add_f32_e32 v9, v9, v91
	v_add_f32_e32 v90, v90, v92
	ds_bpermute_b32 v91, v6, v9
	ds_bpermute_b32 v92, v6, v90
	s_waitcnt lgkmcnt(0)
	v_add_f32_e32 v9, v9, v91
	v_add_f32_e32 v90, v90, v92
	ds_bpermute_b32 v91, v7, v9
	ds_bpermute_b32 v92, v7, v90
	s_waitcnt lgkmcnt(0)
	v_add_f32_e32 v9, v9, v91
	v_add_f32_e32 v90, v90, v92
	ds_bpermute_b32 v91, v8, v9
	ds_bpermute_b32 v92, v8, v90
	s_waitcnt lgkmcnt(0)
	v_add_f32_e32 v9, v9, v91
	v_add_f32_e32 v90, v90, v92
	v_mul_f32_e32 v93, 0x3a800000, v9
	v_mul_f32_e32 v91, 0x3a800000, v90
	v_fma_f32 v91, -v93, v93, v91
	v_max_f32_e32 v91, 0, v91
	v_add_f32_e32 v91, 0x358637bd, v91
	v_rsq_f32_e32 v94, v91
	v_mul_f32_e32 v91, 0.5, v91
	v_mul_f32_e32 v92, v94, v94
	v_fma_f32 v92, -v91, v92, 0.5
	v_fma_f32 v94, v94, v92, v94
	s_add_u32 s2, s12, 0x30
	s_addc_u32 s3, s13, 0
	v_mov_b32_e32 v188, v93
	v_mov_b32_e32 v189, v94
	s_mov_b64 exec, 1
	global_store_dwordx2 v97, v[188:189], s[2:3]
	s_mov_b64 exec, -1
	v_sub_f32_e32 v74, v74, v93
	v_sub_f32_e32 v75, v75, v93
	v_sub_f32_e32 v76, v76, v93
	v_sub_f32_e32 v77, v77, v93
	v_sub_f32_e32 v78, v78, v93
	v_sub_f32_e32 v79, v79, v93
	v_sub_f32_e32 v80, v80, v93
	v_sub_f32_e32 v81, v81, v93
	v_sub_f32_e32 v82, v82, v93
	v_sub_f32_e32 v83, v83, v93
	v_sub_f32_e32 v84, v84, v93
	v_sub_f32_e32 v85, v85, v93
	v_sub_f32_e32 v86, v86, v93
	v_sub_f32_e32 v87, v87, v93
	v_sub_f32_e32 v88, v88, v93
	v_sub_f32_e32 v89, v89, v93
	v_mul_f32_e32 v74, v94, v74
	v_mul_f32_e32 v75, v94, v75
	v_mul_f32_e32 v76, v94, v76
	v_mul_f32_e32 v77, v94, v77
	v_mul_f32_e32 v78, v94, v78
	v_mul_f32_e32 v79, v94, v79
	v_mul_f32_e32 v80, v94, v80
	v_mul_f32_e32 v81, v94, v81
	v_mul_f32_e32 v82, v94, v82
	v_mul_f32_e32 v83, v94, v83
	v_mul_f32_e32 v84, v94, v84
	v_mul_f32_e32 v85, v94, v85
	v_mul_f32_e32 v86, v94, v86
	v_mul_f32_e32 v87, v94, v87
	v_mul_f32_e32 v88, v94, v88
	v_mul_f32_e32 v89, v94, v89
	v_fma_f32 v74, v74, v10, v26
	v_fma_f32 v75, v75, v11, v27
	v_fma_f32 v76, v76, v12, v28
	v_fma_f32 v77, v77, v13, v29
	v_fma_f32 v78, v78, v14, v30
	v_fma_f32 v79, v79, v15, v31
	v_fma_f32 v80, v80, v16, v32
	v_fma_f32 v81, v81, v17, v33
	v_fma_f32 v82, v82, v18, v34
	v_fma_f32 v83, v83, v19, v35
	v_fma_f32 v84, v84, v20, v36
	v_fma_f32 v85, v85, v21, v37
	v_fma_f32 v86, v86, v22, v38
	v_fma_f32 v87, v87, v23, v39
	v_fma_f32 v88, v88, v24, v40
	v_fma_f32 v89, v89, v25, v41
	v_add_f32_e32 v9, v74, v75
	v_add_f32_e32 v91, v76, v77
	v_mul_f32_e32 v90, v74, v74
	v_mul_f32_e32 v92, v75, v75
	v_add_f32_e32 v9, v9, v78
	v_add_f32_e32 v91, v91, v79
	v_add_f32_e32 v9, v9, v80
	v_add_f32_e32 v91, v91, v81
	v_add_f32_e32 v9, v9, v82
	v_add_f32_e32 v91, v91, v83
	v_add_f32_e32 v9, v9, v84
	v_add_f32_e32 v91, v91, v85
	v_add_f32_e32 v9, v9, v86
	v_add_f32_e32 v91, v91, v87
	v_add_f32_e32 v9, v9, v88
	v_add_f32_e32 v91, v91, v89
	v_fmac_f32_e32 v90, v76, v76
	v_fmac_f32_e32 v92, v77, v77
	v_fmac_f32_e32 v90, v78, v78
	v_fmac_f32_e32 v92, v79, v79
	v_fmac_f32_e32 v90, v80, v80
	v_fmac_f32_e32 v92, v81, v81
	v_fmac_f32_e32 v90, v82, v82
	v_fmac_f32_e32 v92, v83, v83
	v_fmac_f32_e32 v90, v84, v84
	v_fmac_f32_e32 v92, v85, v85
	v_fmac_f32_e32 v90, v86, v86
	v_fmac_f32_e32 v92, v87, v87
	v_fmac_f32_e32 v90, v88, v88
	v_fmac_f32_e32 v92, v89, v89
	v_add_f32_e32 v9, v9, v91
	v_add_f32_e32 v90, v90, v92
	ds_bpermute_b32 v91, v3, v9
	ds_bpermute_b32 v92, v3, v90
	s_waitcnt lgkmcnt(0)
; DI unsigned pk2(float lo, float hi) { f32x2 v = {lo, hi}; bf16x2_t b = __builtin_convertvector(v, bf16x2_t); return __builtin_bit_cast(unsigned, b); }
; DI void ln_row_v(const Frame& F, f32x4 (&v)[4], float* xout, const float* g, const float* b, const float* sh, const float* sc, bf16_t* hout, const float* slab, const float* gres, float* stat = nullptr) {
;     ...
;         wave_sum2(s, s2, F.lane);
;         const float mean = s * (1.f / D); const float rstd = 1.f / sqrtf(fmaxf(s2 * (1.f / D) - mean * mean, 0.f) + EPS);
; #pragma unroll
;         for (int j = 0; j < 4; ++j) { const f32x4 hh = ((const f32x4*)sh)[F.lane + 64 * j], cc = ((const f32x4*)sc)[F.lane + 64 * j];
;             const f32x4 o = (v[j] - mean) * rstd * (cc + 1.f) + hh; u32x2 wv; wv.x = pk2(o[0], o[1]); wv.y = pk2(o[2], o[3]);
;             ((u32x2*)hout)[F.lane + 64 * j] = wv; }
;     }
	v_add_f32_e32 v9, v9, v91
	v_add_f32_e32 v90, v90, v92
	ds_bpermute_b32 v91, v4, v9
	ds_bpermute_b32 v92, v4, v90
	s_waitcnt lgkmcnt(0)
	v_add_f32_e32 v9, v9, v91
	v_add_f32_e32 v90, v90, v92
	ds_bpermute_b32 v91, v5, v9
	ds_bpermute_b32 v92, v5, v90
	s_waitcnt lgkmcnt(0)
	v_add_f32_e32 v9, v9, v91
	v_add_f32_e32 v90, v90, v92
	ds_bpermute_b32 v91, v6, v9
	ds_bpermute_b32 v92, v6, v90
	s_waitcnt lgkmcnt(0)
	v_add_f32_e32 v9, v9, v91
	v_add_f32_e32 v90, v90, v92
	ds_bpermute_b32 v91, v7, v9
	ds_bpermute_b32 v92, v7, v90
	s_waitcnt lgkmcnt(0)
	v_add_f32_e32 v9, v9, v91
	v_add_f32_e32 v90, v90, v92
	ds_bpermute_b32 v91, v8, v9
	ds_bpermute_b32 v92, v8, v90
	s_waitcnt lgkmcnt(0)
	v_add_f32_e32 v9, v9, v91
	v_add_f32_e32 v90, v90, v92
	v_mul_f32_e32 v93, 0x3a800000, v9
	v_mul_f32_e32 v91, 0x3a800000, v90
	v_fma_f32 v91, -v93, v93, v91
	v_max_f32_e32 v91, 0, v91
	v_add_f32_e32 v91, 0x358637bd, v91
	v_rsq_f32_e32 v94, v91
	v_mul_f32_e32 v91, 0.5, v91
	v_mul_f32_e32 v92, v94, v94
	v_fma_f32 v92, -v91, v92, 0.5
	v_fma_f32 v94, v94, v92, v94
	v_sub_f32_e32 v74, v74, v93
	v_sub_f32_e32 v75, v75, v93
	v_sub_f32_e32 v76, v76, v93
	v_sub_f32_e32 v77, v77, v93
	v_sub_f32_e32 v78, v78, v93
	v_sub_f32_e32 v79, v79, v93
	v_sub_f32_e32 v80, v80, v93
	v_sub_f32_e32 v81, v81, v93
	v_sub_f32_e32 v82, v82, v93
	v_sub_f32_e32 v83, v83, v93
	v_sub_f32_e32 v84, v84, v93
	v_sub_f32_e32 v85, v85, v93
	v_sub_f32_e32 v86, v86, v93
	v_sub_f32_e32 v87, v87, v93
	v_sub_f32_e32 v88, v88, v93
	v_sub_f32_e32 v89, v89, v93
	v_mul_f32_e32 v74, v94, v74
	v_mul_f32_e32 v75, v94, v75
	v_mul_f32_e32 v76, v94, v76
	v_mul_f32_e32 v77, v94, v77
	v_mul_f32_e32 v78, v94, v78
	v_mul_f32_e32 v79, v94, v79
	v_mul_f32_e32 v80, v94, v80
	v_mul_f32_e32 v81, v94, v81
	v_mul_f32_e32 v82, v94, v82
	v_mul_f32_e32 v83, v94, v83
	v_mul_f32_e32 v84, v94, v84
	v_mul_f32_e32 v85, v94, v85
	v_mul_f32_e32 v86, v94, v86
	v_mul_f32_e32 v87, v94, v87
	v_mul_f32_e32 v88, v94, v88
	v_mul_f32_e32 v89, v94, v89
	v_fma_f32 v74, v74, v130, v114
	v_fma_f32 v75, v75, v131, v115
	v_fma_f32 v76, v76, v132, v116
	v_fma_f32 v77, v77, v133, v117
	v_fma_f32 v78, v78, v134, v118
	v_fma_f32 v79, v79, v135, v119
	v_fma_f32 v80, v80, v136, v120
	v_fma_f32 v81, v81, v137, v121
	v_fma_f32 v82, v82, v138, v122
	v_fma_f32 v83, v83, v139, v123
	v_fma_f32 v84, v84, v140, v124
	v_fma_f32 v85, v85, v141, v125
	v_fma_f32 v86, v86, v142, v126
	v_fma_f32 v87, v87, v143, v127
	v_fma_f32 v88, v88, v144, v128
	v_fma_f32 v89, v89, v145, v129
	v_cvt_pk_bf16_f32 v190, v74, v75
	v_cvt_pk_bf16_f32 v191, v76, v77
	v_cvt_pk_bf16_f32 v192, v78, v79
	v_cvt_pk_bf16_f32 v193, v80, v81
	v_cvt_pk_bf16_f32 v194, v82, v83
	v_cvt_pk_bf16_f32 v195, v84, v85
	v_cvt_pk_bf16_f32 v196, v86, v87
	v_cvt_pk_bf16_f32 v197, v88, v89
	s_add_u32 s2, s10, 0x3000
	s_addc_u32 s3, s11, 0
	global_store_dwordx2 v1, v[190:191], s[2:3]
	global_store_dwordx2 v1, v[192:193], s[2:3] offset:512
	global_store_dwordx2 v1, v[194:195], s[2:3] offset:1024
	global_store_dwordx2 v1, v[196:197], s[2:3] offset:1536
	s_waitcnt vmcnt(19)
	v_add_f32_e32 v9, v98, v99
	v_add_f32_e32 v91, v100, v101
	v_mul_f32_e32 v90, v98, v98
	v_mul_f32_e32 v92, v99, v99
	v_add_f32_e32 v9, v9, v102
	v_add_f32_e32 v91, v91, v103
	v_add_f32_e32 v9, v9, v104
	v_add_f32_e32 v91, v91, v105
	v_add_f32_e32 v9, v9, v106
	v_add_f32_e32 v91, v91, v107
	v_add_f32_e32 v9, v9, v108
	v_add_f32_e32 v91, v91, v109
	v_add_f32_e32 v9, v9, v110
	v_add_f32_e32 v91, v91, v111
	v_add_f32_e32 v9, v9, v112
	v_add_f32_e32 v91, v91, v113
	v_fmac_f32_e32 v90, v100, v100
	v_fmac_f32_e32 v92, v101, v101
	v_fmac_f32_e32 v90, v102, v102
	v_fmac_f32_e32 v92, v103, v103
	v_fmac_f32_e32 v90, v104, v104
	v_fmac_f32_e32 v92, v105, v105
	v_fmac_f32_e32 v90, v106, v106
	v_fmac_f32_e32 v92, v107, v107
	v_fmac_f32_e32 v90, v108, v108
	v_fmac_f32_e32 v92, v109, v109
	v_fmac_f32_e32 v90, v110, v110
	v_fmac_f32_e32 v92, v111, v111
	v_fmac_f32_e32 v90, v112, v112
	v_fmac_f32_e32 v92, v113, v113
	v_add_f32_e32 v9, v9, v91
	v_add_f32_e32 v90, v90, v92
	ds_bpermute_b32 v91, v3, v9
	ds_bpermute_b32 v92, v3, v90
	s_waitcnt lgkmcnt(0)
	v_add_f32_e32 v9, v9, v91
	v_add_f32_e32 v90, v90, v92
	ds_bpermute_b32 v91, v4, v9
	ds_bpermute_b32 v92, v4, v90
	s_waitcnt lgkmcnt(0)
	v_add_f32_e32 v9, v9, v91
	v_add_f32_e32 v90, v90, v92
	ds_bpermute_b32 v91, v5, v9
	ds_bpermute_b32 v92, v5, v90
	s_waitcnt lgkmcnt(0)
	v_add_f32_e32 v9, v9, v91
	v_add_f32_e32 v90, v90, v92
	ds_bpermute_b32 v91, v6, v9
	ds_bpermute_b32 v92, v6, v90
	s_waitcnt lgkmcnt(0)
	v_add_f32_e32 v9, v9, v91
	v_add_f32_e32 v90, v90, v92
	ds_bpermute_b32 v91, v7, v9
	ds_bpermute_b32 v92, v7, v90
	s_waitcnt lgkmcnt(0)
	v_add_f32_e32 v9, v9, v91
	v_add_f32_e32 v90, v90, v92
	ds_bpermute_b32 v91, v8, v9
	ds_bpermute_b32 v92, v8, v90
	s_waitcnt lgkmcnt(0)
; DI void ln_row_v(const Frame& F, f32x4 (&v)[4], float* xout, const float* g, const float* b, const float* sh, const float* sc, bf16_t* hout, const float* slab, const float* gres, float* stat = nullptr) {
;     ...
;     if (g) {
;         float s = 0.f, s2 = 0.f;
; #pragma unroll
;         for (int j = 0; j < 4; ++j) { s += (v[j][0] + v[j][1]) + (v[j][2] + v[j][3]); s2 += (v[j][0] * v[j][0] + v[j][1] * v[j][1]) + (v[j][2] * v[j][2] + v[j][3] * v[j][3]); }
;         wave_sum2(s, s2, F.lane);
;         const float mean = s * (1.f / D); const float rstd = 1.f / sqrtf(fmaxf(s2 * (1.f / D) - mean * mean, 0.f) + EPS);
;         if (stat && F.lane == 0) { f32x2 sv = {mean, rstd}; *(f32x2*)stat = sv; }
; #pragma unroll
;         for (int j = 0; j < 4; ++j) { const f32x4 gg = ((const f32x4*)g)[F.lane + 64 * j], bb = ((const f32x4*)b)[F.lane + 64 * j];
;             v[j] = (v[j] - mean) * rstd * gg + bb; if (xout) ((f32x4*)xout)[F.lane + 64 * j] = v[j]; }
;     }
;     if (hout) {
;         float s = 0.f, s2 = 0.f;
; #pragma unroll
;         for (int j = 0; j < 4; ++j) { s += (v[j][0] + v[j][1]) + (v[j][2] + v[j][3]); s2 += (v[j][0] * v[j][0] + v[j][1] * v[j][1]) + (v[j][2] * v[j][2] + v[j][3] * v[j][3]); }
;         wave_sum2(s, s2, F.lane);
;         const float mean = s * (1.f / D); const float rstd = 1.f / sqrtf(fmaxf(s2 * (1.f / D) - mean * mean, 0.f) + EPS);
; #pragma unroll
;         for (int j = 0; j < 4; ++j) { const f32x4 hh = ((const f32x4*)sh)[F.lane + 64 * j], cc = ((const f32x4*)sc)[F.lane + 64 * j];
;             const f32x4 o = (v[j] - mean) * rstd * (cc + 1.f) + hh; u32x2 wv; wv.x = pk2(o[0], o[1]); wv.y = pk2(o[2], o[3]);
;             ((u32x2*)hout)[F.lane + 64 * j] = wv; }
;     }
; DI void ln_phase(const Frame& F, int which) {
;     const int gw = F.vcu * 8 + F.wave, NGW = F.G * 8; const int l = F.l;
;     const int nrows = (l == NL - 1) ? ML : MT;
;     bf16_t* H = (bf16_t*)(F.ws + WS_HB);
;     const float* g = pin(F, which == 0 ? I_LN1G : I_LN2G) + l * 1024; const float* b = pin(F, which == 0 ? I_LN1B : I_LN2B) + l * 1024;
;     const bool wh = !(which == 1 && l == NL - 1);
;     f32x4 vc[4], vn[4];
;     if (gw < nrows) ln_load(F, xrow_ptr(F, gw), vc);
;     for (int row = gw; row < nrows; row += NGW) {
;         if (row + NGW < nrows) ln_load(F, xrow_ptr(F, row + NGW), vn);
;         const int mr = row < ML ? (row >> 11) : 8;
	v_add_f32_e32 v9, v9, v91
	v_add_f32_e32 v90, v90, v92
	v_mul_f32_e32 v93, 0x3a800000, v9
	v_mul_f32_e32 v91, 0x3a800000, v90
	v_fma_f32 v91, -v93, v93, v91
	v_max_f32_e32 v91, 0, v91
	v_add_f32_e32 v91, 0x358637bd, v91
	v_rsq_f32_e32 v94, v91
	v_mul_f32_e32 v91, 0.5, v91
	v_mul_f32_e32 v92, v94, v94
	v_fma_f32 v92, -v91, v92, 0.5
	v_fma_f32 v94, v94, v92, v94
	s_add_u32 s2, s12, 0x38
	s_addc_u32 s3, s13, 0
	v_mov_b32_e32 v188, v93
	v_mov_b32_e32 v189, v94
	s_mov_b64 exec, 1
	global_store_dwordx2 v97, v[188:189], s[2:3]
	s_mov_b64 exec, -1
	v_sub_f32_e32 v98, v98, v93
	v_sub_f32_e32 v99, v99, v93
	v_sub_f32_e32 v100, v100, v93
	v_sub_f32_e32 v101, v101, v93
	v_sub_f32_e32 v102, v102, v93
	v_sub_f32_e32 v103, v103, v93
	v_sub_f32_e32 v104, v104, v93
	v_sub_f32_e32 v105, v105, v93
	v_sub_f32_e32 v106, v106, v93
	v_sub_f32_e32 v107, v107, v93
	v_sub_f32_e32 v108, v108, v93
	v_sub_f32_e32 v109, v109, v93
	v_sub_f32_e32 v110, v110, v93
	v_sub_f32_e32 v111, v111, v93
	v_sub_f32_e32 v112, v112, v93
	v_sub_f32_e32 v113, v113, v93
	v_mul_f32_e32 v98, v94, v98
	v_mul_f32_e32 v99, v94, v99
	v_mul_f32_e32 v100, v94, v100
	v_mul_f32_e32 v101, v94, v101
	v_mul_f32_e32 v102, v94, v102
	v_mul_f32_e32 v103, v94, v103
	v_mul_f32_e32 v104, v94, v104
	v_mul_f32_e32 v105, v94, v105
	v_mul_f32_e32 v106, v94, v106
	v_mul_f32_e32 v107, v94, v107
	v_mul_f32_e32 v108, v94, v108
	v_mul_f32_e32 v109, v94, v109
	v_mul_f32_e32 v110, v94, v110
	v_mul_f32_e32 v111, v94, v111
	v_mul_f32_e32 v112, v94, v112
	v_mul_f32_e32 v113, v94, v113
	v_fma_f32 v98, v98, v10, v26
	v_fma_f32 v99, v99, v11, v27
	v_fma_f32 v100, v100, v12, v28
	v_fma_f32 v101, v101, v13, v29
	v_fma_f32 v102, v102, v14, v30
	v_fma_f32 v103, v103, v15, v31
	v_fma_f32 v104, v104, v16, v32
	v_fma_f32 v105, v105, v17, v33
	v_fma_f32 v106, v106, v18, v34
	v_fma_f32 v107, v107, v19, v35
	v_fma_f32 v108, v108, v20, v36
	v_fma_f32 v109, v109, v21, v37
	v_fma_f32 v110, v110, v22, v38
	v_fma_f32 v111, v111, v23, v39
	v_fma_f32 v112, v112, v24, v40
	v_fma_f32 v113, v113, v25, v41
	v_add_f32_e32 v9, v98, v99
	v_add_f32_e32 v91, v100, v101
	v_mul_f32_e32 v90, v98, v98
	v_mul_f32_e32 v92, v99, v99
	v_add_f32_e32 v9, v9, v102
	v_add_f32_e32 v91, v91, v103
	v_add_f32_e32 v9, v9, v104
	v_add_f32_e32 v91, v91, v105
	v_add_f32_e32 v9, v9, v106
	v_add_f32_e32 v91, v91, v107
	v_add_f32_e32 v9, v9, v108
	v_add_f32_e32 v91, v91, v109
	v_add_f32_e32 v9, v9, v110
	v_add_f32_e32 v91, v91, v111
	v_add_f32_e32 v9, v9, v112
	v_add_f32_e32 v91, v91, v113
	v_fmac_f32_e32 v90, v100, v100
	v_fmac_f32_e32 v92, v101, v101
	v_fmac_f32_e32 v90, v102, v102
	v_fmac_f32_e32 v92, v103, v103
	v_fmac_f32_e32 v90, v104, v104
	v_fmac_f32_e32 v92, v105, v105
	v_fmac_f32_e32 v90, v106, v106
	v_fmac_f32_e32 v92, v107, v107
	v_fmac_f32_e32 v90, v108, v108
	v_fmac_f32_e32 v92, v109, v109
	v_fmac_f32_e32 v90, v110, v110
	v_fmac_f32_e32 v92, v111, v111
	v_fmac_f32_e32 v90, v112, v112
	v_fmac_f32_e32 v92, v113, v113
	v_add_f32_e32 v9, v9, v91
	v_add_f32_e32 v90, v90, v92
	ds_bpermute_b32 v91, v3, v9
	ds_bpermute_b32 v92, v3, v90
	s_waitcnt lgkmcnt(0)
	v_add_f32_e32 v9, v9, v91
	v_add_f32_e32 v90, v90, v92
	ds_bpermute_b32 v91, v4, v9
	ds_bpermute_b32 v92, v4, v90
	s_waitcnt lgkmcnt(0)
	v_add_f32_e32 v9, v9, v91
	v_add_f32_e32 v90, v90, v92
	ds_bpermute_b32 v91, v5, v9
	ds_bpermute_b32 v92, v5, v90
	s_waitcnt lgkmcnt(0)
	v_add_f32_e32 v9, v9, v91
	v_add_f32_e32 v90, v90, v92
	ds_bpermute_b32 v91, v6, v9
	ds_bpermute_b32 v92, v6, v90
	s_waitcnt lgkmcnt(0)
	v_add_f32_e32 v9, v9, v91
	v_add_f32_e32 v90, v90, v92
	ds_bpermute_b32 v91, v7, v9
	ds_bpermute_b32 v92, v7, v90
	s_waitcnt lgkmcnt(0)
	v_add_f32_e32 v9, v9, v91
	v_add_f32_e32 v90, v90, v92
	ds_bpermute_b32 v91, v8, v9
	ds_bpermute_b32 v92, v8, v90
	s_waitcnt lgkmcnt(0)
	v_add_f32_e32 v9, v9, v91
	v_add_f32_e32 v90, v90, v92
	v_mul_f32_e32 v93, 0x3a800000, v9
	v_mul_f32_e32 v91, 0x3a800000, v90
	v_fma_f32 v91, -v93, v93, v91
	v_max_f32_e32 v91, 0, v91
	v_add_f32_e32 v91, 0x358637bd, v91
	v_rsq_f32_e32 v94, v91
	v_mul_f32_e32 v91, 0.5, v91
	v_mul_f32_e32 v92, v94, v94
	v_fma_f32 v92, -v91, v92, 0.5
	v_fma_f32 v94, v94, v92, v94
	v_sub_f32_e32 v98, v98, v93
	v_sub_f32_e32 v99, v99, v93
	v_sub_f32_e32 v100, v100, v93
	v_sub_f32_e32 v101, v101, v93
	v_sub_f32_e32 v102, v102, v93
	v_sub_f32_e32 v103, v103, v93
	v_sub_f32_e32 v104, v104, v93
	v_sub_f32_e32 v105, v105, v93
	v_sub_f32_e32 v106, v106, v93
	v_sub_f32_e32 v107, v107, v93
	v_sub_f32_e32 v108, v108, v93
	v_sub_f32_e32 v109, v109, v93
	v_sub_f32_e32 v110, v110, v93
	v_sub_f32_e32 v111, v111, v93
	v_sub_f32_e32 v112, v112, v93
	v_sub_f32_e32 v113, v113, v93
	v_mul_f32_e32 v98, v94, v98
	v_mul_f32_e32 v99, v94, v99
	v_mul_f32_e32 v100, v94, v100
	v_mul_f32_e32 v101, v94, v101
	v_mul_f32_e32 v102, v94, v102
	v_mul_f32_e32 v103, v94, v103
	v_mul_f32_e32 v104, v94, v104
	v_mul_f32_e32 v105, v94, v105
	v_mul_f32_e32 v106, v94, v106
	v_mul_f32_e32 v107, v94, v107
	v_mul_f32_e32 v108, v94, v108
	v_mul_f32_e32 v109, v94, v109
	v_mul_f32_e32 v110, v94, v110
	v_mul_f32_e32 v111, v94, v111
	v_mul_f32_e32 v112, v94, v112
	v_mul_f32_e32 v113, v94, v113
	v_fma_f32 v98, v98, v130, v114
	v_fma_f32 v99, v99, v131, v115
	v_fma_f32 v100, v100, v132, v116
	v_fma_f32 v101, v101, v133, v117
	v_fma_f32 v102, v102, v134, v118
	v_fma_f32 v103, v103, v135, v119
	v_fma_f32 v104, v104, v136, v120
	v_fma_f32 v105, v105, v137, v121
	v_fma_f32 v106, v106, v138, v122
	v_fma_f32 v107, v107, v139, v123
	v_fma_f32 v108, v108, v140, v124
	v_fma_f32 v109, v109, v141, v125
	v_fma_f32 v110, v110, v142, v126
	v_fma_f32 v111, v111, v143, v127
	v_fma_f32 v112, v112, v144, v128
	v_fma_f32 v113, v113, v145, v129
	v_cvt_pk_bf16_f32 v190, v98, v99
	v_cvt_pk_bf16_f32 v191, v100, v101
	v_cvt_pk_bf16_f32 v192, v102, v103
	v_cvt_pk_bf16_f32 v193, v104, v105
	v_cvt_pk_bf16_f32 v194, v106, v107
	v_cvt_pk_bf16_f32 v195, v108, v109
	v_cvt_pk_bf16_f32 v196, v110, v111
	v_cvt_pk_bf16_f32 v197, v112, v113
	s_add_u32 s2, s10, 0x3800
	s_addc_u32 s3, s11, 0
	global_store_dwordx2 v1, v[190:191], s[2:3]
	global_store_dwordx2 v1, v[192:193], s[2:3] offset:512
	global_store_dwordx2 v1, v[194:195], s[2:3] offset:1024
	global_store_dwordx2 v1, v[196:197], s[2:3] offset:1536
	s_cmp_eq_u32 s22, 3
	s_cbranch_scc1 .Lln_a_noctx
; DI void ln_row_v(const Frame& F, f32x4 (&v)[4], float* xout, const float* g, const float* b, const float* sh, const float* sc, bf16_t* hout, const float* slab, const float* gres, float* stat = nullptr) {
;     ...
;     if (g) {
;         float s = 0.f, s2 = 0.f;
; #pragma unroll
;         for (int j = 0; j < 4; ++j) { s += (v[j][0] + v[j][1]) + (v[j][2] + v[j][3]); s2 += (v[j][0] * v[j][0] + v[j][1] * v[j][1]) + (v[j][2] * v[j][2] + v[j][3] * v[j][3]); }
;         wave_sum2(s, s2, F.lane);
;         const float mean = s * (1.f / D); const float rstd = 1.f / sqrtf(fmaxf(s2 * (1.f / D) - mean * mean, 0.f) + EPS);
;         if (stat && F.lane == 0) { f32x2 sv = {mean, rstd}; *(f32x2*)stat = sv; }
; #pragma unroll
;         for (int j = 0; j < 4; ++j) { const f32x4 gg = ((const f32x4*)g)[F.lane + 64 * j], bb = ((const f32x4*)b)[F.lane + 64 * j];
;             v[j] = (v[j] - mean) * rstd * gg + bb; if (xout) ((f32x4*)xout)[F.lane + 64 * j] = v[j]; }
;     }
;     if (hout) {
;         float s = 0.f, s2 = 0.f;
; #pragma unroll
;         for (int j = 0; j < 4; ++j) { s += (v[j][0] + v[j][1]) + (v[j][2] + v[j][3]); s2 += (v[j][0] * v[j][0] + v[j][1] * v[j][1]) + (v[j][2] * v[j][2] + v[j][3] * v[j][3]); }
;         wave_sum2(s, s2, F.lane);
;         const float mean = s * (1.f / D); const float rstd = 1.f / sqrtf(fmaxf(s2 * (1.f / D) - mean * mean, 0.f) + EPS);
	s_waitcnt vmcnt(15)
	v_add_f32_e32 v9, v42, v43
	v_add_f32_e32 v91, v44, v45
	v_mul_f32_e32 v90, v42, v42
	v_mul_f32_e32 v92, v43, v43
	v_add_f32_e32 v9, v9, v46
	v_add_f32_e32 v91, v91, v47
	v_add_f32_e32 v9, v9, v48
	v_add_f32_e32 v91, v91, v49
	v_add_f32_e32 v9, v9, v50
	v_add_f32_e32 v91, v91, v51
	v_add_f32_e32 v9, v9, v52
	v_add_f32_e32 v91, v91, v53
	v_add_f32_e32 v9, v9, v54
	v_add_f32_e32 v91, v91, v55
	v_add_f32_e32 v9, v9, v56
	v_add_f32_e32 v91, v91, v57
	v_fmac_f32_e32 v90, v44, v44
	v_fmac_f32_e32 v92, v45, v45
	v_fmac_f32_e32 v90, v46, v46
	v_fmac_f32_e32 v92, v47, v47
	v_fmac_f32_e32 v90, v48, v48
	v_fmac_f32_e32 v92, v49, v49
	v_fmac_f32_e32 v90, v50, v50
	v_fmac_f32_e32 v92, v51, v51
	v_fmac_f32_e32 v90, v52, v52
	v_fmac_f32_e32 v92, v53, v53
	v_fmac_f32_e32 v90, v54, v54
	v_fmac_f32_e32 v92, v55, v55
	v_fmac_f32_e32 v90, v56, v56
	v_fmac_f32_e32 v92, v57, v57
	v_add_f32_e32 v9, v9, v91
	v_add_f32_e32 v90, v90, v92
	ds_bpermute_b32 v91, v3, v9
	ds_bpermute_b32 v92, v3, v90
	s_waitcnt lgkmcnt(0)
	v_add_f32_e32 v9, v9, v91
	v_add_f32_e32 v90, v90, v92
	ds_bpermute_b32 v91, v4, v9
	ds_bpermute_b32 v92, v4, v90
	s_waitcnt lgkmcnt(0)
	v_add_f32_e32 v9, v9, v91
	v_add_f32_e32 v90, v90, v92
	ds_bpermute_b32 v91, v5, v9
	ds_bpermute_b32 v92, v5, v90
	s_waitcnt lgkmcnt(0)
	v_add_f32_e32 v9, v9, v91
	v_add_f32_e32 v90, v90, v92
	ds_bpermute_b32 v91, v6, v9
	ds_bpermute_b32 v92, v6, v90
	s_waitcnt lgkmcnt(0)
	v_add_f32_e32 v9, v9, v91
	v_add_f32_e32 v90, v90, v92
	ds_bpermute_b32 v91, v7, v9
	ds_bpermute_b32 v92, v7, v90
	s_waitcnt lgkmcnt(0)
	v_add_f32_e32 v9, v9, v91
	v_add_f32_e32 v90, v90, v92
	ds_bpermute_b32 v91, v8, v9
	ds_bpermute_b32 v92, v8, v90
	s_waitcnt lgkmcnt(0)
	v_add_f32_e32 v9, v9, v91
	v_add_f32_e32 v90, v90, v92
	v_mul_f32_e32 v93, 0x3a800000, v9
	v_mul_f32_e32 v91, 0x3a800000, v90
	v_fma_f32 v91, -v93, v93, v91
	v_max_f32_e32 v91, 0, v91
	v_add_f32_e32 v91, 0x358637bd, v91
	v_rsq_f32_e32 v94, v91
	v_mul_f32_e32 v91, 0.5, v91
	v_mul_f32_e32 v92, v94, v94
	v_fma_f32 v92, -v91, v92, 0.5
	v_fma_f32 v94, v94, v92, v94
	v_sub_f32_e32 v42, v42, v93
	v_sub_f32_e32 v43, v43, v93
	v_sub_f32_e32 v44, v44, v93
	v_sub_f32_e32 v45, v45, v93
	v_sub_f32_e32 v46, v46, v93
	v_sub_f32_e32 v47, v47, v93
	v_sub_f32_e32 v48, v48, v93
	v_sub_f32_e32 v49, v49, v93
	v_sub_f32_e32 v50, v50, v93
	v_sub_f32_e32 v51, v51, v93
	v_sub_f32_e32 v52, v52, v93
	v_sub_f32_e32 v53, v53, v93
	v_sub_f32_e32 v54, v54, v93
	v_sub_f32_e32 v55, v55, v93
	v_sub_f32_e32 v56, v56, v93
	v_sub_f32_e32 v57, v57, v93
	v_mul_f32_e32 v42, v94, v42
	v_mul_f32_e32 v43, v94, v43
	v_mul_f32_e32 v44, v94, v44
	v_mul_f32_e32 v45, v94, v45
	v_mul_f32_e32 v46, v94, v46
	v_mul_f32_e32 v47, v94, v47
	v_mul_f32_e32 v48, v94, v48
	v_mul_f32_e32 v49, v94, v49
	v_mul_f32_e32 v50, v94, v50
	v_mul_f32_e32 v51, v94, v51
	v_mul_f32_e32 v52, v94, v52
	v_mul_f32_e32 v53, v94, v53
	v_mul_f32_e32 v54, v94, v54
	v_mul_f32_e32 v55, v94, v55
	v_mul_f32_e32 v56, v94, v56
	v_mul_f32_e32 v57, v94, v57
	v_fma_f32 v42, v42, v10, v26
	v_fma_f32 v43, v43, v11, v27
	v_fma_f32 v44, v44, v12, v28
	v_fma_f32 v45, v45, v13, v29
	v_fma_f32 v46, v46, v14, v30
	v_fma_f32 v47, v47, v15, v31
	v_fma_f32 v48, v48, v16, v32
	v_fma_f32 v49, v49, v17, v33
	v_fma_f32 v50, v50, v18, v34
	v_fma_f32 v51, v51, v19, v35
	v_fma_f32 v52, v52, v20, v36
	v_fma_f32 v53, v53, v21, v37
	v_fma_f32 v54, v54, v22, v38
	v_fma_f32 v55, v55, v23, v39
	v_fma_f32 v56, v56, v24, v40
	v_fma_f32 v57, v57, v25, v41
	s_mov_b64 s[2:3], s[20:21]
	global_store_dwordx4 v0, v[42:45], s[2:3]
	global_store_dwordx4 v0, v[46:49], s[2:3] offset:1024
	global_store_dwordx4 v0, v[50:53], s[2:3] offset:2048
	global_store_dwordx4 v0, v[54:57], s[2:3] offset:3072
	v_add_f32_e32 v9, v42, v43
	v_add_f32_e32 v91, v44, v45
	v_mul_f32_e32 v90, v42, v42
	v_mul_f32_e32 v92, v43, v43
	v_add_f32_e32 v9, v9, v46
	v_add_f32_e32 v91, v91, v47
	v_add_f32_e32 v9, v9, v48
	v_add_f32_e32 v91, v91, v49
	v_add_f32_e32 v9, v9, v50
	v_add_f32_e32 v91, v91, v51
	v_add_f32_e32 v9, v9, v52
	v_add_f32_e32 v91, v91, v53
	v_add_f32_e32 v9, v9, v54
	v_add_f32_e32 v91, v91, v55
	v_add_f32_e32 v9, v9, v56
	v_add_f32_e32 v91, v91, v57
	v_fmac_f32_e32 v90, v44, v44
	v_fmac_f32_e32 v92, v45, v45
	v_fmac_f32_e32 v90, v46, v46
	v_fmac_f32_e32 v92, v47, v47
	v_fmac_f32_e32 v90, v48, v48
	v_fmac_f32_e32 v92, v49, v49
	v_fmac_f32_e32 v90, v50, v50
	v_fmac_f32_e32 v92, v51, v51
	v_fmac_f32_e32 v90, v52, v52
	v_fmac_f32_e32 v92, v53, v53
	v_fmac_f32_e32 v90, v54, v54
	v_fmac_f32_e32 v92, v55, v55
	v_fmac_f32_e32 v90, v56, v56
	v_fmac_f32_e32 v92, v57, v57
	v_add_f32_e32 v9, v9, v91
	v_add_f32_e32 v90, v90, v92
	ds_bpermute_b32 v91, v3, v9
	ds_bpermute_b32 v92, v3, v90
	s_waitcnt lgkmcnt(0)
; DI unsigned pk2(float lo, float hi) { f32x2 v = {lo, hi}; bf16x2_t b = __builtin_convertvector(v, bf16x2_t); return __builtin_bit_cast(unsigned, b); }
; DI void ln_row_v(const Frame& F, f32x4 (&v)[4], float* xout, const float* g, const float* b, const float* sh, const float* sc, bf16_t* hout, const float* slab, const float* gres, float* stat = nullptr) {
;     ...
;         wave_sum2(s, s2, F.lane);
;         const float mean = s * (1.f / D); const float rstd = 1.f / sqrtf(fmaxf(s2 * (1.f / D) - mean * mean, 0.f) + EPS);
; #pragma unroll
;         for (int j = 0; j < 4; ++j) { const f32x4 hh = ((const f32x4*)sh)[F.lane + 64 * j], cc = ((const f32x4*)sc)[F.lane + 64 * j];
;             const f32x4 o = (v[j] - mean) * rstd * (cc + 1.f) + hh; u32x2 wv; wv.x = pk2(o[0], o[1]); wv.y = pk2(o[2], o[3]);
;             ((u32x2*)hout)[F.lane + 64 * j] = wv; }
;     }
	v_add_f32_e32 v9, v9, v91
	v_add_f32_e32 v90, v90, v92
	ds_bpermute_b32 v91, v4, v9
	ds_bpermute_b32 v92, v4, v90
	s_waitcnt lgkmcnt(0)
	v_add_f32_e32 v9, v9, v91
	v_add_f32_e32 v90, v90, v92
	ds_bpermute_b32 v91, v5, v9
	ds_bpermute_b32 v92, v5, v90
	s_waitcnt lgkmcnt(0)
	v_add_f32_e32 v9, v9, v91
	v_add_f32_e32 v90, v90, v92
	ds_bpermute_b32 v91, v6, v9
	ds_bpermute_b32 v92, v6, v90
	s_waitcnt lgkmcnt(0)
	v_add_f32_e32 v9, v9, v91
	v_add_f32_e32 v90, v90, v92
	ds_bpermute_b32 v91, v7, v9
	ds_bpermute_b32 v92, v7, v90
	s_waitcnt lgkmcnt(0)
	v_add_f32_e32 v9, v9, v91
	v_add_f32_e32 v90, v90, v92
	ds_bpermute_b32 v91, v8, v9
	ds_bpermute_b32 v92, v8, v90
	s_waitcnt lgkmcnt(0)
	v_add_f32_e32 v9, v9, v91
	v_add_f32_e32 v90, v90, v92
	v_mul_f32_e32 v93, 0x3a800000, v9
	v_mul_f32_e32 v91, 0x3a800000, v90
	v_fma_f32 v91, -v93, v93, v91
	v_max_f32_e32 v91, 0, v91
	v_add_f32_e32 v91, 0x358637bd, v91
	v_rsq_f32_e32 v94, v91
	v_mul_f32_e32 v91, 0.5, v91
	v_mul_f32_e32 v92, v94, v94
	v_fma_f32 v92, -v91, v92, 0.5
	v_fma_f32 v94, v94, v92, v94
	v_sub_f32_e32 v42, v42, v93
	v_sub_f32_e32 v43, v43, v93
	v_sub_f32_e32 v44, v44, v93
	v_sub_f32_e32 v45, v45, v93
	v_sub_f32_e32 v46, v46, v93
	v_sub_f32_e32 v47, v47, v93
	v_sub_f32_e32 v48, v48, v93
	v_sub_f32_e32 v49, v49, v93
	v_sub_f32_e32 v50, v50, v93
	v_sub_f32_e32 v51, v51, v93
	v_sub_f32_e32 v52, v52, v93
	v_sub_f32_e32 v53, v53, v93
	v_sub_f32_e32 v54, v54, v93
	v_sub_f32_e32 v55, v55, v93
	v_sub_f32_e32 v56, v56, v93
	v_sub_f32_e32 v57, v57, v93
	v_add_f32_e32 v162, 1.0, v162
	v_add_f32_e32 v163, 1.0, v163
	v_add_f32_e32 v164, 1.0, v164
	v_add_f32_e32 v165, 1.0, v165
	v_add_f32_e32 v166, 1.0, v166
	v_add_f32_e32 v167, 1.0, v167
	v_add_f32_e32 v168, 1.0, v168
	v_add_f32_e32 v169, 1.0, v169
	v_add_f32_e32 v170, 1.0, v170
	v_add_f32_e32 v171, 1.0, v171
	v_add_f32_e32 v172, 1.0, v172
	v_add_f32_e32 v173, 1.0, v173
	v_add_f32_e32 v174, 1.0, v174
	v_add_f32_e32 v175, 1.0, v175
	v_add_f32_e32 v176, 1.0, v176
	v_add_f32_e32 v177, 1.0, v177
	v_mul_f32_e32 v42, v94, v42
	v_mul_f32_e32 v43, v94, v43
	v_mul_f32_e32 v44, v94, v44
	v_mul_f32_e32 v45, v94, v45
	v_mul_f32_e32 v46, v94, v46
	v_mul_f32_e32 v47, v94, v47
	v_mul_f32_e32 v48, v94, v48
	v_mul_f32_e32 v49, v94, v49
	v_mul_f32_e32 v50, v94, v50
	v_mul_f32_e32 v51, v94, v51
	v_mul_f32_e32 v52, v94, v52
	v_mul_f32_e32 v53, v94, v53
	v_mul_f32_e32 v54, v94, v54
	v_mul_f32_e32 v55, v94, v55
	v_mul_f32_e32 v56, v94, v56
	v_mul_f32_e32 v57, v94, v57
	v_fma_f32 v42, v42, v162, v146
	v_fma_f32 v43, v43, v163, v147
	v_fma_f32 v44, v44, v164, v148
	v_fma_f32 v45, v45, v165, v149
	v_fma_f32 v46, v46, v166, v150
	v_fma_f32 v47, v47, v167, v151
	v_fma_f32 v48, v48, v168, v152
	v_fma_f32 v49, v49, v169, v153
	v_fma_f32 v50, v50, v170, v154
	v_fma_f32 v51, v51, v171, v155
	v_fma_f32 v52, v52, v172, v156
	v_fma_f32 v53, v53, v173, v157
	v_fma_f32 v54, v54, v174, v158
	v_fma_f32 v55, v55, v175, v159
	v_fma_f32 v56, v56, v176, v160
	v_fma_f32 v57, v57, v177, v161
	v_cvt_pk_bf16_f32 v190, v42, v43
	v_cvt_pk_bf16_f32 v191, v44, v45
	v_cvt_pk_bf16_f32 v192, v46, v47
	v_cvt_pk_bf16_f32 v193, v48, v49
	v_cvt_pk_bf16_f32 v194, v50, v51
	v_cvt_pk_bf16_f32 v195, v52, v53
	v_cvt_pk_bf16_f32 v196, v54, v55
	v_cvt_pk_bf16_f32 v197, v56, v57
	s_lshl_b32 s2, s16, 11
	s_add_u32 s2, s94, s2
	s_addc_u32 s3, s95, 0
	s_add_u32 s2, s2, 0x5e00000
	s_addc_u32 s3, s3, 0
	global_store_dwordx2 v1, v[190:191], s[2:3]
	global_store_dwordx2 v1, v[192:193], s[2:3] offset:512
	global_store_dwordx2 v1, v[194:195], s[2:3] offset:1024
	global_store_dwordx2 v1, v[196:197], s[2:3] offset:1536

; DI const float* modp(const Frame& F, int l, int mr, int which) { return (const float*)(F.ws + WS_MOD) + ((size_t)(l * 9 + mr) * 6 + which) * 1024; }
; DI void ln_row_v(const Frame& F, f32x4 (&v)[4], float* xout, const float* g, const float* b, const float* sh, const float* sc, bf16_t* hout, const float* slab, const float* gres, float* stat = nullptr) {
;     ...
;     if (g) {
;         float s = 0.f, s2 = 0.f;
; #pragma unroll
;         for (int j = 0; j < 4; ++j) { s += (v[j][0] + v[j][1]) + (v[j][2] + v[j][3]); s2 += (v[j][0] * v[j][0] + v[j][1] * v[j][1]) + (v[j][2] * v[j][2] + v[j][3] * v[j][3]); }
;         wave_sum2(s, s2, F.lane);
;         const float mean = s * (1.f / D); const float rstd = 1.f / sqrtf(fmaxf(s2 * (1.f / D) - mean * mean, 0.f) + EPS);
; DI void ln_phase(const Frame& F, int which) {
;     const int gw = F.vcu * 8 + F.wave, NGW = F.G * 8; const int l = F.l;
;     const int nrows = (l == NL - 1) ? ML : MT;
;     bf16_t* H = (bf16_t*)(F.ws + WS_HB);
;     const float* g = pin(F, which == 0 ? I_LN1G : I_LN2G) + l * 1024; const float* b = pin(F, which == 0 ? I_LN1B : I_LN2B) + l * 1024;
;     const bool wh = !(which == 1 && l == NL - 1);
;     f32x4 vc[4], vn[4];
;     if (gw < nrows) ln_load(F, xrow_ptr(F, gw), vc);
;     for (int row = gw; row < nrows; row += NGW) {
;         if (row + NGW < nrows) ln_load(F, xrow_ptr(F, row + NGW), vn);
;         const int mr = row < ML ? (row >> 11) : 8;
;         const float* sh = which == 0 ? modp(F, l, mr, 3) : modp(F, l + 1 < NL ? l + 1 : l, mr, 0);
;         const float* sc = which == 0 ? modp(F, l, mr, 4) : modp(F, l + 1 < NL ? l + 1 : l, mr, 1);
;         const bool sl = (which == 1 && row >= ML);
;         const bool st_only = row < ML && !(which == 1 && l == NL - 1);
;         float* stp = st_only ? (float*)(F.ws + (which == 0 ? WS_ST1 : WS_ST2)) + 2 * (size_t)row : nullptr;
;         ln_row_v(F, vc, st_only ? nullptr : xrow_ptr(F, row), g, b, sh, sc, wh ? H + (size_t)row * D : nullptr, sl ? (const float*)(F.ws + WS_KN) + (size_t)(row - ML) * 1024 : nullptr, modp(F, l, mr, 5), stp);
.LBB0_513:
	s_and_b64 vcc, exec, s[2:3]
	s_cbranch_vccz .LBB0_537
	v_readlane_b32 s2, v255, 29
	s_lshl_b32 s2, s2, 3
	v_readlane_b32 s3, v255, 31
	s_add_i32 s16, s3, s2
	v_lshlrev_b32_e32 v0, 4, v186
	v_lshlrev_b32_e32 v1, 3, v186
	v_lshlrev_b32_e32 v96, 2, v186
	v_xor_b32_e32 v3, 4, v96
	v_xor_b32_e32 v4, 8, v96
	v_xor_b32_e32 v5, 16, v96
	v_xor_b32_e32 v6, 32, v96
	v_xor_b32_e32 v7, 64, v96
	v_xor_b32_e32 v8, 128, v96
	s_load_dwordx4 s[4:7], s[62:63], 0xb8
	v_readlane_b32 s22, v255, 35
	v_readlane_b32 s8, v255, 17
	v_readlane_b32 s9, v255, 18
	s_add_u32 s20, s94, 0x3600000
	s_addc_u32 s21, s95, 0
	s_lshl_b32 s2, s16, 12
	s_lshl_b32 s3, s16, 15
	s_add_u32 s8, s8, s3
	s_addc_u32 s9, s9, 0
	s_add_u32 s20, s20, s2
	s_addc_u32 s21, s21, 0
	s_lshl_b32 s2, s16, 14
	s_add_u32 s10, s94, s2
	s_addc_u32 s11, s95, 0
	s_add_u32 s10, s10, 0x3e00000
	s_addc_u32 s11, s11, 0
	s_lshl_b32 s2, s16, 6
	s_add_u32 s12, s94, s2
	s_addc_u32 s13, s95, 0
	s_add_u32 s12, s12, 0x4c0000
	s_addc_u32 s13, s13, 0
	s_add_i32 s3, s22, 1
	s_min_u32 s3, s3, 3
	s_mul_i32 s3, s3, 0x36000
	s_add_u32 s14, s94, s3
	s_addc_u32 s15, s95, 0
	s_add_u32 s14, s14, 0x100000
	s_addc_u32 s15, s15, 0
	s_add_u32 s18, s14, 0x1000
	s_addc_u32 s19, s15, 0
	s_lshl_b32 s2, s22, 12
	s_waitcnt lgkmcnt(0)
	s_add_u32 s4, s4, s2
	s_addc_u32 s5, s5, 0
	s_add_u32 s6, s6, s2
	s_addc_u32 s7, s7, 0
	s_lshl_b32 s2, s16, 12
	s_add_u32 s24, s94, s2
	s_addc_u32 s25, s95, 0
	s_add_u32 s24, s24, 0x9100000
	s_addc_u32 s25, s25, 0
	s_mul_i32 s2, s22, 0x36000
	s_add_u32 s26, s94, s2
	s_addc_u32 s27, s95, 0
	s_add_u32 s26, s26, 0x135000
	s_addc_u32 s27, s27, 0
	s_cmp_eq_u32 s22, 3
	s_cbranch_scc1 .Lln_b_final
	global_load_dwordx4 v[10:13], v0, s[4:5]
	global_load_dwordx4 v[14:17], v0, s[4:5] offset:1024
	global_load_dwordx4 v[18:21], v0, s[4:5] offset:2048
	global_load_dwordx4 v[22:25], v0, s[4:5] offset:3072
	global_load_dwordx4 v[26:29], v0, s[6:7]
	global_load_dwordx4 v[30:33], v0, s[6:7] offset:1024
	global_load_dwordx4 v[34:37], v0, s[6:7] offset:2048
	global_load_dwordx4 v[38:41], v0, s[6:7] offset:3072
	s_add_u32 s2, s8, 0x0
	s_addc_u32 s3, s9, 0
	global_load_dwordx4 v[42:45], v0, s[2:3]
	global_load_dwordx4 v[46:49], v0, s[2:3] offset:1024
	global_load_dwordx4 v[50:53], v0, s[2:3] offset:2048
	global_load_dwordx4 v[54:57], v0, s[2:3] offset:3072
	s_lshr_b32 s23, s16, 8
	s_mul_i32 s23, s23, 0x6000
	s_add_u32 s2, s14, s23
	s_addc_u32 s3, s15, 0
	global_load_dwordx4 v[114:117], v0, s[2:3]
	global_load_dwordx4 v[118:121], v0, s[2:3] offset:1024
	global_load_dwordx4 v[122:125], v0, s[2:3] offset:2048
	global_load_dwordx4 v[126:129], v0, s[2:3] offset:3072
	s_add_u32 s2, s18, s23
	s_addc_u32 s3, s19, 0
	global_load_dwordx4 v[130:133], v0, s[2:3]
	global_load_dwordx4 v[134:137], v0, s[2:3] offset:1024
	global_load_dwordx4 v[138:141], v0, s[2:3] offset:2048
	global_load_dwordx4 v[142:145], v0, s[2:3] offset:3072
	s_add_u32 s2, s8, 0x1000
	s_addc_u32 s3, s9, 0
	global_load_dwordx4 v[58:61], v0, s[2:3]
	global_load_dwordx4 v[62:65], v0, s[2:3] offset:1024
	global_load_dwordx4 v[66:69], v0, s[2:3] offset:2048
	global_load_dwordx4 v[70:73], v0, s[2:3] offset:3072
	s_add_u32 s2, s8, 0x2000
	s_addc_u32 s3, s9, 0
	global_load_dwordx4 v[74:77], v0, s[2:3]
	global_load_dwordx4 v[78:81], v0, s[2:3] offset:1024
	global_load_dwordx4 v[82:85], v0, s[2:3] offset:2048
	global_load_dwordx4 v[86:89], v0, s[2:3] offset:3072
	s_add_u32 s2, s8, 0x3000
	s_addc_u32 s3, s9, 0
	global_load_dwordx4 v[98:101], v0, s[2:3]
	global_load_dwordx4 v[102:105], v0, s[2:3] offset:1024
	global_load_dwordx4 v[106:109], v0, s[2:3] offset:2048
	global_load_dwordx4 v[110:113], v0, s[2:3] offset:3072
	s_waitcnt vmcnt(20)
	v_add_f32_e32 v9, v42, v43
	v_add_f32_e32 v91, v44, v45
	v_mul_f32_e32 v90, v42, v42
	v_mul_f32_e32 v92, v43, v43
	v_add_f32_e32 v9, v9, v46
	v_add_f32_e32 v91, v91, v47
	v_add_f32_e32 v9, v9, v48
	v_add_f32_e32 v91, v91, v49
	v_add_f32_e32 v9, v9, v50
	v_add_f32_e32 v91, v91, v51
	v_add_f32_e32 v9, v9, v52
	v_add_f32_e32 v91, v91, v53
	v_add_f32_e32 v9, v9, v54
	v_add_f32_e32 v91, v91, v55
	v_add_f32_e32 v9, v9, v56
	v_add_f32_e32 v91, v91, v57
	v_fmac_f32_e32 v90, v44, v44
	v_fmac_f32_e32 v92, v45, v45
	v_fmac_f32_e32 v90, v46, v46
	v_fmac_f32_e32 v92, v47, v47
	v_fmac_f32_e32 v90, v48, v48
	v_fmac_f32_e32 v92, v49, v49
	v_fmac_f32_e32 v90, v50, v50
	v_fmac_f32_e32 v92, v51, v51
	v_fmac_f32_e32 v90, v52, v52
	v_fmac_f32_e32 v92, v53, v53
	v_fmac_f32_e32 v90, v54, v54
	v_fmac_f32_e32 v92, v55, v55
	v_fmac_f32_e32 v90, v56, v56
	v_fmac_f32_e32 v92, v57, v57
	v_add_f32_e32 v9, v9, v91
	v_add_f32_e32 v90, v90, v92
	ds_bpermute_b32 v91, v3, v9
	ds_bpermute_b32 v92, v3, v90
	s_waitcnt lgkmcnt(0)
	v_add_f32_e32 v9, v9, v91
	v_add_f32_e32 v90, v90, v92
	ds_bpermute_b32 v91, v4, v9
	ds_bpermute_b32 v92, v4, v90
	s_waitcnt lgkmcnt(0)
	v_add_f32_e32 v9, v9, v91
	v_add_f32_e32 v90, v90, v92
	ds_bpermute_b32 v91, v5, v9
	ds_bpermute_b32 v92, v5, v90
	s_waitcnt lgkmcnt(0)
	v_add_f32_e32 v9, v9, v91
	v_add_f32_e32 v90, v90, v92
	ds_bpermute_b32 v91, v6, v9
	ds_bpermute_b32 v92, v6, v90
	s_waitcnt lgkmcnt(0)
	v_add_f32_e32 v9, v9, v91
	v_add_f32_e32 v90, v90, v92
	ds_bpermute_b32 v91, v7, v9
	ds_bpermute_b32 v92, v7, v90
	s_waitcnt lgkmcnt(0)
	v_add_f32_e32 v9, v9, v91
	v_add_f32_e32 v90, v90, v92
	ds_bpermute_b32 v91, v8, v9
	ds_bpermute_b32 v92, v8, v90
	s_waitcnt lgkmcnt(0)
; DI unsigned pk2(float lo, float hi) { f32x2 v = {lo, hi}; bf16x2_t b = __builtin_convertvector(v, bf16x2_t); return __builtin_bit_cast(unsigned, b); }
; DI void ln_row_v(const Frame& F, f32x4 (&v)[4], float* xout, const float* g, const float* b, const float* sh, const float* sc, bf16_t* hout, const float* slab, const float* gres, float* stat = nullptr) {
;     ...
;     if (g) {
;         float s = 0.f, s2 = 0.f;
; #pragma unroll
;         for (int j = 0; j < 4; ++j) { s += (v[j][0] + v[j][1]) + (v[j][2] + v[j][3]); s2 += (v[j][0] * v[j][0] + v[j][1] * v[j][1]) + (v[j][2] * v[j][2] + v[j][3] * v[j][3]); }
;         wave_sum2(s, s2, F.lane);
;         const float mean = s * (1.f / D); const float rstd = 1.f / sqrtf(fmaxf(s2 * (1.f / D) - mean * mean, 0.f) + EPS);
;         if (stat && F.lane == 0) { f32x2 sv = {mean, rstd}; *(f32x2*)stat = sv; }
; #pragma unroll
;         for (int j = 0; j < 4; ++j) { const f32x4 gg = ((const f32x4*)g)[F.lane + 64 * j], bb = ((const f32x4*)b)[F.lane + 64 * j];
;             v[j] = (v[j] - mean) * rstd * gg + bb; if (xout) ((f32x4*)xout)[F.lane + 64 * j] = v[j]; }
;     }
;     if (hout) {
;         float s = 0.f, s2 = 0.f;
; #pragma unroll
;         for (int j = 0; j < 4; ++j) { s += (v[j][0] + v[j][1]) + (v[j][2] + v[j][3]); s2 += (v[j][0] * v[j][0] + v[j][1] * v[j][1]) + (v[j][2] * v[j][2] + v[j][3] * v[j][3]); }
;         wave_sum2(s, s2, F.lane);
;         const float mean = s * (1.f / D); const float rstd = 1.f / sqrtf(fmaxf(s2 * (1.f / D) - mean * mean, 0.f) + EPS);
; #pragma unroll
;         for (int j = 0; j < 4; ++j) { const f32x4 hh = ((const f32x4*)sh)[F.lane + 64 * j], cc = ((const f32x4*)sc)[F.lane + 64 * j];
;             const f32x4 o = (v[j] - mean) * rstd * (cc + 1.f) + hh; u32x2 wv; wv.x = pk2(o[0], o[1]); wv.y = pk2(o[2], o[3]);
;             ((u32x2*)hout)[F.lane + 64 * j] = wv; }
;     }
	v_add_f32_e32 v9, v9, v91
	v_add_f32_e32 v90, v90, v92
	v_mul_f32_e32 v93, 0x3a800000, v9
	v_mul_f32_e32 v91, 0x3a800000, v90
	v_fma_f32 v91, -v93, v93, v91
	v_max_f32_e32 v91, 0, v91
	v_add_f32_e32 v91, 0x358637bd, v91
	v_rsq_f32_e32 v94, v91
	v_mul_f32_e32 v91, 0.5, v91
	v_mul_f32_e32 v92, v94, v94
	v_fma_f32 v92, -v91, v92, 0.5
	v_fma_f32 v94, v94, v92, v94
	s_add_u32 s2, s12, 0x0
	s_addc_u32 s3, s13, 0
	v_mov_b32_e32 v188, v93
	v_mov_b32_e32 v189, v94
	s_mov_b64 exec, 1
	global_store_dwordx2 v97, v[188:189], s[2:3]
	s_mov_b64 exec, -1
	v_sub_f32_e32 v42, v42, v93
	v_sub_f32_e32 v43, v43, v93
	v_sub_f32_e32 v44, v44, v93
	v_sub_f32_e32 v45, v45, v93
	v_sub_f32_e32 v46, v46, v93
	v_sub_f32_e32 v47, v47, v93
	v_sub_f32_e32 v48, v48, v93
	v_sub_f32_e32 v49, v49, v93
	v_sub_f32_e32 v50, v50, v93
	v_sub_f32_e32 v51, v51, v93
	v_sub_f32_e32 v52, v52, v93
	v_sub_f32_e32 v53, v53, v93
	v_sub_f32_e32 v54, v54, v93
	v_sub_f32_e32 v55, v55, v93
	v_sub_f32_e32 v56, v56, v93
	v_sub_f32_e32 v57, v57, v93
	v_mul_f32_e32 v42, v94, v42
	v_mul_f32_e32 v43, v94, v43
	v_mul_f32_e32 v44, v94, v44
	v_mul_f32_e32 v45, v94, v45
	v_mul_f32_e32 v46, v94, v46
	v_mul_f32_e32 v47, v94, v47
	v_mul_f32_e32 v48, v94, v48
	v_mul_f32_e32 v49, v94, v49
	v_mul_f32_e32 v50, v94, v50
	v_mul_f32_e32 v51, v94, v51
	v_mul_f32_e32 v52, v94, v52
	v_mul_f32_e32 v53, v94, v53
	v_mul_f32_e32 v54, v94, v54
	v_mul_f32_e32 v55, v94, v55
	v_mul_f32_e32 v56, v94, v56
	v_mul_f32_e32 v57, v94, v57
	v_fma_f32 v42, v42, v10, v26
	v_fma_f32 v43, v43, v11, v27
	v_fma_f32 v44, v44, v12, v28
	v_fma_f32 v45, v45, v13, v29
	v_fma_f32 v46, v46, v14, v30
	v_fma_f32 v47, v47, v15, v31
	v_fma_f32 v48, v48, v16, v32
	v_fma_f32 v49, v49, v17, v33
	v_fma_f32 v50, v50, v18, v34
	v_fma_f32 v51, v51, v19, v35
	v_fma_f32 v52, v52, v20, v36
	v_fma_f32 v53, v53, v21, v37
	v_fma_f32 v54, v54, v22, v38
	v_fma_f32 v55, v55, v23, v39
	v_fma_f32 v56, v56, v24, v40
	v_fma_f32 v57, v57, v25, v41
	v_add_f32_e32 v9, v42, v43
	v_add_f32_e32 v91, v44, v45
	v_mul_f32_e32 v90, v42, v42
	v_mul_f32_e32 v92, v43, v43
	v_add_f32_e32 v9, v9, v46
	v_add_f32_e32 v91, v91, v47
	v_add_f32_e32 v9, v9, v48
	v_add_f32_e32 v91, v91, v49
	v_add_f32_e32 v9, v9, v50
	v_add_f32_e32 v91, v91, v51
	v_add_f32_e32 v9, v9, v52
	v_add_f32_e32 v91, v91, v53
	v_add_f32_e32 v9, v9, v54
	v_add_f32_e32 v91, v91, v55
	v_add_f32_e32 v9, v9, v56
	v_add_f32_e32 v91, v91, v57
	v_fmac_f32_e32 v90, v44, v44
	v_fmac_f32_e32 v92, v45, v45
	v_fmac_f32_e32 v90, v46, v46
	v_fmac_f32_e32 v92, v47, v47
	v_fmac_f32_e32 v90, v48, v48
	v_fmac_f32_e32 v92, v49, v49
	v_fmac_f32_e32 v90, v50, v50
	v_fmac_f32_e32 v92, v51, v51
	v_fmac_f32_e32 v90, v52, v52
	v_fmac_f32_e32 v92, v53, v53
	v_fmac_f32_e32 v90, v54, v54
	v_fmac_f32_e32 v92, v55, v55
	v_fmac_f32_e32 v90, v56, v56
	v_fmac_f32_e32 v92, v57, v57
	v_add_f32_e32 v9, v9, v91
	v_add_f32_e32 v90, v90, v92
	ds_bpermute_b32 v91, v3, v9
	ds_bpermute_b32 v92, v3, v90
	s_waitcnt lgkmcnt(0)
	v_add_f32_e32 v9, v9, v91
	v_add_f32_e32 v90, v90, v92
	ds_bpermute_b32 v91, v4, v9
	ds_bpermute_b32 v92, v4, v90
	s_waitcnt lgkmcnt(0)
	v_add_f32_e32 v9, v9, v91
	v_add_f32_e32 v90, v90, v92
	ds_bpermute_b32 v91, v5, v9
	ds_bpermute_b32 v92, v5, v90
	s_waitcnt lgkmcnt(0)
	v_add_f32_e32 v9, v9, v91
	v_add_f32_e32 v90, v90, v92
	ds_bpermute_b32 v91, v6, v9
	ds_bpermute_b32 v92, v6, v90
	s_waitcnt lgkmcnt(0)
	v_add_f32_e32 v9, v9, v91
	v_add_f32_e32 v90, v90, v92
	ds_bpermute_b32 v91, v7, v9
	ds_bpermute_b32 v92, v7, v90
	s_waitcnt lgkmcnt(0)
	v_add_f32_e32 v9, v9, v91
	v_add_f32_e32 v90, v90, v92
	ds_bpermute_b32 v91, v8, v9
	ds_bpermute_b32 v92, v8, v90
	s_waitcnt lgkmcnt(0)
	v_add_f32_e32 v9, v9, v91
	v_add_f32_e32 v90, v90, v92
	v_mul_f32_e32 v93, 0x3a800000, v9
	v_mul_f32_e32 v91, 0x3a800000, v90
	v_fma_f32 v91, -v93, v93, v91
	v_max_f32_e32 v91, 0, v91
	v_add_f32_e32 v91, 0x358637bd, v91
	v_rsq_f32_e32 v94, v91
	v_mul_f32_e32 v91, 0.5, v91
	v_mul_f32_e32 v92, v94, v94
	v_fma_f32 v92, -v91, v92, 0.5
	v_fma_f32 v94, v94, v92, v94
	s_waitcnt vmcnt(13)
	v_sub_f32_e32 v42, v42, v93
	v_sub_f32_e32 v43, v43, v93
	v_sub_f32_e32 v44, v44, v93
	v_sub_f32_e32 v45, v45, v93
	v_sub_f32_e32 v46, v46, v93
	v_sub_f32_e32 v47, v47, v93
	v_sub_f32_e32 v48, v48, v93
	v_sub_f32_e32 v49, v49, v93
	v_sub_f32_e32 v50, v50, v93
	v_sub_f32_e32 v51, v51, v93
	v_sub_f32_e32 v52, v52, v93
	v_sub_f32_e32 v53, v53, v93
	v_sub_f32_e32 v54, v54, v93
	v_sub_f32_e32 v55, v55, v93
	v_sub_f32_e32 v56, v56, v93
	v_sub_f32_e32 v57, v57, v93
	v_add_f32_e32 v130, 1.0, v130
	v_add_f32_e32 v131, 1.0, v131
	v_add_f32_e32 v132, 1.0, v132
	v_add_f32_e32 v133, 1.0, v133
	v_add_f32_e32 v134, 1.0, v134
	v_add_f32_e32 v135, 1.0, v135
	v_add_f32_e32 v136, 1.0, v136
	v_add_f32_e32 v137, 1.0, v137
	v_add_f32_e32 v138, 1.0, v138
	v_add_f32_e32 v139, 1.0, v139
	v_add_f32_e32 v140, 1.0, v140
	v_add_f32_e32 v141, 1.0, v141
	v_add_f32_e32 v142, 1.0, v142
	v_add_f32_e32 v143, 1.0, v143
	v_add_f32_e32 v144, 1.0, v144
	v_add_f32_e32 v145, 1.0, v145
	v_mul_f32_e32 v42, v94, v42
	v_mul_f32_e32 v43, v94, v43
	v_mul_f32_e32 v44, v94, v44
	v_mul_f32_e32 v45, v94, v45
	v_mul_f32_e32 v46, v94, v46
	v_mul_f32_e32 v47, v94, v47
	v_mul_f32_e32 v48, v94, v48
	v_mul_f32_e32 v49, v94, v49
	v_mul_f32_e32 v50, v94, v50
	v_mul_f32_e32 v51, v94, v51
	v_mul_f32_e32 v52, v94, v52
	v_mul_f32_e32 v53, v94, v53
	v_mul_f32_e32 v54, v94, v54
	v_mul_f32_e32 v55, v94, v55
	v_mul_f32_e32 v56, v94, v56
	v_mul_f32_e32 v57, v94, v57
	v_fma_f32 v42, v42, v130, v114
	v_fma_f32 v43, v43, v131, v115
	v_fma_f32 v44, v44, v132, v116
	v_fma_f32 v45, v45, v133, v117
	v_fma_f32 v46, v46, v134, v118
	v_fma_f32 v47, v47, v135, v119
	v_fma_f32 v48, v48, v136, v120
	v_fma_f32 v49, v49, v137, v121
	v_fma_f32 v50, v50, v138, v122
	v_fma_f32 v51, v51, v139, v123
	v_fma_f32 v52, v52, v140, v124
	v_fma_f32 v53, v53, v141, v125
	v_fma_f32 v54, v54, v142, v126
	v_fma_f32 v55, v55, v143, v127
	v_fma_f32 v56, v56, v144, v128
	v_fma_f32 v57, v57, v145, v129
	v_cvt_pk_bf16_f32 v190, v42, v43
	v_cvt_pk_bf16_f32 v191, v44, v45
	v_cvt_pk_bf16_f32 v192, v46, v47
	v_cvt_pk_bf16_f32 v193, v48, v49
	v_cvt_pk_bf16_f32 v194, v50, v51
	v_cvt_pk_bf16_f32 v195, v52, v53
	v_cvt_pk_bf16_f32 v196, v54, v55
	v_cvt_pk_bf16_f32 v197, v56, v57
	s_add_u32 s2, s10, 0x0
	s_addc_u32 s3, s11, 0
	global_store_dwordx2 v1, v[190:191], s[2:3]
	global_store_dwordx2 v1, v[192:193], s[2:3] offset:512
	global_store_dwordx2 v1, v[194:195], s[2:3] offset:1024
	global_store_dwordx2 v1, v[196:197], s[2:3] offset:1536
	s_add_u32 s2, s8, 0x4000
	s_addc_u32 s3, s9, 0
	global_load_dwordx4 v[42:45], v0, s[2:3]
	global_load_dwordx4 v[46:49], v0, s[2:3] offset:1024
	global_load_dwordx4 v[50:53], v0, s[2:3] offset:2048
	global_load_dwordx4 v[54:57], v0, s[2:3] offset:3072
	s_waitcnt vmcnt(17)
; DI void ln_row_v(const Frame& F, f32x4 (&v)[4], float* xout, const float* g, const float* b, const float* sh, const float* sc, bf16_t* hout, const float* slab, const float* gres, float* stat = nullptr) {
;     ...
;     if (g) {
;         float s = 0.f, s2 = 0.f;
; #pragma unroll
;         for (int j = 0; j < 4; ++j) { s += (v[j][0] + v[j][1]) + (v[j][2] + v[j][3]); s2 += (v[j][0] * v[j][0] + v[j][1] * v[j][1]) + (v[j][2] * v[j][2] + v[j][3] * v[j][3]); }
;         wave_sum2(s, s2, F.lane);
;         const float mean = s * (1.f / D); const float rstd = 1.f / sqrtf(fmaxf(s2 * (1.f / D) - mean * mean, 0.f) + EPS);
;         if (stat && F.lane == 0) { f32x2 sv = {mean, rstd}; *(f32x2*)stat = sv; }
; #pragma unroll
;         for (int j = 0; j < 4; ++j) { const f32x4 gg = ((const f32x4*)g)[F.lane + 64 * j], bb = ((const f32x4*)b)[F.lane + 64 * j];
;             v[j] = (v[j] - mean) * rstd * gg + bb; if (xout) ((f32x4*)xout)[F.lane + 64 * j] = v[j]; }
;     }
;     if (hout) {
;         float s = 0.f, s2 = 0.f;
; #pragma unroll
;         for (int j = 0; j < 4; ++j) { s += (v[j][0] + v[j][1]) + (v[j][2] + v[j][3]); s2 += (v[j][0] * v[j][0] + v[j][1] * v[j][1]) + (v[j][2] * v[j][2] + v[j][3] * v[j][3]); }
;         wave_sum2(s, s2, F.lane);
;         const float mean = s * (1.f / D); const float rstd = 1.f / sqrtf(fmaxf(s2 * (1.f / D) - mean * mean, 0.f) + EPS);
	v_add_f32_e32 v9, v58, v59
	v_add_f32_e32 v91, v60, v61
	v_mul_f32_e32 v90, v58, v58
	v_mul_f32_e32 v92, v59, v59
	v_add_f32_e32 v9, v9, v62
	v_add_f32_e32 v91, v91, v63
	v_add_f32_e32 v9, v9, v64
	v_add_f32_e32 v91, v91, v65
	v_add_f32_e32 v9, v9, v66
	v_add_f32_e32 v91, v91, v67
	v_add_f32_e32 v9, v9, v68
	v_add_f32_e32 v91, v91, v69
	v_add_f32_e32 v9, v9, v70
	v_add_f32_e32 v91, v91, v71
	v_add_f32_e32 v9, v9, v72
	v_add_f32_e32 v91, v91, v73
	v_fmac_f32_e32 v90, v60, v60
	v_fmac_f32_e32 v92, v61, v61
	v_fmac_f32_e32 v90, v62, v62
	v_fmac_f32_e32 v92, v63, v63
	v_fmac_f32_e32 v90, v64, v64
	v_fmac_f32_e32 v92, v65, v65
	v_fmac_f32_e32 v90, v66, v66
	v_fmac_f32_e32 v92, v67, v67
	v_fmac_f32_e32 v90, v68, v68
	v_fmac_f32_e32 v92, v69, v69
	v_fmac_f32_e32 v90, v70, v70
	v_fmac_f32_e32 v92, v71, v71
	v_fmac_f32_e32 v90, v72, v72
	v_fmac_f32_e32 v92, v73, v73
	v_add_f32_e32 v9, v9, v91
	v_add_f32_e32 v90, v90, v92
	ds_bpermute_b32 v91, v3, v9
	ds_bpermute_b32 v92, v3, v90
	s_waitcnt lgkmcnt(0)
	v_add_f32_e32 v9, v9, v91
	v_add_f32_e32 v90, v90, v92
	ds_bpermute_b32 v91, v4, v9
	ds_bpermute_b32 v92, v4, v90
	s_waitcnt lgkmcnt(0)
	v_add_f32_e32 v9, v9, v91
	v_add_f32_e32 v90, v90, v92
	ds_bpermute_b32 v91, v5, v9
	ds_bpermute_b32 v92, v5, v90
	s_waitcnt lgkmcnt(0)
	v_add_f32_e32 v9, v9, v91
	v_add_f32_e32 v90, v90, v92
	ds_bpermute_b32 v91, v6, v9
	ds_bpermute_b32 v92, v6, v90
	s_waitcnt lgkmcnt(0)
	v_add_f32_e32 v9, v9, v91
	v_add_f32_e32 v90, v90, v92
	ds_bpermute_b32 v91, v7, v9
	ds_bpermute_b32 v92, v7, v90
	s_waitcnt lgkmcnt(0)
	v_add_f32_e32 v9, v9, v91
	v_add_f32_e32 v90, v90, v92
	ds_bpermute_b32 v91, v8, v9
	ds_bpermute_b32 v92, v8, v90
	s_waitcnt lgkmcnt(0)
	v_add_f32_e32 v9, v9, v91
	v_add_f32_e32 v90, v90, v92
	v_mul_f32_e32 v93, 0x3a800000, v9
	v_mul_f32_e32 v91, 0x3a800000, v90
	v_fma_f32 v91, -v93, v93, v91
	v_max_f32_e32 v91, 0, v91
	v_add_f32_e32 v91, 0x358637bd, v91
	v_rsq_f32_e32 v94, v91
	v_mul_f32_e32 v91, 0.5, v91
	v_mul_f32_e32 v92, v94, v94
	v_fma_f32 v92, -v91, v92, 0.5
	v_fma_f32 v94, v94, v92, v94
	s_add_u32 s2, s12, 0x8
	s_addc_u32 s3, s13, 0
	v_mov_b32_e32 v188, v93
	v_mov_b32_e32 v189, v94
	s_mov_b64 exec, 1
	global_store_dwordx2 v97, v[188:189], s[2:3]
	s_mov_b64 exec, -1
	v_sub_f32_e32 v58, v58, v93
	v_sub_f32_e32 v59, v59, v93
	v_sub_f32_e32 v60, v60, v93
	v_sub_f32_e32 v61, v61, v93
	v_sub_f32_e32 v62, v62, v93
	v_sub_f32_e32 v63, v63, v93
	v_sub_f32_e32 v64, v64, v93
	v_sub_f32_e32 v65, v65, v93
	v_sub_f32_e32 v66, v66, v93
	v_sub_f32_e32 v67, v67, v93
	v_sub_f32_e32 v68, v68, v93
	v_sub_f32_e32 v69, v69, v93
	v_sub_f32_e32 v70, v70, v93
	v_sub_f32_e32 v71, v71, v93
	v_sub_f32_e32 v72, v72, v93
	v_sub_f32_e32 v73, v73, v93
	v_mul_f32_e32 v58, v94, v58
	v_mul_f32_e32 v59, v94, v59
	v_mul_f32_e32 v60, v94, v60
	v_mul_f32_e32 v61, v94, v61
	v_mul_f32_e32 v62, v94, v62
	v_mul_f32_e32 v63, v94, v63
	v_mul_f32_e32 v64, v94, v64
	v_mul_f32_e32 v65, v94, v65
	v_mul_f32_e32 v66, v94, v66
	v_mul_f32_e32 v67, v94, v67
	v_mul_f32_e32 v68, v94, v68
	v_mul_f32_e32 v69, v94, v69
	v_mul_f32_e32 v70, v94, v70
	v_mul_f32_e32 v71, v94, v71
	v_mul_f32_e32 v72, v94, v72
	v_mul_f32_e32 v73, v94, v73
	v_fma_f32 v58, v58, v10, v26
	v_fma_f32 v59, v59, v11, v27
	v_fma_f32 v60, v60, v12, v28
	v_fma_f32 v61, v61, v13, v29
	v_fma_f32 v62, v62, v14, v30
	v_fma_f32 v63, v63, v15, v31
	v_fma_f32 v64, v64, v16, v32
	v_fma_f32 v65, v65, v17, v33
	v_fma_f32 v66, v66, v18, v34
	v_fma_f32 v67, v67, v19, v35
	v_fma_f32 v68, v68, v20, v36
	v_fma_f32 v69, v69, v21, v37
	v_fma_f32 v70, v70, v22, v38
	v_fma_f32 v71, v71, v23, v39
	v_fma_f32 v72, v72, v24, v40
	v_fma_f32 v73, v73, v25, v41
	v_add_f32_e32 v9, v58, v59
	v_add_f32_e32 v91, v60, v61
	v_mul_f32_e32 v90, v58, v58
	v_mul_f32_e32 v92, v59, v59
	v_add_f32_e32 v9, v9, v62
	v_add_f32_e32 v91, v91, v63
	v_add_f32_e32 v9, v9, v64
	v_add_f32_e32 v91, v91, v65
	v_add_f32_e32 v9, v9, v66
	v_add_f32_e32 v91, v91, v67
	v_add_f32_e32 v9, v9, v68
	v_add_f32_e32 v91, v91, v69
	v_add_f32_e32 v9, v9, v70
	v_add_f32_e32 v91, v91, v71
	v_add_f32_e32 v9, v9, v72
	v_add_f32_e32 v91, v91, v73
	v_fmac_f32_e32 v90, v60, v60
	v_fmac_f32_e32 v92, v61, v61
	v_fmac_f32_e32 v90, v62, v62
	v_fmac_f32_e32 v92, v63, v63
	v_fmac_f32_e32 v90, v64, v64
	v_fmac_f32_e32 v92, v65, v65
	v_fmac_f32_e32 v90, v66, v66
	v_fmac_f32_e32 v92, v67, v67
	v_fmac_f32_e32 v90, v68, v68
	v_fmac_f32_e32 v92, v69, v69
	v_fmac_f32_e32 v90, v70, v70
	v_fmac_f32_e32 v92, v71, v71
	v_fmac_f32_e32 v90, v72, v72
	v_fmac_f32_e32 v92, v73, v73
	v_add_f32_e32 v9, v9, v91
	v_add_f32_e32 v90, v90, v92
	ds_bpermute_b32 v91, v3, v9
	ds_bpermute_b32 v92, v3, v90
	s_waitcnt lgkmcnt(0)
	v_add_f32_e32 v9, v9, v91
	v_add_f32_e32 v90, v90, v92
	ds_bpermute_b32 v91, v4, v9
	ds_bpermute_b32 v92, v4, v90
	s_waitcnt lgkmcnt(0)
	v_add_f32_e32 v9, v9, v91
	v_add_f32_e32 v90, v90, v92
	ds_bpermute_b32 v91, v5, v9
	ds_bpermute_b32 v92, v5, v90
	s_waitcnt lgkmcnt(0)
	v_add_f32_e32 v9, v9, v91
	v_add_f32_e32 v90, v90, v92
	ds_bpermute_b32 v91, v6, v9
	ds_bpermute_b32 v92, v6, v90
	s_waitcnt lgkmcnt(0)
	v_add_f32_e32 v9, v9, v91
	v_add_f32_e32 v90, v90, v92
	ds_bpermute_b32 v91, v7, v9
	ds_bpermute_b32 v92, v7, v90
	s_waitcnt lgkmcnt(0)
	v_add_f32_e32 v9, v9, v91
	v_add_f32_e32 v90, v90, v92
	ds_bpermute_b32 v91, v8, v9
	ds_bpermute_b32 v92, v8, v90
	s_waitcnt lgkmcnt(0)
; DI unsigned pk2(float lo, float hi) { f32x2 v = {lo, hi}; bf16x2_t b = __builtin_convertvector(v, bf16x2_t); return __builtin_bit_cast(unsigned, b); }
; DI void ln_row_v(const Frame& F, f32x4 (&v)[4], float* xout, const float* g, const float* b, const float* sh, const float* sc, bf16_t* hout, const float* slab, const float* gres, float* stat = nullptr) {
;     ...
;         const float mean = s * (1.f / D); const float rstd = 1.f / sqrtf(fmaxf(s2 * (1.f / D) - mean * mean, 0.f) + EPS);
; #pragma unroll
;         for (int j = 0; j < 4; ++j) { const f32x4 hh = ((const f32x4*)sh)[F.lane + 64 * j], cc = ((const f32x4*)sc)[F.lane + 64 * j];
;             const f32x4 o = (v[j] - mean) * rstd * (cc + 1.f) + hh; u32x2 wv; wv.x = pk2(o[0], o[1]); wv.y = pk2(o[2], o[3]);
;             ((u32x2*)hout)[F.lane + 64 * j] = wv; }
;     }
	v_add_f32_e32 v9, v9, v91
	v_add_f32_e32 v90, v90, v92
	v_mul_f32_e32 v93, 0x3a800000, v9
	v_mul_f32_e32 v91, 0x3a800000, v90
	v_fma_f32 v91, -v93, v93, v91
	v_max_f32_e32 v91, 0, v91
	v_add_f32_e32 v91, 0x358637bd, v91
	v_rsq_f32_e32 v94, v91
	v_mul_f32_e32 v91, 0.5, v91
	v_mul_f32_e32 v92, v94, v94
	v_fma_f32 v92, -v91, v92, 0.5
	v_fma_f32 v94, v94, v92, v94
	v_sub_f32_e32 v58, v58, v93
	v_sub_f32_e32 v59, v59, v93
	v_sub_f32_e32 v60, v60, v93
	v_sub_f32_e32 v61, v61, v93
	v_sub_f32_e32 v62, v62, v93
	v_sub_f32_e32 v63, v63, v93
	v_sub_f32_e32 v64, v64, v93
	v_sub_f32_e32 v65, v65, v93
	v_sub_f32_e32 v66, v66, v93
	v_sub_f32_e32 v67, v67, v93
	v_sub_f32_e32 v68, v68, v93
	v_sub_f32_e32 v69, v69, v93
	v_sub_f32_e32 v70, v70, v93
	v_sub_f32_e32 v71, v71, v93
	v_sub_f32_e32 v72, v72, v93
	v_sub_f32_e32 v73, v73, v93
	v_mul_f32_e32 v58, v94, v58
	v_mul_f32_e32 v59, v94, v59
	v_mul_f32_e32 v60, v94, v60
	v_mul_f32_e32 v61, v94, v61
	v_mul_f32_e32 v62, v94, v62
	v_mul_f32_e32 v63, v94, v63
	v_mul_f32_e32 v64, v94, v64
	v_mul_f32_e32 v65, v94, v65
	v_mul_f32_e32 v66, v94, v66
	v_mul_f32_e32 v67, v94, v67
	v_mul_f32_e32 v68, v94, v68
	v_mul_f32_e32 v69, v94, v69
	v_mul_f32_e32 v70, v94, v70
	v_mul_f32_e32 v71, v94, v71
	v_mul_f32_e32 v72, v94, v72
	v_mul_f32_e32 v73, v94, v73
	v_fma_f32 v58, v58, v130, v114
	v_fma_f32 v59, v59, v131, v115
	v_fma_f32 v60, v60, v132, v116
	v_fma_f32 v61, v61, v133, v117
	v_fma_f32 v62, v62, v134, v118
	v_fma_f32 v63, v63, v135, v119
	v_fma_f32 v64, v64, v136, v120
	v_fma_f32 v65, v65, v137, v121
	v_fma_f32 v66, v66, v138, v122
	v_fma_f32 v67, v67, v139, v123
	v_fma_f32 v68, v68, v140, v124
	v_fma_f32 v69, v69, v141, v125
	v_fma_f32 v70, v70, v142, v126
	v_fma_f32 v71, v71, v143, v127
	v_fma_f32 v72, v72, v144, v128
	v_fma_f32 v73, v73, v145, v129
	v_cvt_pk_bf16_f32 v190, v58, v59
	v_cvt_pk_bf16_f32 v191, v60, v61
	v_cvt_pk_bf16_f32 v192, v62, v63
	v_cvt_pk_bf16_f32 v193, v64, v65
	v_cvt_pk_bf16_f32 v194, v66, v67
	v_cvt_pk_bf16_f32 v195, v68, v69
	v_cvt_pk_bf16_f32 v196, v70, v71
	v_cvt_pk_bf16_f32 v197, v72, v73
	s_add_u32 s2, s10, 0x800
	s_addc_u32 s3, s11, 0
	global_store_dwordx2 v1, v[190:191], s[2:3]
	global_store_dwordx2 v1, v[192:193], s[2:3] offset:512
	global_store_dwordx2 v1, v[194:195], s[2:3] offset:1024
	global_store_dwordx2 v1, v[196:197], s[2:3] offset:1536
	s_add_u32 s2, s8, 0x5000
	s_addc_u32 s3, s9, 0
	global_load_dwordx4 v[58:61], v0, s[2:3]
	global_load_dwordx4 v[62:65], v0, s[2:3] offset:1024
	global_load_dwordx4 v[66:69], v0, s[2:3] offset:2048
	global_load_dwordx4 v[70:73], v0, s[2:3] offset:3072
	s_waitcnt vmcnt(22)
	v_add_f32_e32 v9, v74, v75
	v_add_f32_e32 v91, v76, v77
	v_mul_f32_e32 v90, v74, v74
	v_mul_f32_e32 v92, v75, v75
	v_add_f32_e32 v9, v9, v78
	v_add_f32_e32 v91, v91, v79
	v_add_f32_e32 v9, v9, v80
	v_add_f32_e32 v91, v91, v81
	v_add_f32_e32 v9, v9, v82
	v_add_f32_e32 v91, v91, v83
	v_add_f32_e32 v9, v9, v84
	v_add_f32_e32 v91, v91, v85
	v_add_f32_e32 v9, v9, v86
	v_add_f32_e32 v91, v91, v87
	v_add_f32_e32 v9, v9, v88
	v_add_f32_e32 v91, v91, v89
	v_fmac_f32_e32 v90, v76, v76
	v_fmac_f32_e32 v92, v77, v77
	v_fmac_f32_e32 v90, v78, v78
	v_fmac_f32_e32 v92, v79, v79
	v_fmac_f32_e32 v90, v80, v80
	v_fmac_f32_e32 v92, v81, v81
	v_fmac_f32_e32 v90, v82, v82
	v_fmac_f32_e32 v92, v83, v83
	v_fmac_f32_e32 v90, v84, v84
	v_fmac_f32_e32 v92, v85, v85
	v_fmac_f32_e32 v90, v86, v86
	v_fmac_f32_e32 v92, v87, v87
	v_fmac_f32_e32 v90, v88, v88
	v_fmac_f32_e32 v92, v89, v89
	v_add_f32_e32 v9, v9, v91
	v_add_f32_e32 v90, v90, v92
	ds_bpermute_b32 v91, v3, v9
	ds_bpermute_b32 v92, v3, v90
	s_waitcnt lgkmcnt(0)
	v_add_f32_e32 v9, v9, v91
	v_add_f32_e32 v90, v90, v92
	ds_bpermute_b32 v91, v4, v9
	ds_bpermute_b32 v92, v4, v90
	s_waitcnt lgkmcnt(0)
	v_add_f32_e32 v9, v9, v91
	v_add_f32_e32 v90, v90, v92
	ds_bpermute_b32 v91, v5, v9
	ds_bpermute_b32 v92, v5, v90
	s_waitcnt lgkmcnt(0)
	v_add_f32_e32 v9, v9, v91
	v_add_f32_e32 v90, v90, v92
	ds_bpermute_b32 v91, v6, v9
	ds_bpermute_b32 v92, v6, v90
	s_waitcnt lgkmcnt(0)
	v_add_f32_e32 v9, v9, v91
	v_add_f32_e32 v90, v90, v92
	ds_bpermute_b32 v91, v7, v9
	ds_bpermute_b32 v92, v7, v90
	s_waitcnt lgkmcnt(0)
	v_add_f32_e32 v9, v9, v91
	v_add_f32_e32 v90, v90, v92
	ds_bpermute_b32 v91, v8, v9
	ds_bpermute_b32 v92, v8, v90
	s_waitcnt lgkmcnt(0)
; DI unsigned pk2(float lo, float hi) { f32x2 v = {lo, hi}; bf16x2_t b = __builtin_convertvector(v, bf16x2_t); return __builtin_bit_cast(unsigned, b); }
; DI void ln_row_v(const Frame& F, f32x4 (&v)[4], float* xout, const float* g, const float* b, const float* sh, const float* sc, bf16_t* hout, const float* slab, const float* gres, float* stat = nullptr) {
;     ...
;     if (g) {
;         float s = 0.f, s2 = 0.f;
; #pragma unroll
;         for (int j = 0; j < 4; ++j) { s += (v[j][0] + v[j][1]) + (v[j][2] + v[j][3]); s2 += (v[j][0] * v[j][0] + v[j][1] * v[j][1]) + (v[j][2] * v[j][2] + v[j][3] * v[j][3]); }
;         wave_sum2(s, s2, F.lane);
;         const float mean = s * (1.f / D); const float rstd = 1.f / sqrtf(fmaxf(s2 * (1.f / D) - mean * mean, 0.f) + EPS);
;         if (stat && F.lane == 0) { f32x2 sv = {mean, rstd}; *(f32x2*)stat = sv; }
; #pragma unroll
;         for (int j = 0; j < 4; ++j) { const f32x4 gg = ((const f32x4*)g)[F.lane + 64 * j], bb = ((const f32x4*)b)[F.lane + 64 * j];
;             v[j] = (v[j] - mean) * rstd * gg + bb; if (xout) ((f32x4*)xout)[F.lane + 64 * j] = v[j]; }
;     }
;     if (hout) {
;         float s = 0.f, s2 = 0.f;
; #pragma unroll
;         for (int j = 0; j < 4; ++j) { s += (v[j][0] + v[j][1]) + (v[j][2] + v[j][3]); s2 += (v[j][0] * v[j][0] + v[j][1] * v[j][1]) + (v[j][2] * v[j][2] + v[j][3] * v[j][3]); }
;         wave_sum2(s, s2, F.lane);
;         const float mean = s * (1.f / D); const float rstd = 1.f / sqrtf(fmaxf(s2 * (1.f / D) - mean * mean, 0.f) + EPS);
; #pragma unroll
;         for (int j = 0; j < 4; ++j) { const f32x4 hh = ((const f32x4*)sh)[F.lane + 64 * j], cc = ((const f32x4*)sc)[F.lane + 64 * j];
;             const f32x4 o = (v[j] - mean) * rstd * (cc + 1.f) + hh; u32x2 wv; wv.x = pk2(o[0], o[1]); wv.y = pk2(o[2], o[3]);
;             ((u32x2*)hout)[F.lane + 64 * j] = wv; }
;     }
	v_add_f32_e32 v9, v9, v91
	v_add_f32_e32 v90, v90, v92
	v_mul_f32_e32 v93, 0x3a800000, v9
	v_mul_f32_e32 v91, 0x3a800000, v90
	v_fma_f32 v91, -v93, v93, v91
	v_max_f32_e32 v91, 0, v91
	v_add_f32_e32 v91, 0x358637bd, v91
	v_rsq_f32_e32 v94, v91
	v_mul_f32_e32 v91, 0.5, v91
	v_mul_f32_e32 v92, v94, v94
	v_fma_f32 v92, -v91, v92, 0.5
	v_fma_f32 v94, v94, v92, v94
	s_add_u32 s2, s12, 0x10
	s_addc_u32 s3, s13, 0
	v_mov_b32_e32 v188, v93
	v_mov_b32_e32 v189, v94
	s_mov_b64 exec, 1
	global_store_dwordx2 v97, v[188:189], s[2:3]
	s_mov_b64 exec, -1
	v_sub_f32_e32 v74, v74, v93
	v_sub_f32_e32 v75, v75, v93
	v_sub_f32_e32 v76, v76, v93
	v_sub_f32_e32 v77, v77, v93
	v_sub_f32_e32 v78, v78, v93
	v_sub_f32_e32 v79, v79, v93
	v_sub_f32_e32 v80, v80, v93
	v_sub_f32_e32 v81, v81, v93
	v_sub_f32_e32 v82, v82, v93
	v_sub_f32_e32 v83, v83, v93
	v_sub_f32_e32 v84, v84, v93
	v_sub_f32_e32 v85, v85, v93
	v_sub_f32_e32 v86, v86, v93
	v_sub_f32_e32 v87, v87, v93
	v_sub_f32_e32 v88, v88, v93
	v_sub_f32_e32 v89, v89, v93
	v_mul_f32_e32 v74, v94, v74
	v_mul_f32_e32 v75, v94, v75
	v_mul_f32_e32 v76, v94, v76
	v_mul_f32_e32 v77, v94, v77
	v_mul_f32_e32 v78, v94, v78
	v_mul_f32_e32 v79, v94, v79
	v_mul_f32_e32 v80, v94, v80
	v_mul_f32_e32 v81, v94, v81
	v_mul_f32_e32 v82, v94, v82
	v_mul_f32_e32 v83, v94, v83
	v_mul_f32_e32 v84, v94, v84
	v_mul_f32_e32 v85, v94, v85
	v_mul_f32_e32 v86, v94, v86
	v_mul_f32_e32 v87, v94, v87
	v_mul_f32_e32 v88, v94, v88
	v_mul_f32_e32 v89, v94, v89
	v_fma_f32 v74, v74, v10, v26
	v_fma_f32 v75, v75, v11, v27
	v_fma_f32 v76, v76, v12, v28
	v_fma_f32 v77, v77, v13, v29
	v_fma_f32 v78, v78, v14, v30
	v_fma_f32 v79, v79, v15, v31
	v_fma_f32 v80, v80, v16, v32
	v_fma_f32 v81, v81, v17, v33
	v_fma_f32 v82, v82, v18, v34
	v_fma_f32 v83, v83, v19, v35
	v_fma_f32 v84, v84, v20, v36
	v_fma_f32 v85, v85, v21, v37
	v_fma_f32 v86, v86, v22, v38
	v_fma_f32 v87, v87, v23, v39
	v_fma_f32 v88, v88, v24, v40
	v_fma_f32 v89, v89, v25, v41
	v_add_f32_e32 v9, v74, v75
	v_add_f32_e32 v91, v76, v77
	v_mul_f32_e32 v90, v74, v74
	v_mul_f32_e32 v92, v75, v75
	v_add_f32_e32 v9, v9, v78
	v_add_f32_e32 v91, v91, v79
	v_add_f32_e32 v9, v9, v80
	v_add_f32_e32 v91, v91, v81
	v_add_f32_e32 v9, v9, v82
	v_add_f32_e32 v91, v91, v83
	v_add_f32_e32 v9, v9, v84
	v_add_f32_e32 v91, v91, v85
	v_add_f32_e32 v9, v9, v86
	v_add_f32_e32 v91, v91, v87
	v_add_f32_e32 v9, v9, v88
	v_add_f32_e32 v91, v91, v89
	v_fmac_f32_e32 v90, v76, v76
	v_fmac_f32_e32 v92, v77, v77
	v_fmac_f32_e32 v90, v78, v78
	v_fmac_f32_e32 v92, v79, v79
	v_fmac_f32_e32 v90, v80, v80
	v_fmac_f32_e32 v92, v81, v81
	v_fmac_f32_e32 v90, v82, v82
	v_fmac_f32_e32 v92, v83, v83
	v_fmac_f32_e32 v90, v84, v84
	v_fmac_f32_e32 v92, v85, v85
	v_fmac_f32_e32 v90, v86, v86
	v_fmac_f32_e32 v92, v87, v87
	v_fmac_f32_e32 v90, v88, v88
	v_fmac_f32_e32 v92, v89, v89
	v_add_f32_e32 v9, v9, v91
	v_add_f32_e32 v90, v90, v92
	ds_bpermute_b32 v91, v3, v9
	ds_bpermute_b32 v92, v3, v90
	s_waitcnt lgkmcnt(0)
	v_add_f32_e32 v9, v9, v91
	v_add_f32_e32 v90, v90, v92
	ds_bpermute_b32 v91, v4, v9
	ds_bpermute_b32 v92, v4, v90
	s_waitcnt lgkmcnt(0)
	v_add_f32_e32 v9, v9, v91
	v_add_f32_e32 v90, v90, v92
	ds_bpermute_b32 v91, v5, v9
	ds_bpermute_b32 v92, v5, v90
	s_waitcnt lgkmcnt(0)
	v_add_f32_e32 v9, v9, v91
	v_add_f32_e32 v90, v90, v92
	ds_bpermute_b32 v91, v6, v9
	ds_bpermute_b32 v92, v6, v90
	s_waitcnt lgkmcnt(0)
	v_add_f32_e32 v9, v9, v91
	v_add_f32_e32 v90, v90, v92
	ds_bpermute_b32 v91, v7, v9
	ds_bpermute_b32 v92, v7, v90
	s_waitcnt lgkmcnt(0)
	v_add_f32_e32 v9, v9, v91
	v_add_f32_e32 v90, v90, v92
	ds_bpermute_b32 v91, v8, v9
	ds_bpermute_b32 v92, v8, v90
	s_waitcnt lgkmcnt(0)
	v_add_f32_e32 v9, v9, v91
	v_add_f32_e32 v90, v90, v92
	v_mul_f32_e32 v93, 0x3a800000, v9
	v_mul_f32_e32 v91, 0x3a800000, v90
	v_fma_f32 v91, -v93, v93, v91
	v_max_f32_e32 v91, 0, v91
	v_add_f32_e32 v91, 0x358637bd, v91
	v_rsq_f32_e32 v94, v91
	v_mul_f32_e32 v91, 0.5, v91
	v_mul_f32_e32 v92, v94, v94
	v_fma_f32 v92, -v91, v92, 0.5
	v_fma_f32 v94, v94, v92, v94
	v_sub_f32_e32 v74, v74, v93
	v_sub_f32_e32 v75, v75, v93
	v_sub_f32_e32 v76, v76, v93
	v_sub_f32_e32 v77, v77, v93
	v_sub_f32_e32 v78, v78, v93
	v_sub_f32_e32 v79, v79, v93
	v_sub_f32_e32 v80, v80, v93
	v_sub_f32_e32 v81, v81, v93
	v_sub_f32_e32 v82, v82, v93
	v_sub_f32_e32 v83, v83, v93
	v_sub_f32_e32 v84, v84, v93
	v_sub_f32_e32 v85, v85, v93
	v_sub_f32_e32 v86, v86, v93
	v_sub_f32_e32 v87, v87, v93
	v_sub_f32_e32 v88, v88, v93
	v_sub_f32_e32 v89, v89, v93
	v_mul_f32_e32 v74, v94, v74
	v_mul_f32_e32 v75, v94, v75
	v_mul_f32_e32 v76, v94, v76
	v_mul_f32_e32 v77, v94, v77
	v_mul_f32_e32 v78, v94, v78
	v_mul_f32_e32 v79, v94, v79
	v_mul_f32_e32 v80, v94, v80
	v_mul_f32_e32 v81, v94, v81
	v_mul_f32_e32 v82, v94, v82
	v_mul_f32_e32 v83, v94, v83
	v_mul_f32_e32 v84, v94, v84
	v_mul_f32_e32 v85, v94, v85
	v_mul_f32_e32 v86, v94, v86
	v_mul_f32_e32 v87, v94, v87
	v_mul_f32_e32 v88, v94, v88
	v_mul_f32_e32 v89, v94, v89
	v_fma_f32 v74, v74, v130, v114
	v_fma_f32 v75, v75, v131, v115
	v_fma_f32 v76, v76, v132, v116
	v_fma_f32 v77, v77, v133, v117
	v_fma_f32 v78, v78, v134, v118
	v_fma_f32 v79, v79, v135, v119
	v_fma_f32 v80, v80, v136, v120
	v_fma_f32 v81, v81, v137, v121
	v_fma_f32 v82, v82, v138, v122
	v_fma_f32 v83, v83, v139, v123
	v_fma_f32 v84, v84, v140, v124
	v_fma_f32 v85, v85, v141, v125
	v_fma_f32 v86, v86, v142, v126
	v_fma_f32 v87, v87, v143, v127
	v_fma_f32 v88, v88, v144, v128
	v_fma_f32 v89, v89, v145, v129
	v_cvt_pk_bf16_f32 v190, v74, v75
	v_cvt_pk_bf16_f32 v191, v76, v77
	v_cvt_pk_bf16_f32 v192, v78, v79
	v_cvt_pk_bf16_f32 v193, v80, v81
	v_cvt_pk_bf16_f32 v194, v82, v83
	v_cvt_pk_bf16_f32 v195, v84, v85
	v_cvt_pk_bf16_f32 v196, v86, v87
	v_cvt_pk_bf16_f32 v197, v88, v89
	s_add_u32 s2, s10, 0x1000
	s_addc_u32 s3, s11, 0
	global_store_dwordx2 v1, v[190:191], s[2:3]
	global_store_dwordx2 v1, v[192:193], s[2:3] offset:512
	global_store_dwordx2 v1, v[194:195], s[2:3] offset:1024
	global_store_dwordx2 v1, v[196:197], s[2:3] offset:1536
	s_add_u32 s2, s8, 0x6000
	s_addc_u32 s3, s9, 0
	global_load_dwordx4 v[74:77], v0, s[2:3]
	global_load_dwordx4 v[78:81], v0, s[2:3] offset:1024
	global_load_dwordx4 v[82:85], v0, s[2:3] offset:2048
	global_load_dwordx4 v[86:89], v0, s[2:3] offset:3072
	s_waitcnt vmcnt(27)
; DI void ln_row_v(const Frame& F, f32x4 (&v)[4], float* xout, const float* g, const float* b, const float* sh, const float* sc, bf16_t* hout, const float* slab, const float* gres, float* stat = nullptr) {
;     ...
;     if (g) {
;         float s = 0.f, s2 = 0.f;
; #pragma unroll
;         for (int j = 0; j < 4; ++j) { s += (v[j][0] + v[j][1]) + (v[j][2] + v[j][3]); s2 += (v[j][0] * v[j][0] + v[j][1] * v[j][1]) + (v[j][2] * v[j][2] + v[j][3] * v[j][3]); }
;         wave_sum2(s, s2, F.lane);
;         const float mean = s * (1.f / D); const float rstd = 1.f / sqrtf(fmaxf(s2 * (1.f / D) - mean * mean, 0.f) + EPS);
;         if (stat && F.lane == 0) { f32x2 sv = {mean, rstd}; *(f32x2*)stat = sv; }
; #pragma unroll
;         for (int j = 0; j < 4; ++j) { const f32x4 gg = ((const f32x4*)g)[F.lane + 64 * j], bb = ((const f32x4*)b)[F.lane + 64 * j];
;             v[j] = (v[j] - mean) * rstd * gg + bb; if (xout) ((f32x4*)xout)[F.lane + 64 * j] = v[j]; }
	v_add_f32_e32 v9, v98, v99
	v_add_f32_e32 v91, v100, v101
	v_mul_f32_e32 v90, v98, v98
	v_mul_f32_e32 v92, v99, v99
	v_add_f32_e32 v9, v9, v102
	v_add_f32_e32 v91, v91, v103
	v_add_f32_e32 v9, v9, v104
	v_add_f32_e32 v91, v91, v105
	v_add_f32_e32 v9, v9, v106
	v_add_f32_e32 v91, v91, v107
	v_add_f32_e32 v9, v9, v108
	v_add_f32_e32 v91, v91, v109
	v_add_f32_e32 v9, v9, v110
	v_add_f32_e32 v91, v91, v111
	v_add_f32_e32 v9, v9, v112
	v_add_f32_e32 v91, v91, v113
	v_fmac_f32_e32 v90, v100, v100
	v_fmac_f32_e32 v92, v101, v101
	v_fmac_f32_e32 v90, v102, v102
	v_fmac_f32_e32 v92, v103, v103
	v_fmac_f32_e32 v90, v104, v104
	v_fmac_f32_e32 v92, v105, v105
	v_fmac_f32_e32 v90, v106, v106
	v_fmac_f32_e32 v92, v107, v107
	v_fmac_f32_e32 v90, v108, v108
	v_fmac_f32_e32 v92, v109, v109
	v_fmac_f32_e32 v90, v110, v110
	v_fmac_f32_e32 v92, v111, v111
	v_fmac_f32_e32 v90, v112, v112
	v_fmac_f32_e32 v92, v113, v113
	v_add_f32_e32 v9, v9, v91
	v_add_f32_e32 v90, v90, v92
	ds_bpermute_b32 v91, v3, v9
	ds_bpermute_b32 v92, v3, v90
	s_waitcnt lgkmcnt(0)
	v_add_f32_e32 v9, v9, v91
	v_add_f32_e32 v90, v90, v92
	ds_bpermute_b32 v91, v4, v9
	ds_bpermute_b32 v92, v4, v90
	s_waitcnt lgkmcnt(0)
	v_add_f32_e32 v9, v9, v91
	v_add_f32_e32 v90, v90, v92
	ds_bpermute_b32 v91, v5, v9
	ds_bpermute_b32 v92, v5, v90
	s_waitcnt lgkmcnt(0)
	v_add_f32_e32 v9, v9, v91
	v_add_f32_e32 v90, v90, v92
	ds_bpermute_b32 v91, v6, v9
	ds_bpermute_b32 v92, v6, v90
	s_waitcnt lgkmcnt(0)
	v_add_f32_e32 v9, v9, v91
	v_add_f32_e32 v90, v90, v92
	ds_bpermute_b32 v91, v7, v9
	ds_bpermute_b32 v92, v7, v90
	s_waitcnt lgkmcnt(0)
	v_add_f32_e32 v9, v9, v91
	v_add_f32_e32 v90, v90, v92
	ds_bpermute_b32 v91, v8, v9
	ds_bpermute_b32 v92, v8, v90
	s_waitcnt lgkmcnt(0)
	v_add_f32_e32 v9, v9, v91
	v_add_f32_e32 v90, v90, v92
	v_mul_f32_e32 v93, 0x3a800000, v9
	v_mul_f32_e32 v91, 0x3a800000, v90
	v_fma_f32 v91, -v93, v93, v91
	v_max_f32_e32 v91, 0, v91
	v_add_f32_e32 v91, 0x358637bd, v91
	v_rsq_f32_e32 v94, v91
	v_mul_f32_e32 v91, 0.5, v91
	v_mul_f32_e32 v92, v94, v94
	v_fma_f32 v92, -v91, v92, 0.5
	v_fma_f32 v94, v94, v92, v94
	s_add_u32 s2, s12, 0x18
	s_addc_u32 s3, s13, 0
	v_mov_b32_e32 v188, v93
	v_mov_b32_e32 v189, v94
	s_mov_b64 exec, 1
	global_store_dwordx2 v97, v[188:189], s[2:3]
	s_mov_b64 exec, -1
	v_sub_f32_e32 v98, v98, v93
	v_sub_f32_e32 v99, v99, v93
	v_sub_f32_e32 v100, v100, v93
	v_sub_f32_e32 v101, v101, v93
	v_sub_f32_e32 v102, v102, v93
	v_sub_f32_e32 v103, v103, v93
	v_sub_f32_e32 v104, v104, v93
	v_sub_f32_e32 v105, v105, v93
	v_sub_f32_e32 v106, v106, v93
	v_sub_f32_e32 v107, v107, v93
	v_sub_f32_e32 v108, v108, v93
	v_sub_f32_e32 v109, v109, v93
	v_sub_f32_e32 v110, v110, v93
	v_sub_f32_e32 v111, v111, v93
	v_sub_f32_e32 v112, v112, v93
	v_sub_f32_e32 v113, v113, v93
	v_mul_f32_e32 v98, v94, v98
	v_mul_f32_e32 v99, v94, v99
	v_mul_f32_e32 v100, v94, v100
	v_mul_f32_e32 v101, v94, v101
	v_mul_f32_e32 v102, v94, v102
	v_mul_f32_e32 v103, v94, v103
	v_mul_f32_e32 v104, v94, v104
	v_mul_f32_e32 v105, v94, v105
	v_mul_f32_e32 v106, v94, v106
	v_mul_f32_e32 v107, v94, v107
	v_mul_f32_e32 v108, v94, v108
	v_mul_f32_e32 v109, v94, v109
	v_mul_f32_e32 v110, v94, v110
	v_mul_f32_e32 v111, v94, v111
	v_mul_f32_e32 v112, v94, v112
	v_mul_f32_e32 v113, v94, v113
	v_fma_f32 v98, v98, v10, v26
	v_fma_f32 v99, v99, v11, v27
	v_fma_f32 v100, v100, v12, v28
	v_fma_f32 v101, v101, v13, v29
	v_fma_f32 v102, v102, v14, v30
	v_fma_f32 v103, v103, v15, v31
	v_fma_f32 v104, v104, v16, v32
	v_fma_f32 v105, v105, v17, v33
	v_fma_f32 v106, v106, v18, v34
	v_fma_f32 v107, v107, v19, v35
	v_fma_f32 v108, v108, v20, v36
	v_fma_f32 v109, v109, v21, v37
	v_fma_f32 v110, v110, v22, v38
	v_fma_f32 v111, v111, v23, v39
	v_fma_f32 v112, v112, v24, v40
	v_fma_f32 v113, v113, v25, v41
	v_add_f32_e32 v9, v98, v99
	v_add_f32_e32 v91, v100, v101
	v_mul_f32_e32 v90, v98, v98
	v_mul_f32_e32 v92, v99, v99
	v_add_f32_e32 v9, v9, v102
	v_add_f32_e32 v91, v91, v103
	v_add_f32_e32 v9, v9, v104
	v_add_f32_e32 v91, v91, v105
	v_add_f32_e32 v9, v9, v106
	v_add_f32_e32 v91, v91, v107
	v_add_f32_e32 v9, v9, v108
	v_add_f32_e32 v91, v91, v109
	v_add_f32_e32 v9, v9, v110
	v_add_f32_e32 v91, v91, v111
	v_add_f32_e32 v9, v9, v112
	v_add_f32_e32 v91, v91, v113
	v_fmac_f32_e32 v90, v100, v100
	v_fmac_f32_e32 v92, v101, v101
	v_fmac_f32_e32 v90, v102, v102
	v_fmac_f32_e32 v92, v103, v103
	v_fmac_f32_e32 v90, v104, v104
	v_fmac_f32_e32 v92, v105, v105
	v_fmac_f32_e32 v90, v106, v106
	v_fmac_f32_e32 v92, v107, v107
	v_fmac_f32_e32 v90, v108, v108
	v_fmac_f32_e32 v92, v109, v109
	v_fmac_f32_e32 v90, v110, v110
	v_fmac_f32_e32 v92, v111, v111
	v_fmac_f32_e32 v90, v112, v112
	v_fmac_f32_e32 v92, v113, v113
	v_add_f32_e32 v9, v9, v91
	v_add_f32_e32 v90, v90, v92
	ds_bpermute_b32 v91, v3, v9
	ds_bpermute_b32 v92, v3, v90
	s_waitcnt lgkmcnt(0)
	v_add_f32_e32 v9, v9, v91
	v_add_f32_e32 v90, v90, v92
	ds_bpermute_b32 v91, v4, v9
	ds_bpermute_b32 v92, v4, v90
	s_waitcnt lgkmcnt(0)
	v_add_f32_e32 v9, v9, v91
	v_add_f32_e32 v90, v90, v92
	ds_bpermute_b32 v91, v5, v9
	ds_bpermute_b32 v92, v5, v90
	s_waitcnt lgkmcnt(0)
	v_add_f32_e32 v9, v9, v91
	v_add_f32_e32 v90, v90, v92
	ds_bpermute_b32 v91, v6, v9
	ds_bpermute_b32 v92, v6, v90
	s_waitcnt lgkmcnt(0)
	v_add_f32_e32 v9, v9, v91
	v_add_f32_e32 v90, v90, v92
	ds_bpermute_b32 v91, v7, v9
	ds_bpermute_b32 v92, v7, v90
	s_waitcnt lgkmcnt(0)
	v_add_f32_e32 v9, v9, v91
	v_add_f32_e32 v90, v90, v92
	ds_bpermute_b32 v91, v8, v9
	ds_bpermute_b32 v92, v8, v90
	s_waitcnt lgkmcnt(0)
; DI unsigned pk2(float lo, float hi) { f32x2 v = {lo, hi}; bf16x2_t b = __builtin_convertvector(v, bf16x2_t); return __builtin_bit_cast(unsigned, b); }
; DI void ln_row_v(const Frame& F, f32x4 (&v)[4], float* xout, const float* g, const float* b, const float* sh, const float* sc, bf16_t* hout, const float* slab, const float* gres, float* stat = nullptr) {
;     ...
;     if (hout) {
;         float s = 0.f, s2 = 0.f;
; #pragma unroll
;         for (int j = 0; j < 4; ++j) { s += (v[j][0] + v[j][1]) + (v[j][2] + v[j][3]); s2 += (v[j][0] * v[j][0] + v[j][1] * v[j][1]) + (v[j][2] * v[j][2] + v[j][3] * v[j][3]); }
;         wave_sum2(s, s2, F.lane);
;         const float mean = s * (1.f / D); const float rstd = 1.f / sqrtf(fmaxf(s2 * (1.f / D) - mean * mean, 0.f) + EPS);
; #pragma unroll
;         for (int j = 0; j < 4; ++j) { const f32x4 hh = ((const f32x4*)sh)[F.lane + 64 * j], cc = ((const f32x4*)sc)[F.lane + 64 * j];
;             const f32x4 o = (v[j] - mean) * rstd * (cc + 1.f) + hh; u32x2 wv; wv.x = pk2(o[0], o[1]); wv.y = pk2(o[2], o[3]);
;             ((u32x2*)hout)[F.lane + 64 * j] = wv; }
;     }
	v_add_f32_e32 v9, v9, v91
	v_add_f32_e32 v90, v90, v92
	v_mul_f32_e32 v93, 0x3a800000, v9
	v_mul_f32_e32 v91, 0x3a800000, v90
	v_fma_f32 v91, -v93, v93, v91
	v_max_f32_e32 v91, 0, v91
	v_add_f32_e32 v91, 0x358637bd, v91
	v_rsq_f32_e32 v94, v91
	v_mul_f32_e32 v91, 0.5, v91
	v_mul_f32_e32 v92, v94, v94
	v_fma_f32 v92, -v91, v92, 0.5
	v_fma_f32 v94, v94, v92, v94
	v_sub_f32_e32 v98, v98, v93
	v_sub_f32_e32 v99, v99, v93
	v_sub_f32_e32 v100, v100, v93
	v_sub_f32_e32 v101, v101, v93
	v_sub_f32_e32 v102, v102, v93
	v_sub_f32_e32 v103, v103, v93
	v_sub_f32_e32 v104, v104, v93
	v_sub_f32_e32 v105, v105, v93
	v_sub_f32_e32 v106, v106, v93
	v_sub_f32_e32 v107, v107, v93
	v_sub_f32_e32 v108, v108, v93
	v_sub_f32_e32 v109, v109, v93
	v_sub_f32_e32 v110, v110, v93
	v_sub_f32_e32 v111, v111, v93
	v_sub_f32_e32 v112, v112, v93
	v_sub_f32_e32 v113, v113, v93
	v_mul_f32_e32 v98, v94, v98
	v_mul_f32_e32 v99, v94, v99
	v_mul_f32_e32 v100, v94, v100
	v_mul_f32_e32 v101, v94, v101
	v_mul_f32_e32 v102, v94, v102
	v_mul_f32_e32 v103, v94, v103
	v_mul_f32_e32 v104, v94, v104
	v_mul_f32_e32 v105, v94, v105
	v_mul_f32_e32 v106, v94, v106
	v_mul_f32_e32 v107, v94, v107
	v_mul_f32_e32 v108, v94, v108
	v_mul_f32_e32 v109, v94, v109
	v_mul_f32_e32 v110, v94, v110
	v_mul_f32_e32 v111, v94, v111
	v_mul_f32_e32 v112, v94, v112
	v_mul_f32_e32 v113, v94, v113
	v_fma_f32 v98, v98, v130, v114
	v_fma_f32 v99, v99, v131, v115
	v_fma_f32 v100, v100, v132, v116
	v_fma_f32 v101, v101, v133, v117
	v_fma_f32 v102, v102, v134, v118
	v_fma_f32 v103, v103, v135, v119
	v_fma_f32 v104, v104, v136, v120
	v_fma_f32 v105, v105, v137, v121
	v_fma_f32 v106, v106, v138, v122
	v_fma_f32 v107, v107, v139, v123
	v_fma_f32 v108, v108, v140, v124
	v_fma_f32 v109, v109, v141, v125
	v_fma_f32 v110, v110, v142, v126
	v_fma_f32 v111, v111, v143, v127
	v_fma_f32 v112, v112, v144, v128
	v_fma_f32 v113, v113, v145, v129
	v_cvt_pk_bf16_f32 v190, v98, v99
	v_cvt_pk_bf16_f32 v191, v100, v101
	v_cvt_pk_bf16_f32 v192, v102, v103
	v_cvt_pk_bf16_f32 v193, v104, v105
	v_cvt_pk_bf16_f32 v194, v106, v107
	v_cvt_pk_bf16_f32 v195, v108, v109
	v_cvt_pk_bf16_f32 v196, v110, v111
	v_cvt_pk_bf16_f32 v197, v112, v113
	s_add_u32 s2, s10, 0x1800
	s_addc_u32 s3, s11, 0
	global_store_dwordx2 v1, v[190:191], s[2:3]
	global_store_dwordx2 v1, v[192:193], s[2:3] offset:512
	global_store_dwordx2 v1, v[194:195], s[2:3] offset:1024
	global_store_dwordx2 v1, v[196:197], s[2:3] offset:1536
	s_add_u32 s2, s8, 0x7000
	s_addc_u32 s3, s9, 0
	global_load_dwordx4 v[98:101], v0, s[2:3]
	global_load_dwordx4 v[102:105], v0, s[2:3] offset:1024
	global_load_dwordx4 v[106:109], v0, s[2:3] offset:2048
	global_load_dwordx4 v[110:113], v0, s[2:3] offset:3072
	s_waitcnt vmcnt(27)
	v_add_f32_e32 v9, v42, v43
	v_add_f32_e32 v91, v44, v45
	v_mul_f32_e32 v90, v42, v42
	v_mul_f32_e32 v92, v43, v43
	v_add_f32_e32 v9, v9, v46
	v_add_f32_e32 v91, v91, v47
	v_add_f32_e32 v9, v9, v48
	v_add_f32_e32 v91, v91, v49
	v_add_f32_e32 v9, v9, v50
	v_add_f32_e32 v91, v91, v51
	v_add_f32_e32 v9, v9, v52
	v_add_f32_e32 v91, v91, v53
	v_add_f32_e32 v9, v9, v54
	v_add_f32_e32 v91, v91, v55
	v_add_f32_e32 v9, v9, v56
	v_add_f32_e32 v91, v91, v57
	v_fmac_f32_e32 v90, v44, v44
	v_fmac_f32_e32 v92, v45, v45
	v_fmac_f32_e32 v90, v46, v46
	v_fmac_f32_e32 v92, v47, v47
	v_fmac_f32_e32 v90, v48, v48
	v_fmac_f32_e32 v92, v49, v49
	v_fmac_f32_e32 v90, v50, v50
	v_fmac_f32_e32 v92, v51, v51
	v_fmac_f32_e32 v90, v52, v52
	v_fmac_f32_e32 v92, v53, v53
	v_fmac_f32_e32 v90, v54, v54
	v_fmac_f32_e32 v92, v55, v55
	v_fmac_f32_e32 v90, v56, v56
	v_fmac_f32_e32 v92, v57, v57
	v_add_f32_e32 v9, v9, v91
	v_add_f32_e32 v90, v90, v92
	ds_bpermute_b32 v91, v3, v9
	ds_bpermute_b32 v92, v3, v90
	s_waitcnt lgkmcnt(0)
	v_add_f32_e32 v9, v9, v91
	v_add_f32_e32 v90, v90, v92
	ds_bpermute_b32 v91, v4, v9
	ds_bpermute_b32 v92, v4, v90
	s_waitcnt lgkmcnt(0)
	v_add_f32_e32 v9, v9, v91
	v_add_f32_e32 v90, v90, v92
	ds_bpermute_b32 v91, v5, v9
	ds_bpermute_b32 v92, v5, v90
	s_waitcnt lgkmcnt(0)
	v_add_f32_e32 v9, v9, v91
	v_add_f32_e32 v90, v90, v92
	ds_bpermute_b32 v91, v6, v9
	ds_bpermute_b32 v92, v6, v90
	s_waitcnt lgkmcnt(0)
	v_add_f32_e32 v9, v9, v91
	v_add_f32_e32 v90, v90, v92
	ds_bpermute_b32 v91, v7, v9
	ds_bpermute_b32 v92, v7, v90
	s_waitcnt lgkmcnt(0)
	v_add_f32_e32 v9, v9, v91
	v_add_f32_e32 v90, v90, v92
	ds_bpermute_b32 v91, v8, v9
	ds_bpermute_b32 v92, v8, v90
	s_waitcnt lgkmcnt(0)
; DI unsigned pk2(float lo, float hi) { f32x2 v = {lo, hi}; bf16x2_t b = __builtin_convertvector(v, bf16x2_t); return __builtin_bit_cast(unsigned, b); }
; DI void ln_row_v(const Frame& F, f32x4 (&v)[4], float* xout, const float* g, const float* b, const float* sh, const float* sc, bf16_t* hout, const float* slab, const float* gres, float* stat = nullptr) {
;     ...
;     if (g) {
;         float s = 0.f, s2 = 0.f;
; #pragma unroll
;         for (int j = 0; j < 4; ++j) { s += (v[j][0] + v[j][1]) + (v[j][2] + v[j][3]); s2 += (v[j][0] * v[j][0] + v[j][1] * v[j][1]) + (v[j][2] * v[j][2] + v[j][3] * v[j][3]); }
;         wave_sum2(s, s2, F.lane);
;         const float mean = s * (1.f / D); const float rstd = 1.f / sqrtf(fmaxf(s2 * (1.f / D) - mean * mean, 0.f) + EPS);
;         if (stat && F.lane == 0) { f32x2 sv = {mean, rstd}; *(f32x2*)stat = sv; }
; #pragma unroll
;         for (int j = 0; j < 4; ++j) { const f32x4 gg = ((const f32x4*)g)[F.lane + 64 * j], bb = ((const f32x4*)b)[F.lane + 64 * j];
;             v[j] = (v[j] - mean) * rstd * gg + bb; if (xout) ((f32x4*)xout)[F.lane + 64 * j] = v[j]; }
;     }
;     if (hout) {
;         float s = 0.f, s2 = 0.f;
; #pragma unroll
;         for (int j = 0; j < 4; ++j) { s += (v[j][0] + v[j][1]) + (v[j][2] + v[j][3]); s2 += (v[j][0] * v[j][0] + v[j][1] * v[j][1]) + (v[j][2] * v[j][2] + v[j][3] * v[j][3]); }
;         wave_sum2(s, s2, F.lane);
;         const float mean = s * (1.f / D); const float rstd = 1.f / sqrtf(fmaxf(s2 * (1.f / D) - mean * mean, 0.f) + EPS);
; #pragma unroll
;         for (int j = 0; j < 4; ++j) { const f32x4 hh = ((const f32x4*)sh)[F.lane + 64 * j], cc = ((const f32x4*)sc)[F.lane + 64 * j];
;             const f32x4 o = (v[j] - mean) * rstd * (cc + 1.f) + hh; u32x2 wv; wv.x = pk2(o[0], o[1]); wv.y = pk2(o[2], o[3]);
;             ((u32x2*)hout)[F.lane + 64 * j] = wv; }
;     }
	v_add_f32_e32 v9, v9, v91
	v_add_f32_e32 v90, v90, v92
	v_mul_f32_e32 v93, 0x3a800000, v9
	v_mul_f32_e32 v91, 0x3a800000, v90
	v_fma_f32 v91, -v93, v93, v91
	v_max_f32_e32 v91, 0, v91
	v_add_f32_e32 v91, 0x358637bd, v91
	v_rsq_f32_e32 v94, v91
	v_mul_f32_e32 v91, 0.5, v91
	v_mul_f32_e32 v92, v94, v94
	v_fma_f32 v92, -v91, v92, 0.5
	v_fma_f32 v94, v94, v92, v94
	s_add_u32 s2, s12, 0x20
	s_addc_u32 s3, s13, 0
	v_mov_b32_e32 v188, v93
	v_mov_b32_e32 v189, v94
	s_mov_b64 exec, 1
	global_store_dwordx2 v97, v[188:189], s[2:3]
	s_mov_b64 exec, -1
	v_sub_f32_e32 v42, v42, v93
	v_sub_f32_e32 v43, v43, v93
	v_sub_f32_e32 v44, v44, v93
	v_sub_f32_e32 v45, v45, v93
	v_sub_f32_e32 v46, v46, v93
	v_sub_f32_e32 v47, v47, v93
	v_sub_f32_e32 v48, v48, v93
	v_sub_f32_e32 v49, v49, v93
	v_sub_f32_e32 v50, v50, v93
	v_sub_f32_e32 v51, v51, v93
	v_sub_f32_e32 v52, v52, v93
	v_sub_f32_e32 v53, v53, v93
	v_sub_f32_e32 v54, v54, v93
	v_sub_f32_e32 v55, v55, v93
	v_sub_f32_e32 v56, v56, v93
	v_sub_f32_e32 v57, v57, v93
	v_mul_f32_e32 v42, v94, v42
	v_mul_f32_e32 v43, v94, v43
	v_mul_f32_e32 v44, v94, v44
	v_mul_f32_e32 v45, v94, v45
	v_mul_f32_e32 v46, v94, v46
	v_mul_f32_e32 v47, v94, v47
	v_mul_f32_e32 v48, v94, v48
	v_mul_f32_e32 v49, v94, v49
	v_mul_f32_e32 v50, v94, v50
	v_mul_f32_e32 v51, v94, v51
	v_mul_f32_e32 v52, v94, v52
	v_mul_f32_e32 v53, v94, v53
	v_mul_f32_e32 v54, v94, v54
	v_mul_f32_e32 v55, v94, v55
	v_mul_f32_e32 v56, v94, v56
	v_mul_f32_e32 v57, v94, v57
	v_fma_f32 v42, v42, v10, v26
	v_fma_f32 v43, v43, v11, v27
	v_fma_f32 v44, v44, v12, v28
	v_fma_f32 v45, v45, v13, v29
	v_fma_f32 v46, v46, v14, v30
	v_fma_f32 v47, v47, v15, v31
	v_fma_f32 v48, v48, v16, v32
	v_fma_f32 v49, v49, v17, v33
	v_fma_f32 v50, v50, v18, v34
	v_fma_f32 v51, v51, v19, v35
	v_fma_f32 v52, v52, v20, v36
	v_fma_f32 v53, v53, v21, v37
	v_fma_f32 v54, v54, v22, v38
	v_fma_f32 v55, v55, v23, v39
	v_fma_f32 v56, v56, v24, v40
	v_fma_f32 v57, v57, v25, v41
	v_add_f32_e32 v9, v42, v43
	v_add_f32_e32 v91, v44, v45
	v_mul_f32_e32 v90, v42, v42
	v_mul_f32_e32 v92, v43, v43
	v_add_f32_e32 v9, v9, v46
	v_add_f32_e32 v91, v91, v47
	v_add_f32_e32 v9, v9, v48
	v_add_f32_e32 v91, v91, v49
	v_add_f32_e32 v9, v9, v50
	v_add_f32_e32 v91, v91, v51
	v_add_f32_e32 v9, v9, v52
	v_add_f32_e32 v91, v91, v53
	v_add_f32_e32 v9, v9, v54
	v_add_f32_e32 v91, v91, v55
	v_add_f32_e32 v9, v9, v56
	v_add_f32_e32 v91, v91, v57
	v_fmac_f32_e32 v90, v44, v44
	v_fmac_f32_e32 v92, v45, v45
	v_fmac_f32_e32 v90, v46, v46
	v_fmac_f32_e32 v92, v47, v47
	v_fmac_f32_e32 v90, v48, v48
	v_fmac_f32_e32 v92, v49, v49
	v_fmac_f32_e32 v90, v50, v50
	v_fmac_f32_e32 v92, v51, v51
	v_fmac_f32_e32 v90, v52, v52
	v_fmac_f32_e32 v92, v53, v53
	v_fmac_f32_e32 v90, v54, v54
	v_fmac_f32_e32 v92, v55, v55
	v_fmac_f32_e32 v90, v56, v56
	v_fmac_f32_e32 v92, v57, v57
	v_add_f32_e32 v9, v9, v91
	v_add_f32_e32 v90, v90, v92
	ds_bpermute_b32 v91, v3, v9
	ds_bpermute_b32 v92, v3, v90
	s_waitcnt lgkmcnt(0)
	v_add_f32_e32 v9, v9, v91
	v_add_f32_e32 v90, v90, v92
	ds_bpermute_b32 v91, v4, v9
	ds_bpermute_b32 v92, v4, v90
	s_waitcnt lgkmcnt(0)
	v_add_f32_e32 v9, v9, v91
	v_add_f32_e32 v90, v90, v92
	ds_bpermute_b32 v91, v5, v9
	ds_bpermute_b32 v92, v5, v90
	s_waitcnt lgkmcnt(0)
	v_add_f32_e32 v9, v9, v91
	v_add_f32_e32 v90, v90, v92
	ds_bpermute_b32 v91, v6, v9
	ds_bpermute_b32 v92, v6, v90
	s_waitcnt lgkmcnt(0)
	v_add_f32_e32 v9, v9, v91
	v_add_f32_e32 v90, v90, v92
	ds_bpermute_b32 v91, v7, v9
	ds_bpermute_b32 v92, v7, v90
	s_waitcnt lgkmcnt(0)
	v_add_f32_e32 v9, v9, v91
	v_add_f32_e32 v90, v90, v92
	ds_bpermute_b32 v91, v8, v9
	ds_bpermute_b32 v92, v8, v90
	s_waitcnt lgkmcnt(0)
	v_add_f32_e32 v9, v9, v91
	v_add_f32_e32 v90, v90, v92
	v_mul_f32_e32 v93, 0x3a800000, v9
	v_mul_f32_e32 v91, 0x3a800000, v90
	v_fma_f32 v91, -v93, v93, v91
	v_max_f32_e32 v91, 0, v91
	v_add_f32_e32 v91, 0x358637bd, v91
	v_rsq_f32_e32 v94, v91
	v_mul_f32_e32 v91, 0.5, v91
	v_mul_f32_e32 v92, v94, v94
	v_fma_f32 v92, -v91, v92, 0.5
	v_fma_f32 v94, v94, v92, v94
	v_sub_f32_e32 v42, v42, v93
	v_sub_f32_e32 v43, v43, v93
	v_sub_f32_e32 v44, v44, v93
	v_sub_f32_e32 v45, v45, v93
	v_sub_f32_e32 v46, v46, v93
	v_sub_f32_e32 v47, v47, v93
	v_sub_f32_e32 v48, v48, v93
	v_sub_f32_e32 v49, v49, v93
	v_sub_f32_e32 v50, v50, v93
	v_sub_f32_e32 v51, v51, v93
	v_sub_f32_e32 v52, v52, v93
	v_sub_f32_e32 v53, v53, v93
	v_sub_f32_e32 v54, v54, v93
	v_sub_f32_e32 v55, v55, v93
	v_sub_f32_e32 v56, v56, v93
	v_sub_f32_e32 v57, v57, v93
	v_mul_f32_e32 v42, v94, v42
	v_mul_f32_e32 v43, v94, v43
	v_mul_f32_e32 v44, v94, v44
	v_mul_f32_e32 v45, v94, v45
	v_mul_f32_e32 v46, v94, v46
	v_mul_f32_e32 v47, v94, v47
	v_mul_f32_e32 v48, v94, v48
	v_mul_f32_e32 v49, v94, v49
	v_mul_f32_e32 v50, v94, v50
	v_mul_f32_e32 v51, v94, v51
	v_mul_f32_e32 v52, v94, v52
	v_mul_f32_e32 v53, v94, v53
	v_mul_f32_e32 v54, v94, v54
	v_mul_f32_e32 v55, v94, v55
	v_mul_f32_e32 v56, v94, v56
	v_mul_f32_e32 v57, v94, v57
	v_fma_f32 v42, v42, v130, v114
	v_fma_f32 v43, v43, v131, v115
	v_fma_f32 v44, v44, v132, v116
	v_fma_f32 v45, v45, v133, v117
	v_fma_f32 v46, v46, v134, v118
	v_fma_f32 v47, v47, v135, v119
	v_fma_f32 v48, v48, v136, v120
	v_fma_f32 v49, v49, v137, v121
	v_fma_f32 v50, v50, v138, v122
	v_fma_f32 v51, v51, v139, v123
	v_fma_f32 v52, v52, v140, v124
	v_fma_f32 v53, v53, v141, v125
	v_fma_f32 v54, v54, v142, v126
	v_fma_f32 v55, v55, v143, v127
	v_fma_f32 v56, v56, v144, v128
	v_fma_f32 v57, v57, v145, v129
	v_cvt_pk_bf16_f32 v190, v42, v43
	v_cvt_pk_bf16_f32 v191, v44, v45
	v_cvt_pk_bf16_f32 v192, v46, v47
	v_cvt_pk_bf16_f32 v193, v48, v49
	v_cvt_pk_bf16_f32 v194, v50, v51
	v_cvt_pk_bf16_f32 v195, v52, v53
	v_cvt_pk_bf16_f32 v196, v54, v55
	v_cvt_pk_bf16_f32 v197, v56, v57
	s_add_u32 s2, s10, 0x2000
	s_addc_u32 s3, s11, 0
	global_store_dwordx2 v1, v[190:191], s[2:3]
	global_store_dwordx2 v1, v[192:193], s[2:3] offset:512
	global_store_dwordx2 v1, v[194:195], s[2:3] offset:1024
	global_store_dwordx2 v1, v[196:197], s[2:3] offset:1536
	s_mov_b64 s[2:3], s[20:21]
	global_load_dwordx4 v[42:45], v0, s[2:3]
	global_load_dwordx4 v[46:49], v0, s[2:3] offset:1024
	global_load_dwordx4 v[50:53], v0, s[2:3] offset:2048
	global_load_dwordx4 v[54:57], v0, s[2:3] offset:3072
	s_waitcnt vmcnt(27)
; DI void ln_row_v(const Frame& F, f32x4 (&v)[4], float* xout, const float* g, const float* b, const float* sh, const float* sc, bf16_t* hout, const float* slab, const float* gres, float* stat = nullptr) {
;     ...
;     if (g) {
;         float s = 0.f, s2 = 0.f;
; #pragma unroll
;         for (int j = 0; j < 4; ++j) { s += (v[j][0] + v[j][1]) + (v[j][2] + v[j][3]); s2 += (v[j][0] * v[j][0] + v[j][1] * v[j][1]) + (v[j][2] * v[j][2] + v[j][3] * v[j][3]); }
;         wave_sum2(s, s2, F.lane);
;         const float mean = s * (1.f / D); const float rstd = 1.f / sqrtf(fmaxf(s2 * (1.f / D) - mean * mean, 0.f) + EPS);
;         if (stat && F.lane == 0) { f32x2 sv = {mean, rstd}; *(f32x2*)stat = sv; }
; #pragma unroll
;         for (int j = 0; j < 4; ++j) { const f32x4 gg = ((const f32x4*)g)[F.lane + 64 * j], bb = ((const f32x4*)b)[F.lane + 64 * j];
;             v[j] = (v[j] - mean) * rstd * gg + bb; if (xout) ((f32x4*)xout)[F.lane + 64 * j] = v[j]; }
	v_add_f32_e32 v9, v58, v59
	v_add_f32_e32 v91, v60, v61
	v_mul_f32_e32 v90, v58, v58
	v_mul_f32_e32 v92, v59, v59
	v_add_f32_e32 v9, v9, v62
	v_add_f32_e32 v91, v91, v63
	v_add_f32_e32 v9, v9, v64
	v_add_f32_e32 v91, v91, v65
	v_add_f32_e32 v9, v9, v66
	v_add_f32_e32 v91, v91, v67
	v_add_f32_e32 v9, v9, v68
	v_add_f32_e32 v91, v91, v69
	v_add_f32_e32 v9, v9, v70
	v_add_f32_e32 v91, v91, v71
	v_add_f32_e32 v9, v9, v72
	v_add_f32_e32 v91, v91, v73
	v_fmac_f32_e32 v90, v60, v60
	v_fmac_f32_e32 v92, v61, v61
	v_fmac_f32_e32 v90, v62, v62
	v_fmac_f32_e32 v92, v63, v63
	v_fmac_f32_e32 v90, v64, v64
	v_fmac_f32_e32 v92, v65, v65
	v_fmac_f32_e32 v90, v66, v66
	v_fmac_f32_e32 v92, v67, v67
	v_fmac_f32_e32 v90, v68, v68
	v_fmac_f32_e32 v92, v69, v69
	v_fmac_f32_e32 v90, v70, v70
	v_fmac_f32_e32 v92, v71, v71
	v_fmac_f32_e32 v90, v72, v72
	v_fmac_f32_e32 v92, v73, v73
	v_add_f32_e32 v9, v9, v91
	v_add_f32_e32 v90, v90, v92
	ds_bpermute_b32 v91, v3, v9
	ds_bpermute_b32 v92, v3, v90
	s_waitcnt lgkmcnt(0)
	v_add_f32_e32 v9, v9, v91
	v_add_f32_e32 v90, v90, v92
	ds_bpermute_b32 v91, v4, v9
	ds_bpermute_b32 v92, v4, v90
	s_waitcnt lgkmcnt(0)
	v_add_f32_e32 v9, v9, v91
	v_add_f32_e32 v90, v90, v92
	ds_bpermute_b32 v91, v5, v9
	ds_bpermute_b32 v92, v5, v90
	s_waitcnt lgkmcnt(0)
	v_add_f32_e32 v9, v9, v91
	v_add_f32_e32 v90, v90, v92
	ds_bpermute_b32 v91, v6, v9
	ds_bpermute_b32 v92, v6, v90
	s_waitcnt lgkmcnt(0)
	v_add_f32_e32 v9, v9, v91
	v_add_f32_e32 v90, v90, v92
	ds_bpermute_b32 v91, v7, v9
	ds_bpermute_b32 v92, v7, v90
	s_waitcnt lgkmcnt(0)
	v_add_f32_e32 v9, v9, v91
	v_add_f32_e32 v90, v90, v92
	ds_bpermute_b32 v91, v8, v9
	ds_bpermute_b32 v92, v8, v90
	s_waitcnt lgkmcnt(0)
	v_add_f32_e32 v9, v9, v91
	v_add_f32_e32 v90, v90, v92
	v_mul_f32_e32 v93, 0x3a800000, v9
	v_mul_f32_e32 v91, 0x3a800000, v90
	v_fma_f32 v91, -v93, v93, v91
	v_max_f32_e32 v91, 0, v91
	v_add_f32_e32 v91, 0x358637bd, v91
	v_rsq_f32_e32 v94, v91
	v_mul_f32_e32 v91, 0.5, v91
	v_mul_f32_e32 v92, v94, v94
	v_fma_f32 v92, -v91, v92, 0.5
	v_fma_f32 v94, v94, v92, v94
	s_add_u32 s2, s12, 0x28
	s_addc_u32 s3, s13, 0
	v_mov_b32_e32 v188, v93
	v_mov_b32_e32 v189, v94
	s_mov_b64 exec, 1
	global_store_dwordx2 v97, v[188:189], s[2:3]
	s_mov_b64 exec, -1
	v_sub_f32_e32 v58, v58, v93
	v_sub_f32_e32 v59, v59, v93
	v_sub_f32_e32 v60, v60, v93
	v_sub_f32_e32 v61, v61, v93
	v_sub_f32_e32 v62, v62, v93
	v_sub_f32_e32 v63, v63, v93
	v_sub_f32_e32 v64, v64, v93
	v_sub_f32_e32 v65, v65, v93
	v_sub_f32_e32 v66, v66, v93
	v_sub_f32_e32 v67, v67, v93
	v_sub_f32_e32 v68, v68, v93
	v_sub_f32_e32 v69, v69, v93
	v_sub_f32_e32 v70, v70, v93
	v_sub_f32_e32 v71, v71, v93
	v_sub_f32_e32 v72, v72, v93
	v_sub_f32_e32 v73, v73, v93
	v_mul_f32_e32 v58, v94, v58
	v_mul_f32_e32 v59, v94, v59
	v_mul_f32_e32 v60, v94, v60
	v_mul_f32_e32 v61, v94, v61
	v_mul_f32_e32 v62, v94, v62
	v_mul_f32_e32 v63, v94, v63
	v_mul_f32_e32 v64, v94, v64
	v_mul_f32_e32 v65, v94, v65
	v_mul_f32_e32 v66, v94, v66
	v_mul_f32_e32 v67, v94, v67
	v_mul_f32_e32 v68, v94, v68
	v_mul_f32_e32 v69, v94, v69
	v_mul_f32_e32 v70, v94, v70
	v_mul_f32_e32 v71, v94, v71
	v_mul_f32_e32 v72, v94, v72
	v_mul_f32_e32 v73, v94, v73
	v_fma_f32 v58, v58, v10, v26
	v_fma_f32 v59, v59, v11, v27
	v_fma_f32 v60, v60, v12, v28
	v_fma_f32 v61, v61, v13, v29
	v_fma_f32 v62, v62, v14, v30
	v_fma_f32 v63, v63, v15, v31
	v_fma_f32 v64, v64, v16, v32
	v_fma_f32 v65, v65, v17, v33
	v_fma_f32 v66, v66, v18, v34
	v_fma_f32 v67, v67, v19, v35
	v_fma_f32 v68, v68, v20, v36
	v_fma_f32 v69, v69, v21, v37
	v_fma_f32 v70, v70, v22, v38
	v_fma_f32 v71, v71, v23, v39
	v_fma_f32 v72, v72, v24, v40
	v_fma_f32 v73, v73, v25, v41
	v_add_f32_e32 v9, v58, v59
	v_add_f32_e32 v91, v60, v61
	v_mul_f32_e32 v90, v58, v58
	v_mul_f32_e32 v92, v59, v59
	v_add_f32_e32 v9, v9, v62
	v_add_f32_e32 v91, v91, v63
	v_add_f32_e32 v9, v9, v64
	v_add_f32_e32 v91, v91, v65
	v_add_f32_e32 v9, v9, v66
	v_add_f32_e32 v91, v91, v67
	v_add_f32_e32 v9, v9, v68
	v_add_f32_e32 v91, v91, v69
	v_add_f32_e32 v9, v9, v70
	v_add_f32_e32 v91, v91, v71
	v_add_f32_e32 v9, v9, v72
	v_add_f32_e32 v91, v91, v73
	v_fmac_f32_e32 v90, v60, v60
	v_fmac_f32_e32 v92, v61, v61
	v_fmac_f32_e32 v90, v62, v62
	v_fmac_f32_e32 v92, v63, v63
	v_fmac_f32_e32 v90, v64, v64
	v_fmac_f32_e32 v92, v65, v65
	v_fmac_f32_e32 v90, v66, v66
	v_fmac_f32_e32 v92, v67, v67
	v_fmac_f32_e32 v90, v68, v68
	v_fmac_f32_e32 v92, v69, v69
	v_fmac_f32_e32 v90, v70, v70
	v_fmac_f32_e32 v92, v71, v71
	v_fmac_f32_e32 v90, v72, v72
	v_fmac_f32_e32 v92, v73, v73
	v_add_f32_e32 v9, v9, v91
	v_add_f32_e32 v90, v90, v92
	ds_bpermute_b32 v91, v3, v9
	ds_bpermute_b32 v92, v3, v90
	s_waitcnt lgkmcnt(0)
	v_add_f32_e32 v9, v9, v91
	v_add_f32_e32 v90, v90, v92
	ds_bpermute_b32 v91, v4, v9
	ds_bpermute_b32 v92, v4, v90
	s_waitcnt lgkmcnt(0)
	v_add_f32_e32 v9, v9, v91
	v_add_f32_e32 v90, v90, v92
	ds_bpermute_b32 v91, v5, v9
	ds_bpermute_b32 v92, v5, v90
	s_waitcnt lgkmcnt(0)
	v_add_f32_e32 v9, v9, v91
	v_add_f32_e32 v90, v90, v92
	ds_bpermute_b32 v91, v6, v9
	ds_bpermute_b32 v92, v6, v90
	s_waitcnt lgkmcnt(0)
	v_add_f32_e32 v9, v9, v91
	v_add_f32_e32 v90, v90, v92
	ds_bpermute_b32 v91, v7, v9
	ds_bpermute_b32 v92, v7, v90
	s_waitcnt lgkmcnt(0)
	v_add_f32_e32 v9, v9, v91
	v_add_f32_e32 v90, v90, v92
	ds_bpermute_b32 v91, v8, v9
	ds_bpermute_b32 v92, v8, v90
	s_waitcnt lgkmcnt(0)
; DI unsigned pk2(float lo, float hi) { f32x2 v = {lo, hi}; bf16x2_t b = __builtin_convertvector(v, bf16x2_t); return __builtin_bit_cast(unsigned, b); }
; DI void ln_row_v(const Frame& F, f32x4 (&v)[4], float* xout, const float* g, const float* b, const float* sh, const float* sc, bf16_t* hout, const float* slab, const float* gres, float* stat = nullptr) {
;     ...
;     if (g) {
;         float s = 0.f, s2 = 0.f;
; #pragma unroll
;         for (int j = 0; j < 4; ++j) { s += (v[j][0] + v[j][1]) + (v[j][2] + v[j][3]); s2 += (v[j][0] * v[j][0] + v[j][1] * v[j][1]) + (v[j][2] * v[j][2] + v[j][3] * v[j][3]); }
;         wave_sum2(s, s2, F.lane);
;         const float mean = s * (1.f / D); const float rstd = 1.f / sqrtf(fmaxf(s2 * (1.f / D) - mean * mean, 0.f) + EPS);
;         if (stat && F.lane == 0) { f32x2 sv = {mean, rstd}; *(f32x2*)stat = sv; }
; #pragma unroll
;         for (int j = 0; j < 4; ++j) { const f32x4 gg = ((const f32x4*)g)[F.lane + 64 * j], bb = ((const f32x4*)b)[F.lane + 64 * j];
;             v[j] = (v[j] - mean) * rstd * gg + bb; if (xout) ((f32x4*)xout)[F.lane + 64 * j] = v[j]; }
;     ...
;     if (hout) {
;         float s = 0.f, s2 = 0.f;
; #pragma unroll
;         for (int j = 0; j < 4; ++j) { s += (v[j][0] + v[j][1]) + (v[j][2] + v[j][3]); s2 += (v[j][0] * v[j][0] + v[j][1] * v[j][1]) + (v[j][2] * v[j][2] + v[j][3] * v[j][3]); }
;         wave_sum2(s, s2, F.lane);
;         const float mean = s * (1.f / D); const float rstd = 1.f / sqrtf(fmaxf(s2 * (1.f / D) - mean * mean, 0.f) + EPS);
; #pragma unroll
;         for (int j = 0; j < 4; ++j) { const f32x4 hh = ((const f32x4*)sh)[F.lane + 64 * j], cc = ((const f32x4*)sc)[F.lane + 64 * j];
;             const f32x4 o = (v[j] - mean) * rstd * (cc + 1.f) + hh; u32x2 wv; wv.x = pk2(o[0], o[1]); wv.y = pk2(o[2], o[3]);
;             ((u32x2*)hout)[F.lane + 64 * j] = wv; }
;     }
	v_add_f32_e32 v9, v9, v91
	v_add_f32_e32 v90, v90, v92
	v_mul_f32_e32 v93, 0x3a800000, v9
	v_mul_f32_e32 v91, 0x3a800000, v90
	v_fma_f32 v91, -v93, v93, v91
	v_max_f32_e32 v91, 0, v91
	v_add_f32_e32 v91, 0x358637bd, v91
	v_rsq_f32_e32 v94, v91
	v_mul_f32_e32 v91, 0.5, v91
	v_mul_f32_e32 v92, v94, v94
	v_fma_f32 v92, -v91, v92, 0.5
	v_fma_f32 v94, v94, v92, v94
	v_sub_f32_e32 v58, v58, v93
	v_sub_f32_e32 v59, v59, v93
	v_sub_f32_e32 v60, v60, v93
	v_sub_f32_e32 v61, v61, v93
	v_sub_f32_e32 v62, v62, v93
	v_sub_f32_e32 v63, v63, v93
	v_sub_f32_e32 v64, v64, v93
	v_sub_f32_e32 v65, v65, v93
	v_sub_f32_e32 v66, v66, v93
	v_sub_f32_e32 v67, v67, v93
	v_sub_f32_e32 v68, v68, v93
	v_sub_f32_e32 v69, v69, v93
	v_sub_f32_e32 v70, v70, v93
	v_sub_f32_e32 v71, v71, v93
	v_sub_f32_e32 v72, v72, v93
	v_sub_f32_e32 v73, v73, v93
	v_mul_f32_e32 v58, v94, v58
	v_mul_f32_e32 v59, v94, v59
	v_mul_f32_e32 v60, v94, v60
	v_mul_f32_e32 v61, v94, v61
	v_mul_f32_e32 v62, v94, v62
	v_mul_f32_e32 v63, v94, v63
	v_mul_f32_e32 v64, v94, v64
	v_mul_f32_e32 v65, v94, v65
	v_mul_f32_e32 v66, v94, v66
	v_mul_f32_e32 v67, v94, v67
	v_mul_f32_e32 v68, v94, v68
	v_mul_f32_e32 v69, v94, v69
	v_mul_f32_e32 v70, v94, v70
	v_mul_f32_e32 v71, v94, v71
	v_mul_f32_e32 v72, v94, v72
	v_mul_f32_e32 v73, v94, v73
	v_fma_f32 v58, v58, v130, v114
	v_fma_f32 v59, v59, v131, v115
	v_fma_f32 v60, v60, v132, v116
	v_fma_f32 v61, v61, v133, v117
	v_fma_f32 v62, v62, v134, v118
	v_fma_f32 v63, v63, v135, v119
	v_fma_f32 v64, v64, v136, v120
	v_fma_f32 v65, v65, v137, v121
	v_fma_f32 v66, v66, v138, v122
	v_fma_f32 v67, v67, v139, v123
	v_fma_f32 v68, v68, v140, v124
	v_fma_f32 v69, v69, v141, v125
	v_fma_f32 v70, v70, v142, v126
	v_fma_f32 v71, v71, v143, v127
	v_fma_f32 v72, v72, v144, v128
	v_fma_f32 v73, v73, v145, v129
	v_cvt_pk_bf16_f32 v190, v58, v59
	v_cvt_pk_bf16_f32 v191, v60, v61
	v_cvt_pk_bf16_f32 v192, v62, v63
	v_cvt_pk_bf16_f32 v193, v64, v65
	v_cvt_pk_bf16_f32 v194, v66, v67
	v_cvt_pk_bf16_f32 v195, v68, v69
	v_cvt_pk_bf16_f32 v196, v70, v71
	v_cvt_pk_bf16_f32 v197, v72, v73
	s_add_u32 s2, s10, 0x2800
	s_addc_u32 s3, s11, 0
	global_store_dwordx2 v1, v[190:191], s[2:3]
	global_store_dwordx2 v1, v[192:193], s[2:3] offset:512
	global_store_dwordx2 v1, v[194:195], s[2:3] offset:1024
	global_store_dwordx2 v1, v[196:197], s[2:3] offset:1536
	s_waitcnt vmcnt(23)
	v_add_f32_e32 v9, v74, v75
	v_add_f32_e32 v91, v76, v77
	v_mul_f32_e32 v90, v74, v74
	v_mul_f32_e32 v92, v75, v75
	v_add_f32_e32 v9, v9, v78
	v_add_f32_e32 v91, v91, v79
	v_add_f32_e32 v9, v9, v80
	v_add_f32_e32 v91, v91, v81
	v_add_f32_e32 v9, v9, v82
	v_add_f32_e32 v91, v91, v83
	v_add_f32_e32 v9, v9, v84
	v_add_f32_e32 v91, v91, v85
	v_add_f32_e32 v9, v9, v86
	v_add_f32_e32 v91, v91, v87
	v_add_f32_e32 v9, v9, v88
	v_add_f32_e32 v91, v91, v89
	v_fmac_f32_e32 v90, v76, v76
	v_fmac_f32_e32 v92, v77, v77
	v_fmac_f32_e32 v90, v78, v78
	v_fmac_f32_e32 v92, v79, v79
	v_fmac_f32_e32 v90, v80, v80
	v_fmac_f32_e32 v92, v81, v81
	v_fmac_f32_e32 v90, v82, v82
	v_fmac_f32_e32 v92, v83, v83
	v_fmac_f32_e32 v90, v84, v84
	v_fmac_f32_e32 v92, v85, v85
	v_fmac_f32_e32 v90, v86, v86
	v_fmac_f32_e32 v92, v87, v87
	v_fmac_f32_e32 v90, v88, v88
	v_fmac_f32_e32 v92, v89, v89
	v_add_f32_e32 v9, v9, v91
	v_add_f32_e32 v90, v90, v92
	ds_bpermute_b32 v91, v3, v9
	ds_bpermute_b32 v92, v3, v90
	s_waitcnt lgkmcnt(0)
	v_add_f32_e32 v9, v9, v91
	v_add_f32_e32 v90, v90, v92
	ds_bpermute_b32 v91, v4, v9
	ds_bpermute_b32 v92, v4, v90
	s_waitcnt lgkmcnt(0)
	v_add_f32_e32 v9, v9, v91
	v_add_f32_e32 v90, v90, v92
	ds_bpermute_b32 v91, v5, v9
	ds_bpermute_b32 v92, v5, v90
	s_waitcnt lgkmcnt(0)
	v_add_f32_e32 v9, v9, v91
	v_add_f32_e32 v90, v90, v92
	ds_bpermute_b32 v91, v6, v9
	ds_bpermute_b32 v92, v6, v90
	s_waitcnt lgkmcnt(0)
	v_add_f32_e32 v9, v9, v91
	v_add_f32_e32 v90, v90, v92
	ds_bpermute_b32 v91, v7, v9
	ds_bpermute_b32 v92, v7, v90
	s_waitcnt lgkmcnt(0)
	v_add_f32_e32 v9, v9, v91
	v_add_f32_e32 v90, v90, v92
	ds_bpermute_b32 v91, v8, v9
	ds_bpermute_b32 v92, v8, v90
	s_waitcnt lgkmcnt(0)
	v_add_f32_e32 v9, v9, v91
	v_add_f32_e32 v90, v90, v92
	v_mul_f32_e32 v93, 0x3a800000, v9
	v_mul_f32_e32 v91, 0x3a800000, v90
	v_fma_f32 v91, -v93, v93, v91
	v_max_f32_e32 v91, 0, v91
	v_add_f32_e32 v91, 0x358637bd, v91
	v_rsq_f32_e32 v94, v91
	v_mul_f32_e32 v91, 0.5, v91
	v_mul_f32_e32 v92, v94, v94
	v_fma_f32 v92, -v91, v92, 0.5
	v_fma_f32 v94, v94, v92, v94
	s_add_u32 s2, s12, 0x30
	s_addc_u32 s3, s13, 0
	v_mov_b32_e32 v188, v93
	v_mov_b32_e32 v189, v94
	s_mov_b64 exec, 1
	global_store_dwordx2 v97, v[188:189], s[2:3]
	s_mov_b64 exec, -1
	v_sub_f32_e32 v74, v74, v93
	v_sub_f32_e32 v75, v75, v93
	v_sub_f32_e32 v76, v76, v93
	v_sub_f32_e32 v77, v77, v93
	v_sub_f32_e32 v78, v78, v93
	v_sub_f32_e32 v79, v79, v93
	v_sub_f32_e32 v80, v80, v93
	v_sub_f32_e32 v81, v81, v93
	v_sub_f32_e32 v82, v82, v93
	v_sub_f32_e32 v83, v83, v93
	v_sub_f32_e32 v84, v84, v93
	v_sub_f32_e32 v85, v85, v93
	v_sub_f32_e32 v86, v86, v93
	v_sub_f32_e32 v87, v87, v93
	v_sub_f32_e32 v88, v88, v93
	v_sub_f32_e32 v89, v89, v93
	v_mul_f32_e32 v74, v94, v74
	v_mul_f32_e32 v75, v94, v75
	v_mul_f32_e32 v76, v94, v76
	v_mul_f32_e32 v77, v94, v77
	v_mul_f32_e32 v78, v94, v78
	v_mul_f32_e32 v79, v94, v79
	v_mul_f32_e32 v80, v94, v80
	v_mul_f32_e32 v81, v94, v81
	v_mul_f32_e32 v82, v94, v82
	v_mul_f32_e32 v83, v94, v83
	v_mul_f32_e32 v84, v94, v84
	v_mul_f32_e32 v85, v94, v85
	v_mul_f32_e32 v86, v94, v86
	v_mul_f32_e32 v87, v94, v87
	v_mul_f32_e32 v88, v94, v88
	v_mul_f32_e32 v89, v94, v89
	v_fma_f32 v74, v74, v10, v26
	v_fma_f32 v75, v75, v11, v27
	v_fma_f32 v76, v76, v12, v28
	v_fma_f32 v77, v77, v13, v29
	v_fma_f32 v78, v78, v14, v30
	v_fma_f32 v79, v79, v15, v31
	v_fma_f32 v80, v80, v16, v32
	v_fma_f32 v81, v81, v17, v33
	v_fma_f32 v82, v82, v18, v34
	v_fma_f32 v83, v83, v19, v35
	v_fma_f32 v84, v84, v20, v36
	v_fma_f32 v85, v85, v21, v37
	v_fma_f32 v86, v86, v22, v38
	v_fma_f32 v87, v87, v23, v39
	v_fma_f32 v88, v88, v24, v40
	v_fma_f32 v89, v89, v25, v41
	v_add_f32_e32 v9, v74, v75
	v_add_f32_e32 v91, v76, v77
	v_mul_f32_e32 v90, v74, v74
	v_mul_f32_e32 v92, v75, v75
	v_add_f32_e32 v9, v9, v78
	v_add_f32_e32 v91, v91, v79
	v_add_f32_e32 v9, v9, v80
	v_add_f32_e32 v91, v91, v81
	v_add_f32_e32 v9, v9, v82
	v_add_f32_e32 v91, v91, v83
	v_add_f32_e32 v9, v9, v84
	v_add_f32_e32 v91, v91, v85
	v_add_f32_e32 v9, v9, v86
	v_add_f32_e32 v91, v91, v87
	v_add_f32_e32 v9, v9, v88
	v_add_f32_e32 v91, v91, v89
	v_fmac_f32_e32 v90, v76, v76
	v_fmac_f32_e32 v92, v77, v77
	v_fmac_f32_e32 v90, v78, v78
	v_fmac_f32_e32 v92, v79, v79
	v_fmac_f32_e32 v90, v80, v80
	v_fmac_f32_e32 v92, v81, v81
	v_fmac_f32_e32 v90, v82, v82
	v_fmac_f32_e32 v92, v83, v83
	v_fmac_f32_e32 v90, v84, v84
	v_fmac_f32_e32 v92, v85, v85
	v_fmac_f32_e32 v90, v86, v86
	v_fmac_f32_e32 v92, v87, v87
	v_fmac_f32_e32 v90, v88, v88
	v_fmac_f32_e32 v92, v89, v89
	v_add_f32_e32 v9, v9, v91
	v_add_f32_e32 v90, v90, v92
	ds_bpermute_b32 v91, v3, v9
	ds_bpermute_b32 v92, v3, v90
	s_waitcnt lgkmcnt(0)
; DI unsigned pk2(float lo, float hi) { f32x2 v = {lo, hi}; bf16x2_t b = __builtin_convertvector(v, bf16x2_t); return __builtin_bit_cast(unsigned, b); }
; DI void ln_row_v(const Frame& F, f32x4 (&v)[4], float* xout, const float* g, const float* b, const float* sh, const float* sc, bf16_t* hout, const float* slab, const float* gres, float* stat = nullptr) {
;     ...
;     if (g) {
;         float s = 0.f, s2 = 0.f;
; #pragma unroll
;         for (int j = 0; j < 4; ++j) { s += (v[j][0] + v[j][1]) + (v[j][2] + v[j][3]); s2 += (v[j][0] * v[j][0] + v[j][1] * v[j][1]) + (v[j][2] * v[j][2] + v[j][3] * v[j][3]); }
;         wave_sum2(s, s2, F.lane);
;         const float mean = s * (1.f / D); const float rstd = 1.f / sqrtf(fmaxf(s2 * (1.f / D) - mean * mean, 0.f) + EPS);
;         if (stat && F.lane == 0) { f32x2 sv = {mean, rstd}; *(f32x2*)stat = sv; }
; #pragma unroll
;         for (int j = 0; j < 4; ++j) { const f32x4 gg = ((const f32x4*)g)[F.lane + 64 * j], bb = ((const f32x4*)b)[F.lane + 64 * j];
;             v[j] = (v[j] - mean) * rstd * gg + bb; if (xout) ((f32x4*)xout)[F.lane + 64 * j] = v[j]; }
;     }
;     if (hout) {
;         float s = 0.f, s2 = 0.f;
; #pragma unroll
;         for (int j = 0; j < 4; ++j) { s += (v[j][0] + v[j][1]) + (v[j][2] + v[j][3]); s2 += (v[j][0] * v[j][0] + v[j][1] * v[j][1]) + (v[j][2] * v[j][2] + v[j][3] * v[j][3]); }
;         wave_sum2(s, s2, F.lane);
;         const float mean = s * (1.f / D); const float rstd = 1.f / sqrtf(fmaxf(s2 * (1.f / D) - mean * mean, 0.f) + EPS);
; #pragma unroll
;         for (int j = 0; j < 4; ++j) { const f32x4 hh = ((const f32x4*)sh)[F.lane + 64 * j], cc = ((const f32x4*)sc)[F.lane + 64 * j];
;             const f32x4 o = (v[j] - mean) * rstd * (cc + 1.f) + hh; u32x2 wv; wv.x = pk2(o[0], o[1]); wv.y = pk2(o[2], o[3]);
;             ((u32x2*)hout)[F.lane + 64 * j] = wv; }
;     }
	v_add_f32_e32 v9, v9, v91
	v_add_f32_e32 v90, v90, v92
	ds_bpermute_b32 v91, v4, v9
	ds_bpermute_b32 v92, v4, v90
	s_waitcnt lgkmcnt(0)
	v_add_f32_e32 v9, v9, v91
	v_add_f32_e32 v90, v90, v92
	ds_bpermute_b32 v91, v5, v9
	ds_bpermute_b32 v92, v5, v90
	s_waitcnt lgkmcnt(0)
	v_add_f32_e32 v9, v9, v91
	v_add_f32_e32 v90, v90, v92
	ds_bpermute_b32 v91, v6, v9
	ds_bpermute_b32 v92, v6, v90
	s_waitcnt lgkmcnt(0)
	v_add_f32_e32 v9, v9, v91
	v_add_f32_e32 v90, v90, v92
	ds_bpermute_b32 v91, v7, v9
	ds_bpermute_b32 v92, v7, v90
	s_waitcnt lgkmcnt(0)
	v_add_f32_e32 v9, v9, v91
	v_add_f32_e32 v90, v90, v92
	ds_bpermute_b32 v91, v8, v9
	ds_bpermute_b32 v92, v8, v90
	s_waitcnt lgkmcnt(0)
	v_add_f32_e32 v9, v9, v91
	v_add_f32_e32 v90, v90, v92
	v_mul_f32_e32 v93, 0x3a800000, v9
	v_mul_f32_e32 v91, 0x3a800000, v90
	v_fma_f32 v91, -v93, v93, v91
	v_max_f32_e32 v91, 0, v91
	v_add_f32_e32 v91, 0x358637bd, v91
	v_rsq_f32_e32 v94, v91
	v_mul_f32_e32 v91, 0.5, v91
	v_mul_f32_e32 v92, v94, v94
	v_fma_f32 v92, -v91, v92, 0.5
	v_fma_f32 v94, v94, v92, v94
	v_sub_f32_e32 v74, v74, v93
	v_sub_f32_e32 v75, v75, v93
	v_sub_f32_e32 v76, v76, v93
	v_sub_f32_e32 v77, v77, v93
	v_sub_f32_e32 v78, v78, v93
	v_sub_f32_e32 v79, v79, v93
	v_sub_f32_e32 v80, v80, v93
	v_sub_f32_e32 v81, v81, v93
	v_sub_f32_e32 v82, v82, v93
	v_sub_f32_e32 v83, v83, v93
	v_sub_f32_e32 v84, v84, v93
	v_sub_f32_e32 v85, v85, v93
	v_sub_f32_e32 v86, v86, v93
	v_sub_f32_e32 v87, v87, v93
	v_sub_f32_e32 v88, v88, v93
	v_sub_f32_e32 v89, v89, v93
	v_mul_f32_e32 v74, v94, v74
	v_mul_f32_e32 v75, v94, v75
	v_mul_f32_e32 v76, v94, v76
	v_mul_f32_e32 v77, v94, v77
	v_mul_f32_e32 v78, v94, v78
	v_mul_f32_e32 v79, v94, v79
	v_mul_f32_e32 v80, v94, v80
	v_mul_f32_e32 v81, v94, v81
	v_mul_f32_e32 v82, v94, v82
	v_mul_f32_e32 v83, v94, v83
	v_mul_f32_e32 v84, v94, v84
	v_mul_f32_e32 v85, v94, v85
	v_mul_f32_e32 v86, v94, v86
	v_mul_f32_e32 v87, v94, v87
	v_mul_f32_e32 v88, v94, v88
	v_mul_f32_e32 v89, v94, v89
	v_fma_f32 v74, v74, v130, v114
	v_fma_f32 v75, v75, v131, v115
	v_fma_f32 v76, v76, v132, v116
	v_fma_f32 v77, v77, v133, v117
	v_fma_f32 v78, v78, v134, v118
	v_fma_f32 v79, v79, v135, v119
	v_fma_f32 v80, v80, v136, v120
	v_fma_f32 v81, v81, v137, v121
	v_fma_f32 v82, v82, v138, v122
	v_fma_f32 v83, v83, v139, v123
	v_fma_f32 v84, v84, v140, v124
	v_fma_f32 v85, v85, v141, v125
	v_fma_f32 v86, v86, v142, v126
	v_fma_f32 v87, v87, v143, v127
	v_fma_f32 v88, v88, v144, v128
	v_fma_f32 v89, v89, v145, v129
	v_cvt_pk_bf16_f32 v190, v74, v75
	v_cvt_pk_bf16_f32 v191, v76, v77
	v_cvt_pk_bf16_f32 v192, v78, v79
	v_cvt_pk_bf16_f32 v193, v80, v81
	v_cvt_pk_bf16_f32 v194, v82, v83
	v_cvt_pk_bf16_f32 v195, v84, v85
	v_cvt_pk_bf16_f32 v196, v86, v87
	v_cvt_pk_bf16_f32 v197, v88, v89
	s_add_u32 s2, s10, 0x3000
	s_addc_u32 s3, s11, 0
	global_store_dwordx2 v1, v[190:191], s[2:3]
	global_store_dwordx2 v1, v[192:193], s[2:3] offset:512
	global_store_dwordx2 v1, v[194:195], s[2:3] offset:1024
	global_store_dwordx2 v1, v[196:197], s[2:3] offset:1536
	s_waitcnt vmcnt(19)
	v_add_f32_e32 v9, v98, v99
	v_add_f32_e32 v91, v100, v101
	v_mul_f32_e32 v90, v98, v98
	v_mul_f32_e32 v92, v99, v99
	v_add_f32_e32 v9, v9, v102
	v_add_f32_e32 v91, v91, v103
	v_add_f32_e32 v9, v9, v104
	v_add_f32_e32 v91, v91, v105
	v_add_f32_e32 v9, v9, v106
	v_add_f32_e32 v91, v91, v107
	v_add_f32_e32 v9, v9, v108
	v_add_f32_e32 v91, v91, v109
	v_add_f32_e32 v9, v9, v110
	v_add_f32_e32 v91, v91, v111
	v_add_f32_e32 v9, v9, v112
	v_add_f32_e32 v91, v91, v113
	v_fmac_f32_e32 v90, v100, v100
	v_fmac_f32_e32 v92, v101, v101
	v_fmac_f32_e32 v90, v102, v102
	v_fmac_f32_e32 v92, v103, v103
	v_fmac_f32_e32 v90, v104, v104
	v_fmac_f32_e32 v92, v105, v105
	v_fmac_f32_e32 v90, v106, v106
	v_fmac_f32_e32 v92, v107, v107
	v_fmac_f32_e32 v90, v108, v108
	v_fmac_f32_e32 v92, v109, v109
	v_fmac_f32_e32 v90, v110, v110
	v_fmac_f32_e32 v92, v111, v111
	v_fmac_f32_e32 v90, v112, v112
	v_fmac_f32_e32 v92, v113, v113
	v_add_f32_e32 v9, v9, v91
	v_add_f32_e32 v90, v90, v92
	ds_bpermute_b32 v91, v3, v9
	ds_bpermute_b32 v92, v3, v90
	s_waitcnt lgkmcnt(0)
	v_add_f32_e32 v9, v9, v91
	v_add_f32_e32 v90, v90, v92
	ds_bpermute_b32 v91, v4, v9
	ds_bpermute_b32 v92, v4, v90
	s_waitcnt lgkmcnt(0)
	v_add_f32_e32 v9, v9, v91
	v_add_f32_e32 v90, v90, v92
	ds_bpermute_b32 v91, v5, v9
	ds_bpermute_b32 v92, v5, v90
	s_waitcnt lgkmcnt(0)
	v_add_f32_e32 v9, v9, v91
	v_add_f32_e32 v90, v90, v92
	ds_bpermute_b32 v91, v6, v9
	ds_bpermute_b32 v92, v6, v90
	s_waitcnt lgkmcnt(0)
	v_add_f32_e32 v9, v9, v91
	v_add_f32_e32 v90, v90, v92
	ds_bpermute_b32 v91, v7, v9
	ds_bpermute_b32 v92, v7, v90
	s_waitcnt lgkmcnt(0)
	v_add_f32_e32 v9, v9, v91
	v_add_f32_e32 v90, v90, v92
	ds_bpermute_b32 v91, v8, v9
	ds_bpermute_b32 v92, v8, v90
	s_waitcnt lgkmcnt(0)
; DI void ln_row_v(const Frame& F, f32x4 (&v)[4], float* xout, const float* g, const float* b, const float* sh, const float* sc, bf16_t* hout, const float* slab, const float* gres, float* stat = nullptr) {
;     ...
;     if (g) {
;         float s = 0.f, s2 = 0.f;
; #pragma unroll
;         for (int j = 0; j < 4; ++j) { s += (v[j][0] + v[j][1]) + (v[j][2] + v[j][3]); s2 += (v[j][0] * v[j][0] + v[j][1] * v[j][1]) + (v[j][2] * v[j][2] + v[j][3] * v[j][3]); }
;         wave_sum2(s, s2, F.lane);
;         const float mean = s * (1.f / D); const float rstd = 1.f / sqrtf(fmaxf(s2 * (1.f / D) - mean * mean, 0.f) + EPS);
;         if (stat && F.lane == 0) { f32x2 sv = {mean, rstd}; *(f32x2*)stat = sv; }
; #pragma unroll
;         for (int j = 0; j < 4; ++j) { const f32x4 gg = ((const f32x4*)g)[F.lane + 64 * j], bb = ((const f32x4*)b)[F.lane + 64 * j];
;             v[j] = (v[j] - mean) * rstd * gg + bb; if (xout) ((f32x4*)xout)[F.lane + 64 * j] = v[j]; }
;     }
;     if (hout) {
;         float s = 0.f, s2 = 0.f;
; #pragma unroll
;         for (int j = 0; j < 4; ++j) { s += (v[j][0] + v[j][1]) + (v[j][2] + v[j][3]); s2 += (v[j][0] * v[j][0] + v[j][1] * v[j][1]) + (v[j][2] * v[j][2] + v[j][3] * v[j][3]); }
;         wave_sum2(s, s2, F.lane);
;         const float mean = s * (1.f / D); const float rstd = 1.f / sqrtf(fmaxf(s2 * (1.f / D) - mean * mean, 0.f) + EPS);
; #pragma unroll
;         for (int j = 0; j < 4; ++j) { const f32x4 hh = ((const f32x4*)sh)[F.lane + 64 * j], cc = ((const f32x4*)sc)[F.lane + 64 * j];
;             const f32x4 o = (v[j] - mean) * rstd * (cc + 1.f) + hh; u32x2 wv; wv.x = pk2(o[0], o[1]); wv.y = pk2(o[2], o[3]);
;             ((u32x2*)hout)[F.lane + 64 * j] = wv; }
;     }
; DI void ln_phase(const Frame& F, int which) {
;     const int gw = F.vcu * 8 + F.wave, NGW = F.G * 8; const int l = F.l;
;     const int nrows = (l == NL - 1) ? ML : MT;
;     bf16_t* H = (bf16_t*)(F.ws + WS_HB);
;     const float* g = pin(F, which == 0 ? I_LN1G : I_LN2G) + l * 1024; const float* b = pin(F, which == 0 ? I_LN1B : I_LN2B) + l * 1024;
;     const bool wh = !(which == 1 && l == NL - 1);
;     f32x4 vc[4], vn[4];
;     if (gw < nrows) ln_load(F, xrow_ptr(F, gw), vc);
;     for (int row = gw; row < nrows; row += NGW) {
;         if (row + NGW < nrows) ln_load(F, xrow_ptr(F, row + NGW), vn);
;         const int mr = row < ML ? (row >> 11) : 8;
	v_add_f32_e32 v9, v9, v91
	v_add_f32_e32 v90, v90, v92
	v_mul_f32_e32 v93, 0x3a800000, v9
	v_mul_f32_e32 v91, 0x3a800000, v90
	v_fma_f32 v91, -v93, v93, v91
	v_max_f32_e32 v91, 0, v91
	v_add_f32_e32 v91, 0x358637bd, v91
	v_rsq_f32_e32 v94, v91
	v_mul_f32_e32 v91, 0.5, v91
	v_mul_f32_e32 v92, v94, v94
	v_fma_f32 v92, -v91, v92, 0.5
	v_fma_f32 v94, v94, v92, v94
	s_add_u32 s2, s12, 0x38
	s_addc_u32 s3, s13, 0
	v_mov_b32_e32 v188, v93
	v_mov_b32_e32 v189, v94
	s_mov_b64 exec, 1
	global_store_dwordx2 v97, v[188:189], s[2:3]
	s_mov_b64 exec, -1
	v_sub_f32_e32 v98, v98, v93
	v_sub_f32_e32 v99, v99, v93
	v_sub_f32_e32 v100, v100, v93
	v_sub_f32_e32 v101, v101, v93
	v_sub_f32_e32 v102, v102, v93
	v_sub_f32_e32 v103, v103, v93
	v_sub_f32_e32 v104, v104, v93
	v_sub_f32_e32 v105, v105, v93
	v_sub_f32_e32 v106, v106, v93
	v_sub_f32_e32 v107, v107, v93
	v_sub_f32_e32 v108, v108, v93
	v_sub_f32_e32 v109, v109, v93
	v_sub_f32_e32 v110, v110, v93
	v_sub_f32_e32 v111, v111, v93
	v_sub_f32_e32 v112, v112, v93
	v_sub_f32_e32 v113, v113, v93
	v_mul_f32_e32 v98, v94, v98
	v_mul_f32_e32 v99, v94, v99
	v_mul_f32_e32 v100, v94, v100
	v_mul_f32_e32 v101, v94, v101
	v_mul_f32_e32 v102, v94, v102
	v_mul_f32_e32 v103, v94, v103
	v_mul_f32_e32 v104, v94, v104
	v_mul_f32_e32 v105, v94, v105
	v_mul_f32_e32 v106, v94, v106
	v_mul_f32_e32 v107, v94, v107
	v_mul_f32_e32 v108, v94, v108
	v_mul_f32_e32 v109, v94, v109
	v_mul_f32_e32 v110, v94, v110
	v_mul_f32_e32 v111, v94, v111
	v_mul_f32_e32 v112, v94, v112
	v_mul_f32_e32 v113, v94, v113
	v_fma_f32 v98, v98, v10, v26
	v_fma_f32 v99, v99, v11, v27
	v_fma_f32 v100, v100, v12, v28
	v_fma_f32 v101, v101, v13, v29
	v_fma_f32 v102, v102, v14, v30
	v_fma_f32 v103, v103, v15, v31
	v_fma_f32 v104, v104, v16, v32
	v_fma_f32 v105, v105, v17, v33
	v_fma_f32 v106, v106, v18, v34
	v_fma_f32 v107, v107, v19, v35
	v_fma_f32 v108, v108, v20, v36
	v_fma_f32 v109, v109, v21, v37
	v_fma_f32 v110, v110, v22, v38
	v_fma_f32 v111, v111, v23, v39
	v_fma_f32 v112, v112, v24, v40
	v_fma_f32 v113, v113, v25, v41
	v_add_f32_e32 v9, v98, v99
	v_add_f32_e32 v91, v100, v101
	v_mul_f32_e32 v90, v98, v98
	v_mul_f32_e32 v92, v99, v99
	v_add_f32_e32 v9, v9, v102
	v_add_f32_e32 v91, v91, v103
	v_add_f32_e32 v9, v9, v104
	v_add_f32_e32 v91, v91, v105
	v_add_f32_e32 v9, v9, v106
	v_add_f32_e32 v91, v91, v107
	v_add_f32_e32 v9, v9, v108
	v_add_f32_e32 v91, v91, v109
	v_add_f32_e32 v9, v9, v110
	v_add_f32_e32 v91, v91, v111
	v_add_f32_e32 v9, v9, v112
	v_add_f32_e32 v91, v91, v113
	v_fmac_f32_e32 v90, v100, v100
	v_fmac_f32_e32 v92, v101, v101
	v_fmac_f32_e32 v90, v102, v102
	v_fmac_f32_e32 v92, v103, v103
	v_fmac_f32_e32 v90, v104, v104
	v_fmac_f32_e32 v92, v105, v105
	v_fmac_f32_e32 v90, v106, v106
	v_fmac_f32_e32 v92, v107, v107
	v_fmac_f32_e32 v90, v108, v108
	v_fmac_f32_e32 v92, v109, v109
	v_fmac_f32_e32 v90, v110, v110
	v_fmac_f32_e32 v92, v111, v111
	v_fmac_f32_e32 v90, v112, v112
	v_fmac_f32_e32 v92, v113, v113
	v_add_f32_e32 v9, v9, v91
	v_add_f32_e32 v90, v90, v92
	ds_bpermute_b32 v91, v3, v9
	ds_bpermute_b32 v92, v3, v90
	s_waitcnt lgkmcnt(0)
	v_add_f32_e32 v9, v9, v91
	v_add_f32_e32 v90, v90, v92
	ds_bpermute_b32 v91, v4, v9
	ds_bpermute_b32 v92, v4, v90
	s_waitcnt lgkmcnt(0)
	v_add_f32_e32 v9, v9, v91
	v_add_f32_e32 v90, v90, v92
	ds_bpermute_b32 v91, v5, v9
	ds_bpermute_b32 v92, v5, v90
	s_waitcnt lgkmcnt(0)
	v_add_f32_e32 v9, v9, v91
	v_add_f32_e32 v90, v90, v92
	ds_bpermute_b32 v91, v6, v9
	ds_bpermute_b32 v92, v6, v90
	s_waitcnt lgkmcnt(0)
	v_add_f32_e32 v9, v9, v91
	v_add_f32_e32 v90, v90, v92
	ds_bpermute_b32 v91, v7, v9
	ds_bpermute_b32 v92, v7, v90
	s_waitcnt lgkmcnt(0)
	v_add_f32_e32 v9, v9, v91
	v_add_f32_e32 v90, v90, v92
	ds_bpermute_b32 v91, v8, v9
	ds_bpermute_b32 v92, v8, v90
	s_waitcnt lgkmcnt(0)
	v_add_f32_e32 v9, v9, v91
	v_add_f32_e32 v90, v90, v92
	v_mul_f32_e32 v93, 0x3a800000, v9
	v_mul_f32_e32 v91, 0x3a800000, v90
	v_fma_f32 v91, -v93, v93, v91
	v_max_f32_e32 v91, 0, v91
	v_add_f32_e32 v91, 0x358637bd, v91
	v_rsq_f32_e32 v94, v91
	v_mul_f32_e32 v91, 0.5, v91
	v_mul_f32_e32 v92, v94, v94
	v_fma_f32 v92, -v91, v92, 0.5
	v_fma_f32 v94, v94, v92, v94
	v_sub_f32_e32 v98, v98, v93
	v_sub_f32_e32 v99, v99, v93
	v_sub_f32_e32 v100, v100, v93
	v_sub_f32_e32 v101, v101, v93
	v_sub_f32_e32 v102, v102, v93
	v_sub_f32_e32 v103, v103, v93
	v_sub_f32_e32 v104, v104, v93
	v_sub_f32_e32 v105, v105, v93
	v_sub_f32_e32 v106, v106, v93
	v_sub_f32_e32 v107, v107, v93
	v_sub_f32_e32 v108, v108, v93
	v_sub_f32_e32 v109, v109, v93
	v_sub_f32_e32 v110, v110, v93
	v_sub_f32_e32 v111, v111, v93
	v_sub_f32_e32 v112, v112, v93
	v_sub_f32_e32 v113, v113, v93
	v_mul_f32_e32 v98, v94, v98
	v_mul_f32_e32 v99, v94, v99
	v_mul_f32_e32 v100, v94, v100
	v_mul_f32_e32 v101, v94, v101
	v_mul_f32_e32 v102, v94, v102
	v_mul_f32_e32 v103, v94, v103
	v_mul_f32_e32 v104, v94, v104
	v_mul_f32_e32 v105, v94, v105
	v_mul_f32_e32 v106, v94, v106
	v_mul_f32_e32 v107, v94, v107
	v_mul_f32_e32 v108, v94, v108
	v_mul_f32_e32 v109, v94, v109
	v_mul_f32_e32 v110, v94, v110
	v_mul_f32_e32 v111, v94, v111
	v_mul_f32_e32 v112, v94, v112
	v_mul_f32_e32 v113, v94, v113
	v_fma_f32 v98, v98, v130, v114
	v_fma_f32 v99, v99, v131, v115
	v_fma_f32 v100, v100, v132, v116
	v_fma_f32 v101, v101, v133, v117
	v_fma_f32 v102, v102, v134, v118
	v_fma_f32 v103, v103, v135, v119
	v_fma_f32 v104, v104, v136, v120
	v_fma_f32 v105, v105, v137, v121
	v_fma_f32 v106, v106, v138, v122
	v_fma_f32 v107, v107, v139, v123
	v_fma_f32 v108, v108, v140, v124
	v_fma_f32 v109, v109, v141, v125
	v_fma_f32 v110, v110, v142, v126
	v_fma_f32 v111, v111, v143, v127
	v_fma_f32 v112, v112, v144, v128
	v_fma_f32 v113, v113, v145, v129
	v_cvt_pk_bf16_f32 v190, v98, v99
	v_cvt_pk_bf16_f32 v191, v100, v101
	v_cvt_pk_bf16_f32 v192, v102, v103
	v_cvt_pk_bf16_f32 v193, v104, v105
	v_cvt_pk_bf16_f32 v194, v106, v107
	v_cvt_pk_bf16_f32 v195, v108, v109
	v_cvt_pk_bf16_f32 v196, v110, v111
	v_cvt_pk_bf16_f32 v197, v112, v113
	s_add_u32 s2, s10, 0x3800
	s_addc_u32 s3, s11, 0
	global_store_dwordx2 v1, v[190:191], s[2:3]
	global_store_dwordx2 v1, v[192:193], s[2:3] offset:512
	global_store_dwordx2 v1, v[194:195], s[2:3] offset:1024
	global_store_dwordx2 v1, v[196:197], s[2:3] offset:1536
	s_cmp_eq_u32 s22, 3
	s_cbranch_scc1 .Lln_b_noctx
; DI void ln_row_v(const Frame& F, f32x4 (&v)[4], float* xout, const float* g, const float* b, const float* sh, const float* sc, bf16_t* hout, const float* slab, const float* gres, float* stat = nullptr) {
;     if (slab) {
; #pragma unroll
;         for (int j = 0; j < 4; ++j) { f32x4 a = ((const f32x4*)slab)[F.lane + 64 * j];
; #pragma unroll
;             for (int z = 1; z < 8; ++z) a += ((const f32x4*)(slab + (size_t)z * MC * 1024))[F.lane + 64 * j];
;             v[j] = v[j] * ALPHA + ((const f32x4*)gres)[F.lane + 64 * j] * a; }
	s_add_u32 s2, s24, 0x0
	s_addc_u32 s3, s25, 0
	global_load_dwordx4 v[58:61], v0, s[2:3]
	global_load_dwordx4 v[62:65], v0, s[2:3] offset:1024
	global_load_dwordx4 v[66:69], v0, s[2:3] offset:2048
	global_load_dwordx4 v[70:73], v0, s[2:3] offset:3072
	s_add_u32 s2, s24, 0x800000
	s_addc_u32 s3, s25, 0
	global_load_dwordx4 v[74:77], v0, s[2:3]
	global_load_dwordx4 v[78:81], v0, s[2:3] offset:1024
	global_load_dwordx4 v[82:85], v0, s[2:3] offset:2048
	global_load_dwordx4 v[86:89], v0, s[2:3] offset:3072
	s_add_u32 s2, s24, 0x1000000
	s_addc_u32 s3, s25, 0
	global_load_dwordx4 v[98:101], v0, s[2:3]
	global_load_dwordx4 v[102:105], v0, s[2:3] offset:1024
	global_load_dwordx4 v[106:109], v0, s[2:3] offset:2048
	global_load_dwordx4 v[110:113], v0, s[2:3] offset:3072
	s_add_u32 s2, s24, 0x1800000
	s_addc_u32 s3, s25, 0
	global_load_dwordx4 v[146:149], v0, s[2:3]
	global_load_dwordx4 v[150:153], v0, s[2:3] offset:1024
	global_load_dwordx4 v[154:157], v0, s[2:3] offset:2048
	global_load_dwordx4 v[158:161], v0, s[2:3] offset:3072
	s_add_u32 s2, s24, 0x2000000
	s_addc_u32 s3, s25, 0
	global_load_dwordx4 v[162:165], v0, s[2:3]
	global_load_dwordx4 v[166:169], v0, s[2:3] offset:1024
	global_load_dwordx4 v[170:173], v0, s[2:3] offset:2048
	global_load_dwordx4 v[174:177], v0, s[2:3] offset:3072
	s_mov_b64 s[2:3], s[26:27]
	global_load_dwordx4 v[226:229], v0, s[2:3]
	global_load_dwordx4 v[230:233], v0, s[2:3] offset:1024
	global_load_dwordx4 v[234:237], v0, s[2:3] offset:2048
	global_load_dwordx4 v[238:241], v0, s[2:3] offset:3072
	s_waitcnt vmcnt(16)
	v_add_f32_e32 v58, v58, v74
	v_add_f32_e32 v59, v59, v75
	v_add_f32_e32 v60, v60, v76
	v_add_f32_e32 v61, v61, v77
	v_add_f32_e32 v62, v62, v78
	v_add_f32_e32 v63, v63, v79
	v_add_f32_e32 v64, v64, v80
	v_add_f32_e32 v65, v65, v81
	v_add_f32_e32 v66, v66, v82
	v_add_f32_e32 v67, v67, v83
	v_add_f32_e32 v68, v68, v84
	v_add_f32_e32 v69, v69, v85
	v_add_f32_e32 v70, v70, v86
	v_add_f32_e32 v71, v71, v87
	v_add_f32_e32 v72, v72, v88
	v_add_f32_e32 v73, v73, v89
	s_add_u32 s2, s24, 0x2800000
	s_addc_u32 s3, s25, 0
	global_load_dwordx4 v[74:77], v0, s[2:3]
	global_load_dwordx4 v[78:81], v0, s[2:3] offset:1024
	global_load_dwordx4 v[82:85], v0, s[2:3] offset:2048
	global_load_dwordx4 v[86:89], v0, s[2:3] offset:3072
	s_waitcnt vmcnt(16)
	v_add_f32_e32 v58, v58, v98
	v_add_f32_e32 v59, v59, v99
	v_add_f32_e32 v60, v60, v100
	v_add_f32_e32 v61, v61, v101
	v_add_f32_e32 v62, v62, v102
	v_add_f32_e32 v63, v63, v103
	v_add_f32_e32 v64, v64, v104
	v_add_f32_e32 v65, v65, v105
	v_add_f32_e32 v66, v66, v106
	v_add_f32_e32 v67, v67, v107
	v_add_f32_e32 v68, v68, v108
	v_add_f32_e32 v69, v69, v109
	v_add_f32_e32 v70, v70, v110
	v_add_f32_e32 v71, v71, v111
	v_add_f32_e32 v72, v72, v112
	v_add_f32_e32 v73, v73, v113
	s_add_u32 s2, s24, 0x3000000
	s_addc_u32 s3, s25, 0
	global_load_dwordx4 v[98:101], v0, s[2:3]
	global_load_dwordx4 v[102:105], v0, s[2:3] offset:1024
	global_load_dwordx4 v[106:109], v0, s[2:3] offset:2048
	global_load_dwordx4 v[110:113], v0, s[2:3] offset:3072
	s_waitcnt vmcnt(16)
	v_add_f32_e32 v58, v58, v146
	v_add_f32_e32 v59, v59, v147
	v_add_f32_e32 v60, v60, v148
	v_add_f32_e32 v61, v61, v149
	v_add_f32_e32 v62, v62, v150
	v_add_f32_e32 v63, v63, v151
	v_add_f32_e32 v64, v64, v152
	v_add_f32_e32 v65, v65, v153
	v_add_f32_e32 v66, v66, v154
	v_add_f32_e32 v67, v67, v155
	v_add_f32_e32 v68, v68, v156
	v_add_f32_e32 v69, v69, v157
	v_add_f32_e32 v70, v70, v158
	v_add_f32_e32 v71, v71, v159
	v_add_f32_e32 v72, v72, v160
	v_add_f32_e32 v73, v73, v161
	s_add_u32 s2, s24, 0x3800000
	s_addc_u32 s3, s25, 0
	global_load_dwordx4 v[146:149], v0, s[2:3]
	global_load_dwordx4 v[150:153], v0, s[2:3] offset:1024
	global_load_dwordx4 v[154:157], v0, s[2:3] offset:2048
	global_load_dwordx4 v[158:161], v0, s[2:3] offset:3072
	s_waitcnt vmcnt(16)
	v_add_f32_e32 v58, v58, v162
	v_add_f32_e32 v59, v59, v163
	v_add_f32_e32 v60, v60, v164
	v_add_f32_e32 v61, v61, v165
	v_add_f32_e32 v62, v62, v166
	v_add_f32_e32 v63, v63, v167
	v_add_f32_e32 v64, v64, v168
	v_add_f32_e32 v65, v65, v169
	v_add_f32_e32 v66, v66, v170
	v_add_f32_e32 v67, v67, v171
	v_add_f32_e32 v68, v68, v172
	v_add_f32_e32 v69, v69, v173
	v_add_f32_e32 v70, v70, v174
	v_add_f32_e32 v71, v71, v175
	v_add_f32_e32 v72, v72, v176
	v_add_f32_e32 v73, v73, v177
	s_waitcnt vmcnt(8)
	v_add_f32_e32 v58, v58, v74
	v_add_f32_e32 v59, v59, v75
	v_add_f32_e32 v60, v60, v76
	v_add_f32_e32 v61, v61, v77
	v_add_f32_e32 v62, v62, v78
	v_add_f32_e32 v63, v63, v79
	v_add_f32_e32 v64, v64, v80
	v_add_f32_e32 v65, v65, v81
	v_add_f32_e32 v66, v66, v82
	v_add_f32_e32 v67, v67, v83
	v_add_f32_e32 v68, v68, v84
	v_add_f32_e32 v69, v69, v85
	v_add_f32_e32 v70, v70, v86
	v_add_f32_e32 v71, v71, v87
	v_add_f32_e32 v72, v72, v88
	v_add_f32_e32 v73, v73, v89
	s_waitcnt vmcnt(4)
	v_add_f32_e32 v58, v58, v98
	v_add_f32_e32 v59, v59, v99
	v_add_f32_e32 v60, v60, v100
	v_add_f32_e32 v61, v61, v101
	v_add_f32_e32 v62, v62, v102
	v_add_f32_e32 v63, v63, v103
	v_add_f32_e32 v64, v64, v104
	v_add_f32_e32 v65, v65, v105
	v_add_f32_e32 v66, v66, v106
	v_add_f32_e32 v67, v67, v107
	v_add_f32_e32 v68, v68, v108
	v_add_f32_e32 v69, v69, v109
	v_add_f32_e32 v70, v70, v110
	v_add_f32_e32 v71, v71, v111
	v_add_f32_e32 v72, v72, v112
	v_add_f32_e32 v73, v73, v113
	s_waitcnt vmcnt(0)
; DI void ln_row_v(const Frame& F, f32x4 (&v)[4], float* xout, const float* g, const float* b, const float* sh, const float* sc, bf16_t* hout, const float* slab, const float* gres, float* stat = nullptr) {
;     if (slab) {
; #pragma unroll
;         for (int j = 0; j < 4; ++j) { f32x4 a = ((const f32x4*)slab)[F.lane + 64 * j];
; #pragma unroll
;             for (int z = 1; z < 8; ++z) a += ((const f32x4*)(slab + (size_t)z * MC * 1024))[F.lane + 64 * j];
;             v[j] = v[j] * ALPHA + ((const f32x4*)gres)[F.lane + 64 * j] * a; }
;     }
;     if (g) {
;         float s = 0.f, s2 = 0.f;
; #pragma unroll
;         for (int j = 0; j < 4; ++j) { s += (v[j][0] + v[j][1]) + (v[j][2] + v[j][3]); s2 += (v[j][0] * v[j][0] + v[j][1] * v[j][1]) + (v[j][2] * v[j][2] + v[j][3] * v[j][3]); }
;         wave_sum2(s, s2, F.lane);
;         const float mean = s * (1.f / D); const float rstd = 1.f / sqrtf(fmaxf(s2 * (1.f / D) - mean * mean, 0.f) + EPS);
;         if (stat && F.lane == 0) { f32x2 sv = {mean, rstd}; *(f32x2*)stat = sv; }
; #pragma unroll
;         for (int j = 0; j < 4; ++j) { const f32x4 gg = ((const f32x4*)g)[F.lane + 64 * j], bb = ((const f32x4*)b)[F.lane + 64 * j];
;             v[j] = (v[j] - mean) * rstd * gg + bb; if (xout) ((f32x4*)xout)[F.lane + 64 * j] = v[j]; }
	v_add_f32_e32 v58, v58, v146
	v_add_f32_e32 v59, v59, v147
	v_add_f32_e32 v60, v60, v148
	v_add_f32_e32 v61, v61, v149
	v_add_f32_e32 v62, v62, v150
	v_add_f32_e32 v63, v63, v151
	v_add_f32_e32 v64, v64, v152
	v_add_f32_e32 v65, v65, v153
	v_add_f32_e32 v66, v66, v154
	v_add_f32_e32 v67, v67, v155
	v_add_f32_e32 v68, v68, v156
	v_add_f32_e32 v69, v69, v157
	v_add_f32_e32 v70, v70, v158
	v_add_f32_e32 v71, v71, v159
	v_add_f32_e32 v72, v72, v160
	v_add_f32_e32 v73, v73, v161
	s_mov_b32 s23, 0x30000
	s_add_u32 s2, s14, s23
	s_addc_u32 s3, s15, 0
	global_load_dwordx4 v[146:149], v0, s[2:3]
	global_load_dwordx4 v[150:153], v0, s[2:3] offset:1024
	global_load_dwordx4 v[154:157], v0, s[2:3] offset:2048
	global_load_dwordx4 v[158:161], v0, s[2:3] offset:3072
	s_add_u32 s2, s18, s23
	s_addc_u32 s3, s19, 0
	global_load_dwordx4 v[162:165], v0, s[2:3]
	global_load_dwordx4 v[166:169], v0, s[2:3] offset:1024
	global_load_dwordx4 v[170:173], v0, s[2:3] offset:2048
	global_load_dwordx4 v[174:177], v0, s[2:3] offset:3072
	v_mul_f32_e32 v42, 0x3fd744fd, v42
	v_mul_f32_e32 v43, 0x3fd744fd, v43
	v_mul_f32_e32 v44, 0x3fd744fd, v44
	v_mul_f32_e32 v45, 0x3fd744fd, v45
	v_mul_f32_e32 v46, 0x3fd744fd, v46
	v_mul_f32_e32 v47, 0x3fd744fd, v47
	v_mul_f32_e32 v48, 0x3fd744fd, v48
	v_mul_f32_e32 v49, 0x3fd744fd, v49
	v_mul_f32_e32 v50, 0x3fd744fd, v50
	v_mul_f32_e32 v51, 0x3fd744fd, v51
	v_mul_f32_e32 v52, 0x3fd744fd, v52
	v_mul_f32_e32 v53, 0x3fd744fd, v53
	v_mul_f32_e32 v54, 0x3fd744fd, v54
	v_mul_f32_e32 v55, 0x3fd744fd, v55
	v_mul_f32_e32 v56, 0x3fd744fd, v56
	v_mul_f32_e32 v57, 0x3fd744fd, v57
	v_fmac_f32_e32 v42, v226, v58
	v_fmac_f32_e32 v43, v227, v59
	v_fmac_f32_e32 v44, v228, v60
	v_fmac_f32_e32 v45, v229, v61
	v_fmac_f32_e32 v46, v230, v62
	v_fmac_f32_e32 v47, v231, v63
	v_fmac_f32_e32 v48, v232, v64
	v_fmac_f32_e32 v49, v233, v65
	v_fmac_f32_e32 v50, v234, v66
	v_fmac_f32_e32 v51, v235, v67
	v_fmac_f32_e32 v52, v236, v68
	v_fmac_f32_e32 v53, v237, v69
	v_fmac_f32_e32 v54, v238, v70
	v_fmac_f32_e32 v55, v239, v71
	v_fmac_f32_e32 v56, v240, v72
	v_fmac_f32_e32 v57, v241, v73
	v_add_f32_e32 v9, v42, v43
	v_add_f32_e32 v91, v44, v45
	v_mul_f32_e32 v90, v42, v42
	v_mul_f32_e32 v92, v43, v43
	v_add_f32_e32 v9, v9, v46
	v_add_f32_e32 v91, v91, v47
	v_add_f32_e32 v9, v9, v48
	v_add_f32_e32 v91, v91, v49
	v_add_f32_e32 v9, v9, v50
	v_add_f32_e32 v91, v91, v51
	v_add_f32_e32 v9, v9, v52
	v_add_f32_e32 v91, v91, v53
	v_add_f32_e32 v9, v9, v54
	v_add_f32_e32 v91, v91, v55
	v_add_f32_e32 v9, v9, v56
	v_add_f32_e32 v91, v91, v57
	v_fmac_f32_e32 v90, v44, v44
	v_fmac_f32_e32 v92, v45, v45
	v_fmac_f32_e32 v90, v46, v46
	v_fmac_f32_e32 v92, v47, v47
	v_fmac_f32_e32 v90, v48, v48
	v_fmac_f32_e32 v92, v49, v49
	v_fmac_f32_e32 v90, v50, v50
	v_fmac_f32_e32 v92, v51, v51
	v_fmac_f32_e32 v90, v52, v52
	v_fmac_f32_e32 v92, v53, v53
	v_fmac_f32_e32 v90, v54, v54
	v_fmac_f32_e32 v92, v55, v55
	v_fmac_f32_e32 v90, v56, v56
	v_fmac_f32_e32 v92, v57, v57
	v_add_f32_e32 v9, v9, v91
	v_add_f32_e32 v90, v90, v92
	ds_bpermute_b32 v91, v3, v9
	ds_bpermute_b32 v92, v3, v90
	s_waitcnt lgkmcnt(0)
	v_add_f32_e32 v9, v9, v91
	v_add_f32_e32 v90, v90, v92
	ds_bpermute_b32 v91, v4, v9
	ds_bpermute_b32 v92, v4, v90
	s_waitcnt lgkmcnt(0)
	v_add_f32_e32 v9, v9, v91
	v_add_f32_e32 v90, v90, v92
	ds_bpermute_b32 v91, v5, v9
	ds_bpermute_b32 v92, v5, v90
	s_waitcnt lgkmcnt(0)
	v_add_f32_e32 v9, v9, v91
	v_add_f32_e32 v90, v90, v92
	ds_bpermute_b32 v91, v6, v9
	ds_bpermute_b32 v92, v6, v90
	s_waitcnt lgkmcnt(0)
	v_add_f32_e32 v9, v9, v91
	v_add_f32_e32 v90, v90, v92
	ds_bpermute_b32 v91, v7, v9
	ds_bpermute_b32 v92, v7, v90
	s_waitcnt lgkmcnt(0)
	v_add_f32_e32 v9, v9, v91
	v_add_f32_e32 v90, v90, v92
	ds_bpermute_b32 v91, v8, v9
	ds_bpermute_b32 v92, v8, v90
	s_waitcnt lgkmcnt(0)
; DI unsigned pk2(float lo, float hi) { f32x2 v = {lo, hi}; bf16x2_t b = __builtin_convertvector(v, bf16x2_t); return __builtin_bit_cast(unsigned, b); }
; DI void ln_row_v(const Frame& F, f32x4 (&v)[4], float* xout, const float* g, const float* b, const float* sh, const float* sc, bf16_t* hout, const float* slab, const float* gres, float* stat = nullptr) {
;     ...
;     if (g) {
;         float s = 0.f, s2 = 0.f;
; #pragma unroll
;         for (int j = 0; j < 4; ++j) { s += (v[j][0] + v[j][1]) + (v[j][2] + v[j][3]); s2 += (v[j][0] * v[j][0] + v[j][1] * v[j][1]) + (v[j][2] * v[j][2] + v[j][3] * v[j][3]); }
;         wave_sum2(s, s2, F.lane);
;         const float mean = s * (1.f / D); const float rstd = 1.f / sqrtf(fmaxf(s2 * (1.f / D) - mean * mean, 0.f) + EPS);
;         if (stat && F.lane == 0) { f32x2 sv = {mean, rstd}; *(f32x2*)stat = sv; }
; #pragma unroll
;         for (int j = 0; j < 4; ++j) { const f32x4 gg = ((const f32x4*)g)[F.lane + 64 * j], bb = ((const f32x4*)b)[F.lane + 64 * j];
;             v[j] = (v[j] - mean) * rstd * gg + bb; if (xout) ((f32x4*)xout)[F.lane + 64 * j] = v[j]; }
;     }
;     if (hout) {
;         float s = 0.f, s2 = 0.f;
; #pragma unroll
;         for (int j = 0; j < 4; ++j) { s += (v[j][0] + v[j][1]) + (v[j][2] + v[j][3]); s2 += (v[j][0] * v[j][0] + v[j][1] * v[j][1]) + (v[j][2] * v[j][2] + v[j][3] * v[j][3]); }
;         wave_sum2(s, s2, F.lane);
;         const float mean = s * (1.f / D); const float rstd = 1.f / sqrtf(fmaxf(s2 * (1.f / D) - mean * mean, 0.f) + EPS);
; #pragma unroll
;         for (int j = 0; j < 4; ++j) { const f32x4 hh = ((const f32x4*)sh)[F.lane + 64 * j], cc = ((const f32x4*)sc)[F.lane + 64 * j];
;             const f32x4 o = (v[j] - mean) * rstd * (cc + 1.f) + hh; u32x2 wv; wv.x = pk2(o[0], o[1]); wv.y = pk2(o[2], o[3]);
;             ((u32x2*)hout)[F.lane + 64 * j] = wv; }
;     }
	v_add_f32_e32 v9, v9, v91
	v_add_f32_e32 v90, v90, v92
	v_mul_f32_e32 v93, 0x3a800000, v9
	v_mul_f32_e32 v91, 0x3a800000, v90
	v_fma_f32 v91, -v93, v93, v91
	v_max_f32_e32 v91, 0, v91
	v_add_f32_e32 v91, 0x358637bd, v91
	v_rsq_f32_e32 v94, v91
	v_mul_f32_e32 v91, 0.5, v91
	v_mul_f32_e32 v92, v94, v94
	v_fma_f32 v92, -v91, v92, 0.5
	v_fma_f32 v94, v94, v92, v94
	v_sub_f32_e32 v42, v42, v93
	v_sub_f32_e32 v43, v43, v93
	v_sub_f32_e32 v44, v44, v93
	v_sub_f32_e32 v45, v45, v93
	v_sub_f32_e32 v46, v46, v93
	v_sub_f32_e32 v47, v47, v93
	v_sub_f32_e32 v48, v48, v93
	v_sub_f32_e32 v49, v49, v93
	v_sub_f32_e32 v50, v50, v93
	v_sub_f32_e32 v51, v51, v93
	v_sub_f32_e32 v52, v52, v93
	v_sub_f32_e32 v53, v53, v93
	v_sub_f32_e32 v54, v54, v93
	v_sub_f32_e32 v55, v55, v93
	v_sub_f32_e32 v56, v56, v93
	v_sub_f32_e32 v57, v57, v93
	v_mul_f32_e32 v42, v94, v42
	v_mul_f32_e32 v43, v94, v43
	v_mul_f32_e32 v44, v94, v44
	v_mul_f32_e32 v45, v94, v45
	v_mul_f32_e32 v46, v94, v46
	v_mul_f32_e32 v47, v94, v47
	v_mul_f32_e32 v48, v94, v48
	v_mul_f32_e32 v49, v94, v49
	v_mul_f32_e32 v50, v94, v50
	v_mul_f32_e32 v51, v94, v51
	v_mul_f32_e32 v52, v94, v52
	v_mul_f32_e32 v53, v94, v53
	v_mul_f32_e32 v54, v94, v54
	v_mul_f32_e32 v55, v94, v55
	v_mul_f32_e32 v56, v94, v56
	v_mul_f32_e32 v57, v94, v57
	v_fma_f32 v42, v42, v10, v26
	v_fma_f32 v43, v43, v11, v27
	v_fma_f32 v44, v44, v12, v28
	v_fma_f32 v45, v45, v13, v29
	v_fma_f32 v46, v46, v14, v30
	v_fma_f32 v47, v47, v15, v31
	v_fma_f32 v48, v48, v16, v32
	v_fma_f32 v49, v49, v17, v33
	v_fma_f32 v50, v50, v18, v34
	v_fma_f32 v51, v51, v19, v35
	v_fma_f32 v52, v52, v20, v36
	v_fma_f32 v53, v53, v21, v37
	v_fma_f32 v54, v54, v22, v38
	v_fma_f32 v55, v55, v23, v39
	v_fma_f32 v56, v56, v24, v40
	v_fma_f32 v57, v57, v25, v41
	s_mov_b64 s[2:3], s[20:21]
	global_store_dwordx4 v0, v[42:45], s[2:3]
	global_store_dwordx4 v0, v[46:49], s[2:3] offset:1024
	global_store_dwordx4 v0, v[50:53], s[2:3] offset:2048
	global_store_dwordx4 v0, v[54:57], s[2:3] offset:3072
	v_add_f32_e32 v9, v42, v43
	v_add_f32_e32 v91, v44, v45
	v_mul_f32_e32 v90, v42, v42
	v_mul_f32_e32 v92, v43, v43
	v_add_f32_e32 v9, v9, v46
	v_add_f32_e32 v91, v91, v47
	v_add_f32_e32 v9, v9, v48
	v_add_f32_e32 v91, v91, v49
	v_add_f32_e32 v9, v9, v50
	v_add_f32_e32 v91, v91, v51
	v_add_f32_e32 v9, v9, v52
	v_add_f32_e32 v91, v91, v53
	v_add_f32_e32 v9, v9, v54
	v_add_f32_e32 v91, v91, v55
	v_add_f32_e32 v9, v9, v56
	v_add_f32_e32 v91, v91, v57
	v_fmac_f32_e32 v90, v44, v44
	v_fmac_f32_e32 v92, v45, v45
	v_fmac_f32_e32 v90, v46, v46
	v_fmac_f32_e32 v92, v47, v47
	v_fmac_f32_e32 v90, v48, v48
	v_fmac_f32_e32 v92, v49, v49
	v_fmac_f32_e32 v90, v50, v50
	v_fmac_f32_e32 v92, v51, v51
	v_fmac_f32_e32 v90, v52, v52
	v_fmac_f32_e32 v92, v53, v53
	v_fmac_f32_e32 v90, v54, v54
	v_fmac_f32_e32 v92, v55, v55
	v_fmac_f32_e32 v90, v56, v56
	v_fmac_f32_e32 v92, v57, v57
	v_add_f32_e32 v9, v9, v91
	v_add_f32_e32 v90, v90, v92
	ds_bpermute_b32 v91, v3, v9
	ds_bpermute_b32 v92, v3, v90
	s_waitcnt lgkmcnt(0)
	v_add_f32_e32 v9, v9, v91
	v_add_f32_e32 v90, v90, v92
	ds_bpermute_b32 v91, v4, v9
	ds_bpermute_b32 v92, v4, v90
	s_waitcnt lgkmcnt(0)
	v_add_f32_e32 v9, v9, v91
	v_add_f32_e32 v90, v90, v92
	ds_bpermute_b32 v91, v5, v9
	ds_bpermute_b32 v92, v5, v90
	s_waitcnt lgkmcnt(0)
	v_add_f32_e32 v9, v9, v91
	v_add_f32_e32 v90, v90, v92
	ds_bpermute_b32 v91, v6, v9
	ds_bpermute_b32 v92, v6, v90
	s_waitcnt lgkmcnt(0)
	v_add_f32_e32 v9, v9, v91
	v_add_f32_e32 v90, v90, v92
	ds_bpermute_b32 v91, v7, v9
	ds_bpermute_b32 v92, v7, v90
	s_waitcnt lgkmcnt(0)
	v_add_f32_e32 v9, v9, v91
	v_add_f32_e32 v90, v90, v92
	ds_bpermute_b32 v91, v8, v9
	ds_bpermute_b32 v92, v8, v90
	s_waitcnt lgkmcnt(0)
	v_add_f32_e32 v9, v9, v91
	v_add_f32_e32 v90, v90, v92
	v_mul_f32_e32 v93, 0x3a800000, v9
	v_mul_f32_e32 v91, 0x3a800000, v90
	v_fma_f32 v91, -v93, v93, v91
	v_max_f32_e32 v91, 0, v91
	v_add_f32_e32 v91, 0x358637bd, v91
	v_rsq_f32_e32 v94, v91
	v_mul_f32_e32 v91, 0.5, v91
	v_mul_f32_e32 v92, v94, v94
	v_fma_f32 v92, -v91, v92, 0.5
	v_fma_f32 v94, v94, v92, v94
	s_waitcnt vmcnt(4)
	v_sub_f32_e32 v42, v42, v93
	v_sub_f32_e32 v43, v43, v93
	v_sub_f32_e32 v44, v44, v93
	v_sub_f32_e32 v45, v45, v93
	v_sub_f32_e32 v46, v46, v93
	v_sub_f32_e32 v47, v47, v93
	v_sub_f32_e32 v48, v48, v93
	v_sub_f32_e32 v49, v49, v93
	v_sub_f32_e32 v50, v50, v93
	v_sub_f32_e32 v51, v51, v93
	v_sub_f32_e32 v52, v52, v93
	v_sub_f32_e32 v53, v53, v93
	v_sub_f32_e32 v54, v54, v93
	v_sub_f32_e32 v55, v55, v93
	v_sub_f32_e32 v56, v56, v93
	v_sub_f32_e32 v57, v57, v93
	v_add_f32_e32 v162, 1.0, v162
	v_add_f32_e32 v163, 1.0, v163
	v_add_f32_e32 v164, 1.0, v164
	v_add_f32_e32 v165, 1.0, v165
	v_add_f32_e32 v166, 1.0, v166
	v_add_f32_e32 v167, 1.0, v167
	v_add_f32_e32 v168, 1.0, v168
	v_add_f32_e32 v169, 1.0, v169
	v_add_f32_e32 v170, 1.0, v170
	v_add_f32_e32 v171, 1.0, v171
	v_add_f32_e32 v172, 1.0, v172
	v_add_f32_e32 v173, 1.0, v173
	v_add_f32_e32 v174, 1.0, v174
	v_add_f32_e32 v175, 1.0, v175
	v_add_f32_e32 v176, 1.0, v176
	v_add_f32_e32 v177, 1.0, v177
	v_mul_f32_e32 v42, v94, v42
	v_mul_f32_e32 v43, v94, v43
	v_mul_f32_e32 v44, v94, v44
	v_mul_f32_e32 v45, v94, v45
	v_mul_f32_e32 v46, v94, v46
	v_mul_f32_e32 v47, v94, v47
	v_mul_f32_e32 v48, v94, v48
	v_mul_f32_e32 v49, v94, v49
	v_mul_f32_e32 v50, v94, v50
	v_mul_f32_e32 v51, v94, v51
	v_mul_f32_e32 v52, v94, v52
	v_mul_f32_e32 v53, v94, v53
	v_mul_f32_e32 v54, v94, v54
	v_mul_f32_e32 v55, v94, v55
	v_mul_f32_e32 v56, v94, v56
	v_mul_f32_e32 v57, v94, v57
	v_fma_f32 v42, v42, v162, v146
	v_fma_f32 v43, v43, v163, v147
	v_fma_f32 v44, v44, v164, v148
	v_fma_f32 v45, v45, v165, v149
	v_fma_f32 v46, v46, v166, v150
	v_fma_f32 v47, v47, v167, v151
	v_fma_f32 v48, v48, v168, v152
	v_fma_f32 v49, v49, v169, v153
	v_fma_f32 v50, v50, v170, v154
	v_fma_f32 v51, v51, v171, v155
	v_fma_f32 v52, v52, v172, v156
	v_fma_f32 v53, v53, v173, v157
	v_fma_f32 v54, v54, v174, v158
	v_fma_f32 v55, v55, v175, v159
	v_fma_f32 v56, v56, v176, v160
	v_fma_f32 v57, v57, v177, v161
	v_cvt_pk_bf16_f32 v190, v42, v43
	v_cvt_pk_bf16_f32 v191, v44, v45
	v_cvt_pk_bf16_f32 v192, v46, v47
	v_cvt_pk_bf16_f32 v193, v48, v49
	v_cvt_pk_bf16_f32 v194, v50, v51
	v_cvt_pk_bf16_f32 v195, v52, v53
	v_cvt_pk_bf16_f32 v196, v54, v55
	v_cvt_pk_bf16_f32 v197, v56, v57
	s_lshl_b32 s2, s16, 11
	s_add_u32 s2, s94, s2
	s_addc_u32 s3, s95, 0
	s_add_u32 s2, s2, 0x5e00000
	s_addc_u32 s3, s3, 0
	global_store_dwordx2 v1, v[190:191], s[2:3]
	global_store_dwordx2 v1, v[192:193], s[2:3] offset:512
	global_store_dwordx2 v1, v[194:195], s[2:3] offset:1024
	global_store_dwordx2 v1, v[196:197], s[2:3] offset:1536

; DI void ln_row_v(const Frame& F, f32x4 (&v)[4], float* xout, const float* g, const float* b, const float* sh, const float* sc, bf16_t* hout, const float* slab, const float* gres, float* stat = nullptr) {
;     ...
;     if (g) {
;         float s = 0.f, s2 = 0.f;
; #pragma unroll
;         for (int j = 0; j < 4; ++j) { s += (v[j][0] + v[j][1]) + (v[j][2] + v[j][3]); s2 += (v[j][0] * v[j][0] + v[j][1] * v[j][1]) + (v[j][2] * v[j][2] + v[j][3] * v[j][3]); }
;         wave_sum2(s, s2, F.lane);
;         const float mean = s * (1.f / D); const float rstd = 1.f / sqrtf(fmaxf(s2 * (1.f / D) - mean * mean, 0.f) + EPS);
;         if (stat && F.lane == 0) { f32x2 sv = {mean, rstd}; *(f32x2*)stat = sv; }
; #pragma unroll
;         for (int j = 0; j < 4; ++j) { const f32x4 gg = ((const f32x4*)g)[F.lane + 64 * j], bb = ((const f32x4*)b)[F.lane + 64 * j];
;             v[j] = (v[j] - mean) * rstd * gg + bb; if (xout) ((f32x4*)xout)[F.lane + 64 * j] = v[j]; }
; DI void ln_phase(const Frame& F, int which) {
;     const int gw = F.vcu * 8 + F.wave, NGW = F.G * 8; const int l = F.l;
;     const int nrows = (l == NL - 1) ? ML : MT;
;     bf16_t* H = (bf16_t*)(F.ws + WS_HB);
;     const float* g = pin(F, which == 0 ? I_LN1G : I_LN2G) + l * 1024; const float* b = pin(F, which == 0 ? I_LN1B : I_LN2B) + l * 1024;
;     const bool wh = !(which == 1 && l == NL - 1);
;     f32x4 vc[4], vn[4];
;     if (gw < nrows) ln_load(F, xrow_ptr(F, gw), vc);
;     for (int row = gw; row < nrows; row += NGW) {
;         if (row + NGW < nrows) ln_load(F, xrow_ptr(F, row + NGW), vn);
.Lln_b_final:
	global_load_dwordx4 v[10:13], v0, s[4:5]
	global_load_dwordx4 v[14:17], v0, s[4:5] offset:1024
	global_load_dwordx4 v[18:21], v0, s[4:5] offset:2048
	global_load_dwordx4 v[22:25], v0, s[4:5] offset:3072
	global_load_dwordx4 v[26:29], v0, s[6:7]
	global_load_dwordx4 v[30:33], v0, s[6:7] offset:1024
	global_load_dwordx4 v[34:37], v0, s[6:7] offset:2048
	global_load_dwordx4 v[38:41], v0, s[6:7] offset:3072
	s_add_u32 s2, s8, 0x0
	s_addc_u32 s3, s9, 0
	global_load_dwordx4 v[42:45], v0, s[2:3]
	global_load_dwordx4 v[46:49], v0, s[2:3] offset:1024
	global_load_dwordx4 v[50:53], v0, s[2:3] offset:2048
	global_load_dwordx4 v[54:57], v0, s[2:3] offset:3072
	s_add_u32 s2, s8, 0x1000
	s_addc_u32 s3, s9, 0
	global_load_dwordx4 v[58:61], v0, s[2:3]
	global_load_dwordx4 v[62:65], v0, s[2:3] offset:1024
	global_load_dwordx4 v[66:69], v0, s[2:3] offset:2048
	global_load_dwordx4 v[70:73], v0, s[2:3] offset:3072
	s_add_u32 s2, s8, 0x2000
	s_addc_u32 s3, s9, 0
	global_load_dwordx4 v[74:77], v0, s[2:3]
	global_load_dwordx4 v[78:81], v0, s[2:3] offset:1024
	global_load_dwordx4 v[82:85], v0, s[2:3] offset:2048
	global_load_dwordx4 v[86:89], v0, s[2:3] offset:3072
	s_add_u32 s2, s8, 0x3000
	s_addc_u32 s3, s9, 0
	global_load_dwordx4 v[98:101], v0, s[2:3]
	global_load_dwordx4 v[102:105], v0, s[2:3] offset:1024
	global_load_dwordx4 v[106:109], v0, s[2:3] offset:2048
	global_load_dwordx4 v[110:113], v0, s[2:3] offset:3072
	s_waitcnt vmcnt(12)
	v_add_f32_e32 v9, v42, v43
	v_add_f32_e32 v91, v44, v45
	v_mul_f32_e32 v90, v42, v42
	v_mul_f32_e32 v92, v43, v43
	v_add_f32_e32 v9, v9, v46
	v_add_f32_e32 v91, v91, v47
	v_add_f32_e32 v9, v9, v48
	v_add_f32_e32 v91, v91, v49
	v_add_f32_e32 v9, v9, v50
	v_add_f32_e32 v91, v91, v51
	v_add_f32_e32 v9, v9, v52
	v_add_f32_e32 v91, v91, v53
	v_add_f32_e32 v9, v9, v54
	v_add_f32_e32 v91, v91, v55
	v_add_f32_e32 v9, v9, v56
	v_add_f32_e32 v91, v91, v57
	v_fmac_f32_e32 v90, v44, v44
	v_fmac_f32_e32 v92, v45, v45
	v_fmac_f32_e32 v90, v46, v46
	v_fmac_f32_e32 v92, v47, v47
	v_fmac_f32_e32 v90, v48, v48
	v_fmac_f32_e32 v92, v49, v49
	v_fmac_f32_e32 v90, v50, v50
	v_fmac_f32_e32 v92, v51, v51
	v_fmac_f32_e32 v90, v52, v52
	v_fmac_f32_e32 v92, v53, v53
	v_fmac_f32_e32 v90, v54, v54
	v_fmac_f32_e32 v92, v55, v55
	v_fmac_f32_e32 v90, v56, v56
	v_fmac_f32_e32 v92, v57, v57
	v_add_f32_e32 v9, v9, v91
	v_add_f32_e32 v90, v90, v92
	ds_bpermute_b32 v91, v3, v9
	ds_bpermute_b32 v92, v3, v90
	s_waitcnt lgkmcnt(0)
	v_add_f32_e32 v9, v9, v91
	v_add_f32_e32 v90, v90, v92
	ds_bpermute_b32 v91, v4, v9
	ds_bpermute_b32 v92, v4, v90
	s_waitcnt lgkmcnt(0)
	v_add_f32_e32 v9, v9, v91
	v_add_f32_e32 v90, v90, v92
	ds_bpermute_b32 v91, v5, v9
	ds_bpermute_b32 v92, v5, v90
	s_waitcnt lgkmcnt(0)
	v_add_f32_e32 v9, v9, v91
	v_add_f32_e32 v90, v90, v92
	ds_bpermute_b32 v91, v6, v9
	ds_bpermute_b32 v92, v6, v90
	s_waitcnt lgkmcnt(0)
	v_add_f32_e32 v9, v9, v91
	v_add_f32_e32 v90, v90, v92
	ds_bpermute_b32 v91, v7, v9
	ds_bpermute_b32 v92, v7, v90
	s_waitcnt lgkmcnt(0)
	v_add_f32_e32 v9, v9, v91
	v_add_f32_e32 v90, v90, v92
	ds_bpermute_b32 v91, v8, v9
	ds_bpermute_b32 v92, v8, v90
	s_waitcnt lgkmcnt(0)
	v_add_f32_e32 v9, v9, v91
	v_add_f32_e32 v90, v90, v92
	v_mul_f32_e32 v93, 0x3a800000, v9
	v_mul_f32_e32 v91, 0x3a800000, v90
	v_fma_f32 v91, -v93, v93, v91
	v_max_f32_e32 v91, 0, v91
	v_add_f32_e32 v91, 0x358637bd, v91
	v_rsq_f32_e32 v94, v91
	v_mul_f32_e32 v91, 0.5, v91
	v_mul_f32_e32 v92, v94, v94
	v_fma_f32 v92, -v91, v92, 0.5
	v_fma_f32 v94, v94, v92, v94
	v_sub_f32_e32 v42, v42, v93
	v_sub_f32_e32 v43, v43, v93
	v_sub_f32_e32 v44, v44, v93
	v_sub_f32_e32 v45, v45, v93
	v_sub_f32_e32 v46, v46, v93
	v_sub_f32_e32 v47, v47, v93
	v_sub_f32_e32 v48, v48, v93
	v_sub_f32_e32 v49, v49, v93
	v_sub_f32_e32 v50, v50, v93
	v_sub_f32_e32 v51, v51, v93
	v_sub_f32_e32 v52, v52, v93
	v_sub_f32_e32 v53, v53, v93
	v_sub_f32_e32 v54, v54, v93
	v_sub_f32_e32 v55, v55, v93
	v_sub_f32_e32 v56, v56, v93
	v_sub_f32_e32 v57, v57, v93
	v_mul_f32_e32 v42, v94, v42
	v_mul_f32_e32 v43, v94, v43
	v_mul_f32_e32 v44, v94, v44
	v_mul_f32_e32 v45, v94, v45
	v_mul_f32_e32 v46, v94, v46
	v_mul_f32_e32 v47, v94, v47
	v_mul_f32_e32 v48, v94, v48
	v_mul_f32_e32 v49, v94, v49
	v_mul_f32_e32 v50, v94, v50
	v_mul_f32_e32 v51, v94, v51
	v_mul_f32_e32 v52, v94, v52
	v_mul_f32_e32 v53, v94, v53
	v_mul_f32_e32 v54, v94, v54
	v_mul_f32_e32 v55, v94, v55
	v_mul_f32_e32 v56, v94, v56
	v_mul_f32_e32 v57, v94, v57
	v_fma_f32 v42, v42, v10, v26
	v_fma_f32 v43, v43, v11, v27
	v_fma_f32 v44, v44, v12, v28
	v_fma_f32 v45, v45, v13, v29
	v_fma_f32 v46, v46, v14, v30
	v_fma_f32 v47, v47, v15, v31
	v_fma_f32 v48, v48, v16, v32
	v_fma_f32 v49, v49, v17, v33
	v_fma_f32 v50, v50, v18, v34
	v_fma_f32 v51, v51, v19, v35
	v_fma_f32 v52, v52, v20, v36
	v_fma_f32 v53, v53, v21, v37
	v_fma_f32 v54, v54, v22, v38
	v_fma_f32 v55, v55, v23, v39
	v_fma_f32 v56, v56, v24, v40
	v_fma_f32 v57, v57, v25, v41
	s_add_u32 s2, s8, 0x0
	s_addc_u32 s3, s9, 0
	global_store_dwordx4 v0, v[42:45], s[2:3]
	global_store_dwordx4 v0, v[46:49], s[2:3] offset:1024
	global_store_dwordx4 v0, v[50:53], s[2:3] offset:2048
	global_store_dwordx4 v0, v[54:57], s[2:3] offset:3072
	s_add_u32 s2, s8, 0x4000
	s_addc_u32 s3, s9, 0
	global_load_dwordx4 v[42:45], v0, s[2:3]
	global_load_dwordx4 v[46:49], v0, s[2:3] offset:1024
	global_load_dwordx4 v[50:53], v0, s[2:3] offset:2048
	global_load_dwordx4 v[54:57], v0, s[2:3] offset:3072
	s_waitcnt vmcnt(16)
; DI void ln_row_v(const Frame& F, f32x4 (&v)[4], float* xout, const float* g, const float* b, const float* sh, const float* sc, bf16_t* hout, const float* slab, const float* gres, float* stat = nullptr) {
;     ...
;     if (g) {
;         float s = 0.f, s2 = 0.f;
; #pragma unroll
;         for (int j = 0; j < 4; ++j) { s += (v[j][0] + v[j][1]) + (v[j][2] + v[j][3]); s2 += (v[j][0] * v[j][0] + v[j][1] * v[j][1]) + (v[j][2] * v[j][2] + v[j][3] * v[j][3]); }
;         wave_sum2(s, s2, F.lane);
;         const float mean = s * (1.f / D); const float rstd = 1.f / sqrtf(fmaxf(s2 * (1.f / D) - mean * mean, 0.f) + EPS);
;         if (stat && F.lane == 0) { f32x2 sv = {mean, rstd}; *(f32x2*)stat = sv; }
; #pragma unroll
;         for (int j = 0; j < 4; ++j) { const f32x4 gg = ((const f32x4*)g)[F.lane + 64 * j], bb = ((const f32x4*)b)[F.lane + 64 * j];
;             v[j] = (v[j] - mean) * rstd * gg + bb; if (xout) ((f32x4*)xout)[F.lane + 64 * j] = v[j]; }
	v_add_f32_e32 v9, v58, v59
	v_add_f32_e32 v91, v60, v61
	v_mul_f32_e32 v90, v58, v58
	v_mul_f32_e32 v92, v59, v59
	v_add_f32_e32 v9, v9, v62
	v_add_f32_e32 v91, v91, v63
	v_add_f32_e32 v9, v9, v64
	v_add_f32_e32 v91, v91, v65
	v_add_f32_e32 v9, v9, v66
	v_add_f32_e32 v91, v91, v67
	v_add_f32_e32 v9, v9, v68
	v_add_f32_e32 v91, v91, v69
	v_add_f32_e32 v9, v9, v70
	v_add_f32_e32 v91, v91, v71
	v_add_f32_e32 v9, v9, v72
	v_add_f32_e32 v91, v91, v73
	v_fmac_f32_e32 v90, v60, v60
	v_fmac_f32_e32 v92, v61, v61
	v_fmac_f32_e32 v90, v62, v62
	v_fmac_f32_e32 v92, v63, v63
	v_fmac_f32_e32 v90, v64, v64
	v_fmac_f32_e32 v92, v65, v65
	v_fmac_f32_e32 v90, v66, v66
	v_fmac_f32_e32 v92, v67, v67
	v_fmac_f32_e32 v90, v68, v68
	v_fmac_f32_e32 v92, v69, v69
	v_fmac_f32_e32 v90, v70, v70
	v_fmac_f32_e32 v92, v71, v71
	v_fmac_f32_e32 v90, v72, v72
	v_fmac_f32_e32 v92, v73, v73
	v_add_f32_e32 v9, v9, v91
	v_add_f32_e32 v90, v90, v92
	ds_bpermute_b32 v91, v3, v9
	ds_bpermute_b32 v92, v3, v90
	s_waitcnt lgkmcnt(0)
	v_add_f32_e32 v9, v9, v91
	v_add_f32_e32 v90, v90, v92
	ds_bpermute_b32 v91, v4, v9
	ds_bpermute_b32 v92, v4, v90
	s_waitcnt lgkmcnt(0)
	v_add_f32_e32 v9, v9, v91
	v_add_f32_e32 v90, v90, v92
	ds_bpermute_b32 v91, v5, v9
	ds_bpermute_b32 v92, v5, v90
	s_waitcnt lgkmcnt(0)
	v_add_f32_e32 v9, v9, v91
	v_add_f32_e32 v90, v90, v92
	ds_bpermute_b32 v91, v6, v9
	ds_bpermute_b32 v92, v6, v90
	s_waitcnt lgkmcnt(0)
	v_add_f32_e32 v9, v9, v91
	v_add_f32_e32 v90, v90, v92
	ds_bpermute_b32 v91, v7, v9
	ds_bpermute_b32 v92, v7, v90
	s_waitcnt lgkmcnt(0)
	v_add_f32_e32 v9, v9, v91
	v_add_f32_e32 v90, v90, v92
	ds_bpermute_b32 v91, v8, v9
	ds_bpermute_b32 v92, v8, v90
	s_waitcnt lgkmcnt(0)
	v_add_f32_e32 v9, v9, v91
	v_add_f32_e32 v90, v90, v92
	v_mul_f32_e32 v93, 0x3a800000, v9
	v_mul_f32_e32 v91, 0x3a800000, v90
	v_fma_f32 v91, -v93, v93, v91
	v_max_f32_e32 v91, 0, v91
	v_add_f32_e32 v91, 0x358637bd, v91
	v_rsq_f32_e32 v94, v91
	v_mul_f32_e32 v91, 0.5, v91
	v_mul_f32_e32 v92, v94, v94
	v_fma_f32 v92, -v91, v92, 0.5
	v_fma_f32 v94, v94, v92, v94
	v_sub_f32_e32 v58, v58, v93
	v_sub_f32_e32 v59, v59, v93
	v_sub_f32_e32 v60, v60, v93
	v_sub_f32_e32 v61, v61, v93
	v_sub_f32_e32 v62, v62, v93
	v_sub_f32_e32 v63, v63, v93
	v_sub_f32_e32 v64, v64, v93
	v_sub_f32_e32 v65, v65, v93
	v_sub_f32_e32 v66, v66, v93
	v_sub_f32_e32 v67, v67, v93
	v_sub_f32_e32 v68, v68, v93
	v_sub_f32_e32 v69, v69, v93
	v_sub_f32_e32 v70, v70, v93
	v_sub_f32_e32 v71, v71, v93
	v_sub_f32_e32 v72, v72, v93
	v_sub_f32_e32 v73, v73, v93
	v_mul_f32_e32 v58, v94, v58
	v_mul_f32_e32 v59, v94, v59
	v_mul_f32_e32 v60, v94, v60
	v_mul_f32_e32 v61, v94, v61
	v_mul_f32_e32 v62, v94, v62
	v_mul_f32_e32 v63, v94, v63
	v_mul_f32_e32 v64, v94, v64
	v_mul_f32_e32 v65, v94, v65
	v_mul_f32_e32 v66, v94, v66
	v_mul_f32_e32 v67, v94, v67
	v_mul_f32_e32 v68, v94, v68
	v_mul_f32_e32 v69, v94, v69
	v_mul_f32_e32 v70, v94, v70
	v_mul_f32_e32 v71, v94, v71
	v_mul_f32_e32 v72, v94, v72
	v_mul_f32_e32 v73, v94, v73
	v_fma_f32 v58, v58, v10, v26
	v_fma_f32 v59, v59, v11, v27
	v_fma_f32 v60, v60, v12, v28
	v_fma_f32 v61, v61, v13, v29
	v_fma_f32 v62, v62, v14, v30
	v_fma_f32 v63, v63, v15, v31
	v_fma_f32 v64, v64, v16, v32
	v_fma_f32 v65, v65, v17, v33
	v_fma_f32 v66, v66, v18, v34
	v_fma_f32 v67, v67, v19, v35
	v_fma_f32 v68, v68, v20, v36
	v_fma_f32 v69, v69, v21, v37
	v_fma_f32 v70, v70, v22, v38
	v_fma_f32 v71, v71, v23, v39
	v_fma_f32 v72, v72, v24, v40
	v_fma_f32 v73, v73, v25, v41
	s_add_u32 s2, s8, 0x1000
	s_addc_u32 s3, s9, 0
	global_store_dwordx4 v0, v[58:61], s[2:3]
	global_store_dwordx4 v0, v[62:65], s[2:3] offset:1024
	global_store_dwordx4 v0, v[66:69], s[2:3] offset:2048
	global_store_dwordx4 v0, v[70:73], s[2:3] offset:3072
	s_add_u32 s2, s8, 0x5000
	s_addc_u32 s3, s9, 0
	global_load_dwordx4 v[58:61], v0, s[2:3]
	global_load_dwordx4 v[62:65], v0, s[2:3] offset:1024
	global_load_dwordx4 v[66:69], v0, s[2:3] offset:2048
	global_load_dwordx4 v[70:73], v0, s[2:3] offset:3072
	s_waitcnt vmcnt(20)
	v_add_f32_e32 v9, v74, v75
	v_add_f32_e32 v91, v76, v77
	v_mul_f32_e32 v90, v74, v74
	v_mul_f32_e32 v92, v75, v75
	v_add_f32_e32 v9, v9, v78
	v_add_f32_e32 v91, v91, v79
	v_add_f32_e32 v9, v9, v80
	v_add_f32_e32 v91, v91, v81
	v_add_f32_e32 v9, v9, v82
	v_add_f32_e32 v91, v91, v83
	v_add_f32_e32 v9, v9, v84
	v_add_f32_e32 v91, v91, v85
	v_add_f32_e32 v9, v9, v86
	v_add_f32_e32 v91, v91, v87
	v_add_f32_e32 v9, v9, v88
	v_add_f32_e32 v91, v91, v89
	v_fmac_f32_e32 v90, v76, v76
	v_fmac_f32_e32 v92, v77, v77
	v_fmac_f32_e32 v90, v78, v78
	v_fmac_f32_e32 v92, v79, v79
	v_fmac_f32_e32 v90, v80, v80
	v_fmac_f32_e32 v92, v81, v81
	v_fmac_f32_e32 v90, v82, v82
	v_fmac_f32_e32 v92, v83, v83
	v_fmac_f32_e32 v90, v84, v84
	v_fmac_f32_e32 v92, v85, v85
	v_fmac_f32_e32 v90, v86, v86
	v_fmac_f32_e32 v92, v87, v87
	v_fmac_f32_e32 v90, v88, v88
	v_fmac_f32_e32 v92, v89, v89
	v_add_f32_e32 v9, v9, v91
	v_add_f32_e32 v90, v90, v92
	ds_bpermute_b32 v91, v3, v9
	ds_bpermute_b32 v92, v3, v90
	s_waitcnt lgkmcnt(0)
	v_add_f32_e32 v9, v9, v91
	v_add_f32_e32 v90, v90, v92
	ds_bpermute_b32 v91, v4, v9
	ds_bpermute_b32 v92, v4, v90
	s_waitcnt lgkmcnt(0)
	v_add_f32_e32 v9, v9, v91
	v_add_f32_e32 v90, v90, v92
	ds_bpermute_b32 v91, v5, v9
	ds_bpermute_b32 v92, v5, v90
	s_waitcnt lgkmcnt(0)
	v_add_f32_e32 v9, v9, v91
	v_add_f32_e32 v90, v90, v92
	ds_bpermute_b32 v91, v6, v9
	ds_bpermute_b32 v92, v6, v90
	s_waitcnt lgkmcnt(0)
	v_add_f32_e32 v9, v9, v91
	v_add_f32_e32 v90, v90, v92
	ds_bpermute_b32 v91, v7, v9
	ds_bpermute_b32 v92, v7, v90
	s_waitcnt lgkmcnt(0)
	v_add_f32_e32 v9, v9, v91
	v_add_f32_e32 v90, v90, v92
	ds_bpermute_b32 v91, v8, v9
	ds_bpermute_b32 v92, v8, v90
	s_waitcnt lgkmcnt(0)
; DI void ln_row_v(const Frame& F, f32x4 (&v)[4], float* xout, const float* g, const float* b, const float* sh, const float* sc, bf16_t* hout, const float* slab, const float* gres, float* stat = nullptr) {
;     ...
;     if (g) {
;         float s = 0.f, s2 = 0.f;
; #pragma unroll
;         for (int j = 0; j < 4; ++j) { s += (v[j][0] + v[j][1]) + (v[j][2] + v[j][3]); s2 += (v[j][0] * v[j][0] + v[j][1] * v[j][1]) + (v[j][2] * v[j][2] + v[j][3] * v[j][3]); }
;         wave_sum2(s, s2, F.lane);
;         const float mean = s * (1.f / D); const float rstd = 1.f / sqrtf(fmaxf(s2 * (1.f / D) - mean * mean, 0.f) + EPS);
;         if (stat && F.lane == 0) { f32x2 sv = {mean, rstd}; *(f32x2*)stat = sv; }
; #pragma unroll
;         for (int j = 0; j < 4; ++j) { const f32x4 gg = ((const f32x4*)g)[F.lane + 64 * j], bb = ((const f32x4*)b)[F.lane + 64 * j];
;             v[j] = (v[j] - mean) * rstd * gg + bb; if (xout) ((f32x4*)xout)[F.lane + 64 * j] = v[j]; }
	v_add_f32_e32 v9, v9, v91
	v_add_f32_e32 v90, v90, v92
	v_mul_f32_e32 v93, 0x3a800000, v9
	v_mul_f32_e32 v91, 0x3a800000, v90
	v_fma_f32 v91, -v93, v93, v91
	v_max_f32_e32 v91, 0, v91
	v_add_f32_e32 v91, 0x358637bd, v91
	v_rsq_f32_e32 v94, v91
	v_mul_f32_e32 v91, 0.5, v91
	v_mul_f32_e32 v92, v94, v94
	v_fma_f32 v92, -v91, v92, 0.5
	v_fma_f32 v94, v94, v92, v94
	v_sub_f32_e32 v74, v74, v93
	v_sub_f32_e32 v75, v75, v93
	v_sub_f32_e32 v76, v76, v93
	v_sub_f32_e32 v77, v77, v93
	v_sub_f32_e32 v78, v78, v93
	v_sub_f32_e32 v79, v79, v93
	v_sub_f32_e32 v80, v80, v93
	v_sub_f32_e32 v81, v81, v93
	v_sub_f32_e32 v82, v82, v93
	v_sub_f32_e32 v83, v83, v93
	v_sub_f32_e32 v84, v84, v93
	v_sub_f32_e32 v85, v85, v93
	v_sub_f32_e32 v86, v86, v93
	v_sub_f32_e32 v87, v87, v93
	v_sub_f32_e32 v88, v88, v93
	v_sub_f32_e32 v89, v89, v93
	v_mul_f32_e32 v74, v94, v74
	v_mul_f32_e32 v75, v94, v75
	v_mul_f32_e32 v76, v94, v76
	v_mul_f32_e32 v77, v94, v77
	v_mul_f32_e32 v78, v94, v78
	v_mul_f32_e32 v79, v94, v79
	v_mul_f32_e32 v80, v94, v80
	v_mul_f32_e32 v81, v94, v81
	v_mul_f32_e32 v82, v94, v82
	v_mul_f32_e32 v83, v94, v83
	v_mul_f32_e32 v84, v94, v84
	v_mul_f32_e32 v85, v94, v85
	v_mul_f32_e32 v86, v94, v86
	v_mul_f32_e32 v87, v94, v87
	v_mul_f32_e32 v88, v94, v88
	v_mul_f32_e32 v89, v94, v89
	v_fma_f32 v74, v74, v10, v26
	v_fma_f32 v75, v75, v11, v27
	v_fma_f32 v76, v76, v12, v28
	v_fma_f32 v77, v77, v13, v29
	v_fma_f32 v78, v78, v14, v30
	v_fma_f32 v79, v79, v15, v31
	v_fma_f32 v80, v80, v16, v32
	v_fma_f32 v81, v81, v17, v33
	v_fma_f32 v82, v82, v18, v34
	v_fma_f32 v83, v83, v19, v35
	v_fma_f32 v84, v84, v20, v36
	v_fma_f32 v85, v85, v21, v37
	v_fma_f32 v86, v86, v22, v38
	v_fma_f32 v87, v87, v23, v39
	v_fma_f32 v88, v88, v24, v40
	v_fma_f32 v89, v89, v25, v41
	s_add_u32 s2, s8, 0x2000
	s_addc_u32 s3, s9, 0
	global_store_dwordx4 v0, v[74:77], s[2:3]
	global_store_dwordx4 v0, v[78:81], s[2:3] offset:1024
	global_store_dwordx4 v0, v[82:85], s[2:3] offset:2048
	global_store_dwordx4 v0, v[86:89], s[2:3] offset:3072
	s_add_u32 s2, s8, 0x6000
	s_addc_u32 s3, s9, 0
	global_load_dwordx4 v[74:77], v0, s[2:3]
	global_load_dwordx4 v[78:81], v0, s[2:3] offset:1024
	global_load_dwordx4 v[82:85], v0, s[2:3] offset:2048
	global_load_dwordx4 v[86:89], v0, s[2:3] offset:3072
	s_waitcnt vmcnt(24)
	v_add_f32_e32 v9, v98, v99
	v_add_f32_e32 v91, v100, v101
	v_mul_f32_e32 v90, v98, v98
	v_mul_f32_e32 v92, v99, v99
	v_add_f32_e32 v9, v9, v102
	v_add_f32_e32 v91, v91, v103
	v_add_f32_e32 v9, v9, v104
	v_add_f32_e32 v91, v91, v105
	v_add_f32_e32 v9, v9, v106
	v_add_f32_e32 v91, v91, v107
	v_add_f32_e32 v9, v9, v108
	v_add_f32_e32 v91, v91, v109
	v_add_f32_e32 v9, v9, v110
	v_add_f32_e32 v91, v91, v111
	v_add_f32_e32 v9, v9, v112
	v_add_f32_e32 v91, v91, v113
	v_fmac_f32_e32 v90, v100, v100
	v_fmac_f32_e32 v92, v101, v101
	v_fmac_f32_e32 v90, v102, v102
	v_fmac_f32_e32 v92, v103, v103
	v_fmac_f32_e32 v90, v104, v104
	v_fmac_f32_e32 v92, v105, v105
	v_fmac_f32_e32 v90, v106, v106
	v_fmac_f32_e32 v92, v107, v107
	v_fmac_f32_e32 v90, v108, v108
	v_fmac_f32_e32 v92, v109, v109
	v_fmac_f32_e32 v90, v110, v110
	v_fmac_f32_e32 v92, v111, v111
	v_fmac_f32_e32 v90, v112, v112
	v_fmac_f32_e32 v92, v113, v113
	v_add_f32_e32 v9, v9, v91
	v_add_f32_e32 v90, v90, v92
	ds_bpermute_b32 v91, v3, v9
	ds_bpermute_b32 v92, v3, v90
	s_waitcnt lgkmcnt(0)
	v_add_f32_e32 v9, v9, v91
	v_add_f32_e32 v90, v90, v92
	ds_bpermute_b32 v91, v4, v9
	ds_bpermute_b32 v92, v4, v90
	s_waitcnt lgkmcnt(0)
	v_add_f32_e32 v9, v9, v91
	v_add_f32_e32 v90, v90, v92
	ds_bpermute_b32 v91, v5, v9
	ds_bpermute_b32 v92, v5, v90
	s_waitcnt lgkmcnt(0)
	v_add_f32_e32 v9, v9, v91
	v_add_f32_e32 v90, v90, v92
	ds_bpermute_b32 v91, v6, v9
	ds_bpermute_b32 v92, v6, v90
	s_waitcnt lgkmcnt(0)
	v_add_f32_e32 v9, v9, v91
	v_add_f32_e32 v90, v90, v92
	ds_bpermute_b32 v91, v7, v9
	ds_bpermute_b32 v92, v7, v90
	s_waitcnt lgkmcnt(0)
	v_add_f32_e32 v9, v9, v91
	v_add_f32_e32 v90, v90, v92
	ds_bpermute_b32 v91, v8, v9
	ds_bpermute_b32 v92, v8, v90
	s_waitcnt lgkmcnt(0)
	v_add_f32_e32 v9, v9, v91
	v_add_f32_e32 v90, v90, v92
	v_mul_f32_e32 v93, 0x3a800000, v9
	v_mul_f32_e32 v91, 0x3a800000, v90
	v_fma_f32 v91, -v93, v93, v91
	v_max_f32_e32 v91, 0, v91
	v_add_f32_e32 v91, 0x358637bd, v91
	v_rsq_f32_e32 v94, v91
	v_mul_f32_e32 v91, 0.5, v91
	v_mul_f32_e32 v92, v94, v94
	v_fma_f32 v92, -v91, v92, 0.5
	v_fma_f32 v94, v94, v92, v94
	v_sub_f32_e32 v98, v98, v93
	v_sub_f32_e32 v99, v99, v93
	v_sub_f32_e32 v100, v100, v93
	v_sub_f32_e32 v101, v101, v93
	v_sub_f32_e32 v102, v102, v93
	v_sub_f32_e32 v103, v103, v93
	v_sub_f32_e32 v104, v104, v93
	v_sub_f32_e32 v105, v105, v93
	v_sub_f32_e32 v106, v106, v93
	v_sub_f32_e32 v107, v107, v93
	v_sub_f32_e32 v108, v108, v93
	v_sub_f32_e32 v109, v109, v93
	v_sub_f32_e32 v110, v110, v93
	v_sub_f32_e32 v111, v111, v93
	v_sub_f32_e32 v112, v112, v93
	v_sub_f32_e32 v113, v113, v93
	v_mul_f32_e32 v98, v94, v98
	v_mul_f32_e32 v99, v94, v99
	v_mul_f32_e32 v100, v94, v100
	v_mul_f32_e32 v101, v94, v101
	v_mul_f32_e32 v102, v94, v102
	v_mul_f32_e32 v103, v94, v103
	v_mul_f32_e32 v104, v94, v104
	v_mul_f32_e32 v105, v94, v105
	v_mul_f32_e32 v106, v94, v106
	v_mul_f32_e32 v107, v94, v107
	v_mul_f32_e32 v108, v94, v108
	v_mul_f32_e32 v109, v94, v109
	v_mul_f32_e32 v110, v94, v110
	v_mul_f32_e32 v111, v94, v111
	v_mul_f32_e32 v112, v94, v112
	v_mul_f32_e32 v113, v94, v113
	v_fma_f32 v98, v98, v10, v26
	v_fma_f32 v99, v99, v11, v27
	v_fma_f32 v100, v100, v12, v28
	v_fma_f32 v101, v101, v13, v29
	v_fma_f32 v102, v102, v14, v30
	v_fma_f32 v103, v103, v15, v31
	v_fma_f32 v104, v104, v16, v32
	v_fma_f32 v105, v105, v17, v33
	v_fma_f32 v106, v106, v18, v34
	v_fma_f32 v107, v107, v19, v35
	v_fma_f32 v108, v108, v20, v36
	v_fma_f32 v109, v109, v21, v37
	v_fma_f32 v110, v110, v22, v38
	v_fma_f32 v111, v111, v23, v39
	v_fma_f32 v112, v112, v24, v40
	v_fma_f32 v113, v113, v25, v41
	s_add_u32 s2, s8, 0x3000
	s_addc_u32 s3, s9, 0
	global_store_dwordx4 v0, v[98:101], s[2:3]
	global_store_dwordx4 v0, v[102:105], s[2:3] offset:1024
	global_store_dwordx4 v0, v[106:109], s[2:3] offset:2048
	global_store_dwordx4 v0, v[110:113], s[2:3] offset:3072
	s_add_u32 s2, s8, 0x7000
	s_addc_u32 s3, s9, 0
	global_load_dwordx4 v[98:101], v0, s[2:3]
	global_load_dwordx4 v[102:105], v0, s[2:3] offset:1024
	global_load_dwordx4 v[106:109], v0, s[2:3] offset:2048
	global_load_dwordx4 v[110:113], v0, s[2:3] offset:3072
	s_waitcnt vmcnt(24)
; DI void ln_row_v(const Frame& F, f32x4 (&v)[4], float* xout, const float* g, const float* b, const float* sh, const float* sc, bf16_t* hout, const float* slab, const float* gres, float* stat = nullptr) {
;     ...
;     if (g) {
;         float s = 0.f, s2 = 0.f;
; #pragma unroll
;         for (int j = 0; j < 4; ++j) { s += (v[j][0] + v[j][1]) + (v[j][2] + v[j][3]); s2 += (v[j][0] * v[j][0] + v[j][1] * v[j][1]) + (v[j][2] * v[j][2] + v[j][3] * v[j][3]); }
;         wave_sum2(s, s2, F.lane);
;         const float mean = s * (1.f / D); const float rstd = 1.f / sqrtf(fmaxf(s2 * (1.f / D) - mean * mean, 0.f) + EPS);
;         if (stat && F.lane == 0) { f32x2 sv = {mean, rstd}; *(f32x2*)stat = sv; }
; #pragma unroll
;         for (int j = 0; j < 4; ++j) { const f32x4 gg = ((const f32x4*)g)[F.lane + 64 * j], bb = ((const f32x4*)b)[F.lane + 64 * j];
;             v[j] = (v[j] - mean) * rstd * gg + bb; if (xout) ((f32x4*)xout)[F.lane + 64 * j] = v[j]; }
	v_add_f32_e32 v9, v42, v43
	v_add_f32_e32 v91, v44, v45
	v_mul_f32_e32 v90, v42, v42
	v_mul_f32_e32 v92, v43, v43
	v_add_f32_e32 v9, v9, v46
	v_add_f32_e32 v91, v91, v47
	v_add_f32_e32 v9, v9, v48
	v_add_f32_e32 v91, v91, v49
	v_add_f32_e32 v9, v9, v50
	v_add_f32_e32 v91, v91, v51
	v_add_f32_e32 v9, v9, v52
	v_add_f32_e32 v91, v91, v53
	v_add_f32_e32 v9, v9, v54
	v_add_f32_e32 v91, v91, v55
	v_add_f32_e32 v9, v9, v56
	v_add_f32_e32 v91, v91, v57
	v_fmac_f32_e32 v90, v44, v44
	v_fmac_f32_e32 v92, v45, v45
	v_fmac_f32_e32 v90, v46, v46
	v_fmac_f32_e32 v92, v47, v47
	v_fmac_f32_e32 v90, v48, v48
	v_fmac_f32_e32 v92, v49, v49
	v_fmac_f32_e32 v90, v50, v50
	v_fmac_f32_e32 v92, v51, v51
	v_fmac_f32_e32 v90, v52, v52
	v_fmac_f32_e32 v92, v53, v53
	v_fmac_f32_e32 v90, v54, v54
	v_fmac_f32_e32 v92, v55, v55
	v_fmac_f32_e32 v90, v56, v56
	v_fmac_f32_e32 v92, v57, v57
	v_add_f32_e32 v9, v9, v91
	v_add_f32_e32 v90, v90, v92
	ds_bpermute_b32 v91, v3, v9
	ds_bpermute_b32 v92, v3, v90
	s_waitcnt lgkmcnt(0)
	v_add_f32_e32 v9, v9, v91
	v_add_f32_e32 v90, v90, v92
	ds_bpermute_b32 v91, v4, v9
	ds_bpermute_b32 v92, v4, v90
	s_waitcnt lgkmcnt(0)
	v_add_f32_e32 v9, v9, v91
	v_add_f32_e32 v90, v90, v92
	ds_bpermute_b32 v91, v5, v9
	ds_bpermute_b32 v92, v5, v90
	s_waitcnt lgkmcnt(0)
	v_add_f32_e32 v9, v9, v91
	v_add_f32_e32 v90, v90, v92
	ds_bpermute_b32 v91, v6, v9
	ds_bpermute_b32 v92, v6, v90
	s_waitcnt lgkmcnt(0)
	v_add_f32_e32 v9, v9, v91
	v_add_f32_e32 v90, v90, v92
	ds_bpermute_b32 v91, v7, v9
	ds_bpermute_b32 v92, v7, v90
	s_waitcnt lgkmcnt(0)
	v_add_f32_e32 v9, v9, v91
	v_add_f32_e32 v90, v90, v92
	ds_bpermute_b32 v91, v8, v9
	ds_bpermute_b32 v92, v8, v90
	s_waitcnt lgkmcnt(0)
	v_add_f32_e32 v9, v9, v91
	v_add_f32_e32 v90, v90, v92
	v_mul_f32_e32 v93, 0x3a800000, v9
	v_mul_f32_e32 v91, 0x3a800000, v90
	v_fma_f32 v91, -v93, v93, v91
	v_max_f32_e32 v91, 0, v91
	v_add_f32_e32 v91, 0x358637bd, v91
	v_rsq_f32_e32 v94, v91
	v_mul_f32_e32 v91, 0.5, v91
	v_mul_f32_e32 v92, v94, v94
	v_fma_f32 v92, -v91, v92, 0.5
	v_fma_f32 v94, v94, v92, v94
	v_sub_f32_e32 v42, v42, v93
	v_sub_f32_e32 v43, v43, v93
	v_sub_f32_e32 v44, v44, v93
	v_sub_f32_e32 v45, v45, v93
	v_sub_f32_e32 v46, v46, v93
	v_sub_f32_e32 v47, v47, v93
	v_sub_f32_e32 v48, v48, v93
	v_sub_f32_e32 v49, v49, v93
	v_sub_f32_e32 v50, v50, v93
	v_sub_f32_e32 v51, v51, v93
	v_sub_f32_e32 v52, v52, v93
	v_sub_f32_e32 v53, v53, v93
	v_sub_f32_e32 v54, v54, v93
	v_sub_f32_e32 v55, v55, v93
	v_sub_f32_e32 v56, v56, v93
	v_sub_f32_e32 v57, v57, v93
	v_mul_f32_e32 v42, v94, v42
	v_mul_f32_e32 v43, v94, v43
	v_mul_f32_e32 v44, v94, v44
	v_mul_f32_e32 v45, v94, v45
	v_mul_f32_e32 v46, v94, v46
	v_mul_f32_e32 v47, v94, v47
	v_mul_f32_e32 v48, v94, v48
	v_mul_f32_e32 v49, v94, v49
	v_mul_f32_e32 v50, v94, v50
	v_mul_f32_e32 v51, v94, v51
	v_mul_f32_e32 v52, v94, v52
	v_mul_f32_e32 v53, v94, v53
	v_mul_f32_e32 v54, v94, v54
	v_mul_f32_e32 v55, v94, v55
	v_mul_f32_e32 v56, v94, v56
	v_mul_f32_e32 v57, v94, v57
	v_fma_f32 v42, v42, v10, v26
	v_fma_f32 v43, v43, v11, v27
	v_fma_f32 v44, v44, v12, v28
	v_fma_f32 v45, v45, v13, v29
	v_fma_f32 v46, v46, v14, v30
	v_fma_f32 v47, v47, v15, v31
	v_fma_f32 v48, v48, v16, v32
	v_fma_f32 v49, v49, v17, v33
	v_fma_f32 v50, v50, v18, v34
	v_fma_f32 v51, v51, v19, v35
	v_fma_f32 v52, v52, v20, v36
	v_fma_f32 v53, v53, v21, v37
	v_fma_f32 v54, v54, v22, v38
	v_fma_f32 v55, v55, v23, v39
	v_fma_f32 v56, v56, v24, v40
	v_fma_f32 v57, v57, v25, v41
	s_add_u32 s2, s8, 0x4000
	s_addc_u32 s3, s9, 0
	global_store_dwordx4 v0, v[42:45], s[2:3]
	global_store_dwordx4 v0, v[46:49], s[2:3] offset:1024
	global_store_dwordx4 v0, v[50:53], s[2:3] offset:2048
	global_store_dwordx4 v0, v[54:57], s[2:3] offset:3072
	s_waitcnt vmcnt(20)
	v_add_f32_e32 v9, v58, v59
	v_add_f32_e32 v91, v60, v61
	v_mul_f32_e32 v90, v58, v58
	v_mul_f32_e32 v92, v59, v59
	v_add_f32_e32 v9, v9, v62
	v_add_f32_e32 v91, v91, v63
	v_add_f32_e32 v9, v9, v64
	v_add_f32_e32 v91, v91, v65
	v_add_f32_e32 v9, v9, v66
	v_add_f32_e32 v91, v91, v67
	v_add_f32_e32 v9, v9, v68
	v_add_f32_e32 v91, v91, v69
	v_add_f32_e32 v9, v9, v70
	v_add_f32_e32 v91, v91, v71
	v_add_f32_e32 v9, v9, v72
	v_add_f32_e32 v91, v91, v73
	v_fmac_f32_e32 v90, v60, v60
	v_fmac_f32_e32 v92, v61, v61
	v_fmac_f32_e32 v90, v62, v62
	v_fmac_f32_e32 v92, v63, v63
	v_fmac_f32_e32 v90, v64, v64
	v_fmac_f32_e32 v92, v65, v65
	v_fmac_f32_e32 v90, v66, v66
	v_fmac_f32_e32 v92, v67, v67
	v_fmac_f32_e32 v90, v68, v68
	v_fmac_f32_e32 v92, v69, v69
	v_fmac_f32_e32 v90, v70, v70
	v_fmac_f32_e32 v92, v71, v71
	v_fmac_f32_e32 v90, v72, v72
	v_fmac_f32_e32 v92, v73, v73
	v_add_f32_e32 v9, v9, v91
	v_add_f32_e32 v90, v90, v92
	ds_bpermute_b32 v91, v3, v9
	ds_bpermute_b32 v92, v3, v90
	s_waitcnt lgkmcnt(0)
	v_add_f32_e32 v9, v9, v91
	v_add_f32_e32 v90, v90, v92
	ds_bpermute_b32 v91, v4, v9
	ds_bpermute_b32 v92, v4, v90
	s_waitcnt lgkmcnt(0)
	v_add_f32_e32 v9, v9, v91
	v_add_f32_e32 v90, v90, v92
	ds_bpermute_b32 v91, v5, v9
	ds_bpermute_b32 v92, v5, v90
	s_waitcnt lgkmcnt(0)
	v_add_f32_e32 v9, v9, v91
	v_add_f32_e32 v90, v90, v92
	ds_bpermute_b32 v91, v6, v9
	ds_bpermute_b32 v92, v6, v90
	s_waitcnt lgkmcnt(0)
	v_add_f32_e32 v9, v9, v91
	v_add_f32_e32 v90, v90, v92
	ds_bpermute_b32 v91, v7, v9
	ds_bpermute_b32 v92, v7, v90
	s_waitcnt lgkmcnt(0)
	v_add_f32_e32 v9, v9, v91
	v_add_f32_e32 v90, v90, v92
	ds_bpermute_b32 v91, v8, v9
	ds_bpermute_b32 v92, v8, v90
	s_waitcnt lgkmcnt(0)
; DI void ln_row_v(const Frame& F, f32x4 (&v)[4], float* xout, const float* g, const float* b, const float* sh, const float* sc, bf16_t* hout, const float* slab, const float* gres, float* stat = nullptr) {
;     ...
;     if (g) {
;         float s = 0.f, s2 = 0.f;
; #pragma unroll
;         for (int j = 0; j < 4; ++j) { s += (v[j][0] + v[j][1]) + (v[j][2] + v[j][3]); s2 += (v[j][0] * v[j][0] + v[j][1] * v[j][1]) + (v[j][2] * v[j][2] + v[j][3] * v[j][3]); }
;         wave_sum2(s, s2, F.lane);
;         const float mean = s * (1.f / D); const float rstd = 1.f / sqrtf(fmaxf(s2 * (1.f / D) - mean * mean, 0.f) + EPS);
;         if (stat && F.lane == 0) { f32x2 sv = {mean, rstd}; *(f32x2*)stat = sv; }
; #pragma unroll
;         for (int j = 0; j < 4; ++j) { const f32x4 gg = ((const f32x4*)g)[F.lane + 64 * j], bb = ((const f32x4*)b)[F.lane + 64 * j];
;             v[j] = (v[j] - mean) * rstd * gg + bb; if (xout) ((f32x4*)xout)[F.lane + 64 * j] = v[j]; }
	v_add_f32_e32 v9, v9, v91
	v_add_f32_e32 v90, v90, v92
	v_mul_f32_e32 v93, 0x3a800000, v9
	v_mul_f32_e32 v91, 0x3a800000, v90
	v_fma_f32 v91, -v93, v93, v91
	v_max_f32_e32 v91, 0, v91
	v_add_f32_e32 v91, 0x358637bd, v91
	v_rsq_f32_e32 v94, v91
	v_mul_f32_e32 v91, 0.5, v91
	v_mul_f32_e32 v92, v94, v94
	v_fma_f32 v92, -v91, v92, 0.5
	v_fma_f32 v94, v94, v92, v94
	v_sub_f32_e32 v58, v58, v93
	v_sub_f32_e32 v59, v59, v93
	v_sub_f32_e32 v60, v60, v93
	v_sub_f32_e32 v61, v61, v93
	v_sub_f32_e32 v62, v62, v93
	v_sub_f32_e32 v63, v63, v93
	v_sub_f32_e32 v64, v64, v93
	v_sub_f32_e32 v65, v65, v93
	v_sub_f32_e32 v66, v66, v93
	v_sub_f32_e32 v67, v67, v93
	v_sub_f32_e32 v68, v68, v93
	v_sub_f32_e32 v69, v69, v93
	v_sub_f32_e32 v70, v70, v93
	v_sub_f32_e32 v71, v71, v93
	v_sub_f32_e32 v72, v72, v93
	v_sub_f32_e32 v73, v73, v93
	v_mul_f32_e32 v58, v94, v58
	v_mul_f32_e32 v59, v94, v59
	v_mul_f32_e32 v60, v94, v60
	v_mul_f32_e32 v61, v94, v61
	v_mul_f32_e32 v62, v94, v62
	v_mul_f32_e32 v63, v94, v63
	v_mul_f32_e32 v64, v94, v64
	v_mul_f32_e32 v65, v94, v65
	v_mul_f32_e32 v66, v94, v66
	v_mul_f32_e32 v67, v94, v67
	v_mul_f32_e32 v68, v94, v68
	v_mul_f32_e32 v69, v94, v69
	v_mul_f32_e32 v70, v94, v70
	v_mul_f32_e32 v71, v94, v71
	v_mul_f32_e32 v72, v94, v72
	v_mul_f32_e32 v73, v94, v73
	v_fma_f32 v58, v58, v10, v26
	v_fma_f32 v59, v59, v11, v27
	v_fma_f32 v60, v60, v12, v28
	v_fma_f32 v61, v61, v13, v29
	v_fma_f32 v62, v62, v14, v30
	v_fma_f32 v63, v63, v15, v31
	v_fma_f32 v64, v64, v16, v32
	v_fma_f32 v65, v65, v17, v33
	v_fma_f32 v66, v66, v18, v34
	v_fma_f32 v67, v67, v19, v35
	v_fma_f32 v68, v68, v20, v36
	v_fma_f32 v69, v69, v21, v37
	v_fma_f32 v70, v70, v22, v38
	v_fma_f32 v71, v71, v23, v39
	v_fma_f32 v72, v72, v24, v40
	v_fma_f32 v73, v73, v25, v41
	s_add_u32 s2, s8, 0x5000
	s_addc_u32 s3, s9, 0
	global_store_dwordx4 v0, v[58:61], s[2:3]
	global_store_dwordx4 v0, v[62:65], s[2:3] offset:1024
	global_store_dwordx4 v0, v[66:69], s[2:3] offset:2048
	global_store_dwordx4 v0, v[70:73], s[2:3] offset:3072
	s_waitcnt vmcnt(16)
	v_add_f32_e32 v9, v74, v75
	v_add_f32_e32 v91, v76, v77
	v_mul_f32_e32 v90, v74, v74
	v_mul_f32_e32 v92, v75, v75
	v_add_f32_e32 v9, v9, v78
	v_add_f32_e32 v91, v91, v79
	v_add_f32_e32 v9, v9, v80
	v_add_f32_e32 v91, v91, v81
	v_add_f32_e32 v9, v9, v82
	v_add_f32_e32 v91, v91, v83
	v_add_f32_e32 v9, v9, v84
	v_add_f32_e32 v91, v91, v85
	v_add_f32_e32 v9, v9, v86
	v_add_f32_e32 v91, v91, v87
	v_add_f32_e32 v9, v9, v88
	v_add_f32_e32 v91, v91, v89
	v_fmac_f32_e32 v90, v76, v76
	v_fmac_f32_e32 v92, v77, v77
	v_fmac_f32_e32 v90, v78, v78
	v_fmac_f32_e32 v92, v79, v79
	v_fmac_f32_e32 v90, v80, v80
	v_fmac_f32_e32 v92, v81, v81
	v_fmac_f32_e32 v90, v82, v82
	v_fmac_f32_e32 v92, v83, v83
	v_fmac_f32_e32 v90, v84, v84
	v_fmac_f32_e32 v92, v85, v85
	v_fmac_f32_e32 v90, v86, v86
	v_fmac_f32_e32 v92, v87, v87
	v_fmac_f32_e32 v90, v88, v88
	v_fmac_f32_e32 v92, v89, v89
	v_add_f32_e32 v9, v9, v91
	v_add_f32_e32 v90, v90, v92
	ds_bpermute_b32 v91, v3, v9
	ds_bpermute_b32 v92, v3, v90
	s_waitcnt lgkmcnt(0)
	v_add_f32_e32 v9, v9, v91
	v_add_f32_e32 v90, v90, v92
	ds_bpermute_b32 v91, v4, v9
	ds_bpermute_b32 v92, v4, v90
	s_waitcnt lgkmcnt(0)
	v_add_f32_e32 v9, v9, v91
	v_add_f32_e32 v90, v90, v92
	ds_bpermute_b32 v91, v5, v9
	ds_bpermute_b32 v92, v5, v90
	s_waitcnt lgkmcnt(0)
	v_add_f32_e32 v9, v9, v91
	v_add_f32_e32 v90, v90, v92
	ds_bpermute_b32 v91, v6, v9
	ds_bpermute_b32 v92, v6, v90
	s_waitcnt lgkmcnt(0)
	v_add_f32_e32 v9, v9, v91
	v_add_f32_e32 v90, v90, v92
	ds_bpermute_b32 v91, v7, v9
	ds_bpermute_b32 v92, v7, v90
	s_waitcnt lgkmcnt(0)
	v_add_f32_e32 v9, v9, v91
	v_add_f32_e32 v90, v90, v92
	ds_bpermute_b32 v91, v8, v9
	ds_bpermute_b32 v92, v8, v90
	s_waitcnt lgkmcnt(0)
	v_add_f32_e32 v9, v9, v91
	v_add_f32_e32 v90, v90, v92
	v_mul_f32_e32 v93, 0x3a800000, v9
	v_mul_f32_e32 v91, 0x3a800000, v90
	v_fma_f32 v91, -v93, v93, v91
	v_max_f32_e32 v91, 0, v91
	v_add_f32_e32 v91, 0x358637bd, v91
	v_rsq_f32_e32 v94, v91
	v_mul_f32_e32 v91, 0.5, v91
	v_mul_f32_e32 v92, v94, v94
	v_fma_f32 v92, -v91, v92, 0.5
	v_fma_f32 v94, v94, v92, v94
	v_sub_f32_e32 v74, v74, v93
	v_sub_f32_e32 v75, v75, v93
	v_sub_f32_e32 v76, v76, v93
	v_sub_f32_e32 v77, v77, v93
	v_sub_f32_e32 v78, v78, v93
	v_sub_f32_e32 v79, v79, v93
	v_sub_f32_e32 v80, v80, v93
	v_sub_f32_e32 v81, v81, v93
	v_sub_f32_e32 v82, v82, v93
	v_sub_f32_e32 v83, v83, v93
	v_sub_f32_e32 v84, v84, v93
	v_sub_f32_e32 v85, v85, v93
	v_sub_f32_e32 v86, v86, v93
	v_sub_f32_e32 v87, v87, v93
	v_sub_f32_e32 v88, v88, v93
	v_sub_f32_e32 v89, v89, v93
	v_mul_f32_e32 v74, v94, v74
	v_mul_f32_e32 v75, v94, v75
	v_mul_f32_e32 v76, v94, v76
	v_mul_f32_e32 v77, v94, v77
	v_mul_f32_e32 v78, v94, v78
	v_mul_f32_e32 v79, v94, v79
	v_mul_f32_e32 v80, v94, v80
	v_mul_f32_e32 v81, v94, v81
	v_mul_f32_e32 v82, v94, v82
	v_mul_f32_e32 v83, v94, v83
	v_mul_f32_e32 v84, v94, v84
	v_mul_f32_e32 v85, v94, v85
	v_mul_f32_e32 v86, v94, v86
	v_mul_f32_e32 v87, v94, v87
	v_mul_f32_e32 v88, v94, v88
	v_mul_f32_e32 v89, v94, v89
	v_fma_f32 v74, v74, v10, v26
	v_fma_f32 v75, v75, v11, v27
	v_fma_f32 v76, v76, v12, v28
	v_fma_f32 v77, v77, v13, v29
	v_fma_f32 v78, v78, v14, v30
	v_fma_f32 v79, v79, v15, v31
	v_fma_f32 v80, v80, v16, v32
	v_fma_f32 v81, v81, v17, v33
	v_fma_f32 v82, v82, v18, v34
	v_fma_f32 v83, v83, v19, v35
	v_fma_f32 v84, v84, v20, v36
	v_fma_f32 v85, v85, v21, v37
	v_fma_f32 v86, v86, v22, v38
	v_fma_f32 v87, v87, v23, v39
	v_fma_f32 v88, v88, v24, v40
	v_fma_f32 v89, v89, v25, v41
	s_add_u32 s2, s8, 0x6000
	s_addc_u32 s3, s9, 0
	global_store_dwordx4 v0, v[74:77], s[2:3]
	global_store_dwordx4 v0, v[78:81], s[2:3] offset:1024
	global_store_dwordx4 v0, v[82:85], s[2:3] offset:2048
	global_store_dwordx4 v0, v[86:89], s[2:3] offset:3072
	s_waitcnt vmcnt(12)
; DI void ln_row_v(const Frame& F, f32x4 (&v)[4], float* xout, const float* g, const float* b, const float* sh, const float* sc, bf16_t* hout, const float* slab, const float* gres, float* stat = nullptr) {
;     ...
;     if (g) {
;         float s = 0.f, s2 = 0.f;
; #pragma unroll
;         for (int j = 0; j < 4; ++j) { s += (v[j][0] + v[j][1]) + (v[j][2] + v[j][3]); s2 += (v[j][0] * v[j][0] + v[j][1] * v[j][1]) + (v[j][2] * v[j][2] + v[j][3] * v[j][3]); }
;         wave_sum2(s, s2, F.lane);
;         const float mean = s * (1.f / D); const float rstd = 1.f / sqrtf(fmaxf(s2 * (1.f / D) - mean * mean, 0.f) + EPS);
;         if (stat && F.lane == 0) { f32x2 sv = {mean, rstd}; *(f32x2*)stat = sv; }
; #pragma unroll
;         for (int j = 0; j < 4; ++j) { const f32x4 gg = ((const f32x4*)g)[F.lane + 64 * j], bb = ((const f32x4*)b)[F.lane + 64 * j];
;             v[j] = (v[j] - mean) * rstd * gg + bb; if (xout) ((f32x4*)xout)[F.lane + 64 * j] = v[j]; }
	v_add_f32_e32 v9, v98, v99
	v_add_f32_e32 v91, v100, v101
	v_mul_f32_e32 v90, v98, v98
	v_mul_f32_e32 v92, v99, v99
	v_add_f32_e32 v9, v9, v102
	v_add_f32_e32 v91, v91, v103
	v_add_f32_e32 v9, v9, v104
	v_add_f32_e32 v91, v91, v105
	v_add_f32_e32 v9, v9, v106
	v_add_f32_e32 v91, v91, v107
	v_add_f32_e32 v9, v9, v108
	v_add_f32_e32 v91, v91, v109
	v_add_f32_e32 v9, v9, v110
	v_add_f32_e32 v91, v91, v111
	v_add_f32_e32 v9, v9, v112
	v_add_f32_e32 v91, v91, v113
	v_fmac_f32_e32 v90, v100, v100
	v_fmac_f32_e32 v92, v101, v101
	v_fmac_f32_e32 v90, v102, v102
	v_fmac_f32_e32 v92, v103, v103
	v_fmac_f32_e32 v90, v104, v104
	v_fmac_f32_e32 v92, v105, v105
	v_fmac_f32_e32 v90, v106, v106
	v_fmac_f32_e32 v92, v107, v107
	v_fmac_f32_e32 v90, v108, v108
	v_fmac_f32_e32 v92, v109, v109
	v_fmac_f32_e32 v90, v110, v110
	v_fmac_f32_e32 v92, v111, v111
	v_fmac_f32_e32 v90, v112, v112
	v_fmac_f32_e32 v92, v113, v113
	v_add_f32_e32 v9, v9, v91
	v_add_f32_e32 v90, v90, v92
	ds_bpermute_b32 v91, v3, v9
	ds_bpermute_b32 v92, v3, v90
	s_waitcnt lgkmcnt(0)
	v_add_f32_e32 v9, v9, v91
	v_add_f32_e32 v90, v90, v92
	ds_bpermute_b32 v91, v4, v9
	ds_bpermute_b32 v92, v4, v90
	s_waitcnt lgkmcnt(0)
	v_add_f32_e32 v9, v9, v91
	v_add_f32_e32 v90, v90, v92
	ds_bpermute_b32 v91, v5, v9
	ds_bpermute_b32 v92, v5, v90
	s_waitcnt lgkmcnt(0)
	v_add_f32_e32 v9, v9, v91
	v_add_f32_e32 v90, v90, v92
	ds_bpermute_b32 v91, v6, v9
	ds_bpermute_b32 v92, v6, v90
	s_waitcnt lgkmcnt(0)
	v_add_f32_e32 v9, v9, v91
	v_add_f32_e32 v90, v90, v92
	ds_bpermute_b32 v91, v7, v9
	ds_bpermute_b32 v92, v7, v90
	s_waitcnt lgkmcnt(0)
	v_add_f32_e32 v9, v9, v91
	v_add_f32_e32 v90, v90, v92
	ds_bpermute_b32 v91, v8, v9
	ds_bpermute_b32 v92, v8, v90
	s_waitcnt lgkmcnt(0)
	v_add_f32_e32 v9, v9, v91
	v_add_f32_e32 v90, v90, v92
	v_mul_f32_e32 v93, 0x3a800000, v9
	v_mul_f32_e32 v91, 0x3a800000, v90
	v_fma_f32 v91, -v93, v93, v91
	v_max_f32_e32 v91, 0, v91
	v_add_f32_e32 v91, 0x358637bd, v91
	v_rsq_f32_e32 v94, v91
	v_mul_f32_e32 v91, 0.5, v91
	v_mul_f32_e32 v92, v94, v94
	v_fma_f32 v92, -v91, v92, 0.5
	v_fma_f32 v94, v94, v92, v94
	v_sub_f32_e32 v98, v98, v93
	v_sub_f32_e32 v99, v99, v93
	v_sub_f32_e32 v100, v100, v93
	v_sub_f32_e32 v101, v101, v93
	v_sub_f32_e32 v102, v102, v93
	v_sub_f32_e32 v103, v103, v93
	v_sub_f32_e32 v104, v104, v93
	v_sub_f32_e32 v105, v105, v93
	v_sub_f32_e32 v106, v106, v93
	v_sub_f32_e32 v107, v107, v93
	v_sub_f32_e32 v108, v108, v93
	v_sub_f32_e32 v109, v109, v93
	v_sub_f32_e32 v110, v110, v93
	v_sub_f32_e32 v111, v111, v93
	v_sub_f32_e32 v112, v112, v93
	v_sub_f32_e32 v113, v113, v93
	v_mul_f32_e32 v98, v94, v98
	v_mul_f32_e32 v99, v94, v99
	v_mul_f32_e32 v100, v94, v100
	v_mul_f32_e32 v101, v94, v101
	v_mul_f32_e32 v102, v94, v102
	v_mul_f32_e32 v103, v94, v103
	v_mul_f32_e32 v104, v94, v104
	v_mul_f32_e32 v105, v94, v105
	v_mul_f32_e32 v106, v94, v106
	v_mul_f32_e32 v107, v94, v107
	v_mul_f32_e32 v108, v94, v108
	v_mul_f32_e32 v109, v94, v109
	v_mul_f32_e32 v110, v94, v110
	v_mul_f32_e32 v111, v94, v111
	v_mul_f32_e32 v112, v94, v112
	v_mul_f32_e32 v113, v94, v113
	v_fma_f32 v98, v98, v10, v26
	v_fma_f32 v99, v99, v11, v27
	v_fma_f32 v100, v100, v12, v28
	v_fma_f32 v101, v101, v13, v29
	v_fma_f32 v102, v102, v14, v30
	v_fma_f32 v103, v103, v15, v31
	v_fma_f32 v104, v104, v16, v32
	v_fma_f32 v105, v105, v17, v33
	v_fma_f32 v106, v106, v18, v34
	v_fma_f32 v107, v107, v19, v35
	v_fma_f32 v108, v108, v20, v36
	v_fma_f32 v109, v109, v21, v37
	v_fma_f32 v110, v110, v22, v38
	v_fma_f32 v111, v111, v23, v39
	v_fma_f32 v112, v112, v24, v40
	v_fma_f32 v113, v113, v25, v41
	s_add_u32 s2, s8, 0x7000
	s_addc_u32 s3, s9, 0
	global_store_dwordx4 v0, v[98:101], s[2:3]
	global_store_dwordx4 v0, v[102:105], s[2:3] offset:1024
	global_store_dwordx4 v0, v[106:109], s[2:3] offset:2048
	global_store_dwordx4 v0, v[110:113], s[2:3] offset:3072
	s_waitcnt vmcnt(0)

; DI void ln_row_v(const Frame& F, f32x4 (&v)[4], float* xout, const float* g, const float* b, const float* sh, const float* sc, bf16_t* hout, const float* slab, const float* gres, float* stat = nullptr) {
;     ...
;     if (g) {
;         float s = 0.f, s2 = 0.f;
; #pragma unroll
;         for (int j = 0; j < 4; ++j) { s += (v[j][0] + v[j][1]) + (v[j][2] + v[j][3]); s2 += (v[j][0] * v[j][0] + v[j][1] * v[j][1]) + (v[j][2] * v[j][2] + v[j][3] * v[j][3]); }
;         wave_sum2(s, s2, F.lane);
;         const float mean = s * (1.f / D); const float rstd = 1.f / sqrtf(fmaxf(s2 * (1.f / D) - mean * mean, 0.f) + EPS);
;         if (stat && F.lane == 0) { f32x2 sv = {mean, rstd}; *(f32x2*)stat = sv; }
; #pragma unroll
;         for (int j = 0; j < 4; ++j) { const f32x4 gg = ((const f32x4*)g)[F.lane + 64 * j], bb = ((const f32x4*)b)[F.lane + 64 * j];
;             v[j] = (v[j] - mean) * rstd * gg + bb; if (xout) ((f32x4*)xout)[F.lane + 64 * j] = v[j]; }
; DI void ln_phase(const Frame& F, int which) {
;     const int gw = F.vcu * 8 + F.wave, NGW = F.G * 8; const int l = F.l;
;     const int nrows = (l == NL - 1) ? ML : MT;
;     bf16_t* H = (bf16_t*)(F.ws + WS_HB);
;     const float* g = pin(F, which == 0 ? I_LN1G : I_LN2G) + l * 1024; const float* b = pin(F, which == 0 ? I_LN1B : I_LN2B) + l * 1024;
;     const bool wh = !(which == 1 && l == NL - 1);
;     f32x4 vc[4], vn[4];
;     if (gw < nrows) ln_load(F, xrow_ptr(F, gw), vc);
;     for (int row = gw; row < nrows; row += NGW) {
;         if (row + NGW < nrows) ln_load(F, xrow_ptr(F, row + NGW), vn);
;         const int mr = row < ML ? (row >> 11) : 8;
;         const float* sh = which == 0 ? modp(F, l, mr, 3) : modp(F, l + 1 < NL ? l + 1 : l, mr, 0);
;         const float* sc = which == 0 ? modp(F, l, mr, 4) : modp(F, l + 1 < NL ? l + 1 : l, mr, 1);
;         const bool sl = (which == 1 && row >= ML);
;         const bool st_only = row < ML && !(which == 1 && l == NL - 1);
;         float* stp = st_only ? (float*)(F.ws + (which == 0 ? WS_ST1 : WS_ST2)) + 2 * (size_t)row : nullptr;
;         ln_row_v(F, vc, st_only ? nullptr : xrow_ptr(F, row), g, b, sh, sc, wh ? H + (size_t)row * D : nullptr, sl ? (const float*)(F.ws + WS_KN) + (size_t)(row - ML) * 1024 : nullptr, modp(F, l, mr, 5), stp);
.LBB0_663:
	s_and_b64 vcc, exec, s[2:3]
	s_cbranch_vccz .LBB0_671
	v_readlane_b32 s2, v255, 29
	s_lshl_b32 s2, s2, 3
	v_readlane_b32 s3, v255, 31
	s_add_i32 s16, s3, s2
	v_lshlrev_b32_e32 v0, 4, v186
	v_lshlrev_b32_e32 v1, 3, v186
	v_lshlrev_b32_e32 v96, 2, v186
	v_xor_b32_e32 v3, 4, v96
	v_xor_b32_e32 v4, 8, v96
	v_xor_b32_e32 v5, 16, v96
	v_xor_b32_e32 v6, 32, v96
	v_xor_b32_e32 v7, 64, v96
	v_xor_b32_e32 v8, 128, v96
	s_load_dwordx2 s[8:9], s[62:63], 0x0
	s_load_dwordx2 s[20:21], s[62:63], 0x10
	s_mov_b32 s22, 0
	s_lshl_b32 s2, s16, 12
	s_lshl_b32 s3, s16, 15
	s_waitcnt lgkmcnt(0)
	s_add_u32 s8, s8, s3
	s_addc_u32 s9, s9, 0
	s_add_u32 s20, s20, s2
	s_addc_u32 s21, s21, 0
	s_lshl_b32 s2, s16, 14
	s_add_u32 s10, s94, s2
	s_addc_u32 s11, s95, 0
	s_add_u32 s10, s10, 0x3e00000
	s_addc_u32 s11, s11, 0
	s_lshl_b32 s2, s16, 6
	s_add_u32 s12, s94, s2
	s_addc_u32 s13, s95, 0
	s_add_u32 s12, s12, 0x4c0000
	s_addc_u32 s13, s13, 0
	s_mov_b32 s3, 0
	s_mul_i32 s3, s3, 0x36000
	s_add_u32 s14, s94, s3
	s_addc_u32 s15, s95, 0
	s_add_u32 s14, s14, 0x100000
	s_addc_u32 s15, s15, 0
	s_add_u32 s18, s14, 0x1000
	s_addc_u32 s19, s15, 0
	s_add_u32 s2, s8, 0x0
	s_addc_u32 s3, s9, 0
	global_load_dwordx4 v[42:45], v0, s[2:3]
	global_load_dwordx4 v[46:49], v0, s[2:3] offset:1024
	global_load_dwordx4 v[50:53], v0, s[2:3] offset:2048
	global_load_dwordx4 v[54:57], v0, s[2:3] offset:3072
	s_lshr_b32 s23, s16, 8
	s_mul_i32 s23, s23, 0x6000
	s_add_u32 s2, s14, s23
	s_addc_u32 s3, s15, 0
	global_load_dwordx4 v[114:117], v0, s[2:3]
	global_load_dwordx4 v[118:121], v0, s[2:3] offset:1024
	global_load_dwordx4 v[122:125], v0, s[2:3] offset:2048
	global_load_dwordx4 v[126:129], v0, s[2:3] offset:3072
	s_add_u32 s2, s18, s23
	s_addc_u32 s3, s19, 0
	global_load_dwordx4 v[130:133], v0, s[2:3]
	global_load_dwordx4 v[134:137], v0, s[2:3] offset:1024
	global_load_dwordx4 v[138:141], v0, s[2:3] offset:2048
	global_load_dwordx4 v[142:145], v0, s[2:3] offset:3072
	s_add_u32 s2, s8, 0x1000
	s_addc_u32 s3, s9, 0
	global_load_dwordx4 v[58:61], v0, s[2:3]
	global_load_dwordx4 v[62:65], v0, s[2:3] offset:1024
	global_load_dwordx4 v[66:69], v0, s[2:3] offset:2048
	global_load_dwordx4 v[70:73], v0, s[2:3] offset:3072
	s_mov_b32 s23, 0x30000
	s_add_u32 s2, s14, s23
	s_addc_u32 s3, s15, 0
	global_load_dwordx4 v[146:149], v0, s[2:3]
	global_load_dwordx4 v[150:153], v0, s[2:3] offset:1024
	global_load_dwordx4 v[154:157], v0, s[2:3] offset:2048
	global_load_dwordx4 v[158:161], v0, s[2:3] offset:3072
	s_add_u32 s2, s18, s23
	s_addc_u32 s3, s19, 0
	global_load_dwordx4 v[162:165], v0, s[2:3]
	global_load_dwordx4 v[166:169], v0, s[2:3] offset:1024
	global_load_dwordx4 v[170:173], v0, s[2:3] offset:2048
	global_load_dwordx4 v[174:177], v0, s[2:3] offset:3072
	s_add_u32 s2, s8, 0x2000
	s_addc_u32 s3, s9, 0
	global_load_dwordx4 v[74:77], v0, s[2:3]
	global_load_dwordx4 v[78:81], v0, s[2:3] offset:1024
	global_load_dwordx4 v[82:85], v0, s[2:3] offset:2048
	global_load_dwordx4 v[86:89], v0, s[2:3] offset:3072
	s_add_u32 s2, s8, 0x3000
	s_addc_u32 s3, s9, 0
	global_load_dwordx4 v[98:101], v0, s[2:3]
	global_load_dwordx4 v[102:105], v0, s[2:3] offset:1024
	global_load_dwordx4 v[106:109], v0, s[2:3] offset:2048
	global_load_dwordx4 v[110:113], v0, s[2:3] offset:3072
	s_waitcnt vmcnt(28)
	v_add_f32_e32 v9, v42, v43
	v_add_f32_e32 v91, v44, v45
	v_mul_f32_e32 v90, v42, v42
	v_mul_f32_e32 v92, v43, v43
	v_add_f32_e32 v9, v9, v46
	v_add_f32_e32 v91, v91, v47
	v_add_f32_e32 v9, v9, v48
	v_add_f32_e32 v91, v91, v49
	v_add_f32_e32 v9, v9, v50
	v_add_f32_e32 v91, v91, v51
	v_add_f32_e32 v9, v9, v52
	v_add_f32_e32 v91, v91, v53
	v_add_f32_e32 v9, v9, v54
	v_add_f32_e32 v91, v91, v55
	v_add_f32_e32 v9, v9, v56
	v_add_f32_e32 v91, v91, v57
	v_fmac_f32_e32 v90, v44, v44
	v_fmac_f32_e32 v92, v45, v45
	v_fmac_f32_e32 v90, v46, v46
	v_fmac_f32_e32 v92, v47, v47
	v_fmac_f32_e32 v90, v48, v48
	v_fmac_f32_e32 v92, v49, v49
	v_fmac_f32_e32 v90, v50, v50
	v_fmac_f32_e32 v92, v51, v51
	v_fmac_f32_e32 v90, v52, v52
	v_fmac_f32_e32 v92, v53, v53
	v_fmac_f32_e32 v90, v54, v54
	v_fmac_f32_e32 v92, v55, v55
	v_fmac_f32_e32 v90, v56, v56
	v_fmac_f32_e32 v92, v57, v57
	v_add_f32_e32 v9, v9, v91
	v_add_f32_e32 v90, v90, v92
	ds_bpermute_b32 v91, v3, v9
	ds_bpermute_b32 v92, v3, v90
	s_waitcnt lgkmcnt(0)
	v_add_f32_e32 v9, v9, v91
	v_add_f32_e32 v90, v90, v92
	ds_bpermute_b32 v91, v4, v9
	ds_bpermute_b32 v92, v4, v90
	s_waitcnt lgkmcnt(0)
	v_add_f32_e32 v9, v9, v91
	v_add_f32_e32 v90, v90, v92
	ds_bpermute_b32 v91, v5, v9
	ds_bpermute_b32 v92, v5, v90
	s_waitcnt lgkmcnt(0)
	v_add_f32_e32 v9, v9, v91
	v_add_f32_e32 v90, v90, v92
	ds_bpermute_b32 v91, v6, v9
	ds_bpermute_b32 v92, v6, v90
	s_waitcnt lgkmcnt(0)
	v_add_f32_e32 v9, v9, v91
	v_add_f32_e32 v90, v90, v92
	ds_bpermute_b32 v91, v7, v9
	ds_bpermute_b32 v92, v7, v90
	s_waitcnt lgkmcnt(0)
	v_add_f32_e32 v9, v9, v91
	v_add_f32_e32 v90, v90, v92
	ds_bpermute_b32 v91, v8, v9
	ds_bpermute_b32 v92, v8, v90
	s_waitcnt lgkmcnt(0)
	v_add_f32_e32 v9, v9, v91
	v_add_f32_e32 v90, v90, v92
	v_mul_f32_e32 v93, 0x3a800000, v9
	v_mul_f32_e32 v91, 0x3a800000, v90
	v_fma_f32 v91, -v93, v93, v91
	v_max_f32_e32 v91, 0, v91
	v_add_f32_e32 v91, 0x358637bd, v91
	v_rsq_f32_e32 v94, v91
	v_mul_f32_e32 v91, 0.5, v91
	v_mul_f32_e32 v92, v94, v94
	v_fma_f32 v92, -v91, v92, 0.5
	v_fma_f32 v94, v94, v92, v94
	s_waitcnt vmcnt(20)
; DI unsigned pk2(float lo, float hi) { f32x2 v = {lo, hi}; bf16x2_t b = __builtin_convertvector(v, bf16x2_t); return __builtin_bit_cast(unsigned, b); }
; DI void ln_row_v(const Frame& F, f32x4 (&v)[4], float* xout, const float* g, const float* b, const float* sh, const float* sc, bf16_t* hout, const float* slab, const float* gres, float* stat = nullptr) {
;     ...
;     if (g) {
;         float s = 0.f, s2 = 0.f;
; #pragma unroll
;         for (int j = 0; j < 4; ++j) { s += (v[j][0] + v[j][1]) + (v[j][2] + v[j][3]); s2 += (v[j][0] * v[j][0] + v[j][1] * v[j][1]) + (v[j][2] * v[j][2] + v[j][3] * v[j][3]); }
;         wave_sum2(s, s2, F.lane);
;         const float mean = s * (1.f / D); const float rstd = 1.f / sqrtf(fmaxf(s2 * (1.f / D) - mean * mean, 0.f) + EPS);
;         if (stat && F.lane == 0) { f32x2 sv = {mean, rstd}; *(f32x2*)stat = sv; }
; #pragma unroll
;         for (int j = 0; j < 4; ++j) { const f32x4 gg = ((const f32x4*)g)[F.lane + 64 * j], bb = ((const f32x4*)b)[F.lane + 64 * j];
;             v[j] = (v[j] - mean) * rstd * gg + bb; if (xout) ((f32x4*)xout)[F.lane + 64 * j] = v[j]; }
;     ...
;     if (hout) {
;         float s = 0.f, s2 = 0.f;
; #pragma unroll
;         for (int j = 0; j < 4; ++j) { s += (v[j][0] + v[j][1]) + (v[j][2] + v[j][3]); s2 += (v[j][0] * v[j][0] + v[j][1] * v[j][1]) + (v[j][2] * v[j][2] + v[j][3] * v[j][3]); }
;         wave_sum2(s, s2, F.lane);
;         const float mean = s * (1.f / D); const float rstd = 1.f / sqrtf(fmaxf(s2 * (1.f / D) - mean * mean, 0.f) + EPS);
; #pragma unroll
;         for (int j = 0; j < 4; ++j) { const f32x4 hh = ((const f32x4*)sh)[F.lane + 64 * j], cc = ((const f32x4*)sc)[F.lane + 64 * j];
;             const f32x4 o = (v[j] - mean) * rstd * (cc + 1.f) + hh; u32x2 wv; wv.x = pk2(o[0], o[1]); wv.y = pk2(o[2], o[3]);
;             ((u32x2*)hout)[F.lane + 64 * j] = wv; }
;     }
	v_sub_f32_e32 v42, v42, v93
	v_sub_f32_e32 v43, v43, v93
	v_sub_f32_e32 v44, v44, v93
	v_sub_f32_e32 v45, v45, v93
	v_sub_f32_e32 v46, v46, v93
	v_sub_f32_e32 v47, v47, v93
	v_sub_f32_e32 v48, v48, v93
	v_sub_f32_e32 v49, v49, v93
	v_sub_f32_e32 v50, v50, v93
	v_sub_f32_e32 v51, v51, v93
	v_sub_f32_e32 v52, v52, v93
	v_sub_f32_e32 v53, v53, v93
	v_sub_f32_e32 v54, v54, v93
	v_sub_f32_e32 v55, v55, v93
	v_sub_f32_e32 v56, v56, v93
	v_sub_f32_e32 v57, v57, v93
	v_add_f32_e32 v130, 1.0, v130
	v_add_f32_e32 v131, 1.0, v131
	v_add_f32_e32 v132, 1.0, v132
	v_add_f32_e32 v133, 1.0, v133
	v_add_f32_e32 v134, 1.0, v134
	v_add_f32_e32 v135, 1.0, v135
	v_add_f32_e32 v136, 1.0, v136
	v_add_f32_e32 v137, 1.0, v137
	v_add_f32_e32 v138, 1.0, v138
	v_add_f32_e32 v139, 1.0, v139
	v_add_f32_e32 v140, 1.0, v140
	v_add_f32_e32 v141, 1.0, v141
	v_add_f32_e32 v142, 1.0, v142
	v_add_f32_e32 v143, 1.0, v143
	v_add_f32_e32 v144, 1.0, v144
	v_add_f32_e32 v145, 1.0, v145
	v_mul_f32_e32 v42, v94, v42
	v_mul_f32_e32 v43, v94, v43
	v_mul_f32_e32 v44, v94, v44
	v_mul_f32_e32 v45, v94, v45
	v_mul_f32_e32 v46, v94, v46
	v_mul_f32_e32 v47, v94, v47
	v_mul_f32_e32 v48, v94, v48
	v_mul_f32_e32 v49, v94, v49
	v_mul_f32_e32 v50, v94, v50
	v_mul_f32_e32 v51, v94, v51
	v_mul_f32_e32 v52, v94, v52
	v_mul_f32_e32 v53, v94, v53
	v_mul_f32_e32 v54, v94, v54
	v_mul_f32_e32 v55, v94, v55
	v_mul_f32_e32 v56, v94, v56
	v_mul_f32_e32 v57, v94, v57
	v_fma_f32 v42, v42, v130, v114
	v_fma_f32 v43, v43, v131, v115
	v_fma_f32 v44, v44, v132, v116
	v_fma_f32 v45, v45, v133, v117
	v_fma_f32 v46, v46, v134, v118
	v_fma_f32 v47, v47, v135, v119
	v_fma_f32 v48, v48, v136, v120
	v_fma_f32 v49, v49, v137, v121
	v_fma_f32 v50, v50, v138, v122
	v_fma_f32 v51, v51, v139, v123
	v_fma_f32 v52, v52, v140, v124
	v_fma_f32 v53, v53, v141, v125
	v_fma_f32 v54, v54, v142, v126
	v_fma_f32 v55, v55, v143, v127
	v_fma_f32 v56, v56, v144, v128
	v_fma_f32 v57, v57, v145, v129
	v_cvt_pk_bf16_f32 v190, v42, v43
	v_cvt_pk_bf16_f32 v191, v44, v45
	v_cvt_pk_bf16_f32 v192, v46, v47
	v_cvt_pk_bf16_f32 v193, v48, v49
	v_cvt_pk_bf16_f32 v194, v50, v51
	v_cvt_pk_bf16_f32 v195, v52, v53
	v_cvt_pk_bf16_f32 v196, v54, v55
	v_cvt_pk_bf16_f32 v197, v56, v57
	s_add_u32 s2, s10, 0x0
	s_addc_u32 s3, s11, 0
	global_store_dwordx2 v1, v[190:191], s[2:3]
	global_store_dwordx2 v1, v[192:193], s[2:3] offset:512
	global_store_dwordx2 v1, v[194:195], s[2:3] offset:1024
	global_store_dwordx2 v1, v[196:197], s[2:3] offset:1536
	s_add_u32 s2, s8, 0x4000
	s_addc_u32 s3, s9, 0
	global_load_dwordx4 v[42:45], v0, s[2:3]
	global_load_dwordx4 v[46:49], v0, s[2:3] offset:1024
	global_load_dwordx4 v[50:53], v0, s[2:3] offset:2048
	global_load_dwordx4 v[54:57], v0, s[2:3] offset:3072
	s_waitcnt vmcnt(24)
	v_add_f32_e32 v9, v58, v59
	v_add_f32_e32 v91, v60, v61
	v_mul_f32_e32 v90, v58, v58
	v_mul_f32_e32 v92, v59, v59
	v_add_f32_e32 v9, v9, v62
	v_add_f32_e32 v91, v91, v63
	v_add_f32_e32 v9, v9, v64
	v_add_f32_e32 v91, v91, v65
	v_add_f32_e32 v9, v9, v66
	v_add_f32_e32 v91, v91, v67
	v_add_f32_e32 v9, v9, v68
	v_add_f32_e32 v91, v91, v69
	v_add_f32_e32 v9, v9, v70
	v_add_f32_e32 v91, v91, v71
	v_add_f32_e32 v9, v9, v72
	v_add_f32_e32 v91, v91, v73
	v_fmac_f32_e32 v90, v60, v60
	v_fmac_f32_e32 v92, v61, v61
	v_fmac_f32_e32 v90, v62, v62
	v_fmac_f32_e32 v92, v63, v63
	v_fmac_f32_e32 v90, v64, v64
	v_fmac_f32_e32 v92, v65, v65
	v_fmac_f32_e32 v90, v66, v66
	v_fmac_f32_e32 v92, v67, v67
	v_fmac_f32_e32 v90, v68, v68
	v_fmac_f32_e32 v92, v69, v69
	v_fmac_f32_e32 v90, v70, v70
	v_fmac_f32_e32 v92, v71, v71
	v_fmac_f32_e32 v90, v72, v72
	v_fmac_f32_e32 v92, v73, v73
	v_add_f32_e32 v9, v9, v91
	v_add_f32_e32 v90, v90, v92
	ds_bpermute_b32 v91, v3, v9
	ds_bpermute_b32 v92, v3, v90
	s_waitcnt lgkmcnt(0)
	v_add_f32_e32 v9, v9, v91
	v_add_f32_e32 v90, v90, v92
	ds_bpermute_b32 v91, v4, v9
	ds_bpermute_b32 v92, v4, v90
	s_waitcnt lgkmcnt(0)
	v_add_f32_e32 v9, v9, v91
	v_add_f32_e32 v90, v90, v92
	ds_bpermute_b32 v91, v5, v9
	ds_bpermute_b32 v92, v5, v90
	s_waitcnt lgkmcnt(0)
	v_add_f32_e32 v9, v9, v91
	v_add_f32_e32 v90, v90, v92
	ds_bpermute_b32 v91, v6, v9
	ds_bpermute_b32 v92, v6, v90
	s_waitcnt lgkmcnt(0)
	v_add_f32_e32 v9, v9, v91
	v_add_f32_e32 v90, v90, v92
	ds_bpermute_b32 v91, v7, v9
	ds_bpermute_b32 v92, v7, v90
	s_waitcnt lgkmcnt(0)
	v_add_f32_e32 v9, v9, v91
	v_add_f32_e32 v90, v90, v92
	ds_bpermute_b32 v91, v8, v9
	ds_bpermute_b32 v92, v8, v90
	s_waitcnt lgkmcnt(0)
; DI unsigned pk2(float lo, float hi) { f32x2 v = {lo, hi}; bf16x2_t b = __builtin_convertvector(v, bf16x2_t); return __builtin_bit_cast(unsigned, b); }
; DI void ln_row_v(const Frame& F, f32x4 (&v)[4], float* xout, const float* g, const float* b, const float* sh, const float* sc, bf16_t* hout, const float* slab, const float* gres, float* stat = nullptr) {
;     ...
;         float s = 0.f, s2 = 0.f;
; #pragma unroll
;         for (int j = 0; j < 4; ++j) { s += (v[j][0] + v[j][1]) + (v[j][2] + v[j][3]); s2 += (v[j][0] * v[j][0] + v[j][1] * v[j][1]) + (v[j][2] * v[j][2] + v[j][3] * v[j][3]); }
;         wave_sum2(s, s2, F.lane);
;         const float mean = s * (1.f / D); const float rstd = 1.f / sqrtf(fmaxf(s2 * (1.f / D) - mean * mean, 0.f) + EPS);
; #pragma unroll
;         for (int j = 0; j < 4; ++j) { const f32x4 hh = ((const f32x4*)sh)[F.lane + 64 * j], cc = ((const f32x4*)sc)[F.lane + 64 * j];
;             const f32x4 o = (v[j] - mean) * rstd * (cc + 1.f) + hh; u32x2 wv; wv.x = pk2(o[0], o[1]); wv.y = pk2(o[2], o[3]);
;             ((u32x2*)hout)[F.lane + 64 * j] = wv; }
	v_add_f32_e32 v9, v9, v91
	v_add_f32_e32 v90, v90, v92
	v_mul_f32_e32 v93, 0x3a800000, v9
	v_mul_f32_e32 v91, 0x3a800000, v90
	v_fma_f32 v91, -v93, v93, v91
	v_max_f32_e32 v91, 0, v91
	v_add_f32_e32 v91, 0x358637bd, v91
	v_rsq_f32_e32 v94, v91
	v_mul_f32_e32 v91, 0.5, v91
	v_mul_f32_e32 v92, v94, v94
	v_fma_f32 v92, -v91, v92, 0.5
	v_fma_f32 v94, v94, v92, v94
	v_sub_f32_e32 v58, v58, v93
	v_sub_f32_e32 v59, v59, v93
	v_sub_f32_e32 v60, v60, v93
	v_sub_f32_e32 v61, v61, v93
	v_sub_f32_e32 v62, v62, v93
	v_sub_f32_e32 v63, v63, v93
	v_sub_f32_e32 v64, v64, v93
	v_sub_f32_e32 v65, v65, v93
	v_sub_f32_e32 v66, v66, v93
	v_sub_f32_e32 v67, v67, v93
	v_sub_f32_e32 v68, v68, v93
	v_sub_f32_e32 v69, v69, v93
	v_sub_f32_e32 v70, v70, v93
	v_sub_f32_e32 v71, v71, v93
	v_sub_f32_e32 v72, v72, v93
	v_sub_f32_e32 v73, v73, v93
	v_mul_f32_e32 v58, v94, v58
	v_mul_f32_e32 v59, v94, v59
	v_mul_f32_e32 v60, v94, v60
	v_mul_f32_e32 v61, v94, v61
	v_mul_f32_e32 v62, v94, v62
	v_mul_f32_e32 v63, v94, v63
	v_mul_f32_e32 v64, v94, v64
	v_mul_f32_e32 v65, v94, v65
	v_mul_f32_e32 v66, v94, v66
	v_mul_f32_e32 v67, v94, v67
	v_mul_f32_e32 v68, v94, v68
	v_mul_f32_e32 v69, v94, v69
	v_mul_f32_e32 v70, v94, v70
	v_mul_f32_e32 v71, v94, v71
	v_mul_f32_e32 v72, v94, v72
	v_mul_f32_e32 v73, v94, v73
	v_fma_f32 v58, v58, v130, v114
	v_fma_f32 v59, v59, v131, v115
	v_fma_f32 v60, v60, v132, v116
	v_fma_f32 v61, v61, v133, v117
	v_fma_f32 v62, v62, v134, v118
	v_fma_f32 v63, v63, v135, v119
	v_fma_f32 v64, v64, v136, v120
	v_fma_f32 v65, v65, v137, v121
	v_fma_f32 v66, v66, v138, v122
	v_fma_f32 v67, v67, v139, v123
	v_fma_f32 v68, v68, v140, v124
	v_fma_f32 v69, v69, v141, v125
	v_fma_f32 v70, v70, v142, v126
	v_fma_f32 v71, v71, v143, v127
	v_fma_f32 v72, v72, v144, v128
	v_fma_f32 v73, v73, v145, v129
	v_cvt_pk_bf16_f32 v190, v58, v59
	v_cvt_pk_bf16_f32 v191, v60, v61
	v_cvt_pk_bf16_f32 v192, v62, v63
	v_cvt_pk_bf16_f32 v193, v64, v65
	v_cvt_pk_bf16_f32 v194, v66, v67
	v_cvt_pk_bf16_f32 v195, v68, v69
	v_cvt_pk_bf16_f32 v196, v70, v71
	v_cvt_pk_bf16_f32 v197, v72, v73
	s_add_u32 s2, s10, 0x800
	s_addc_u32 s3, s11, 0
	global_store_dwordx2 v1, v[190:191], s[2:3]
	global_store_dwordx2 v1, v[192:193], s[2:3] offset:512
	global_store_dwordx2 v1, v[194:195], s[2:3] offset:1024
	global_store_dwordx2 v1, v[196:197], s[2:3] offset:1536
	s_add_u32 s2, s8, 0x5000
	s_addc_u32 s3, s9, 0
	global_load_dwordx4 v[58:61], v0, s[2:3]
	global_load_dwordx4 v[62:65], v0, s[2:3] offset:1024
	global_load_dwordx4 v[66:69], v0, s[2:3] offset:2048
	global_load_dwordx4 v[70:73], v0, s[2:3] offset:3072
	s_waitcnt vmcnt(20)
	v_add_f32_e32 v9, v74, v75
	v_add_f32_e32 v91, v76, v77
	v_mul_f32_e32 v90, v74, v74
	v_mul_f32_e32 v92, v75, v75
	v_add_f32_e32 v9, v9, v78
	v_add_f32_e32 v91, v91, v79
	v_add_f32_e32 v9, v9, v80
	v_add_f32_e32 v91, v91, v81
	v_add_f32_e32 v9, v9, v82
	v_add_f32_e32 v91, v91, v83
	v_add_f32_e32 v9, v9, v84
	v_add_f32_e32 v91, v91, v85
	v_add_f32_e32 v9, v9, v86
	v_add_f32_e32 v91, v91, v87
	v_add_f32_e32 v9, v9, v88
	v_add_f32_e32 v91, v91, v89
	v_fmac_f32_e32 v90, v76, v76
	v_fmac_f32_e32 v92, v77, v77
	v_fmac_f32_e32 v90, v78, v78
	v_fmac_f32_e32 v92, v79, v79
	v_fmac_f32_e32 v90, v80, v80
	v_fmac_f32_e32 v92, v81, v81
	v_fmac_f32_e32 v90, v82, v82
	v_fmac_f32_e32 v92, v83, v83
	v_fmac_f32_e32 v90, v84, v84
	v_fmac_f32_e32 v92, v85, v85
	v_fmac_f32_e32 v90, v86, v86
	v_fmac_f32_e32 v92, v87, v87
	v_fmac_f32_e32 v90, v88, v88
	v_fmac_f32_e32 v92, v89, v89
	v_add_f32_e32 v9, v9, v91
	v_add_f32_e32 v90, v90, v92
	ds_bpermute_b32 v91, v3, v9
	ds_bpermute_b32 v92, v3, v90
	s_waitcnt lgkmcnt(0)
	v_add_f32_e32 v9, v9, v91
	v_add_f32_e32 v90, v90, v92
	ds_bpermute_b32 v91, v4, v9
	ds_bpermute_b32 v92, v4, v90
	s_waitcnt lgkmcnt(0)
	v_add_f32_e32 v9, v9, v91
	v_add_f32_e32 v90, v90, v92
	ds_bpermute_b32 v91, v5, v9
	ds_bpermute_b32 v92, v5, v90
	s_waitcnt lgkmcnt(0)
	v_add_f32_e32 v9, v9, v91
	v_add_f32_e32 v90, v90, v92
	ds_bpermute_b32 v91, v6, v9
	ds_bpermute_b32 v92, v6, v90
	s_waitcnt lgkmcnt(0)
	v_add_f32_e32 v9, v9, v91
	v_add_f32_e32 v90, v90, v92
	ds_bpermute_b32 v91, v7, v9
	ds_bpermute_b32 v92, v7, v90
	s_waitcnt lgkmcnt(0)
	v_add_f32_e32 v9, v9, v91
	v_add_f32_e32 v90, v90, v92
	ds_bpermute_b32 v91, v8, v9
	ds_bpermute_b32 v92, v8, v90
	s_waitcnt lgkmcnt(0)
	v_add_f32_e32 v9, v9, v91
	v_add_f32_e32 v90, v90, v92
	v_mul_f32_e32 v93, 0x3a800000, v9
	v_mul_f32_e32 v91, 0x3a800000, v90
	v_fma_f32 v91, -v93, v93, v91
	v_max_f32_e32 v91, 0, v91
	v_add_f32_e32 v91, 0x358637bd, v91
	v_rsq_f32_e32 v94, v91
	v_mul_f32_e32 v91, 0.5, v91
	v_mul_f32_e32 v92, v94, v94
	v_fma_f32 v92, -v91, v92, 0.5
	v_fma_f32 v94, v94, v92, v94
	v_sub_f32_e32 v74, v74, v93
	v_sub_f32_e32 v75, v75, v93
	v_sub_f32_e32 v76, v76, v93
	v_sub_f32_e32 v77, v77, v93
	v_sub_f32_e32 v78, v78, v93
	v_sub_f32_e32 v79, v79, v93
	v_sub_f32_e32 v80, v80, v93
	v_sub_f32_e32 v81, v81, v93
	v_sub_f32_e32 v82, v82, v93
	v_sub_f32_e32 v83, v83, v93
	v_sub_f32_e32 v84, v84, v93
	v_sub_f32_e32 v85, v85, v93
	v_sub_f32_e32 v86, v86, v93
	v_sub_f32_e32 v87, v87, v93
	v_sub_f32_e32 v88, v88, v93
	v_sub_f32_e32 v89, v89, v93
	v_mul_f32_e32 v74, v94, v74
	v_mul_f32_e32 v75, v94, v75
	v_mul_f32_e32 v76, v94, v76
	v_mul_f32_e32 v77, v94, v77
	v_mul_f32_e32 v78, v94, v78
	v_mul_f32_e32 v79, v94, v79
	v_mul_f32_e32 v80, v94, v80
	v_mul_f32_e32 v81, v94, v81
	v_mul_f32_e32 v82, v94, v82
	v_mul_f32_e32 v83, v94, v83
	v_mul_f32_e32 v84, v94, v84
	v_mul_f32_e32 v85, v94, v85
	v_mul_f32_e32 v86, v94, v86
	v_mul_f32_e32 v87, v94, v87
	v_mul_f32_e32 v88, v94, v88
	v_mul_f32_e32 v89, v94, v89
	v_fma_f32 v74, v74, v130, v114
	v_fma_f32 v75, v75, v131, v115
	v_fma_f32 v76, v76, v132, v116
	v_fma_f32 v77, v77, v133, v117
	v_fma_f32 v78, v78, v134, v118
	v_fma_f32 v79, v79, v135, v119
	v_fma_f32 v80, v80, v136, v120
	v_fma_f32 v81, v81, v137, v121
	v_fma_f32 v82, v82, v138, v122
	v_fma_f32 v83, v83, v139, v123
	v_fma_f32 v84, v84, v140, v124
	v_fma_f32 v85, v85, v141, v125
	v_fma_f32 v86, v86, v142, v126
	v_fma_f32 v87, v87, v143, v127
	v_fma_f32 v88, v88, v144, v128
	v_fma_f32 v89, v89, v145, v129
	v_cvt_pk_bf16_f32 v190, v74, v75
	v_cvt_pk_bf16_f32 v191, v76, v77
	v_cvt_pk_bf16_f32 v192, v78, v79
	v_cvt_pk_bf16_f32 v193, v80, v81
	v_cvt_pk_bf16_f32 v194, v82, v83
	v_cvt_pk_bf16_f32 v195, v84, v85
	v_cvt_pk_bf16_f32 v196, v86, v87
	v_cvt_pk_bf16_f32 v197, v88, v89
	s_add_u32 s2, s10, 0x1000
	s_addc_u32 s3, s11, 0
	global_store_dwordx2 v1, v[190:191], s[2:3]
	global_store_dwordx2 v1, v[192:193], s[2:3] offset:512
	global_store_dwordx2 v1, v[194:195], s[2:3] offset:1024
	global_store_dwordx2 v1, v[196:197], s[2:3] offset:1536
	s_add_u32 s2, s8, 0x6000
	s_addc_u32 s3, s9, 0
	global_load_dwordx4 v[74:77], v0, s[2:3]
	global_load_dwordx4 v[78:81], v0, s[2:3] offset:1024
	global_load_dwordx4 v[82:85], v0, s[2:3] offset:2048
	global_load_dwordx4 v[86:89], v0, s[2:3] offset:3072
	s_waitcnt vmcnt(24)
; DI unsigned pk2(float lo, float hi) { f32x2 v = {lo, hi}; bf16x2_t b = __builtin_convertvector(v, bf16x2_t); return __builtin_bit_cast(unsigned, b); }
; DI void ln_row_v(const Frame& F, f32x4 (&v)[4], float* xout, const float* g, const float* b, const float* sh, const float* sc, bf16_t* hout, const float* slab, const float* gres, float* stat = nullptr) {
;     ...
;         float s = 0.f, s2 = 0.f;
; #pragma unroll
;         for (int j = 0; j < 4; ++j) { s += (v[j][0] + v[j][1]) + (v[j][2] + v[j][3]); s2 += (v[j][0] * v[j][0] + v[j][1] * v[j][1]) + (v[j][2] * v[j][2] + v[j][3] * v[j][3]); }
;         wave_sum2(s, s2, F.lane);
;         const float mean = s * (1.f / D); const float rstd = 1.f / sqrtf(fmaxf(s2 * (1.f / D) - mean * mean, 0.f) + EPS);
; #pragma unroll
;         for (int j = 0; j < 4; ++j) { const f32x4 hh = ((const f32x4*)sh)[F.lane + 64 * j], cc = ((const f32x4*)sc)[F.lane + 64 * j];
;             const f32x4 o = (v[j] - mean) * rstd * (cc + 1.f) + hh; u32x2 wv; wv.x = pk2(o[0], o[1]); wv.y = pk2(o[2], o[3]);
;             ((u32x2*)hout)[F.lane + 64 * j] = wv; }
	v_add_f32_e32 v9, v98, v99
	v_add_f32_e32 v91, v100, v101
	v_mul_f32_e32 v90, v98, v98
	v_mul_f32_e32 v92, v99, v99
	v_add_f32_e32 v9, v9, v102
	v_add_f32_e32 v91, v91, v103
	v_add_f32_e32 v9, v9, v104
	v_add_f32_e32 v91, v91, v105
	v_add_f32_e32 v9, v9, v106
	v_add_f32_e32 v91, v91, v107
	v_add_f32_e32 v9, v9, v108
	v_add_f32_e32 v91, v91, v109
	v_add_f32_e32 v9, v9, v110
	v_add_f32_e32 v91, v91, v111
	v_add_f32_e32 v9, v9, v112
	v_add_f32_e32 v91, v91, v113
	v_fmac_f32_e32 v90, v100, v100
	v_fmac_f32_e32 v92, v101, v101
	v_fmac_f32_e32 v90, v102, v102
	v_fmac_f32_e32 v92, v103, v103
	v_fmac_f32_e32 v90, v104, v104
	v_fmac_f32_e32 v92, v105, v105
	v_fmac_f32_e32 v90, v106, v106
	v_fmac_f32_e32 v92, v107, v107
	v_fmac_f32_e32 v90, v108, v108
	v_fmac_f32_e32 v92, v109, v109
	v_fmac_f32_e32 v90, v110, v110
	v_fmac_f32_e32 v92, v111, v111
	v_fmac_f32_e32 v90, v112, v112
	v_fmac_f32_e32 v92, v113, v113
	v_add_f32_e32 v9, v9, v91
	v_add_f32_e32 v90, v90, v92
	ds_bpermute_b32 v91, v3, v9
	ds_bpermute_b32 v92, v3, v90
	s_waitcnt lgkmcnt(0)
	v_add_f32_e32 v9, v9, v91
	v_add_f32_e32 v90, v90, v92
	ds_bpermute_b32 v91, v4, v9
	ds_bpermute_b32 v92, v4, v90
	s_waitcnt lgkmcnt(0)
	v_add_f32_e32 v9, v9, v91
	v_add_f32_e32 v90, v90, v92
	ds_bpermute_b32 v91, v5, v9
	ds_bpermute_b32 v92, v5, v90
	s_waitcnt lgkmcnt(0)
	v_add_f32_e32 v9, v9, v91
	v_add_f32_e32 v90, v90, v92
	ds_bpermute_b32 v91, v6, v9
	ds_bpermute_b32 v92, v6, v90
	s_waitcnt lgkmcnt(0)
	v_add_f32_e32 v9, v9, v91
	v_add_f32_e32 v90, v90, v92
	ds_bpermute_b32 v91, v7, v9
	ds_bpermute_b32 v92, v7, v90
	s_waitcnt lgkmcnt(0)
	v_add_f32_e32 v9, v9, v91
	v_add_f32_e32 v90, v90, v92
	ds_bpermute_b32 v91, v8, v9
	ds_bpermute_b32 v92, v8, v90
	s_waitcnt lgkmcnt(0)
	v_add_f32_e32 v9, v9, v91
	v_add_f32_e32 v90, v90, v92
	v_mul_f32_e32 v93, 0x3a800000, v9
	v_mul_f32_e32 v91, 0x3a800000, v90
	v_fma_f32 v91, -v93, v93, v91
	v_max_f32_e32 v91, 0, v91
	v_add_f32_e32 v91, 0x358637bd, v91
	v_rsq_f32_e32 v94, v91
	v_mul_f32_e32 v91, 0.5, v91
	v_mul_f32_e32 v92, v94, v94
	v_fma_f32 v92, -v91, v92, 0.5
	v_fma_f32 v94, v94, v92, v94
	v_sub_f32_e32 v98, v98, v93
	v_sub_f32_e32 v99, v99, v93
	v_sub_f32_e32 v100, v100, v93
	v_sub_f32_e32 v101, v101, v93
	v_sub_f32_e32 v102, v102, v93
	v_sub_f32_e32 v103, v103, v93
	v_sub_f32_e32 v104, v104, v93
	v_sub_f32_e32 v105, v105, v93
	v_sub_f32_e32 v106, v106, v93
	v_sub_f32_e32 v107, v107, v93
	v_sub_f32_e32 v108, v108, v93
	v_sub_f32_e32 v109, v109, v93
	v_sub_f32_e32 v110, v110, v93
	v_sub_f32_e32 v111, v111, v93
	v_sub_f32_e32 v112, v112, v93
	v_sub_f32_e32 v113, v113, v93
	v_mul_f32_e32 v98, v94, v98
	v_mul_f32_e32 v99, v94, v99
	v_mul_f32_e32 v100, v94, v100
	v_mul_f32_e32 v101, v94, v101
	v_mul_f32_e32 v102, v94, v102
	v_mul_f32_e32 v103, v94, v103
	v_mul_f32_e32 v104, v94, v104
	v_mul_f32_e32 v105, v94, v105
	v_mul_f32_e32 v106, v94, v106
	v_mul_f32_e32 v107, v94, v107
	v_mul_f32_e32 v108, v94, v108
	v_mul_f32_e32 v109, v94, v109
	v_mul_f32_e32 v110, v94, v110
	v_mul_f32_e32 v111, v94, v111
	v_mul_f32_e32 v112, v94, v112
	v_mul_f32_e32 v113, v94, v113
	v_fma_f32 v98, v98, v130, v114
	v_fma_f32 v99, v99, v131, v115
	v_fma_f32 v100, v100, v132, v116
	v_fma_f32 v101, v101, v133, v117
	v_fma_f32 v102, v102, v134, v118
	v_fma_f32 v103, v103, v135, v119
	v_fma_f32 v104, v104, v136, v120
	v_fma_f32 v105, v105, v137, v121
	v_fma_f32 v106, v106, v138, v122
	v_fma_f32 v107, v107, v139, v123
	v_fma_f32 v108, v108, v140, v124
	v_fma_f32 v109, v109, v141, v125
	v_fma_f32 v110, v110, v142, v126
	v_fma_f32 v111, v111, v143, v127
	v_fma_f32 v112, v112, v144, v128
	v_fma_f32 v113, v113, v145, v129
	v_cvt_pk_bf16_f32 v190, v98, v99
	v_cvt_pk_bf16_f32 v191, v100, v101
	v_cvt_pk_bf16_f32 v192, v102, v103
	v_cvt_pk_bf16_f32 v193, v104, v105
	v_cvt_pk_bf16_f32 v194, v106, v107
	v_cvt_pk_bf16_f32 v195, v108, v109
	v_cvt_pk_bf16_f32 v196, v110, v111
	v_cvt_pk_bf16_f32 v197, v112, v113
	s_add_u32 s2, s10, 0x1800
	s_addc_u32 s3, s11, 0
	global_store_dwordx2 v1, v[190:191], s[2:3]
	global_store_dwordx2 v1, v[192:193], s[2:3] offset:512
	global_store_dwordx2 v1, v[194:195], s[2:3] offset:1024
	global_store_dwordx2 v1, v[196:197], s[2:3] offset:1536
	s_add_u32 s2, s8, 0x7000
	s_addc_u32 s3, s9, 0
	global_load_dwordx4 v[98:101], v0, s[2:3]
	global_load_dwordx4 v[102:105], v0, s[2:3] offset:1024
	global_load_dwordx4 v[106:109], v0, s[2:3] offset:2048
	global_load_dwordx4 v[110:113], v0, s[2:3] offset:3072
	s_waitcnt vmcnt(24)
	v_add_f32_e32 v9, v42, v43
	v_add_f32_e32 v91, v44, v45
	v_mul_f32_e32 v90, v42, v42
	v_mul_f32_e32 v92, v43, v43
	v_add_f32_e32 v9, v9, v46
	v_add_f32_e32 v91, v91, v47
	v_add_f32_e32 v9, v9, v48
	v_add_f32_e32 v91, v91, v49
	v_add_f32_e32 v9, v9, v50
	v_add_f32_e32 v91, v91, v51
	v_add_f32_e32 v9, v9, v52
	v_add_f32_e32 v91, v91, v53
	v_add_f32_e32 v9, v9, v54
	v_add_f32_e32 v91, v91, v55
	v_add_f32_e32 v9, v9, v56
	v_add_f32_e32 v91, v91, v57
	v_fmac_f32_e32 v90, v44, v44
	v_fmac_f32_e32 v92, v45, v45
	v_fmac_f32_e32 v90, v46, v46
	v_fmac_f32_e32 v92, v47, v47
	v_fmac_f32_e32 v90, v48, v48
	v_fmac_f32_e32 v92, v49, v49
	v_fmac_f32_e32 v90, v50, v50
	v_fmac_f32_e32 v92, v51, v51
	v_fmac_f32_e32 v90, v52, v52
	v_fmac_f32_e32 v92, v53, v53
	v_fmac_f32_e32 v90, v54, v54
	v_fmac_f32_e32 v92, v55, v55
	v_fmac_f32_e32 v90, v56, v56
	v_fmac_f32_e32 v92, v57, v57
	v_add_f32_e32 v9, v9, v91
	v_add_f32_e32 v90, v90, v92
	ds_bpermute_b32 v91, v3, v9
	ds_bpermute_b32 v92, v3, v90
	s_waitcnt lgkmcnt(0)
	v_add_f32_e32 v9, v9, v91
	v_add_f32_e32 v90, v90, v92
	ds_bpermute_b32 v91, v4, v9
	ds_bpermute_b32 v92, v4, v90
	s_waitcnt lgkmcnt(0)
; DI unsigned pk2(float lo, float hi) { f32x2 v = {lo, hi}; bf16x2_t b = __builtin_convertvector(v, bf16x2_t); return __builtin_bit_cast(unsigned, b); }
; DI const float* modp(const Frame& F, int l, int mr, int which) { return (const float*)(F.ws + WS_MOD) + ((size_t)(l * 9 + mr) * 6 + which) * 1024; }
; DI void ln_row_v(const Frame& F, f32x4 (&v)[4], float* xout, const float* g, const float* b, const float* sh, const float* sc, bf16_t* hout, const float* slab, const float* gres, float* stat = nullptr) {
;     ...
;         float s = 0.f, s2 = 0.f;
; #pragma unroll
;         for (int j = 0; j < 4; ++j) { s += (v[j][0] + v[j][1]) + (v[j][2] + v[j][3]); s2 += (v[j][0] * v[j][0] + v[j][1] * v[j][1]) + (v[j][2] * v[j][2] + v[j][3] * v[j][3]); }
;         wave_sum2(s, s2, F.lane);
;         const float mean = s * (1.f / D); const float rstd = 1.f / sqrtf(fmaxf(s2 * (1.f / D) - mean * mean, 0.f) + EPS);
; #pragma unroll
;         for (int j = 0; j < 4; ++j) { const f32x4 hh = ((const f32x4*)sh)[F.lane + 64 * j], cc = ((const f32x4*)sc)[F.lane + 64 * j];
;             const f32x4 o = (v[j] - mean) * rstd * (cc + 1.f) + hh; u32x2 wv; wv.x = pk2(o[0], o[1]); wv.y = pk2(o[2], o[3]);
;             ((u32x2*)hout)[F.lane + 64 * j] = wv; }
; DI void prologue_b(const Frame& F) {
;     ...
;     for (int row = gw; row < MT; row += NGW) {
;         const int mr = row < ML ? (row >> 11) : 8;
;         const float* xi = row < ML ? pin(F, I_X) + (size_t)row * D : pin(F, I_CTX) + (size_t)(row - ML) * D;
;         ln_row(F, xi, nullptr, nullptr, nullptr, modp(F, 0, mr, 0), modp(F, 0, mr, 1), H + (size_t)row * D);
	v_add_f32_e32 v9, v9, v91
	v_add_f32_e32 v90, v90, v92
	ds_bpermute_b32 v91, v5, v9
	ds_bpermute_b32 v92, v5, v90
	s_waitcnt lgkmcnt(0)
	v_add_f32_e32 v9, v9, v91
	v_add_f32_e32 v90, v90, v92
	ds_bpermute_b32 v91, v6, v9
	ds_bpermute_b32 v92, v6, v90
	s_waitcnt lgkmcnt(0)
	v_add_f32_e32 v9, v9, v91
	v_add_f32_e32 v90, v90, v92
	ds_bpermute_b32 v91, v7, v9
	ds_bpermute_b32 v92, v7, v90
	s_waitcnt lgkmcnt(0)
	v_add_f32_e32 v9, v9, v91
	v_add_f32_e32 v90, v90, v92
	ds_bpermute_b32 v91, v8, v9
	ds_bpermute_b32 v92, v8, v90
	s_waitcnt lgkmcnt(0)
	v_add_f32_e32 v9, v9, v91
	v_add_f32_e32 v90, v90, v92
	v_mul_f32_e32 v93, 0x3a800000, v9
	v_mul_f32_e32 v91, 0x3a800000, v90
	v_fma_f32 v91, -v93, v93, v91
	v_max_f32_e32 v91, 0, v91
	v_add_f32_e32 v91, 0x358637bd, v91
	v_rsq_f32_e32 v94, v91
	v_mul_f32_e32 v91, 0.5, v91
	v_mul_f32_e32 v92, v94, v94
	v_fma_f32 v92, -v91, v92, 0.5
	v_fma_f32 v94, v94, v92, v94
	v_sub_f32_e32 v42, v42, v93
	v_sub_f32_e32 v43, v43, v93
	v_sub_f32_e32 v44, v44, v93
	v_sub_f32_e32 v45, v45, v93
	v_sub_f32_e32 v46, v46, v93
	v_sub_f32_e32 v47, v47, v93
	v_sub_f32_e32 v48, v48, v93
	v_sub_f32_e32 v49, v49, v93
	v_sub_f32_e32 v50, v50, v93
	v_sub_f32_e32 v51, v51, v93
	v_sub_f32_e32 v52, v52, v93
	v_sub_f32_e32 v53, v53, v93
	v_sub_f32_e32 v54, v54, v93
	v_sub_f32_e32 v55, v55, v93
	v_sub_f32_e32 v56, v56, v93
	v_sub_f32_e32 v57, v57, v93
	v_mul_f32_e32 v42, v94, v42
	v_mul_f32_e32 v43, v94, v43
	v_mul_f32_e32 v44, v94, v44
	v_mul_f32_e32 v45, v94, v45
	v_mul_f32_e32 v46, v94, v46
	v_mul_f32_e32 v47, v94, v47
	v_mul_f32_e32 v48, v94, v48
	v_mul_f32_e32 v49, v94, v49
	v_mul_f32_e32 v50, v94, v50
	v_mul_f32_e32 v51, v94, v51
	v_mul_f32_e32 v52, v94, v52
	v_mul_f32_e32 v53, v94, v53
	v_mul_f32_e32 v54, v94, v54
	v_mul_f32_e32 v55, v94, v55
	v_mul_f32_e32 v56, v94, v56
	v_mul_f32_e32 v57, v94, v57
	v_fma_f32 v42, v42, v130, v114
	v_fma_f32 v43, v43, v131, v115
	v_fma_f32 v44, v44, v132, v116
	v_fma_f32 v45, v45, v133, v117
	v_fma_f32 v46, v46, v134, v118
	v_fma_f32 v47, v47, v135, v119
	v_fma_f32 v48, v48, v136, v120
	v_fma_f32 v49, v49, v137, v121
	v_fma_f32 v50, v50, v138, v122
	v_fma_f32 v51, v51, v139, v123
	v_fma_f32 v52, v52, v140, v124
	v_fma_f32 v53, v53, v141, v125
	v_fma_f32 v54, v54, v142, v126
	v_fma_f32 v55, v55, v143, v127
	v_fma_f32 v56, v56, v144, v128
	v_fma_f32 v57, v57, v145, v129
	v_cvt_pk_bf16_f32 v190, v42, v43
	v_cvt_pk_bf16_f32 v191, v44, v45
	v_cvt_pk_bf16_f32 v192, v46, v47
	v_cvt_pk_bf16_f32 v193, v48, v49
	v_cvt_pk_bf16_f32 v194, v50, v51
	v_cvt_pk_bf16_f32 v195, v52, v53
	v_cvt_pk_bf16_f32 v196, v54, v55
	v_cvt_pk_bf16_f32 v197, v56, v57
	s_add_u32 s2, s10, 0x2000
	s_addc_u32 s3, s11, 0
	global_store_dwordx2 v1, v[190:191], s[2:3]
	global_store_dwordx2 v1, v[192:193], s[2:3] offset:512
	global_store_dwordx2 v1, v[194:195], s[2:3] offset:1024
	global_store_dwordx2 v1, v[196:197], s[2:3] offset:1536
	s_mov_b64 s[2:3], s[20:21]
	global_load_dwordx4 v[42:45], v0, s[2:3]
	global_load_dwordx4 v[46:49], v0, s[2:3] offset:1024
	global_load_dwordx4 v[50:53], v0, s[2:3] offset:2048
	global_load_dwordx4 v[54:57], v0, s[2:3] offset:3072
	s_waitcnt vmcnt(24)
	v_add_f32_e32 v9, v58, v59
	v_add_f32_e32 v91, v60, v61
	v_mul_f32_e32 v90, v58, v58
	v_mul_f32_e32 v92, v59, v59
	v_add_f32_e32 v9, v9, v62
	v_add_f32_e32 v91, v91, v63
	v_add_f32_e32 v9, v9, v64
	v_add_f32_e32 v91, v91, v65
	v_add_f32_e32 v9, v9, v66
	v_add_f32_e32 v91, v91, v67
	v_add_f32_e32 v9, v9, v68
	v_add_f32_e32 v91, v91, v69
	v_add_f32_e32 v9, v9, v70
	v_add_f32_e32 v91, v91, v71
	v_add_f32_e32 v9, v9, v72
	v_add_f32_e32 v91, v91, v73
	v_fmac_f32_e32 v90, v60, v60
	v_fmac_f32_e32 v92, v61, v61
	v_fmac_f32_e32 v90, v62, v62
	v_fmac_f32_e32 v92, v63, v63
	v_fmac_f32_e32 v90, v64, v64
	v_fmac_f32_e32 v92, v65, v65
	v_fmac_f32_e32 v90, v66, v66
	v_fmac_f32_e32 v92, v67, v67
	v_fmac_f32_e32 v90, v68, v68
	v_fmac_f32_e32 v92, v69, v69
	v_fmac_f32_e32 v90, v70, v70
	v_fmac_f32_e32 v92, v71, v71
	v_fmac_f32_e32 v90, v72, v72
	v_fmac_f32_e32 v92, v73, v73
	v_add_f32_e32 v9, v9, v91
	v_add_f32_e32 v90, v90, v92
	ds_bpermute_b32 v91, v3, v9
	ds_bpermute_b32 v92, v3, v90
	s_waitcnt lgkmcnt(0)
	v_add_f32_e32 v9, v9, v91
	v_add_f32_e32 v90, v90, v92
	ds_bpermute_b32 v91, v4, v9
	ds_bpermute_b32 v92, v4, v90
	s_waitcnt lgkmcnt(0)
	v_add_f32_e32 v9, v9, v91
	v_add_f32_e32 v90, v90, v92
	ds_bpermute_b32 v91, v5, v9
	ds_bpermute_b32 v92, v5, v90
	s_waitcnt lgkmcnt(0)
	v_add_f32_e32 v9, v9, v91
	v_add_f32_e32 v90, v90, v92
	ds_bpermute_b32 v91, v6, v9
	ds_bpermute_b32 v92, v6, v90
	s_waitcnt lgkmcnt(0)
	v_add_f32_e32 v9, v9, v91
	v_add_f32_e32 v90, v90, v92
	ds_bpermute_b32 v91, v7, v9
	ds_bpermute_b32 v92, v7, v90
	s_waitcnt lgkmcnt(0)
	v_add_f32_e32 v9, v9, v91
	v_add_f32_e32 v90, v90, v92
	ds_bpermute_b32 v91, v8, v9
	ds_bpermute_b32 v92, v8, v90
	s_waitcnt lgkmcnt(0)
; DI unsigned pk2(float lo, float hi) { f32x2 v = {lo, hi}; bf16x2_t b = __builtin_convertvector(v, bf16x2_t); return __builtin_bit_cast(unsigned, b); }
; DI void ln_row_v(const Frame& F, f32x4 (&v)[4], float* xout, const float* g, const float* b, const float* sh, const float* sc, bf16_t* hout, const float* slab, const float* gres, float* stat = nullptr) {
;     ...
;         float s = 0.f, s2 = 0.f;
; #pragma unroll
;         for (int j = 0; j < 4; ++j) { s += (v[j][0] + v[j][1]) + (v[j][2] + v[j][3]); s2 += (v[j][0] * v[j][0] + v[j][1] * v[j][1]) + (v[j][2] * v[j][2] + v[j][3] * v[j][3]); }
;         wave_sum2(s, s2, F.lane);
;         const float mean = s * (1.f / D); const float rstd = 1.f / sqrtf(fmaxf(s2 * (1.f / D) - mean * mean, 0.f) + EPS);
; #pragma unroll
;         for (int j = 0; j < 4; ++j) { const f32x4 hh = ((const f32x4*)sh)[F.lane + 64 * j], cc = ((const f32x4*)sc)[F.lane + 64 * j];
;             const f32x4 o = (v[j] - mean) * rstd * (cc + 1.f) + hh; u32x2 wv; wv.x = pk2(o[0], o[1]); wv.y = pk2(o[2], o[3]);
;             ((u32x2*)hout)[F.lane + 64 * j] = wv; }
	v_add_f32_e32 v9, v9, v91
	v_add_f32_e32 v90, v90, v92
	v_mul_f32_e32 v93, 0x3a800000, v9
	v_mul_f32_e32 v91, 0x3a800000, v90
	v_fma_f32 v91, -v93, v93, v91
	v_max_f32_e32 v91, 0, v91
	v_add_f32_e32 v91, 0x358637bd, v91
	v_rsq_f32_e32 v94, v91
	v_mul_f32_e32 v91, 0.5, v91
	v_mul_f32_e32 v92, v94, v94
	v_fma_f32 v92, -v91, v92, 0.5
	v_fma_f32 v94, v94, v92, v94
	v_sub_f32_e32 v58, v58, v93
	v_sub_f32_e32 v59, v59, v93
	v_sub_f32_e32 v60, v60, v93
	v_sub_f32_e32 v61, v61, v93
	v_sub_f32_e32 v62, v62, v93
	v_sub_f32_e32 v63, v63, v93
	v_sub_f32_e32 v64, v64, v93
	v_sub_f32_e32 v65, v65, v93
	v_sub_f32_e32 v66, v66, v93
	v_sub_f32_e32 v67, v67, v93
	v_sub_f32_e32 v68, v68, v93
	v_sub_f32_e32 v69, v69, v93
	v_sub_f32_e32 v70, v70, v93
	v_sub_f32_e32 v71, v71, v93
	v_sub_f32_e32 v72, v72, v93
	v_sub_f32_e32 v73, v73, v93
	v_mul_f32_e32 v58, v94, v58
	v_mul_f32_e32 v59, v94, v59
	v_mul_f32_e32 v60, v94, v60
	v_mul_f32_e32 v61, v94, v61
	v_mul_f32_e32 v62, v94, v62
	v_mul_f32_e32 v63, v94, v63
	v_mul_f32_e32 v64, v94, v64
	v_mul_f32_e32 v65, v94, v65
	v_mul_f32_e32 v66, v94, v66
	v_mul_f32_e32 v67, v94, v67
	v_mul_f32_e32 v68, v94, v68
	v_mul_f32_e32 v69, v94, v69
	v_mul_f32_e32 v70, v94, v70
	v_mul_f32_e32 v71, v94, v71
	v_mul_f32_e32 v72, v94, v72
	v_mul_f32_e32 v73, v94, v73
	v_fma_f32 v58, v58, v130, v114
	v_fma_f32 v59, v59, v131, v115
	v_fma_f32 v60, v60, v132, v116
	v_fma_f32 v61, v61, v133, v117
	v_fma_f32 v62, v62, v134, v118
	v_fma_f32 v63, v63, v135, v119
	v_fma_f32 v64, v64, v136, v120
	v_fma_f32 v65, v65, v137, v121
	v_fma_f32 v66, v66, v138, v122
	v_fma_f32 v67, v67, v139, v123
	v_fma_f32 v68, v68, v140, v124
	v_fma_f32 v69, v69, v141, v125
	v_fma_f32 v70, v70, v142, v126
	v_fma_f32 v71, v71, v143, v127
	v_fma_f32 v72, v72, v144, v128
	v_fma_f32 v73, v73, v145, v129
	v_cvt_pk_bf16_f32 v190, v58, v59
	v_cvt_pk_bf16_f32 v191, v60, v61
	v_cvt_pk_bf16_f32 v192, v62, v63
	v_cvt_pk_bf16_f32 v193, v64, v65
	v_cvt_pk_bf16_f32 v194, v66, v67
	v_cvt_pk_bf16_f32 v195, v68, v69
	v_cvt_pk_bf16_f32 v196, v70, v71
	v_cvt_pk_bf16_f32 v197, v72, v73
	s_add_u32 s2, s10, 0x2800
	s_addc_u32 s3, s11, 0
	global_store_dwordx2 v1, v[190:191], s[2:3]
	global_store_dwordx2 v1, v[192:193], s[2:3] offset:512
	global_store_dwordx2 v1, v[194:195], s[2:3] offset:1024
	global_store_dwordx2 v1, v[196:197], s[2:3] offset:1536
	s_waitcnt vmcnt(20)
	v_add_f32_e32 v9, v74, v75
	v_add_f32_e32 v91, v76, v77
	v_mul_f32_e32 v90, v74, v74
	v_mul_f32_e32 v92, v75, v75
	v_add_f32_e32 v9, v9, v78
	v_add_f32_e32 v91, v91, v79
	v_add_f32_e32 v9, v9, v80
	v_add_f32_e32 v91, v91, v81
	v_add_f32_e32 v9, v9, v82
	v_add_f32_e32 v91, v91, v83
	v_add_f32_e32 v9, v9, v84
	v_add_f32_e32 v91, v91, v85
	v_add_f32_e32 v9, v9, v86
	v_add_f32_e32 v91, v91, v87
	v_add_f32_e32 v9, v9, v88
	v_add_f32_e32 v91, v91, v89
	v_fmac_f32_e32 v90, v76, v76
	v_fmac_f32_e32 v92, v77, v77
	v_fmac_f32_e32 v90, v78, v78
	v_fmac_f32_e32 v92, v79, v79
	v_fmac_f32_e32 v90, v80, v80
	v_fmac_f32_e32 v92, v81, v81
	v_fmac_f32_e32 v90, v82, v82
	v_fmac_f32_e32 v92, v83, v83
	v_fmac_f32_e32 v90, v84, v84
	v_fmac_f32_e32 v92, v85, v85
	v_fmac_f32_e32 v90, v86, v86
	v_fmac_f32_e32 v92, v87, v87
	v_fmac_f32_e32 v90, v88, v88
	v_fmac_f32_e32 v92, v89, v89
	v_add_f32_e32 v9, v9, v91
	v_add_f32_e32 v90, v90, v92
	ds_bpermute_b32 v91, v3, v9
	ds_bpermute_b32 v92, v3, v90
	s_waitcnt lgkmcnt(0)
	v_add_f32_e32 v9, v9, v91
	v_add_f32_e32 v90, v90, v92
	ds_bpermute_b32 v91, v4, v9
	ds_bpermute_b32 v92, v4, v90
	s_waitcnt lgkmcnt(0)
	v_add_f32_e32 v9, v9, v91
	v_add_f32_e32 v90, v90, v92
	ds_bpermute_b32 v91, v5, v9
	ds_bpermute_b32 v92, v5, v90
	s_waitcnt lgkmcnt(0)
	v_add_f32_e32 v9, v9, v91
	v_add_f32_e32 v90, v90, v92
	ds_bpermute_b32 v91, v6, v9
	ds_bpermute_b32 v92, v6, v90
	s_waitcnt lgkmcnt(0)
	v_add_f32_e32 v9, v9, v91
	v_add_f32_e32 v90, v90, v92
	ds_bpermute_b32 v91, v7, v9
	ds_bpermute_b32 v92, v7, v90
	s_waitcnt lgkmcnt(0)
	v_add_f32_e32 v9, v9, v91
	v_add_f32_e32 v90, v90, v92
	ds_bpermute_b32 v91, v8, v9
	ds_bpermute_b32 v92, v8, v90
	s_waitcnt lgkmcnt(0)
	v_add_f32_e32 v9, v9, v91
	v_add_f32_e32 v90, v90, v92
	v_mul_f32_e32 v93, 0x3a800000, v9
	v_mul_f32_e32 v91, 0x3a800000, v90
	v_fma_f32 v91, -v93, v93, v91
	v_max_f32_e32 v91, 0, v91
	v_add_f32_e32 v91, 0x358637bd, v91
	v_rsq_f32_e32 v94, v91
	v_mul_f32_e32 v91, 0.5, v91
	v_mul_f32_e32 v92, v94, v94
	v_fma_f32 v92, -v91, v92, 0.5
	v_fma_f32 v94, v94, v92, v94
	v_sub_f32_e32 v74, v74, v93
	v_sub_f32_e32 v75, v75, v93
	v_sub_f32_e32 v76, v76, v93
	v_sub_f32_e32 v77, v77, v93
	v_sub_f32_e32 v78, v78, v93
	v_sub_f32_e32 v79, v79, v93
	v_sub_f32_e32 v80, v80, v93
	v_sub_f32_e32 v81, v81, v93
	v_sub_f32_e32 v82, v82, v93
	v_sub_f32_e32 v83, v83, v93
	v_sub_f32_e32 v84, v84, v93
	v_sub_f32_e32 v85, v85, v93
	v_sub_f32_e32 v86, v86, v93
	v_sub_f32_e32 v87, v87, v93
	v_sub_f32_e32 v88, v88, v93
	v_sub_f32_e32 v89, v89, v93
	v_mul_f32_e32 v74, v94, v74
	v_mul_f32_e32 v75, v94, v75
	v_mul_f32_e32 v76, v94, v76
	v_mul_f32_e32 v77, v94, v77
	v_mul_f32_e32 v78, v94, v78
	v_mul_f32_e32 v79, v94, v79
	v_mul_f32_e32 v80, v94, v80
	v_mul_f32_e32 v81, v94, v81
	v_mul_f32_e32 v82, v94, v82
	v_mul_f32_e32 v83, v94, v83
	v_mul_f32_e32 v84, v94, v84
	v_mul_f32_e32 v85, v94, v85
	v_mul_f32_e32 v86, v94, v86
	v_mul_f32_e32 v87, v94, v87
	v_mul_f32_e32 v88, v94, v88
	v_mul_f32_e32 v89, v94, v89
	v_fma_f32 v74, v74, v130, v114
	v_fma_f32 v75, v75, v131, v115
	v_fma_f32 v76, v76, v132, v116
	v_fma_f32 v77, v77, v133, v117
	v_fma_f32 v78, v78, v134, v118
	v_fma_f32 v79, v79, v135, v119
	v_fma_f32 v80, v80, v136, v120
	v_fma_f32 v81, v81, v137, v121
	v_fma_f32 v82, v82, v138, v122
	v_fma_f32 v83, v83, v139, v123
	v_fma_f32 v84, v84, v140, v124
	v_fma_f32 v85, v85, v141, v125
	v_fma_f32 v86, v86, v142, v126
	v_fma_f32 v87, v87, v143, v127
	v_fma_f32 v88, v88, v144, v128
	v_fma_f32 v89, v89, v145, v129
	v_cvt_pk_bf16_f32 v190, v74, v75
	v_cvt_pk_bf16_f32 v191, v76, v77
	v_cvt_pk_bf16_f32 v192, v78, v79
	v_cvt_pk_bf16_f32 v193, v80, v81
	v_cvt_pk_bf16_f32 v194, v82, v83
	v_cvt_pk_bf16_f32 v195, v84, v85
	v_cvt_pk_bf16_f32 v196, v86, v87
	v_cvt_pk_bf16_f32 v197, v88, v89
	s_add_u32 s2, s10, 0x3000
	s_addc_u32 s3, s11, 0
	global_store_dwordx2 v1, v[190:191], s[2:3]
	global_store_dwordx2 v1, v[192:193], s[2:3] offset:512
	global_store_dwordx2 v1, v[194:195], s[2:3] offset:1024
	global_store_dwordx2 v1, v[196:197], s[2:3] offset:1536
	s_waitcnt vmcnt(16)
; DI unsigned pk2(float lo, float hi) { f32x2 v = {lo, hi}; bf16x2_t b = __builtin_convertvector(v, bf16x2_t); return __builtin_bit_cast(unsigned, b); }
; DI void ln_row_v(const Frame& F, f32x4 (&v)[4], float* xout, const float* g, const float* b, const float* sh, const float* sc, bf16_t* hout, const float* slab, const float* gres, float* stat = nullptr) {
;     ...
;         float s = 0.f, s2 = 0.f;
; #pragma unroll
;         for (int j = 0; j < 4; ++j) { s += (v[j][0] + v[j][1]) + (v[j][2] + v[j][3]); s2 += (v[j][0] * v[j][0] + v[j][1] * v[j][1]) + (v[j][2] * v[j][2] + v[j][3] * v[j][3]); }
;         wave_sum2(s, s2, F.lane);
;         const float mean = s * (1.f / D); const float rstd = 1.f / sqrtf(fmaxf(s2 * (1.f / D) - mean * mean, 0.f) + EPS);
; #pragma unroll
;         for (int j = 0; j < 4; ++j) { const f32x4 hh = ((const f32x4*)sh)[F.lane + 64 * j], cc = ((const f32x4*)sc)[F.lane + 64 * j];
;             const f32x4 o = (v[j] - mean) * rstd * (cc + 1.f) + hh; u32x2 wv; wv.x = pk2(o[0], o[1]); wv.y = pk2(o[2], o[3]);
;             ((u32x2*)hout)[F.lane + 64 * j] = wv; }
	v_add_f32_e32 v9, v98, v99
	v_add_f32_e32 v91, v100, v101
	v_mul_f32_e32 v90, v98, v98
	v_mul_f32_e32 v92, v99, v99
	v_add_f32_e32 v9, v9, v102
	v_add_f32_e32 v91, v91, v103
	v_add_f32_e32 v9, v9, v104
	v_add_f32_e32 v91, v91, v105
	v_add_f32_e32 v9, v9, v106
	v_add_f32_e32 v91, v91, v107
	v_add_f32_e32 v9, v9, v108
	v_add_f32_e32 v91, v91, v109
	v_add_f32_e32 v9, v9, v110
	v_add_f32_e32 v91, v91, v111
	v_add_f32_e32 v9, v9, v112
	v_add_f32_e32 v91, v91, v113
	v_fmac_f32_e32 v90, v100, v100
	v_fmac_f32_e32 v92, v101, v101
	v_fmac_f32_e32 v90, v102, v102
	v_fmac_f32_e32 v92, v103, v103
	v_fmac_f32_e32 v90, v104, v104
	v_fmac_f32_e32 v92, v105, v105
	v_fmac_f32_e32 v90, v106, v106
	v_fmac_f32_e32 v92, v107, v107
	v_fmac_f32_e32 v90, v108, v108
	v_fmac_f32_e32 v92, v109, v109
	v_fmac_f32_e32 v90, v110, v110
	v_fmac_f32_e32 v92, v111, v111
	v_fmac_f32_e32 v90, v112, v112
	v_fmac_f32_e32 v92, v113, v113
	v_add_f32_e32 v9, v9, v91
	v_add_f32_e32 v90, v90, v92
	ds_bpermute_b32 v91, v3, v9
	ds_bpermute_b32 v92, v3, v90
	s_waitcnt lgkmcnt(0)
	v_add_f32_e32 v9, v9, v91
	v_add_f32_e32 v90, v90, v92
	ds_bpermute_b32 v91, v4, v9
	ds_bpermute_b32 v92, v4, v90
	s_waitcnt lgkmcnt(0)
	v_add_f32_e32 v9, v9, v91
	v_add_f32_e32 v90, v90, v92
	ds_bpermute_b32 v91, v5, v9
	ds_bpermute_b32 v92, v5, v90
	s_waitcnt lgkmcnt(0)
	v_add_f32_e32 v9, v9, v91
	v_add_f32_e32 v90, v90, v92
	ds_bpermute_b32 v91, v6, v9
	ds_bpermute_b32 v92, v6, v90
	s_waitcnt lgkmcnt(0)
	v_add_f32_e32 v9, v9, v91
	v_add_f32_e32 v90, v90, v92
	ds_bpermute_b32 v91, v7, v9
	ds_bpermute_b32 v92, v7, v90
	s_waitcnt lgkmcnt(0)
	v_add_f32_e32 v9, v9, v91
	v_add_f32_e32 v90, v90, v92
	ds_bpermute_b32 v91, v8, v9
	ds_bpermute_b32 v92, v8, v90
	s_waitcnt lgkmcnt(0)
	v_add_f32_e32 v9, v9, v91
	v_add_f32_e32 v90, v90, v92
	v_mul_f32_e32 v93, 0x3a800000, v9
	v_mul_f32_e32 v91, 0x3a800000, v90
	v_fma_f32 v91, -v93, v93, v91
	v_max_f32_e32 v91, 0, v91
	v_add_f32_e32 v91, 0x358637bd, v91
	v_rsq_f32_e32 v94, v91
	v_mul_f32_e32 v91, 0.5, v91
	v_mul_f32_e32 v92, v94, v94
	v_fma_f32 v92, -v91, v92, 0.5
	v_fma_f32 v94, v94, v92, v94
	v_sub_f32_e32 v98, v98, v93
	v_sub_f32_e32 v99, v99, v93
	v_sub_f32_e32 v100, v100, v93
	v_sub_f32_e32 v101, v101, v93
	v_sub_f32_e32 v102, v102, v93
	v_sub_f32_e32 v103, v103, v93
	v_sub_f32_e32 v104, v104, v93
	v_sub_f32_e32 v105, v105, v93
	v_sub_f32_e32 v106, v106, v93
	v_sub_f32_e32 v107, v107, v93
	v_sub_f32_e32 v108, v108, v93
	v_sub_f32_e32 v109, v109, v93
	v_sub_f32_e32 v110, v110, v93
	v_sub_f32_e32 v111, v111, v93
	v_sub_f32_e32 v112, v112, v93
	v_sub_f32_e32 v113, v113, v93
	v_mul_f32_e32 v98, v94, v98
	v_mul_f32_e32 v99, v94, v99
	v_mul_f32_e32 v100, v94, v100
	v_mul_f32_e32 v101, v94, v101
	v_mul_f32_e32 v102, v94, v102
	v_mul_f32_e32 v103, v94, v103
	v_mul_f32_e32 v104, v94, v104
	v_mul_f32_e32 v105, v94, v105
	v_mul_f32_e32 v106, v94, v106
	v_mul_f32_e32 v107, v94, v107
	v_mul_f32_e32 v108, v94, v108
	v_mul_f32_e32 v109, v94, v109
	v_mul_f32_e32 v110, v94, v110
	v_mul_f32_e32 v111, v94, v111
	v_mul_f32_e32 v112, v94, v112
	v_mul_f32_e32 v113, v94, v113
	v_fma_f32 v98, v98, v130, v114
	v_fma_f32 v99, v99, v131, v115
	v_fma_f32 v100, v100, v132, v116
	v_fma_f32 v101, v101, v133, v117
	v_fma_f32 v102, v102, v134, v118
	v_fma_f32 v103, v103, v135, v119
	v_fma_f32 v104, v104, v136, v120
	v_fma_f32 v105, v105, v137, v121
	v_fma_f32 v106, v106, v138, v122
	v_fma_f32 v107, v107, v139, v123
	v_fma_f32 v108, v108, v140, v124
	v_fma_f32 v109, v109, v141, v125
	v_fma_f32 v110, v110, v142, v126
	v_fma_f32 v111, v111, v143, v127
	v_fma_f32 v112, v112, v144, v128
	v_fma_f32 v113, v113, v145, v129
	v_cvt_pk_bf16_f32 v190, v98, v99
	v_cvt_pk_bf16_f32 v191, v100, v101
	v_cvt_pk_bf16_f32 v192, v102, v103
	v_cvt_pk_bf16_f32 v193, v104, v105
	v_cvt_pk_bf16_f32 v194, v106, v107
	v_cvt_pk_bf16_f32 v195, v108, v109
	v_cvt_pk_bf16_f32 v196, v110, v111
	v_cvt_pk_bf16_f32 v197, v112, v113
	s_add_u32 s2, s10, 0x3800
	s_addc_u32 s3, s11, 0
	global_store_dwordx2 v1, v[190:191], s[2:3]
	global_store_dwordx2 v1, v[192:193], s[2:3] offset:512
	global_store_dwordx2 v1, v[194:195], s[2:3] offset:1024
	global_store_dwordx2 v1, v[196:197], s[2:3] offset:1536
	s_waitcnt vmcnt(12)
	v_add_f32_e32 v9, v42, v43
	v_add_f32_e32 v91, v44, v45
	v_mul_f32_e32 v90, v42, v42
	v_mul_f32_e32 v92, v43, v43
	v_add_f32_e32 v9, v9, v46
	v_add_f32_e32 v91, v91, v47
	v_add_f32_e32 v9, v9, v48
	v_add_f32_e32 v91, v91, v49
	v_add_f32_e32 v9, v9, v50
	v_add_f32_e32 v91, v91, v51
	v_add_f32_e32 v9, v9, v52
	v_add_f32_e32 v91, v91, v53
	v_add_f32_e32 v9, v9, v54
	v_add_f32_e32 v91, v91, v55
	v_add_f32_e32 v9, v9, v56
	v_add_f32_e32 v91, v91, v57
	v_fmac_f32_e32 v90, v44, v44
	v_fmac_f32_e32 v92, v45, v45
	v_fmac_f32_e32 v90, v46, v46
	v_fmac_f32_e32 v92, v47, v47
	v_fmac_f32_e32 v90, v48, v48
	v_fmac_f32_e32 v92, v49, v49
	v_fmac_f32_e32 v90, v50, v50
	v_fmac_f32_e32 v92, v51, v51
	v_fmac_f32_e32 v90, v52, v52
	v_fmac_f32_e32 v92, v53, v53
	v_fmac_f32_e32 v90, v54, v54
	v_fmac_f32_e32 v92, v55, v55
	v_fmac_f32_e32 v90, v56, v56
	v_fmac_f32_e32 v92, v57, v57
	v_add_f32_e32 v9, v9, v91
	v_add_f32_e32 v90, v90, v92
	ds_bpermute_b32 v91, v3, v9
	ds_bpermute_b32 v92, v3, v90
	s_waitcnt lgkmcnt(0)
; DI unsigned pk2(float lo, float hi) { f32x2 v = {lo, hi}; bf16x2_t b = __builtin_convertvector(v, bf16x2_t); return __builtin_bit_cast(unsigned, b); }
; DI const float* modp(const Frame& F, int l, int mr, int which) { return (const float*)(F.ws + WS_MOD) + ((size_t)(l * 9 + mr) * 6 + which) * 1024; }
; DI void ln_row_v(const Frame& F, f32x4 (&v)[4], float* xout, const float* g, const float* b, const float* sh, const float* sc, bf16_t* hout, const float* slab, const float* gres, float* stat = nullptr) {
;     ...
;         float s = 0.f, s2 = 0.f;
; #pragma unroll
;         for (int j = 0; j < 4; ++j) { s += (v[j][0] + v[j][1]) + (v[j][2] + v[j][3]); s2 += (v[j][0] * v[j][0] + v[j][1] * v[j][1]) + (v[j][2] * v[j][2] + v[j][3] * v[j][3]); }
;         wave_sum2(s, s2, F.lane);
;         const float mean = s * (1.f / D); const float rstd = 1.f / sqrtf(fmaxf(s2 * (1.f / D) - mean * mean, 0.f) + EPS);
; #pragma unroll
;         for (int j = 0; j < 4; ++j) { const f32x4 hh = ((const f32x4*)sh)[F.lane + 64 * j], cc = ((const f32x4*)sc)[F.lane + 64 * j];
;             const f32x4 o = (v[j] - mean) * rstd * (cc + 1.f) + hh; u32x2 wv; wv.x = pk2(o[0], o[1]); wv.y = pk2(o[2], o[3]);
;             ((u32x2*)hout)[F.lane + 64 * j] = wv; }
; DI void prologue_b(const Frame& F) {
;     ...
;     for (int row = gw; row < MT; row += NGW) {
;         const int mr = row < ML ? (row >> 11) : 8;
;         const float* xi = row < ML ? pin(F, I_X) + (size_t)row * D : pin(F, I_CTX) + (size_t)(row - ML) * D;
;         ln_row(F, xi, nullptr, nullptr, nullptr, modp(F, 0, mr, 0), modp(F, 0, mr, 1), H + (size_t)row * D);
	v_add_f32_e32 v9, v9, v91
	v_add_f32_e32 v90, v90, v92
	ds_bpermute_b32 v91, v4, v9
	ds_bpermute_b32 v92, v4, v90
	s_waitcnt lgkmcnt(0)
	v_add_f32_e32 v9, v9, v91
	v_add_f32_e32 v90, v90, v92
	ds_bpermute_b32 v91, v5, v9
	ds_bpermute_b32 v92, v5, v90
	s_waitcnt lgkmcnt(0)
	v_add_f32_e32 v9, v9, v91
	v_add_f32_e32 v90, v90, v92
	ds_bpermute_b32 v91, v6, v9
	ds_bpermute_b32 v92, v6, v90
	s_waitcnt lgkmcnt(0)
	v_add_f32_e32 v9, v9, v91
	v_add_f32_e32 v90, v90, v92
	ds_bpermute_b32 v91, v7, v9
	ds_bpermute_b32 v92, v7, v90
	s_waitcnt lgkmcnt(0)
	v_add_f32_e32 v9, v9, v91
	v_add_f32_e32 v90, v90, v92
	ds_bpermute_b32 v91, v8, v9
	ds_bpermute_b32 v92, v8, v90
	s_waitcnt lgkmcnt(0)
	v_add_f32_e32 v9, v9, v91
	v_add_f32_e32 v90, v90, v92
	v_mul_f32_e32 v93, 0x3a800000, v9
	v_mul_f32_e32 v91, 0x3a800000, v90
	v_fma_f32 v91, -v93, v93, v91
	v_max_f32_e32 v91, 0, v91
	v_add_f32_e32 v91, 0x358637bd, v91
	v_rsq_f32_e32 v94, v91
	v_mul_f32_e32 v91, 0.5, v91
	v_mul_f32_e32 v92, v94, v94
	v_fma_f32 v92, -v91, v92, 0.5
	v_fma_f32 v94, v94, v92, v94
	v_sub_f32_e32 v42, v42, v93
	v_sub_f32_e32 v43, v43, v93
	v_sub_f32_e32 v44, v44, v93
	v_sub_f32_e32 v45, v45, v93
	v_sub_f32_e32 v46, v46, v93
	v_sub_f32_e32 v47, v47, v93
	v_sub_f32_e32 v48, v48, v93
	v_sub_f32_e32 v49, v49, v93
	v_sub_f32_e32 v50, v50, v93
	v_sub_f32_e32 v51, v51, v93
	v_sub_f32_e32 v52, v52, v93
	v_sub_f32_e32 v53, v53, v93
	v_sub_f32_e32 v54, v54, v93
	v_sub_f32_e32 v55, v55, v93
	v_sub_f32_e32 v56, v56, v93
	v_sub_f32_e32 v57, v57, v93
	v_add_f32_e32 v162, 1.0, v162
	v_add_f32_e32 v163, 1.0, v163
	v_add_f32_e32 v164, 1.0, v164
	v_add_f32_e32 v165, 1.0, v165
	v_add_f32_e32 v166, 1.0, v166
	v_add_f32_e32 v167, 1.0, v167
	v_add_f32_e32 v168, 1.0, v168
	v_add_f32_e32 v169, 1.0, v169
	v_add_f32_e32 v170, 1.0, v170
	v_add_f32_e32 v171, 1.0, v171
	v_add_f32_e32 v172, 1.0, v172
	v_add_f32_e32 v173, 1.0, v173
	v_add_f32_e32 v174, 1.0, v174
	v_add_f32_e32 v175, 1.0, v175
	v_add_f32_e32 v176, 1.0, v176
	v_add_f32_e32 v177, 1.0, v177
	v_mul_f32_e32 v42, v94, v42
	v_mul_f32_e32 v43, v94, v43
	v_mul_f32_e32 v44, v94, v44
	v_mul_f32_e32 v45, v94, v45
	v_mul_f32_e32 v46, v94, v46
	v_mul_f32_e32 v47, v94, v47
	v_mul_f32_e32 v48, v94, v48
	v_mul_f32_e32 v49, v94, v49
	v_mul_f32_e32 v50, v94, v50
	v_mul_f32_e32 v51, v94, v51
	v_mul_f32_e32 v52, v94, v52
	v_mul_f32_e32 v53, v94, v53
	v_mul_f32_e32 v54, v94, v54
	v_mul_f32_e32 v55, v94, v55
	v_mul_f32_e32 v56, v94, v56
	v_mul_f32_e32 v57, v94, v57
	v_fma_f32 v42, v42, v162, v146
	v_fma_f32 v43, v43, v163, v147
	v_fma_f32 v44, v44, v164, v148
	v_fma_f32 v45, v45, v165, v149
	v_fma_f32 v46, v46, v166, v150
	v_fma_f32 v47, v47, v167, v151
	v_fma_f32 v48, v48, v168, v152
	v_fma_f32 v49, v49, v169, v153
	v_fma_f32 v50, v50, v170, v154
	v_fma_f32 v51, v51, v171, v155
	v_fma_f32 v52, v52, v172, v156
	v_fma_f32 v53, v53, v173, v157
	v_fma_f32 v54, v54, v174, v158
	v_fma_f32 v55, v55, v175, v159
	v_fma_f32 v56, v56, v176, v160
	v_fma_f32 v57, v57, v177, v161
	v_cvt_pk_bf16_f32 v190, v42, v43
	v_cvt_pk_bf16_f32 v191, v44, v45
	v_cvt_pk_bf16_f32 v192, v46, v47
	v_cvt_pk_bf16_f32 v193, v48, v49
	v_cvt_pk_bf16_f32 v194, v50, v51
	v_cvt_pk_bf16_f32 v195, v52, v53
	v_cvt_pk_bf16_f32 v196, v54, v55
	v_cvt_pk_bf16_f32 v197, v56, v57
	s_lshl_b32 s2, s16, 11
	s_add_u32 s2, s94, s2
	s_addc_u32 s3, s95, 0
	s_add_u32 s2, s2, 0x5e00000
	s_addc_u32 s3, s3, 0
	global_store_dwordx2 v1, v[190:191], s[2:3]
	global_store_dwordx2 v1, v[192:193], s[2:3] offset:512
	global_store_dwordx2 v1, v[194:195], s[2:3] offset:1024
	global_store_dwordx2 v1, v[196:197], s[2:3] offset:1536
	s_waitcnt vmcnt(0)
	s_add_i32 s16, s16, 0x4800
	s_cmpk_gt_u32 s16, 0x47ff
	s_cbranch_scc1 .LBB0_671
	s_lshl_b64 s[2:3], s[44:45], 3
	s_add_u32 s4, s62, s2
	s_addc_u32 s5, s63, s3
	v_lshlrev_b32_e32 v0, 2, v186
	v_lshlrev_b32_e32 v96, 3, v186
	s_add_u32 s18, s94, 0x100000
	v_xor_b32_e32 v18, 4, v0
	v_xor_b32_e32 v19, 8, v0
	v_xor_b32_e32 v20, 16, v0
	v_xor_b32_e32 v21, 32, v0
	v_xor_b32_e32 v22, 64, v0
	v_xor_b32_e32 v23, 0x80, v0
	v_or_b32_e32 v0, 64, v186
	v_or_b32_e32 v2, 0x80, v186
	v_or_b32_e32 v4, 0xc0, v186
	v_lshl_add_u64 v[6:7], s[94:95], 0, v[96:97]
	s_mov_b64 s[2:3], 0x3e00000
	s_addc_u32 s19, s95, 0
	v_lshl_add_u64 v[16:17], v[6:7], 0, s[2:3]
	s_lshl_b32 s20, s93, 3
	s_lshl_b64 s[6:7], s[16:17], 12
	s_lshl_b32 s21, s93, 15
	v_lshlrev_b32_e32 v24, 4, v186
	v_lshlrev_b32_e32 v25, 4, v0
	v_lshlrev_b32_e32 v26, 4, v2
	v_lshlrev_b32_e32 v27, 4, v4
	s_mov_b64 s[8:9], s[16:17]
	s_branch .LBB0_668
